# all s_setprio toggles removed from the 7 GEMM K-loops (priority stays 0)
# speedup vs baseline: 1.0022x; 1.0010x over previous
; #define PG8_STAGE(bufoff, gbase, voff) do { _Pragma("unroll") for (int _i = 0; _i < 2; ++_i) \
;         __builtin_amdgcn_global_load_lds((const unsigned*)((const char*)(gbase) + (voff)[_i]), (PG8_LAS unsigned*)(lds + (bufoff) + ldsw + _i * 8192), 16, 0, 0); } while (0)
; #define PG8_LDA(dst, b, h) do { _Pragma("unroll") for (int m = 0; m < 4; ++m) _Pragma("unroll") for (int k = 0; k < 2; ++k) dst[m][k] = *(const PG8_LAS bf16x8*)(lds + PG8_SA(b, h) + aoff + m * 2048 + k * 1024); } while (0)
; #define PG8_LDB(dst, b, h) do { _Pragma("unroll") for (int n = 0; n < 2; ++n) _Pragma("unroll") for (int k = 0; k < 2; ++k) dst[n][k] = *(const PG8_LAS bf16x8*)(lds + PG8_SB(b, h) + boff + n * 2048 + k * 1024); } while (0)
; #define PG8_WAIT_V(n) asm volatile("s_waitcnt vmcnt(" #n ")" ::: "memory")
; #define PG8_WAIT_L(n) asm volatile("s_waitcnt lgkmcnt(" #n ")" ::: "memory")
; #define PG8_BAR __builtin_amdgcn_s_barrier()
; #define PG8_SCHED __builtin_amdgcn_sched_barrier(0)
; template <class Epi, class Sched, bool ALIGN_EPI = false, bool SP2 = false, bool I8 = false>
; __device__ __forceinline__ void gemm_phase(PG8_LAS unsigned char* lds, const Gemm g, const Sched& S, const Epi& E) {
;     ...
;         const char* nA = has_next ? (const char*)g.A + (size_t)nxt.pm * tstep : cA; const char* nB = has_next ? (const char*)g.Bt + (size_t)nxt.pn * tstep : cB;
;         for (int t = 0; t < nt; t += 2) {
;             const bool last = (t == nt - 2);
;             const char* a1 = cA + (size_t)(t + 1) * kstep;
;             const char* a2 = last ? nA : cA + (size_t)(t + 2) * kstep; const char* b2 = last ? nB : cB + (size_t)(t + 2) * kstep;
;             const char* a3 = a2 + kstep; const char* b3 = b2 + kstep;
;             if (last && has_next) S.a_ready(nxt);
;             if constexpr (SP2) {
;             PG8_LDB(B0, 0, 0); PG8_LDB(B1, 0, 1); PG8_SCHED; PG8_LDA(At, 0, 0); PG8_STAGE(PG8_SA(1, 1), a1 + hstep, voffA);
;             PG8_WAIT_V(8); PG8_WAIT_L(0); PG8_BAR; PG8_MMA(0, 0, At, B0); PG8_MMA(0, 1, At, B1); PG8_BAR; PG8_SCHED;
;             PG8_LDA(At, 0, 1); PG8_STAGE(PG8_SB(0, 0), b2, voffB); PG8_STAGE(PG8_SB(0, 1), b2 + hstep, voffB); PG8_STAGE(PG8_SA(0, 0), a2, voffA);
;             PG8_WAIT_V(8); PG8_WAIT_L(0); PG8_BAR; PG8_MMA(1, 0, At, B0); PG8_MMA(1, 1, At, B1); PG8_BAR; PG8_SCHED;
.LBB0_207:
	s_ashr_i32 s19, s18, 31
	s_lshl_b64 s[22:23], s[18:19], 20
	s_add_u32 s22, s28, s22
	s_addc_u32 s23, s34, s23
	s_and_b64 s[24:25], s[6:7], exec
	s_cselect_b32 s19, s23, s27
	s_cselect_b32 s64, s22, s26
	s_ashr_i32 s17, s16, 31
	s_lshl_b64 s[24:25], s[16:17], 20
	s_add_u32 s24, s35, s24
	s_addc_u32 s25, s42, s25
	s_and_b64 s[40:41], s[6:7], exec
	s_cselect_b32 s17, s25, s37
	s_cselect_b32 s65, s24, s36
	s_add_u32 s26, s26, 0x80080
	s_addc_u32 s27, s27, 0
	s_add_u32 s72, s36, 0x100
	s_addc_u32 s73, s37, 0
	s_mov_b32 s76, -2
	s_add_u32 s36, s26, 0xfff80080
	s_addc_u32 s37, s27, -1
	s_add_i32 s50, 0, 0x10000
	s_cmp_eq_u32 s76, 28
	s_cselect_b32 s41, s19, s37
	s_cselect_b32 s40, s64, s36
	s_cselect_b32 s37, s17, s73
	s_cselect_b32 s36, s65, s72
	s_add_i32 s56, 0, 0x14000
	v_add_u32_e32 v136, s50, v175
	v_add_u32_e32 v172, s56, v175
	ds_read_b128 v[116:119], v136
	ds_read_b128 v[124:127], v136 offset:1024
	ds_read_b128 v[132:135], v136 offset:2048
	ds_read_b128 v[136:139], v136 offset:3072
	ds_read_b128 v[160:163], v172
	ds_read_b128 v[164:167], v172 offset:1024
	ds_read_b128 v[168:171], v172 offset:2048
	ds_read_b128 v[178:181], v172 offset:3072
	v_lshl_add_u64 v[172:173], s[26:27], 0, v[156:157]
	s_add_i32 m0, s44, 0xc000
	ds_read_b128 v[182:185], v177
	ds_read_b128 v[186:189], v177 offset:1024
	ds_read_b128 v[204:207], v177 offset:2048
	ds_read_b128 v[208:211], v177 offset:3072
	ds_read_b128 v[212:215], v177 offset:4096
	ds_read_b128 v[216:219], v177 offset:5120
	ds_read_b128 v[220:223], v177 offset:6144
	ds_read_b128 v[224:227], v177 offset:7168
	global_load_lds_dwordx4 v[172:173], off
	v_lshl_add_u64 v[172:173], s[26:27], 0, v[158:159]
	s_add_i32 m0, s44, 0xe000
	s_nop 0
	global_load_lds_dwordx4 v[172:173], off
	s_waitcnt vmcnt(8)
	s_waitcnt lgkmcnt(0)
	s_barrier
	s_waitcnt lgkmcnt(0)
	v_mfma_i32_16x16x64_i8 v[144:147], v[116:119], v[182:185], 0
	v_mfma_i32_16x16x64_i8 v[144:147], v[124:127], v[186:189], v[144:147]
	v_mfma_i32_16x16x64_i8 v[112:115], v[124:127], v[208:211], 0
	v_mfma_i32_16x16x64_i8 v[112:115], v[116:119], v[204:207], v[112:115]
	v_mfma_i32_16x16x64_i8 v[96:99], v[116:119], v[212:215], 0
	v_mfma_i32_16x16x64_i8 v[96:99], v[124:127], v[216:219], v[96:99]
	v_mfma_i32_16x16x64_i8 v[80:83], v[124:127], v[224:227], 0
	v_mfma_i32_16x16x64_i8 v[80:83], v[116:119], v[220:223], v[80:83]
	v_mfma_i32_16x16x64_i8 v[76:79], v[132:135], v[220:223], 0
	v_mfma_i32_16x16x64_i8 v[76:79], v[136:139], v[224:227], v[76:79]
	v_mfma_i32_16x16x64_i8 v[92:95], v[136:139], v[216:219], 0
	v_mfma_i32_16x16x64_i8 v[92:95], v[132:135], v[212:215], v[92:95]
	v_mfma_i32_16x16x64_i8 v[108:111], v[132:135], v[204:207], 0
	v_mfma_i32_16x16x64_i8 v[108:111], v[136:139], v[208:211], v[108:111]
	v_mfma_i32_16x16x64_i8 v[140:143], v[136:139], v[186:189], 0
	v_mfma_i32_16x16x64_i8 v[140:143], v[132:135], v[182:185], v[140:143]
	v_mfma_i32_16x16x64_i8 v[128:131], v[160:163], v[182:185], 0
	v_mfma_i32_16x16x64_i8 v[128:131], v[164:167], v[186:189], v[128:131]
	v_mfma_i32_16x16x64_i8 v[104:107], v[164:167], v[208:211], 0
	v_mfma_i32_16x16x64_i8 v[104:107], v[160:163], v[204:207], v[104:107]
	v_mfma_i32_16x16x64_i8 v[88:91], v[160:163], v[212:215], 0
	v_mfma_i32_16x16x64_i8 v[88:91], v[164:167], v[216:219], v[88:91]
	v_mfma_i32_16x16x64_i8 v[72:75], v[164:167], v[224:227], 0
	v_mfma_i32_16x16x64_i8 v[72:75], v[160:163], v[220:223], v[72:75]
	v_mfma_i32_16x16x64_i8 v[68:71], v[168:171], v[220:223], 0
	v_mfma_i32_16x16x64_i8 v[68:71], v[178:181], v[224:227], v[68:71]
	v_mfma_i32_16x16x64_i8 v[84:87], v[178:181], v[216:219], 0
	v_mfma_i32_16x16x64_i8 v[84:87], v[168:171], v[212:215], v[84:87]
	v_mfma_i32_16x16x64_i8 v[100:103], v[168:171], v[204:207], 0
	v_mfma_i32_16x16x64_i8 v[100:103], v[178:181], v[208:211], v[100:103]
	v_mfma_i32_16x16x64_i8 v[120:123], v[178:181], v[186:189], 0
	v_mfma_i32_16x16x64_i8 v[120:123], v[168:171], v[182:185], v[120:123]
	s_barrier
	s_add_i32 s50, s50, s43
	v_lshl_add_u64 v[172:173], s[36:37], 0, v[2:3]
	s_mov_b32 m0, s50
	ds_read_b128 v[182:185], v177 offset:16384
	ds_read_b128 v[186:189], v177 offset:17408
	ds_read_b128 v[204:207], v177 offset:18432
	ds_read_b128 v[208:211], v177 offset:19456
	ds_read_b128 v[212:215], v177 offset:20480
	ds_read_b128 v[216:219], v177 offset:21504
	ds_read_b128 v[220:223], v177 offset:22528
	ds_read_b128 v[224:227], v177 offset:23552
	global_load_lds_dwordx4 v[172:173], off
	s_add_i32 m0, s50, 0x2000
	s_add_u32 s50, s36, 0x80000
	v_lshl_add_u64 v[190:191], s[36:37], 0, v[148:149]
	s_addc_u32 s51, s37, 0
	s_add_i32 s56, s56, s43
	global_load_lds_dwordx4 v[190:191], off
	v_lshl_add_u64 v[228:229], s[50:51], 0, v[2:3]
	s_mov_b32 m0, s56
	v_lshl_add_u64 v[240:241], s[40:41], 0, v[150:151]
	global_load_lds_dwordx4 v[228:229], off
	v_lshl_add_u64 v[228:229], s[50:51], 0, v[148:149]
	s_add_i32 m0, s56, 0x2000
	s_nop 0
	global_load_lds_dwordx4 v[228:229], off
	v_lshl_add_u64 v[228:229], s[40:41], 0, v[152:153]
	s_mov_b32 m0, s44
	s_nop 0
	global_load_lds_dwordx4 v[228:229], off
	s_mov_b32 m0, s45
	s_nop 0
	global_load_lds_dwordx4 v[240:241], off
	s_waitcnt vmcnt(8)
	s_waitcnt lgkmcnt(0)
	s_barrier
; #define PG8_STAGE(bufoff, gbase, voff) do { _Pragma("unroll") for (int _i = 0; _i < 2; ++_i) \
;         __builtin_amdgcn_global_load_lds((const unsigned*)((const char*)(gbase) + (voff)[_i]), (PG8_LAS unsigned*)(lds + (bufoff) + ldsw + _i * 8192), 16, 0, 0); } while (0)
; #define PG8_LDA(dst, b, h) do { _Pragma("unroll") for (int m = 0; m < 4; ++m) _Pragma("unroll") for (int k = 0; k < 2; ++k) dst[m][k] = *(const PG8_LAS bf16x8*)(lds + PG8_SA(b, h) + aoff + m * 2048 + k * 1024); } while (0)
; #define PG8_LDB(dst, b, h) do { _Pragma("unroll") for (int n = 0; n < 2; ++n) _Pragma("unroll") for (int k = 0; k < 2; ++k) dst[n][k] = *(const PG8_LAS bf16x8*)(lds + PG8_SB(b, h) + boff + n * 2048 + k * 1024); } while (0)
; #define PG8_WAIT_V(n) asm volatile("s_waitcnt vmcnt(" #n ")" ::: "memory")
; #define PG8_WAIT_L(n) asm volatile("s_waitcnt lgkmcnt(" #n ")" ::: "memory")
; #define PG8_BAR __builtin_amdgcn_s_barrier()
; #define PG8_SCHED __builtin_amdgcn_sched_barrier(0)
; template <class Epi, class Sched, bool ALIGN_EPI = false, bool SP2 = false, bool I8 = false>
; __device__ __forceinline__ void gemm_phase(PG8_LAS unsigned char* lds, const Gemm g, const Sched& S, const Epi& E) {
;     ...
;             PG8_WAIT_V(8); PG8_WAIT_L(0); PG8_BAR; PG8_MMA(0, 0, At, B0); PG8_MMA(0, 1, At, B1); PG8_BAR; PG8_SCHED;
;             PG8_LDA(At, 0, 1); PG8_STAGE(PG8_SB(0, 0), b2, voffB); PG8_STAGE(PG8_SB(0, 1), b2 + hstep, voffB); PG8_STAGE(PG8_SA(0, 0), a2, voffA);
;             PG8_WAIT_V(8); PG8_WAIT_L(0); PG8_BAR; PG8_MMA(1, 0, At, B0); PG8_MMA(1, 1, At, B1); PG8_BAR; PG8_SCHED;
;             PG8_LDB(B0, 1, 0); PG8_LDB(B1, 1, 1); PG8_SCHED; PG8_LDA(At, 1, 0); PG8_STAGE(PG8_SA(0, 1), a2 + hstep, voffA);
;             PG8_WAIT_V(8); PG8_WAIT_L(0); PG8_BAR; PG8_MMA(0, 0, At, B0); PG8_MMA(0, 1, At, B1); PG8_BAR; PG8_SCHED;
	s_waitcnt lgkmcnt(0)
	v_mfma_i32_16x16x64_i8 v[64:67], v[116:119], v[182:185], 0
	v_mfma_i32_16x16x64_i8 v[64:67], v[124:127], v[186:189], v[64:67]
	v_mfma_i32_16x16x64_i8 v[48:51], v[124:127], v[208:211], 0
	v_mfma_i32_16x16x64_i8 v[48:51], v[116:119], v[204:207], v[48:51]
	v_mfma_i32_16x16x64_i8 v[32:35], v[116:119], v[212:215], 0
	v_mfma_i32_16x16x64_i8 v[32:35], v[124:127], v[216:219], v[32:35]
	v_mfma_i32_16x16x64_i8 v[16:19], v[124:127], v[224:227], 0
	v_mfma_i32_16x16x64_i8 v[16:19], v[116:119], v[220:223], v[16:19]
	v_mfma_i32_16x16x64_i8 v[12:15], v[132:135], v[220:223], 0
	v_mfma_i32_16x16x64_i8 v[12:15], v[136:139], v[224:227], v[12:15]
	v_mfma_i32_16x16x64_i8 v[28:31], v[136:139], v[216:219], 0
	v_mfma_i32_16x16x64_i8 v[28:31], v[132:135], v[212:215], v[28:31]
	v_mfma_i32_16x16x64_i8 v[44:47], v[132:135], v[204:207], 0
	v_mfma_i32_16x16x64_i8 v[44:47], v[136:139], v[208:211], v[44:47]
	v_mfma_i32_16x16x64_i8 v[60:63], v[136:139], v[186:189], 0
	v_mfma_i32_16x16x64_i8 v[60:63], v[132:135], v[182:185], v[60:63]
	v_mfma_i32_16x16x64_i8 v[56:59], v[160:163], v[182:185], 0
	v_mfma_i32_16x16x64_i8 v[56:59], v[164:167], v[186:189], v[56:59]
	v_mfma_i32_16x16x64_i8 v[40:43], v[164:167], v[208:211], 0
	v_mfma_i32_16x16x64_i8 v[40:43], v[160:163], v[204:207], v[40:43]
	v_mfma_i32_16x16x64_i8 v[24:27], v[160:163], v[212:215], 0
	v_mfma_i32_16x16x64_i8 v[24:27], v[164:167], v[216:219], v[24:27]
	v_mfma_i32_16x16x64_i8 v[8:11], v[164:167], v[224:227], 0
	v_mfma_i32_16x16x64_i8 v[8:11], v[160:163], v[220:223], v[8:11]
	v_mfma_i32_16x16x64_i8 v[4:7], v[168:171], v[220:223], 0
	v_mfma_i32_16x16x64_i8 v[4:7], v[178:181], v[224:227], v[4:7]
	v_mfma_i32_16x16x64_i8 v[20:23], v[178:181], v[216:219], 0
	v_mfma_i32_16x16x64_i8 v[20:23], v[168:171], v[212:215], v[20:23]
	v_mfma_i32_16x16x64_i8 v[36:39], v[168:171], v[204:207], 0
	v_mfma_i32_16x16x64_i8 v[36:39], v[178:181], v[208:211], v[36:39]
	v_mfma_i32_16x16x64_i8 v[52:55], v[178:181], v[186:189], 0
	v_mfma_i32_16x16x64_i8 v[52:55], v[168:171], v[182:185], v[52:55]
	s_barrier
	s_add_i32 s50, 0, 0x18000
	s_add_i32 s51, 0, 0x1c000
	v_add_u32_e32 v136, s50, v175
	v_add_u32_e32 v178, s51, v175
	ds_read_b128 v[116:119], v136
	ds_read_b128 v[124:127], v136 offset:1024
	ds_read_b128 v[132:135], v136 offset:2048
	ds_read_b128 v[136:139], v136 offset:3072
	ds_read_b128 v[160:163], v178
	ds_read_b128 v[164:167], v178 offset:1024
	ds_read_b128 v[168:171], v178 offset:2048
	ds_read_b128 v[178:181], v178 offset:3072
	s_add_u32 s40, s40, 0x80000
	s_addc_u32 s41, s41, 0
	s_mov_b32 m0, s46
	v_lshl_add_u64 v[242:243], s[40:41], 0, v[152:153]
	ds_read_b128 v[182:185], v177 offset:32768
	ds_read_b128 v[186:189], v177 offset:33792
	ds_read_b128 v[204:207], v177 offset:34816
	ds_read_b128 v[208:211], v177 offset:35840
	ds_read_b128 v[212:215], v177 offset:36864
	ds_read_b128 v[216:219], v177 offset:37888
	ds_read_b128 v[220:223], v177 offset:38912
	ds_read_b128 v[224:227], v177 offset:39936
	global_load_lds_dwordx4 v[242:243], off
	v_lshl_add_u64 v[242:243], s[40:41], 0, v[150:151]
	s_mov_b32 m0, s47
	s_nop 0
	global_load_lds_dwordx4 v[242:243], off
	s_waitcnt vmcnt(8)
	s_waitcnt lgkmcnt(0)
	s_barrier
	s_waitcnt lgkmcnt(0)
	v_mfma_i32_16x16x64_i8 v[144:147], v[116:119], v[182:185], v[144:147]
	v_mfma_i32_16x16x64_i8 v[144:147], v[124:127], v[186:189], v[144:147]
	v_mfma_i32_16x16x64_i8 v[112:115], v[124:127], v[208:211], v[112:115]
	v_mfma_i32_16x16x64_i8 v[112:115], v[116:119], v[204:207], v[112:115]
	v_mfma_i32_16x16x64_i8 v[96:99], v[116:119], v[212:215], v[96:99]
	v_mfma_i32_16x16x64_i8 v[96:99], v[124:127], v[216:219], v[96:99]
	v_mfma_i32_16x16x64_i8 v[80:83], v[124:127], v[224:227], v[80:83]
	v_mfma_i32_16x16x64_i8 v[80:83], v[116:119], v[220:223], v[80:83]
	v_mfma_i32_16x16x64_i8 v[76:79], v[132:135], v[220:223], v[76:79]
	v_mfma_i32_16x16x64_i8 v[76:79], v[136:139], v[224:227], v[76:79]
	v_mfma_i32_16x16x64_i8 v[92:95], v[136:139], v[216:219], v[92:95]
	v_mfma_i32_16x16x64_i8 v[92:95], v[132:135], v[212:215], v[92:95]
	v_mfma_i32_16x16x64_i8 v[108:111], v[132:135], v[204:207], v[108:111]
	v_mfma_i32_16x16x64_i8 v[108:111], v[136:139], v[208:211], v[108:111]
	v_mfma_i32_16x16x64_i8 v[140:143], v[136:139], v[186:189], v[140:143]
	v_mfma_i32_16x16x64_i8 v[140:143], v[132:135], v[182:185], v[140:143]
	v_mfma_i32_16x16x64_i8 v[128:131], v[160:163], v[182:185], v[128:131]
	v_mfma_i32_16x16x64_i8 v[128:131], v[164:167], v[186:189], v[128:131]
	v_mfma_i32_16x16x64_i8 v[104:107], v[164:167], v[208:211], v[104:107]
	v_mfma_i32_16x16x64_i8 v[104:107], v[160:163], v[204:207], v[104:107]
	v_mfma_i32_16x16x64_i8 v[88:91], v[160:163], v[212:215], v[88:91]
	v_mfma_i32_16x16x64_i8 v[88:91], v[164:167], v[216:219], v[88:91]
	v_mfma_i32_16x16x64_i8 v[72:75], v[164:167], v[224:227], v[72:75]
	v_mfma_i32_16x16x64_i8 v[72:75], v[160:163], v[220:223], v[72:75]
	v_mfma_i32_16x16x64_i8 v[68:71], v[168:171], v[220:223], v[68:71]
	v_mfma_i32_16x16x64_i8 v[68:71], v[178:181], v[224:227], v[68:71]
	v_mfma_i32_16x16x64_i8 v[84:87], v[178:181], v[216:219], v[84:87]
	v_mfma_i32_16x16x64_i8 v[84:87], v[168:171], v[212:215], v[84:87]
	v_mfma_i32_16x16x64_i8 v[100:103], v[168:171], v[204:207], v[100:103]
	v_mfma_i32_16x16x64_i8 v[100:103], v[178:181], v[208:211], v[100:103]
	v_mfma_i32_16x16x64_i8 v[120:123], v[178:181], v[186:189], v[120:123]
	v_mfma_i32_16x16x64_i8 v[120:123], v[168:171], v[182:185], v[120:123]
	s_barrier
; #define PG8_STAGE(bufoff, gbase, voff) do { _Pragma("unroll") for (int _i = 0; _i < 2; ++_i) \
;         __builtin_amdgcn_global_load_lds((const unsigned*)((const char*)(gbase) + (voff)[_i]), (PG8_LAS unsigned*)(lds + (bufoff) + ldsw + _i * 8192), 16, 0, 0); } while (0)
; #define PG8_LDA(dst, b, h) do { _Pragma("unroll") for (int m = 0; m < 4; ++m) _Pragma("unroll") for (int k = 0; k < 2; ++k) dst[m][k] = *(const PG8_LAS bf16x8*)(lds + PG8_SA(b, h) + aoff + m * 2048 + k * 1024); } while (0)
; #define PG8_LDB(dst, b, h) do { _Pragma("unroll") for (int n = 0; n < 2; ++n) _Pragma("unroll") for (int k = 0; k < 2; ++k) dst[n][k] = *(const PG8_LAS bf16x8*)(lds + PG8_SB(b, h) + boff + n * 2048 + k * 1024); } while (0)
; #define PG8_WAIT_V(n) asm volatile("s_waitcnt vmcnt(" #n ")" ::: "memory")
; #define PG8_WAIT_L(n) asm volatile("s_waitcnt lgkmcnt(" #n ")" ::: "memory")
; #define PG8_BAR __builtin_amdgcn_s_barrier()
; #define PG8_SCHED __builtin_amdgcn_sched_barrier(0)
; template <class Epi, class Sched, bool ALIGN_EPI = false, bool SP2 = false, bool I8 = false>
; __device__ __forceinline__ void gemm_phase(PG8_LAS unsigned char* lds, const Gemm g, const Sched& S, const Epi& E) {
;     ...
;             const bool last = (t == nt - 2);
;             const char* a1 = cA + (size_t)(t + 1) * kstep;
;             const char* a2 = last ? nA : cA + (size_t)(t + 2) * kstep; const char* b2 = last ? nB : cB + (size_t)(t + 2) * kstep;
;             const char* a3 = a2 + kstep; const char* b3 = b2 + kstep;
;             if (last && has_next) S.a_ready(nxt);
;             if constexpr (SP2) {
;             PG8_LDB(B0, 0, 0); PG8_LDB(B1, 0, 1); PG8_SCHED; PG8_LDA(At, 0, 0); PG8_STAGE(PG8_SA(1, 1), a1 + hstep, voffA);
;             PG8_WAIT_V(8); PG8_WAIT_L(0); PG8_BAR; PG8_MMA(0, 0, At, B0); PG8_MMA(0, 1, At, B1); PG8_BAR; PG8_SCHED;
;     ...
;             PG8_LDA(At, 1, 1); PG8_STAGE(PG8_SB(1, 0), b3, voffB); PG8_STAGE(PG8_SB(1, 1), b3 + hstep, voffB); PG8_STAGE(PG8_SA(1, 0), a3, voffA);
;             PG8_WAIT_V(8); PG8_WAIT_L(0); PG8_BAR; PG8_MMA(1, 0, At, B0); PG8_MMA(1, 1, At, B1); PG8_BAR; PG8_SCHED;
	s_add_i32 s40, s50, s43
	v_lshl_add_u64 v[172:173], v[172:173], 0, s[84:85]
	s_mov_b32 m0, s40
	ds_read_b128 v[182:185], v177 offset:49152
	ds_read_b128 v[186:189], v177 offset:50176
	ds_read_b128 v[204:207], v177 offset:51200
	ds_read_b128 v[208:211], v177 offset:52224
	ds_read_b128 v[212:215], v177 offset:53248
	ds_read_b128 v[216:219], v177 offset:54272
	ds_read_b128 v[220:223], v177 offset:55296
	ds_read_b128 v[224:227], v177 offset:56320
	global_load_lds_dwordx4 v[172:173], off
	s_add_i32 m0, s40, 0x2000
	s_add_u32 s36, s36, 0x80080
	v_lshl_add_u64 v[172:173], v[190:191], 0, s[84:85]
	s_addc_u32 s37, s37, 0
	s_add_i32 s40, s51, s43
	global_load_lds_dwordx4 v[172:173], off
	v_lshl_add_u64 v[172:173], s[36:37], 0, v[2:3]
	s_mov_b32 m0, s40
	s_nop 0
	global_load_lds_dwordx4 v[172:173], off
	v_lshl_add_u64 v[172:173], s[36:37], 0, v[148:149]
	s_add_i32 m0, s40, 0x2000
	s_nop 0
	global_load_lds_dwordx4 v[172:173], off
	v_lshl_add_u64 v[172:173], v[228:229], 0, s[84:85]
	s_mov_b32 m0, s52
	s_nop 0
	global_load_lds_dwordx4 v[172:173], off
	v_lshl_add_u64 v[172:173], v[240:241], 0, s[84:85]
	s_mov_b32 m0, s53
	s_nop 0
	global_load_lds_dwordx4 v[172:173], off
	s_waitcnt vmcnt(8)
	s_waitcnt lgkmcnt(0)
	s_barrier
	s_waitcnt lgkmcnt(0)
	v_mfma_i32_16x16x64_i8 v[64:67], v[116:119], v[182:185], v[64:67]
	v_mfma_i32_16x16x64_i8 v[64:67], v[124:127], v[186:189], v[64:67]
	v_mfma_i32_16x16x64_i8 v[48:51], v[124:127], v[208:211], v[48:51]
	v_mfma_i32_16x16x64_i8 v[48:51], v[116:119], v[204:207], v[48:51]
	v_mfma_i32_16x16x64_i8 v[32:35], v[116:119], v[212:215], v[32:35]
	v_mfma_i32_16x16x64_i8 v[32:35], v[124:127], v[216:219], v[32:35]
	v_mfma_i32_16x16x64_i8 v[16:19], v[124:127], v[224:227], v[16:19]
	v_mfma_i32_16x16x64_i8 v[16:19], v[116:119], v[220:223], v[16:19]
	v_mfma_i32_16x16x64_i8 v[12:15], v[132:135], v[220:223], v[12:15]
	v_mfma_i32_16x16x64_i8 v[12:15], v[136:139], v[224:227], v[12:15]
	v_mfma_i32_16x16x64_i8 v[28:31], v[136:139], v[216:219], v[28:31]
	v_mfma_i32_16x16x64_i8 v[28:31], v[132:135], v[212:215], v[28:31]
	v_mfma_i32_16x16x64_i8 v[44:47], v[132:135], v[204:207], v[44:47]
	v_mfma_i32_16x16x64_i8 v[44:47], v[136:139], v[208:211], v[44:47]
	v_mfma_i32_16x16x64_i8 v[60:63], v[136:139], v[186:189], v[60:63]
	v_mfma_i32_16x16x64_i8 v[60:63], v[132:135], v[182:185], v[60:63]
	v_mfma_i32_16x16x64_i8 v[56:59], v[160:163], v[182:185], v[56:59]
	v_mfma_i32_16x16x64_i8 v[56:59], v[164:167], v[186:189], v[56:59]
	v_mfma_i32_16x16x64_i8 v[40:43], v[164:167], v[208:211], v[40:43]
	v_mfma_i32_16x16x64_i8 v[40:43], v[160:163], v[204:207], v[40:43]
	v_mfma_i32_16x16x64_i8 v[24:27], v[160:163], v[212:215], v[24:27]
	v_mfma_i32_16x16x64_i8 v[24:27], v[164:167], v[216:219], v[24:27]
	v_mfma_i32_16x16x64_i8 v[8:11], v[164:167], v[224:227], v[8:11]
	v_mfma_i32_16x16x64_i8 v[8:11], v[160:163], v[220:223], v[8:11]
	v_mfma_i32_16x16x64_i8 v[4:7], v[168:171], v[220:223], v[4:7]
	v_mfma_i32_16x16x64_i8 v[4:7], v[178:181], v[224:227], v[4:7]
	v_mfma_i32_16x16x64_i8 v[20:23], v[178:181], v[216:219], v[20:23]
	v_mfma_i32_16x16x64_i8 v[20:23], v[168:171], v[212:215], v[20:23]
	v_mfma_i32_16x16x64_i8 v[36:39], v[168:171], v[204:207], v[36:39]
	v_mfma_i32_16x16x64_i8 v[36:39], v[178:181], v[208:211], v[36:39]
	v_mfma_i32_16x16x64_i8 v[52:55], v[178:181], v[186:189], v[52:55]
	v_mfma_i32_16x16x64_i8 v[52:55], v[168:171], v[182:185], v[52:55]
	s_barrier
	s_add_i32 s76, s76, 2
	s_add_u32 s26, s26, 0x100
	s_addc_u32 s27, s27, 0
	s_add_u32 s72, s72, 0x100
	s_addc_u32 s73, s73, 0
	s_cmp_gt_u32 s76, 29
	s_cbranch_scc1 .Lkloop_exit_0
.LBB0_208:
	s_add_u32 s36, s26, 0xfff80080
	s_addc_u32 s37, s27, -1
	s_add_i32 s50, 0, 0x10000
	s_cmp_eq_u32 s76, 28
	s_cselect_b32 s41, s19, s37
	s_cselect_b32 s40, s64, s36
	s_cselect_b32 s37, s17, s73
	s_cselect_b32 s36, s65, s72
	s_add_i32 s56, 0, 0x14000
	v_add_u32_e32 v136, s50, v175
	v_add_u32_e32 v172, s56, v175
	ds_read_b128 v[116:119], v136
	ds_read_b128 v[124:127], v136 offset:1024
	ds_read_b128 v[132:135], v136 offset:2048
	ds_read_b128 v[136:139], v136 offset:3072
	ds_read_b128 v[160:163], v172
	ds_read_b128 v[164:167], v172 offset:1024
	ds_read_b128 v[168:171], v172 offset:2048
	ds_read_b128 v[178:181], v172 offset:3072
	v_lshl_add_u64 v[172:173], s[26:27], 0, v[156:157]
	s_add_i32 m0, s44, 0xc000
	ds_read_b128 v[182:185], v177
	ds_read_b128 v[186:189], v177 offset:1024
	ds_read_b128 v[204:207], v177 offset:2048
	ds_read_b128 v[208:211], v177 offset:3072
	ds_read_b128 v[212:215], v177 offset:4096
	ds_read_b128 v[216:219], v177 offset:5120
	ds_read_b128 v[220:223], v177 offset:6144
	ds_read_b128 v[224:227], v177 offset:7168
	global_load_lds_dwordx4 v[172:173], off
	v_lshl_add_u64 v[172:173], s[26:27], 0, v[158:159]
	s_add_i32 m0, s44, 0xe000
	s_nop 0
	global_load_lds_dwordx4 v[172:173], off
	s_waitcnt vmcnt(8)
	s_waitcnt lgkmcnt(0)
	s_barrier
; #define PG8_STAGE(bufoff, gbase, voff) do { _Pragma("unroll") for (int _i = 0; _i < 2; ++_i) \
;         __builtin_amdgcn_global_load_lds((const unsigned*)((const char*)(gbase) + (voff)[_i]), (PG8_LAS unsigned*)(lds + (bufoff) + ldsw + _i * 8192), 16, 0, 0); } while (0)
; #define PG8_LDA(dst, b, h) do { _Pragma("unroll") for (int m = 0; m < 4; ++m) _Pragma("unroll") for (int k = 0; k < 2; ++k) dst[m][k] = *(const PG8_LAS bf16x8*)(lds + PG8_SA(b, h) + aoff + m * 2048 + k * 1024); } while (0)
; #define PG8_WAIT_V(n) asm volatile("s_waitcnt vmcnt(" #n ")" ::: "memory")
; #define PG8_WAIT_L(n) asm volatile("s_waitcnt lgkmcnt(" #n ")" ::: "memory")
; #define PG8_BAR __builtin_amdgcn_s_barrier()
; #define PG8_SCHED __builtin_amdgcn_sched_barrier(0)
; template <class Epi, class Sched, bool ALIGN_EPI = false, bool SP2 = false, bool I8 = false>
; __device__ __forceinline__ void gemm_phase(PG8_LAS unsigned char* lds, const Gemm g, const Sched& S, const Epi& E) {
;     ...
;             PG8_WAIT_V(8); PG8_WAIT_L(0); PG8_BAR; PG8_MMA(0, 0, At, B0); PG8_MMA(0, 1, At, B1); PG8_BAR; PG8_SCHED;
;             PG8_LDA(At, 0, 1); PG8_STAGE(PG8_SB(0, 0), b2, voffB); PG8_STAGE(PG8_SB(0, 1), b2 + hstep, voffB); PG8_STAGE(PG8_SA(0, 0), a2, voffA);
;             PG8_WAIT_V(8); PG8_WAIT_L(0); PG8_BAR; PG8_MMA(1, 0, At, B0); PG8_MMA(1, 1, At, B1); PG8_BAR; PG8_SCHED;
	s_waitcnt lgkmcnt(0)
	v_mfma_i32_16x16x64_i8 v[144:147], v[116:119], v[182:185], v[144:147]
	v_mfma_i32_16x16x64_i8 v[144:147], v[124:127], v[186:189], v[144:147]
	v_mfma_i32_16x16x64_i8 v[112:115], v[124:127], v[208:211], v[112:115]
	v_mfma_i32_16x16x64_i8 v[112:115], v[116:119], v[204:207], v[112:115]
	v_mfma_i32_16x16x64_i8 v[96:99], v[116:119], v[212:215], v[96:99]
	v_mfma_i32_16x16x64_i8 v[96:99], v[124:127], v[216:219], v[96:99]
	v_mfma_i32_16x16x64_i8 v[80:83], v[124:127], v[224:227], v[80:83]
	v_mfma_i32_16x16x64_i8 v[80:83], v[116:119], v[220:223], v[80:83]
	v_mfma_i32_16x16x64_i8 v[76:79], v[132:135], v[220:223], v[76:79]
	v_mfma_i32_16x16x64_i8 v[76:79], v[136:139], v[224:227], v[76:79]
	v_mfma_i32_16x16x64_i8 v[92:95], v[136:139], v[216:219], v[92:95]
	v_mfma_i32_16x16x64_i8 v[92:95], v[132:135], v[212:215], v[92:95]
	v_mfma_i32_16x16x64_i8 v[108:111], v[132:135], v[204:207], v[108:111]
	v_mfma_i32_16x16x64_i8 v[108:111], v[136:139], v[208:211], v[108:111]
	v_mfma_i32_16x16x64_i8 v[140:143], v[136:139], v[186:189], v[140:143]
	v_mfma_i32_16x16x64_i8 v[140:143], v[132:135], v[182:185], v[140:143]
	v_mfma_i32_16x16x64_i8 v[128:131], v[160:163], v[182:185], v[128:131]
	v_mfma_i32_16x16x64_i8 v[128:131], v[164:167], v[186:189], v[128:131]
	v_mfma_i32_16x16x64_i8 v[104:107], v[164:167], v[208:211], v[104:107]
	v_mfma_i32_16x16x64_i8 v[104:107], v[160:163], v[204:207], v[104:107]
	v_mfma_i32_16x16x64_i8 v[88:91], v[160:163], v[212:215], v[88:91]
	v_mfma_i32_16x16x64_i8 v[88:91], v[164:167], v[216:219], v[88:91]
	v_mfma_i32_16x16x64_i8 v[72:75], v[164:167], v[224:227], v[72:75]
	v_mfma_i32_16x16x64_i8 v[72:75], v[160:163], v[220:223], v[72:75]
	v_mfma_i32_16x16x64_i8 v[68:71], v[168:171], v[220:223], v[68:71]
	v_mfma_i32_16x16x64_i8 v[68:71], v[178:181], v[224:227], v[68:71]
	v_mfma_i32_16x16x64_i8 v[84:87], v[178:181], v[216:219], v[84:87]
	v_mfma_i32_16x16x64_i8 v[84:87], v[168:171], v[212:215], v[84:87]
	v_mfma_i32_16x16x64_i8 v[100:103], v[168:171], v[204:207], v[100:103]
	v_mfma_i32_16x16x64_i8 v[100:103], v[178:181], v[208:211], v[100:103]
	v_mfma_i32_16x16x64_i8 v[120:123], v[178:181], v[186:189], v[120:123]
	v_mfma_i32_16x16x64_i8 v[120:123], v[168:171], v[182:185], v[120:123]
	s_barrier
	s_add_i32 s50, s50, s43
	v_lshl_add_u64 v[172:173], s[36:37], 0, v[2:3]
	s_mov_b32 m0, s50
	ds_read_b128 v[182:185], v177 offset:16384
	ds_read_b128 v[186:189], v177 offset:17408
	ds_read_b128 v[204:207], v177 offset:18432
	ds_read_b128 v[208:211], v177 offset:19456
	ds_read_b128 v[212:215], v177 offset:20480
	ds_read_b128 v[216:219], v177 offset:21504
	ds_read_b128 v[220:223], v177 offset:22528
	ds_read_b128 v[224:227], v177 offset:23552
	global_load_lds_dwordx4 v[172:173], off
	s_add_i32 m0, s50, 0x2000
	s_add_u32 s50, s36, 0x80000
	v_lshl_add_u64 v[190:191], s[36:37], 0, v[148:149]
	s_addc_u32 s51, s37, 0
	s_add_i32 s56, s56, s43
	global_load_lds_dwordx4 v[190:191], off
	v_lshl_add_u64 v[228:229], s[50:51], 0, v[2:3]
	s_mov_b32 m0, s56
	v_lshl_add_u64 v[240:241], s[40:41], 0, v[150:151]
	global_load_lds_dwordx4 v[228:229], off
	v_lshl_add_u64 v[228:229], s[50:51], 0, v[148:149]
	s_add_i32 m0, s56, 0x2000
	s_nop 0
	global_load_lds_dwordx4 v[228:229], off
	v_lshl_add_u64 v[228:229], s[40:41], 0, v[152:153]
	s_mov_b32 m0, s44
	s_nop 0
	global_load_lds_dwordx4 v[228:229], off
	s_mov_b32 m0, s45
	s_nop 0
	global_load_lds_dwordx4 v[240:241], off
	s_waitcnt vmcnt(8)
	s_waitcnt lgkmcnt(0)
	s_barrier
	s_waitcnt lgkmcnt(0)
	v_mfma_i32_16x16x64_i8 v[64:67], v[116:119], v[182:185], v[64:67]
	v_mfma_i32_16x16x64_i8 v[64:67], v[124:127], v[186:189], v[64:67]
	v_mfma_i32_16x16x64_i8 v[48:51], v[124:127], v[208:211], v[48:51]
	v_mfma_i32_16x16x64_i8 v[48:51], v[116:119], v[204:207], v[48:51]
	v_mfma_i32_16x16x64_i8 v[32:35], v[116:119], v[212:215], v[32:35]
	v_mfma_i32_16x16x64_i8 v[32:35], v[124:127], v[216:219], v[32:35]
	v_mfma_i32_16x16x64_i8 v[16:19], v[124:127], v[224:227], v[16:19]
	v_mfma_i32_16x16x64_i8 v[16:19], v[116:119], v[220:223], v[16:19]
	v_mfma_i32_16x16x64_i8 v[12:15], v[132:135], v[220:223], v[12:15]
	v_mfma_i32_16x16x64_i8 v[12:15], v[136:139], v[224:227], v[12:15]
	v_mfma_i32_16x16x64_i8 v[28:31], v[136:139], v[216:219], v[28:31]
	v_mfma_i32_16x16x64_i8 v[28:31], v[132:135], v[212:215], v[28:31]
	v_mfma_i32_16x16x64_i8 v[44:47], v[132:135], v[204:207], v[44:47]
	v_mfma_i32_16x16x64_i8 v[44:47], v[136:139], v[208:211], v[44:47]
	v_mfma_i32_16x16x64_i8 v[60:63], v[136:139], v[186:189], v[60:63]
	v_mfma_i32_16x16x64_i8 v[60:63], v[132:135], v[182:185], v[60:63]
	v_mfma_i32_16x16x64_i8 v[56:59], v[160:163], v[182:185], v[56:59]
	v_mfma_i32_16x16x64_i8 v[56:59], v[164:167], v[186:189], v[56:59]
	v_mfma_i32_16x16x64_i8 v[40:43], v[164:167], v[208:211], v[40:43]
	v_mfma_i32_16x16x64_i8 v[40:43], v[160:163], v[204:207], v[40:43]
	v_mfma_i32_16x16x64_i8 v[24:27], v[160:163], v[212:215], v[24:27]
	v_mfma_i32_16x16x64_i8 v[24:27], v[164:167], v[216:219], v[24:27]
	v_mfma_i32_16x16x64_i8 v[8:11], v[164:167], v[224:227], v[8:11]
	v_mfma_i32_16x16x64_i8 v[8:11], v[160:163], v[220:223], v[8:11]
	v_mfma_i32_16x16x64_i8 v[4:7], v[168:171], v[220:223], v[4:7]
	v_mfma_i32_16x16x64_i8 v[4:7], v[178:181], v[224:227], v[4:7]
	v_mfma_i32_16x16x64_i8 v[20:23], v[178:181], v[216:219], v[20:23]
	v_mfma_i32_16x16x64_i8 v[20:23], v[168:171], v[212:215], v[20:23]
	v_mfma_i32_16x16x64_i8 v[36:39], v[168:171], v[204:207], v[36:39]
	v_mfma_i32_16x16x64_i8 v[36:39], v[178:181], v[208:211], v[36:39]
	v_mfma_i32_16x16x64_i8 v[52:55], v[178:181], v[186:189], v[52:55]
	v_mfma_i32_16x16x64_i8 v[52:55], v[168:171], v[182:185], v[52:55]
	s_barrier
; #define PG8_STAGE(bufoff, gbase, voff) do { _Pragma("unroll") for (int _i = 0; _i < 2; ++_i) \
;         __builtin_amdgcn_global_load_lds((const unsigned*)((const char*)(gbase) + (voff)[_i]), (PG8_LAS unsigned*)(lds + (bufoff) + ldsw + _i * 8192), 16, 0, 0); } while (0)
; #define PG8_LDA(dst, b, h) do { _Pragma("unroll") for (int m = 0; m < 4; ++m) _Pragma("unroll") for (int k = 0; k < 2; ++k) dst[m][k] = *(const PG8_LAS bf16x8*)(lds + PG8_SA(b, h) + aoff + m * 2048 + k * 1024); } while (0)
; #define PG8_LDB(dst, b, h) do { _Pragma("unroll") for (int n = 0; n < 2; ++n) _Pragma("unroll") for (int k = 0; k < 2; ++k) dst[n][k] = *(const PG8_LAS bf16x8*)(lds + PG8_SB(b, h) + boff + n * 2048 + k * 1024); } while (0)
; #define PG8_WAIT_V(n) asm volatile("s_waitcnt vmcnt(" #n ")" ::: "memory")
; #define PG8_WAIT_L(n) asm volatile("s_waitcnt lgkmcnt(" #n ")" ::: "memory")
; #define PG8_BAR __builtin_amdgcn_s_barrier()
; #define PG8_SCHED __builtin_amdgcn_sched_barrier(0)
; template <class Epi, class Sched, bool ALIGN_EPI = false, bool SP2 = false, bool I8 = false>
; __device__ __forceinline__ void gemm_phase(PG8_LAS unsigned char* lds, const Gemm g, const Sched& S, const Epi& E) {
;     ...
;             PG8_LDB(B0, 1, 0); PG8_LDB(B1, 1, 1); PG8_SCHED; PG8_LDA(At, 1, 0); PG8_STAGE(PG8_SA(0, 1), a2 + hstep, voffA);
;             PG8_WAIT_V(8); PG8_WAIT_L(0); PG8_BAR; PG8_MMA(0, 0, At, B0); PG8_MMA(0, 1, At, B1); PG8_BAR; PG8_SCHED;
;             PG8_LDA(At, 1, 1); PG8_STAGE(PG8_SB(1, 0), b3, voffB); PG8_STAGE(PG8_SB(1, 1), b3 + hstep, voffB); PG8_STAGE(PG8_SA(1, 0), a3, voffA);
;             PG8_WAIT_V(8); PG8_WAIT_L(0); PG8_BAR; PG8_MMA(1, 0, At, B0); PG8_MMA(1, 1, At, B1); PG8_BAR; PG8_SCHED;
	s_add_i32 s50, 0, 0x18000
	s_add_i32 s51, 0, 0x1c000
	v_add_u32_e32 v136, s50, v175
	v_add_u32_e32 v178, s51, v175
	ds_read_b128 v[116:119], v136
	ds_read_b128 v[124:127], v136 offset:1024
	ds_read_b128 v[132:135], v136 offset:2048
	ds_read_b128 v[136:139], v136 offset:3072
	ds_read_b128 v[160:163], v178
	ds_read_b128 v[164:167], v178 offset:1024
	ds_read_b128 v[168:171], v178 offset:2048
	ds_read_b128 v[178:181], v178 offset:3072
	s_add_u32 s40, s40, 0x80000
	s_addc_u32 s41, s41, 0
	s_mov_b32 m0, s46
	v_lshl_add_u64 v[242:243], s[40:41], 0, v[152:153]
	ds_read_b128 v[182:185], v177 offset:32768
	ds_read_b128 v[186:189], v177 offset:33792
	ds_read_b128 v[204:207], v177 offset:34816
	ds_read_b128 v[208:211], v177 offset:35840
	ds_read_b128 v[212:215], v177 offset:36864
	ds_read_b128 v[216:219], v177 offset:37888
	ds_read_b128 v[220:223], v177 offset:38912
	ds_read_b128 v[224:227], v177 offset:39936
	global_load_lds_dwordx4 v[242:243], off
	v_lshl_add_u64 v[242:243], s[40:41], 0, v[150:151]
	s_mov_b32 m0, s47
	s_nop 0
	global_load_lds_dwordx4 v[242:243], off
	s_waitcnt vmcnt(8)
	s_waitcnt lgkmcnt(0)
	s_barrier
	s_waitcnt lgkmcnt(0)
	v_mfma_i32_16x16x64_i8 v[144:147], v[116:119], v[182:185], v[144:147]
	v_mfma_i32_16x16x64_i8 v[144:147], v[124:127], v[186:189], v[144:147]
	v_mfma_i32_16x16x64_i8 v[112:115], v[124:127], v[208:211], v[112:115]
	v_mfma_i32_16x16x64_i8 v[112:115], v[116:119], v[204:207], v[112:115]
	v_mfma_i32_16x16x64_i8 v[96:99], v[116:119], v[212:215], v[96:99]
	v_mfma_i32_16x16x64_i8 v[96:99], v[124:127], v[216:219], v[96:99]
	v_mfma_i32_16x16x64_i8 v[80:83], v[124:127], v[224:227], v[80:83]
	v_mfma_i32_16x16x64_i8 v[80:83], v[116:119], v[220:223], v[80:83]
	v_mfma_i32_16x16x64_i8 v[76:79], v[132:135], v[220:223], v[76:79]
	v_mfma_i32_16x16x64_i8 v[76:79], v[136:139], v[224:227], v[76:79]
	v_mfma_i32_16x16x64_i8 v[92:95], v[136:139], v[216:219], v[92:95]
	v_mfma_i32_16x16x64_i8 v[92:95], v[132:135], v[212:215], v[92:95]
	v_mfma_i32_16x16x64_i8 v[108:111], v[132:135], v[204:207], v[108:111]
	v_mfma_i32_16x16x64_i8 v[108:111], v[136:139], v[208:211], v[108:111]
	v_mfma_i32_16x16x64_i8 v[140:143], v[136:139], v[186:189], v[140:143]
	v_mfma_i32_16x16x64_i8 v[140:143], v[132:135], v[182:185], v[140:143]
	v_mfma_i32_16x16x64_i8 v[128:131], v[160:163], v[182:185], v[128:131]
	v_mfma_i32_16x16x64_i8 v[128:131], v[164:167], v[186:189], v[128:131]
	v_mfma_i32_16x16x64_i8 v[104:107], v[164:167], v[208:211], v[104:107]
	v_mfma_i32_16x16x64_i8 v[104:107], v[160:163], v[204:207], v[104:107]
	v_mfma_i32_16x16x64_i8 v[88:91], v[160:163], v[212:215], v[88:91]
	v_mfma_i32_16x16x64_i8 v[88:91], v[164:167], v[216:219], v[88:91]
	v_mfma_i32_16x16x64_i8 v[72:75], v[164:167], v[224:227], v[72:75]
	v_mfma_i32_16x16x64_i8 v[72:75], v[160:163], v[220:223], v[72:75]
	v_mfma_i32_16x16x64_i8 v[68:71], v[168:171], v[220:223], v[68:71]
	v_mfma_i32_16x16x64_i8 v[68:71], v[178:181], v[224:227], v[68:71]
	v_mfma_i32_16x16x64_i8 v[84:87], v[178:181], v[216:219], v[84:87]
	v_mfma_i32_16x16x64_i8 v[84:87], v[168:171], v[212:215], v[84:87]
	v_mfma_i32_16x16x64_i8 v[100:103], v[168:171], v[204:207], v[100:103]
	v_mfma_i32_16x16x64_i8 v[100:103], v[178:181], v[208:211], v[100:103]
	v_mfma_i32_16x16x64_i8 v[120:123], v[178:181], v[186:189], v[120:123]
	v_mfma_i32_16x16x64_i8 v[120:123], v[168:171], v[182:185], v[120:123]
	s_barrier
	s_add_i32 s40, s50, s43
	v_lshl_add_u64 v[172:173], v[172:173], 0, s[84:85]
	s_mov_b32 m0, s40
	ds_read_b128 v[182:185], v177 offset:49152
	ds_read_b128 v[186:189], v177 offset:50176
	ds_read_b128 v[204:207], v177 offset:51200
	ds_read_b128 v[208:211], v177 offset:52224
	ds_read_b128 v[212:215], v177 offset:53248
	ds_read_b128 v[216:219], v177 offset:54272
	ds_read_b128 v[220:223], v177 offset:55296
	ds_read_b128 v[224:227], v177 offset:56320
	global_load_lds_dwordx4 v[172:173], off
	s_add_i32 m0, s40, 0x2000
	s_add_u32 s36, s36, 0x80080
	v_lshl_add_u64 v[172:173], v[190:191], 0, s[84:85]
	s_addc_u32 s37, s37, 0
	s_add_i32 s40, s51, s43
	global_load_lds_dwordx4 v[172:173], off
	v_lshl_add_u64 v[172:173], s[36:37], 0, v[2:3]
	s_mov_b32 m0, s40
	s_nop 0
	global_load_lds_dwordx4 v[172:173], off
	v_lshl_add_u64 v[172:173], s[36:37], 0, v[148:149]
	s_add_i32 m0, s40, 0x2000
	s_nop 0
	global_load_lds_dwordx4 v[172:173], off
	v_lshl_add_u64 v[172:173], v[228:229], 0, s[84:85]
	s_mov_b32 m0, s52
	s_nop 0
	global_load_lds_dwordx4 v[172:173], off
	v_lshl_add_u64 v[172:173], v[240:241], 0, s[84:85]
	s_mov_b32 m0, s53
	s_nop 0
	global_load_lds_dwordx4 v[172:173], off
	s_waitcnt vmcnt(8)
	s_waitcnt lgkmcnt(0)
	s_barrier
	s_waitcnt lgkmcnt(0)
	v_mfma_i32_16x16x64_i8 v[64:67], v[116:119], v[182:185], v[64:67]
	v_mfma_i32_16x16x64_i8 v[64:67], v[124:127], v[186:189], v[64:67]
	v_mfma_i32_16x16x64_i8 v[48:51], v[124:127], v[208:211], v[48:51]
	v_mfma_i32_16x16x64_i8 v[48:51], v[116:119], v[204:207], v[48:51]
	v_mfma_i32_16x16x64_i8 v[32:35], v[116:119], v[212:215], v[32:35]
	v_mfma_i32_16x16x64_i8 v[32:35], v[124:127], v[216:219], v[32:35]
	v_mfma_i32_16x16x64_i8 v[16:19], v[124:127], v[224:227], v[16:19]
	v_mfma_i32_16x16x64_i8 v[16:19], v[116:119], v[220:223], v[16:19]
	v_mfma_i32_16x16x64_i8 v[12:15], v[132:135], v[220:223], v[12:15]
	v_mfma_i32_16x16x64_i8 v[12:15], v[136:139], v[224:227], v[12:15]
	v_mfma_i32_16x16x64_i8 v[28:31], v[136:139], v[216:219], v[28:31]
	v_mfma_i32_16x16x64_i8 v[28:31], v[132:135], v[212:215], v[28:31]
	v_mfma_i32_16x16x64_i8 v[44:47], v[132:135], v[204:207], v[44:47]
	v_mfma_i32_16x16x64_i8 v[44:47], v[136:139], v[208:211], v[44:47]
	v_mfma_i32_16x16x64_i8 v[60:63], v[136:139], v[186:189], v[60:63]
	v_mfma_i32_16x16x64_i8 v[60:63], v[132:135], v[182:185], v[60:63]
	v_mfma_i32_16x16x64_i8 v[56:59], v[160:163], v[182:185], v[56:59]
	v_mfma_i32_16x16x64_i8 v[56:59], v[164:167], v[186:189], v[56:59]
	v_mfma_i32_16x16x64_i8 v[40:43], v[164:167], v[208:211], v[40:43]
	v_mfma_i32_16x16x64_i8 v[40:43], v[160:163], v[204:207], v[40:43]
	v_mfma_i32_16x16x64_i8 v[24:27], v[160:163], v[212:215], v[24:27]
	v_mfma_i32_16x16x64_i8 v[24:27], v[164:167], v[216:219], v[24:27]
	v_mfma_i32_16x16x64_i8 v[8:11], v[164:167], v[224:227], v[8:11]
	v_mfma_i32_16x16x64_i8 v[8:11], v[160:163], v[220:223], v[8:11]
	v_mfma_i32_16x16x64_i8 v[4:7], v[168:171], v[220:223], v[4:7]
	v_mfma_i32_16x16x64_i8 v[4:7], v[178:181], v[224:227], v[4:7]
	v_mfma_i32_16x16x64_i8 v[20:23], v[178:181], v[216:219], v[20:23]
	v_mfma_i32_16x16x64_i8 v[20:23], v[168:171], v[212:215], v[20:23]
	v_mfma_i32_16x16x64_i8 v[36:39], v[168:171], v[204:207], v[36:39]
	v_mfma_i32_16x16x64_i8 v[36:39], v[178:181], v[208:211], v[36:39]
	v_mfma_i32_16x16x64_i8 v[52:55], v[178:181], v[186:189], v[52:55]
	v_mfma_i32_16x16x64_i8 v[52:55], v[168:171], v[182:185], v[52:55]
	s_barrier
	s_add_i32 s76, s76, 2
	s_add_u32 s26, s26, 0x100
	s_addc_u32 s27, s27, 0
	s_add_u32 s72, s72, 0x100
	s_addc_u32 s73, s73, 0
	s_cmp_gt_u32 s76, 29
	s_cbranch_scc0 .LBB0_208

; #define PG8_STAGE(bufoff, gbase, voff) do { _Pragma("unroll") for (int _i = 0; _i < 2; ++_i) \
;         __builtin_amdgcn_global_load_lds((const unsigned*)((const char*)(gbase) + (voff)[_i]), (PG8_LAS unsigned*)(lds + (bufoff) + ldsw + _i * 8192), 16, 0, 0); } while (0)
; #define PG8_LDA(dst, b, h) do { _Pragma("unroll") for (int m = 0; m < 4; ++m) _Pragma("unroll") for (int k = 0; k < 2; ++k) dst[m][k] = *(const PG8_LAS bf16x8*)(lds + PG8_SA(b, h) + aoff + m * 2048 + k * 1024); } while (0)
; #define PG8_LDB(dst, b, h) do { _Pragma("unroll") for (int n = 0; n < 2; ++n) _Pragma("unroll") for (int k = 0; k < 2; ++k) dst[n][k] = *(const PG8_LAS bf16x8*)(lds + PG8_SB(b, h) + boff + n * 2048 + k * 1024); } while (0)
; #define PG8_WAIT_V(n) asm volatile("s_waitcnt vmcnt(" #n ")" ::: "memory")
; #define PG8_WAIT_L(n) asm volatile("s_waitcnt lgkmcnt(" #n ")" ::: "memory")
; #define PG8_BAR __builtin_amdgcn_s_barrier()
; #define PG8_SCHED __builtin_amdgcn_sched_barrier(0)
; template <class Epi, class Sched, bool ALIGN_EPI = false, bool SP2 = false, bool I8 = false>
; __device__ __forceinline__ void gemm_phase(PG8_LAS unsigned char* lds, const Gemm g, const Sched& S, const Epi& E) {
;     ...
;         const char* nA = has_next ? (const char*)g.A + (size_t)nxt.pm * tstep : cA; const char* nB = has_next ? (const char*)g.Bt + (size_t)nxt.pn * tstep : cB;
;         for (int t = 0; t < nt; t += 2) {
;             const bool last = (t == nt - 2);
;             const char* a1 = cA + (size_t)(t + 1) * kstep;
;             const char* a2 = last ? nA : cA + (size_t)(t + 2) * kstep; const char* b2 = last ? nB : cB + (size_t)(t + 2) * kstep;
;             const char* a3 = a2 + kstep; const char* b3 = b2 + kstep;
;             if (last && has_next) S.a_ready(nxt);
;             if constexpr (SP2) {
;             PG8_LDB(B0, 0, 0); PG8_LDB(B1, 0, 1); PG8_SCHED; PG8_LDA(At, 0, 0); PG8_STAGE(PG8_SA(1, 1), a1 + hstep, voffA);
;             PG8_WAIT_V(8); PG8_WAIT_L(0); PG8_BAR; PG8_MMA(0, 0, At, B0); PG8_MMA(0, 1, At, B1); PG8_BAR; PG8_SCHED;
;             PG8_LDA(At, 0, 1); PG8_STAGE(PG8_SB(0, 0), b2, voffB); PG8_STAGE(PG8_SB(0, 1), b2 + hstep, voffB); PG8_STAGE(PG8_SA(0, 0), a2, voffA);
;             PG8_WAIT_V(8); PG8_WAIT_L(0); PG8_BAR; PG8_MMA(1, 0, At, B0); PG8_MMA(1, 1, At, B1); PG8_BAR; PG8_SCHED;
.LBB0_229:
	s_ashr_i32 s37, s36, 31
	s_lshl_b64 s[34:35], s[36:37], 21
	s_add_u32 s40, s42, s34
	s_addc_u32 s41, s43, s35
	s_and_b64 s[34:35], s[8:9], exec
	s_cselect_b32 s11, s41, s13
	s_cselect_b32 s34, s40, s12
	s_ashr_i32 s27, s26, 31
	s_lshl_b64 s[50:51], s[26:27], 21
	s_add_u32 s54, s44, s50
	s_addc_u32 s55, s45, s51
	s_and_b64 s[50:51], s[8:9], exec
	s_cselect_b32 s27, s55, s73
	s_cselect_b32 s35, s54, s72
	s_add_u32 s12, s12, 0x100080
	s_addc_u32 s13, s13, 0
	s_add_u32 s37, s72, 0x100
	s_addc_u32 s61, s73, 0
	s_mov_b32 s97, -2
	s_add_u32 s50, s12, 0xfff00080
	s_addc_u32 s51, s13, -1
	s_add_i32 s56, 0, 0x10000
	s_cmp_eq_u32 s97, 60
	s_cselect_b32 s77, s11, s51
	s_cselect_b32 s76, s34, s50
	s_cselect_b32 s73, s27, s61
	s_cselect_b32 s72, s35, s37
	s_add_i32 s57, 0, 0x14000
	v_add_u32_e32 v156, s56, v171
	v_add_u32_e32 v168, s57, v171
	s_waitcnt vmcnt(0)
	ds_read_b128 v[112:115], v156
	ds_read_b128 v[120:123], v156 offset:1024
	ds_read_b128 v[152:155], v156 offset:2048
	ds_read_b128 v[156:159], v156 offset:3072
	ds_read_b128 v[160:163], v168
	ds_read_b128 v[164:167], v168 offset:1024
	s_waitcnt lgkmcnt(0)
	ds_read_b128 v[176:179], v168 offset:2048
	ds_read_b128 v[180:183], v168 offset:3072
	v_lshl_add_u64 v[168:169], s[12:13], 0, v[148:149]
	s_add_i32 m0, s47, 0xc000
	ds_read_b128 v[184:187], v173
	ds_read_b128 v[188:191], v173 offset:1024
	ds_read_b128 v[204:207], v173 offset:2048
	ds_read_b128 v[208:211], v173 offset:3072
	ds_read_b128 v[212:215], v173 offset:4096
	ds_read_b128 v[216:219], v173 offset:5120
	ds_read_b128 v[220:223], v173 offset:6144
	ds_read_b128 v[224:227], v173 offset:7168
	global_load_lds_dwordx4 v[168:169], off
	v_lshl_add_u64 v[168:169], s[12:13], 0, v[150:151]
	s_add_i32 m0, s47, 0xe000
	s_nop 0
	global_load_lds_dwordx4 v[168:169], off
	s_waitcnt vmcnt(8)
	s_waitcnt lgkmcnt(0)
	s_barrier
	s_waitcnt lgkmcnt(0)
	v_mfma_f32_16x16x32_bf16 v[136:139], v[112:115], v[184:187], 0
	v_mfma_f32_16x16x32_bf16 v[136:139], v[120:123], v[188:191], v[136:139]
	v_mfma_f32_16x16x32_bf16 v[116:119], v[120:123], v[208:211], 0
	v_mfma_f32_16x16x32_bf16 v[116:119], v[112:115], v[204:207], v[116:119]
	v_mfma_f32_16x16x32_bf16 v[96:99], v[112:115], v[212:215], 0
	v_mfma_f32_16x16x32_bf16 v[96:99], v[120:123], v[216:219], v[96:99]
	v_mfma_f32_16x16x32_bf16 v[80:83], v[120:123], v[224:227], 0
	v_mfma_f32_16x16x32_bf16 v[80:83], v[112:115], v[220:223], v[80:83]
	v_mfma_f32_16x16x32_bf16 v[76:79], v[152:155], v[220:223], 0
	v_mfma_f32_16x16x32_bf16 v[76:79], v[156:159], v[224:227], v[76:79]
	v_mfma_f32_16x16x32_bf16 v[92:95], v[156:159], v[216:219], 0
	v_mfma_f32_16x16x32_bf16 v[92:95], v[152:155], v[212:215], v[92:95]
	v_mfma_f32_16x16x32_bf16 v[108:111], v[152:155], v[204:207], 0
	v_mfma_f32_16x16x32_bf16 v[108:111], v[156:159], v[208:211], v[108:111]
	v_mfma_f32_16x16x32_bf16 v[132:135], v[156:159], v[188:191], 0
	v_mfma_f32_16x16x32_bf16 v[132:135], v[152:155], v[184:187], v[132:135]
	v_mfma_f32_16x16x32_bf16 v[128:131], v[160:163], v[184:187], 0
	v_mfma_f32_16x16x32_bf16 v[128:131], v[164:167], v[188:191], v[128:131]
	v_mfma_f32_16x16x32_bf16 v[104:107], v[164:167], v[208:211], 0
	v_mfma_f32_16x16x32_bf16 v[104:107], v[160:163], v[204:207], v[104:107]
	v_mfma_f32_16x16x32_bf16 v[88:91], v[160:163], v[212:215], 0
	v_mfma_f32_16x16x32_bf16 v[88:91], v[164:167], v[216:219], v[88:91]
	v_mfma_f32_16x16x32_bf16 v[72:75], v[164:167], v[224:227], 0
	v_mfma_f32_16x16x32_bf16 v[72:75], v[160:163], v[220:223], v[72:75]
	v_mfma_f32_16x16x32_bf16 v[68:71], v[176:179], v[220:223], 0
	v_mfma_f32_16x16x32_bf16 v[68:71], v[180:183], v[224:227], v[68:71]
	v_mfma_f32_16x16x32_bf16 v[84:87], v[180:183], v[216:219], 0
	v_mfma_f32_16x16x32_bf16 v[84:87], v[176:179], v[212:215], v[84:87]
	v_mfma_f32_16x16x32_bf16 v[100:103], v[176:179], v[204:207], 0
	v_mfma_f32_16x16x32_bf16 v[100:103], v[180:183], v[208:211], v[100:103]
	v_mfma_f32_16x16x32_bf16 v[124:127], v[180:183], v[188:191], 0
	v_mfma_f32_16x16x32_bf16 v[124:127], v[176:179], v[184:187], v[124:127]
	s_barrier
	s_add_i32 s50, s56, s46
	v_lshl_add_u64 v[168:169], s[72:73], 0, v[2:3]
	s_mov_b32 m0, s50
	ds_read_b128 v[184:187], v173 offset:16384
	ds_read_b128 v[188:191], v173 offset:17408
	ds_read_b128 v[204:207], v173 offset:18432
	ds_read_b128 v[208:211], v173 offset:19456
	ds_read_b128 v[212:215], v173 offset:20480
	ds_read_b128 v[216:219], v173 offset:21504
	ds_read_b128 v[220:223], v173 offset:22528
	ds_read_b128 v[224:227], v173 offset:23552
	global_load_lds_dwordx4 v[168:169], off
	s_add_i32 m0, s50, 0x2000
	s_add_u32 s50, s72, 0x100000
	v_lshl_add_u64 v[228:229], s[72:73], 0, v[144:145]
	s_addc_u32 s51, s73, 0
	s_add_i32 s56, s57, s46
	global_load_lds_dwordx4 v[228:229], off
	v_lshl_add_u64 v[240:241], s[50:51], 0, v[2:3]
	s_mov_b32 m0, s56
	v_lshl_add_u64 v[242:243], s[76:77], 0, v[142:143]
	global_load_lds_dwordx4 v[240:241], off
	v_lshl_add_u64 v[240:241], s[50:51], 0, v[144:145]
	s_add_i32 m0, s56, 0x2000
	s_nop 0
	global_load_lds_dwordx4 v[240:241], off
	v_lshl_add_u64 v[240:241], s[76:77], 0, v[140:141]
	s_mov_b32 m0, s47
	s_nop 0
	global_load_lds_dwordx4 v[240:241], off
	s_mov_b32 m0, s52
	s_nop 0
	global_load_lds_dwordx4 v[242:243], off
	s_waitcnt vmcnt(8)
	s_waitcnt lgkmcnt(0)
	s_barrier
; #define PG8_STAGE(bufoff, gbase, voff) do { _Pragma("unroll") for (int _i = 0; _i < 2; ++_i) \
;         __builtin_amdgcn_global_load_lds((const unsigned*)((const char*)(gbase) + (voff)[_i]), (PG8_LAS unsigned*)(lds + (bufoff) + ldsw + _i * 8192), 16, 0, 0); } while (0)
; #define PG8_LDA(dst, b, h) do { _Pragma("unroll") for (int m = 0; m < 4; ++m) _Pragma("unroll") for (int k = 0; k < 2; ++k) dst[m][k] = *(const PG8_LAS bf16x8*)(lds + PG8_SA(b, h) + aoff + m * 2048 + k * 1024); } while (0)
; #define PG8_LDB(dst, b, h) do { _Pragma("unroll") for (int n = 0; n < 2; ++n) _Pragma("unroll") for (int k = 0; k < 2; ++k) dst[n][k] = *(const PG8_LAS bf16x8*)(lds + PG8_SB(b, h) + boff + n * 2048 + k * 1024); } while (0)
; #define PG8_WAIT_V(n) asm volatile("s_waitcnt vmcnt(" #n ")" ::: "memory")
; #define PG8_WAIT_L(n) asm volatile("s_waitcnt lgkmcnt(" #n ")" ::: "memory")
; #define PG8_BAR __builtin_amdgcn_s_barrier()
; #define PG8_SCHED __builtin_amdgcn_sched_barrier(0)
; template <class Epi, class Sched, bool ALIGN_EPI = false, bool SP2 = false, bool I8 = false>
; __device__ __forceinline__ void gemm_phase(PG8_LAS unsigned char* lds, const Gemm g, const Sched& S, const Epi& E) {
;     ...
;             PG8_WAIT_V(8); PG8_WAIT_L(0); PG8_BAR; PG8_MMA(1, 0, At, B0); PG8_MMA(1, 1, At, B1); PG8_BAR; PG8_SCHED;
;             PG8_LDB(B0, 1, 0); PG8_LDB(B1, 1, 1); PG8_SCHED; PG8_LDA(At, 1, 0); PG8_STAGE(PG8_SA(0, 1), a2 + hstep, voffA);
;             PG8_WAIT_V(8); PG8_WAIT_L(0); PG8_BAR; PG8_MMA(0, 0, At, B0); PG8_MMA(0, 1, At, B1); PG8_BAR; PG8_SCHED;
	s_waitcnt lgkmcnt(0)
	v_mfma_f32_16x16x32_bf16 v[64:67], v[112:115], v[184:187], 0
	v_mfma_f32_16x16x32_bf16 v[64:67], v[120:123], v[188:191], v[64:67]
	v_mfma_f32_16x16x32_bf16 v[48:51], v[120:123], v[208:211], 0
	v_mfma_f32_16x16x32_bf16 v[48:51], v[112:115], v[204:207], v[48:51]
	v_mfma_f32_16x16x32_bf16 v[32:35], v[112:115], v[212:215], 0
	v_mfma_f32_16x16x32_bf16 v[32:35], v[120:123], v[216:219], v[32:35]
	v_mfma_f32_16x16x32_bf16 v[16:19], v[120:123], v[224:227], 0
	v_mfma_f32_16x16x32_bf16 v[16:19], v[112:115], v[220:223], v[16:19]
	v_mfma_f32_16x16x32_bf16 v[12:15], v[152:155], v[220:223], 0
	v_mfma_f32_16x16x32_bf16 v[12:15], v[156:159], v[224:227], v[12:15]
	v_mfma_f32_16x16x32_bf16 v[28:31], v[156:159], v[216:219], 0
	v_mfma_f32_16x16x32_bf16 v[28:31], v[152:155], v[212:215], v[28:31]
	v_mfma_f32_16x16x32_bf16 v[44:47], v[152:155], v[204:207], 0
	v_mfma_f32_16x16x32_bf16 v[44:47], v[156:159], v[208:211], v[44:47]
	v_mfma_f32_16x16x32_bf16 v[60:63], v[156:159], v[188:191], 0
	v_mfma_f32_16x16x32_bf16 v[60:63], v[152:155], v[184:187], v[60:63]
	v_mfma_f32_16x16x32_bf16 v[56:59], v[160:163], v[184:187], 0
	v_mfma_f32_16x16x32_bf16 v[56:59], v[164:167], v[188:191], v[56:59]
	v_mfma_f32_16x16x32_bf16 v[40:43], v[164:167], v[208:211], 0
	v_mfma_f32_16x16x32_bf16 v[40:43], v[160:163], v[204:207], v[40:43]
	v_mfma_f32_16x16x32_bf16 v[24:27], v[160:163], v[212:215], 0
	v_mfma_f32_16x16x32_bf16 v[24:27], v[164:167], v[216:219], v[24:27]
	v_mfma_f32_16x16x32_bf16 v[8:11], v[164:167], v[224:227], 0
	v_mfma_f32_16x16x32_bf16 v[8:11], v[160:163], v[220:223], v[8:11]
	v_mfma_f32_16x16x32_bf16 v[4:7], v[176:179], v[220:223], 0
	v_mfma_f32_16x16x32_bf16 v[4:7], v[180:183], v[224:227], v[4:7]
	v_mfma_f32_16x16x32_bf16 v[20:23], v[180:183], v[216:219], 0
	v_mfma_f32_16x16x32_bf16 v[20:23], v[176:179], v[212:215], v[20:23]
	v_mfma_f32_16x16x32_bf16 v[36:39], v[176:179], v[204:207], 0
	v_mfma_f32_16x16x32_bf16 v[36:39], v[180:183], v[208:211], v[36:39]
	v_mfma_f32_16x16x32_bf16 v[52:55], v[180:183], v[188:191], 0
	v_mfma_f32_16x16x32_bf16 v[52:55], v[176:179], v[184:187], v[52:55]
	s_barrier
	s_add_i32 s56, 0, 0x18000
	s_add_i32 s57, 0, 0x1c000
	v_add_u32_e32 v156, s56, v171
	v_add_u32_e32 v175, s57, v171
	ds_read_b128 v[112:115], v156
	ds_read_b128 v[120:123], v156 offset:1024
	ds_read_b128 v[152:155], v156 offset:2048
	ds_read_b128 v[156:159], v156 offset:3072
	ds_read_b128 v[160:163], v175
	ds_read_b128 v[164:167], v175 offset:1024
	ds_read_b128 v[176:179], v175 offset:2048
	ds_read_b128 v[180:183], v175 offset:3072
	s_add_u32 s50, s76, 0x100000
	s_addc_u32 s51, s77, 0
	s_mov_b32 m0, s53
	v_lshl_add_u64 v[244:245], s[50:51], 0, v[140:141]
	ds_read_b128 v[184:187], v173 offset:32768
	ds_read_b128 v[188:191], v173 offset:33792
	ds_read_b128 v[204:207], v173 offset:34816
	ds_read_b128 v[208:211], v173 offset:35840
	ds_read_b128 v[212:215], v173 offset:36864
	ds_read_b128 v[216:219], v173 offset:37888
	ds_read_b128 v[220:223], v173 offset:38912
	ds_read_b128 v[224:227], v173 offset:39936
	global_load_lds_dwordx4 v[244:245], off
	v_lshl_add_u64 v[244:245], s[50:51], 0, v[142:143]
	s_mov_b32 m0, s64
	s_nop 0
	global_load_lds_dwordx4 v[244:245], off
	s_waitcnt vmcnt(8)
	s_waitcnt lgkmcnt(0)
	s_barrier
	s_waitcnt lgkmcnt(0)
	v_mfma_f32_16x16x32_bf16 v[136:139], v[112:115], v[184:187], v[136:139]
	v_mfma_f32_16x16x32_bf16 v[136:139], v[120:123], v[188:191], v[136:139]
	v_mfma_f32_16x16x32_bf16 v[116:119], v[120:123], v[208:211], v[116:119]
	v_mfma_f32_16x16x32_bf16 v[116:119], v[112:115], v[204:207], v[116:119]
	v_mfma_f32_16x16x32_bf16 v[96:99], v[112:115], v[212:215], v[96:99]
	v_mfma_f32_16x16x32_bf16 v[96:99], v[120:123], v[216:219], v[96:99]
	v_mfma_f32_16x16x32_bf16 v[80:83], v[120:123], v[224:227], v[80:83]
	v_mfma_f32_16x16x32_bf16 v[80:83], v[112:115], v[220:223], v[80:83]
	v_mfma_f32_16x16x32_bf16 v[76:79], v[152:155], v[220:223], v[76:79]
	v_mfma_f32_16x16x32_bf16 v[76:79], v[156:159], v[224:227], v[76:79]
	v_mfma_f32_16x16x32_bf16 v[92:95], v[156:159], v[216:219], v[92:95]
	v_mfma_f32_16x16x32_bf16 v[92:95], v[152:155], v[212:215], v[92:95]
	v_mfma_f32_16x16x32_bf16 v[108:111], v[152:155], v[204:207], v[108:111]
	v_mfma_f32_16x16x32_bf16 v[108:111], v[156:159], v[208:211], v[108:111]
	v_mfma_f32_16x16x32_bf16 v[132:135], v[156:159], v[188:191], v[132:135]
	v_mfma_f32_16x16x32_bf16 v[132:135], v[152:155], v[184:187], v[132:135]
	v_mfma_f32_16x16x32_bf16 v[128:131], v[160:163], v[184:187], v[128:131]
	v_mfma_f32_16x16x32_bf16 v[128:131], v[164:167], v[188:191], v[128:131]
	v_mfma_f32_16x16x32_bf16 v[104:107], v[164:167], v[208:211], v[104:107]
	v_mfma_f32_16x16x32_bf16 v[104:107], v[160:163], v[204:207], v[104:107]
	v_mfma_f32_16x16x32_bf16 v[88:91], v[160:163], v[212:215], v[88:91]
	v_mfma_f32_16x16x32_bf16 v[88:91], v[164:167], v[216:219], v[88:91]
	v_mfma_f32_16x16x32_bf16 v[72:75], v[164:167], v[224:227], v[72:75]
	v_mfma_f32_16x16x32_bf16 v[72:75], v[160:163], v[220:223], v[72:75]
	v_mfma_f32_16x16x32_bf16 v[68:71], v[176:179], v[220:223], v[68:71]
	v_mfma_f32_16x16x32_bf16 v[68:71], v[180:183], v[224:227], v[68:71]
	v_mfma_f32_16x16x32_bf16 v[84:87], v[180:183], v[216:219], v[84:87]
	v_mfma_f32_16x16x32_bf16 v[84:87], v[176:179], v[212:215], v[84:87]
	v_mfma_f32_16x16x32_bf16 v[100:103], v[176:179], v[204:207], v[100:103]
	v_mfma_f32_16x16x32_bf16 v[100:103], v[180:183], v[208:211], v[100:103]
	v_mfma_f32_16x16x32_bf16 v[124:127], v[180:183], v[188:191], v[124:127]
	v_mfma_f32_16x16x32_bf16 v[124:127], v[176:179], v[184:187], v[124:127]
	s_barrier
; #define PG8_STAGE(bufoff, gbase, voff) do { _Pragma("unroll") for (int _i = 0; _i < 2; ++_i) \
;         __builtin_amdgcn_global_load_lds((const unsigned*)((const char*)(gbase) + (voff)[_i]), (PG8_LAS unsigned*)(lds + (bufoff) + ldsw + _i * 8192), 16, 0, 0); } while (0)
; #define PG8_LDA(dst, b, h) do { _Pragma("unroll") for (int m = 0; m < 4; ++m) _Pragma("unroll") for (int k = 0; k < 2; ++k) dst[m][k] = *(const PG8_LAS bf16x8*)(lds + PG8_SA(b, h) + aoff + m * 2048 + k * 1024); } while (0)
; #define PG8_LDB(dst, b, h) do { _Pragma("unroll") for (int n = 0; n < 2; ++n) _Pragma("unroll") for (int k = 0; k < 2; ++k) dst[n][k] = *(const PG8_LAS bf16x8*)(lds + PG8_SB(b, h) + boff + n * 2048 + k * 1024); } while (0)
; #define PG8_WAIT_V(n) asm volatile("s_waitcnt vmcnt(" #n ")" ::: "memory")
; #define PG8_WAIT_L(n) asm volatile("s_waitcnt lgkmcnt(" #n ")" ::: "memory")
; #define PG8_BAR __builtin_amdgcn_s_barrier()
; #define PG8_SCHED __builtin_amdgcn_sched_barrier(0)
; template <class Epi, class Sched, bool ALIGN_EPI = false, bool SP2 = false, bool I8 = false>
; __device__ __forceinline__ void gemm_phase(PG8_LAS unsigned char* lds, const Gemm g, const Sched& S, const Epi& E) {
;     ...
;             const bool last = (t == nt - 2);
;             const char* a1 = cA + (size_t)(t + 1) * kstep;
;             const char* a2 = last ? nA : cA + (size_t)(t + 2) * kstep; const char* b2 = last ? nB : cB + (size_t)(t + 2) * kstep;
;             const char* a3 = a2 + kstep; const char* b3 = b2 + kstep;
;             if (last && has_next) S.a_ready(nxt);
;             if constexpr (SP2) {
;             PG8_LDB(B0, 0, 0); PG8_LDB(B1, 0, 1); PG8_SCHED; PG8_LDA(At, 0, 0); PG8_STAGE(PG8_SA(1, 1), a1 + hstep, voffA);
;             PG8_WAIT_V(8); PG8_WAIT_L(0); PG8_BAR; PG8_MMA(0, 0, At, B0); PG8_MMA(0, 1, At, B1); PG8_BAR; PG8_SCHED;
;     ...
;             PG8_LDA(At, 1, 1); PG8_STAGE(PG8_SB(1, 0), b3, voffB); PG8_STAGE(PG8_SB(1, 1), b3 + hstep, voffB); PG8_STAGE(PG8_SA(1, 0), a3, voffA);
;             PG8_WAIT_V(8); PG8_WAIT_L(0); PG8_BAR; PG8_MMA(1, 0, At, B0); PG8_MMA(1, 1, At, B1); PG8_BAR; PG8_SCHED;
	s_add_i32 s50, s56, s46
	v_lshl_add_u64 v[168:169], v[168:169], 0, s[84:85]
	s_mov_b32 m0, s50
	ds_read_b128 v[184:187], v173 offset:49152
	ds_read_b128 v[188:191], v173 offset:50176
	ds_read_b128 v[204:207], v173 offset:51200
	ds_read_b128 v[208:211], v173 offset:52224
	ds_read_b128 v[212:215], v173 offset:53248
	ds_read_b128 v[216:219], v173 offset:54272
	ds_read_b128 v[220:223], v173 offset:55296
	ds_read_b128 v[224:227], v173 offset:56320
	global_load_lds_dwordx4 v[168:169], off
	s_add_i32 m0, s50, 0x2000
	s_add_u32 s50, s72, 0x100080
	v_lshl_add_u64 v[168:169], v[228:229], 0, s[84:85]
	s_addc_u32 s51, s73, 0
	s_add_i32 s56, s57, s46
	global_load_lds_dwordx4 v[168:169], off
	v_lshl_add_u64 v[168:169], s[50:51], 0, v[2:3]
	s_mov_b32 m0, s56
	s_nop 0
	global_load_lds_dwordx4 v[168:169], off
	v_lshl_add_u64 v[168:169], s[50:51], 0, v[144:145]
	s_add_i32 m0, s56, 0x2000
	s_nop 0
	global_load_lds_dwordx4 v[168:169], off
	v_lshl_add_u64 v[168:169], v[240:241], 0, s[84:85]
	s_mov_b32 m0, s28
	s_nop 0
	global_load_lds_dwordx4 v[168:169], off
	v_lshl_add_u64 v[168:169], v[242:243], 0, s[84:85]
	s_mov_b32 m0, s65
	s_nop 0
	global_load_lds_dwordx4 v[168:169], off
	s_waitcnt vmcnt(8)
	s_waitcnt lgkmcnt(0)
	s_barrier
	s_waitcnt lgkmcnt(0)
	v_mfma_f32_16x16x32_bf16 v[64:67], v[112:115], v[184:187], v[64:67]
	v_mfma_f32_16x16x32_bf16 v[64:67], v[120:123], v[188:191], v[64:67]
	v_mfma_f32_16x16x32_bf16 v[48:51], v[120:123], v[208:211], v[48:51]
	v_mfma_f32_16x16x32_bf16 v[48:51], v[112:115], v[204:207], v[48:51]
	v_mfma_f32_16x16x32_bf16 v[32:35], v[112:115], v[212:215], v[32:35]
	v_mfma_f32_16x16x32_bf16 v[32:35], v[120:123], v[216:219], v[32:35]
	v_mfma_f32_16x16x32_bf16 v[16:19], v[120:123], v[224:227], v[16:19]
	v_mfma_f32_16x16x32_bf16 v[16:19], v[112:115], v[220:223], v[16:19]
	v_mfma_f32_16x16x32_bf16 v[12:15], v[152:155], v[220:223], v[12:15]
	v_mfma_f32_16x16x32_bf16 v[12:15], v[156:159], v[224:227], v[12:15]
	v_mfma_f32_16x16x32_bf16 v[28:31], v[156:159], v[216:219], v[28:31]
	v_mfma_f32_16x16x32_bf16 v[28:31], v[152:155], v[212:215], v[28:31]
	v_mfma_f32_16x16x32_bf16 v[44:47], v[152:155], v[204:207], v[44:47]
	v_mfma_f32_16x16x32_bf16 v[44:47], v[156:159], v[208:211], v[44:47]
	v_mfma_f32_16x16x32_bf16 v[60:63], v[156:159], v[188:191], v[60:63]
	v_mfma_f32_16x16x32_bf16 v[60:63], v[152:155], v[184:187], v[60:63]
	v_mfma_f32_16x16x32_bf16 v[56:59], v[160:163], v[184:187], v[56:59]
	v_mfma_f32_16x16x32_bf16 v[56:59], v[164:167], v[188:191], v[56:59]
	v_mfma_f32_16x16x32_bf16 v[40:43], v[164:167], v[208:211], v[40:43]
	v_mfma_f32_16x16x32_bf16 v[40:43], v[160:163], v[204:207], v[40:43]
	v_mfma_f32_16x16x32_bf16 v[24:27], v[160:163], v[212:215], v[24:27]
	v_mfma_f32_16x16x32_bf16 v[24:27], v[164:167], v[216:219], v[24:27]
	v_mfma_f32_16x16x32_bf16 v[8:11], v[164:167], v[224:227], v[8:11]
	v_mfma_f32_16x16x32_bf16 v[8:11], v[160:163], v[220:223], v[8:11]
	v_mfma_f32_16x16x32_bf16 v[4:7], v[176:179], v[220:223], v[4:7]
	v_mfma_f32_16x16x32_bf16 v[4:7], v[180:183], v[224:227], v[4:7]
	v_mfma_f32_16x16x32_bf16 v[20:23], v[180:183], v[216:219], v[20:23]
	v_mfma_f32_16x16x32_bf16 v[20:23], v[176:179], v[212:215], v[20:23]
	v_mfma_f32_16x16x32_bf16 v[36:39], v[176:179], v[204:207], v[36:39]
	v_mfma_f32_16x16x32_bf16 v[36:39], v[180:183], v[208:211], v[36:39]
	v_mfma_f32_16x16x32_bf16 v[52:55], v[180:183], v[188:191], v[52:55]
	v_mfma_f32_16x16x32_bf16 v[52:55], v[176:179], v[184:187], v[52:55]
	s_barrier
	s_add_i32 s97, s97, 2
	s_add_u32 s12, s12, 0x100
	s_addc_u32 s13, s13, 0
	s_add_u32 s37, s37, 0x100
	s_addc_u32 s61, s61, 0
	s_cmp_gt_u32 s97, 61
	s_cbranch_scc1 .Lkloop_exit_1
.LBB0_230:
	s_add_u32 s50, s12, 0xfff00080
	s_addc_u32 s51, s13, -1
	s_add_i32 s56, 0, 0x10000
	s_cmp_eq_u32 s97, 60
	s_cselect_b32 s77, s11, s51
	s_cselect_b32 s76, s34, s50
	s_cselect_b32 s73, s27, s61
	s_cselect_b32 s72, s35, s37
	s_add_i32 s57, 0, 0x14000
	v_add_u32_e32 v156, s56, v171
	v_add_u32_e32 v168, s57, v171
	s_waitcnt vmcnt(0)
	ds_read_b128 v[112:115], v156
	ds_read_b128 v[120:123], v156 offset:1024
	ds_read_b128 v[152:155], v156 offset:2048
	ds_read_b128 v[156:159], v156 offset:3072
	ds_read_b128 v[160:163], v168
	ds_read_b128 v[164:167], v168 offset:1024
	s_waitcnt lgkmcnt(0)
	ds_read_b128 v[176:179], v168 offset:2048
	ds_read_b128 v[180:183], v168 offset:3072
	v_lshl_add_u64 v[168:169], s[12:13], 0, v[148:149]
	s_add_i32 m0, s47, 0xc000
	ds_read_b128 v[184:187], v173
	ds_read_b128 v[188:191], v173 offset:1024
	ds_read_b128 v[204:207], v173 offset:2048
	ds_read_b128 v[208:211], v173 offset:3072
	ds_read_b128 v[212:215], v173 offset:4096
	ds_read_b128 v[216:219], v173 offset:5120
	ds_read_b128 v[220:223], v173 offset:6144
	ds_read_b128 v[224:227], v173 offset:7168
	global_load_lds_dwordx4 v[168:169], off
	v_lshl_add_u64 v[168:169], s[12:13], 0, v[150:151]
	s_add_i32 m0, s47, 0xe000
	s_nop 0
	global_load_lds_dwordx4 v[168:169], off
	s_waitcnt vmcnt(8)
	s_waitcnt lgkmcnt(0)
	s_barrier
; #define PG8_STAGE(bufoff, gbase, voff) do { _Pragma("unroll") for (int _i = 0; _i < 2; ++_i) \
;         __builtin_amdgcn_global_load_lds((const unsigned*)((const char*)(gbase) + (voff)[_i]), (PG8_LAS unsigned*)(lds + (bufoff) + ldsw + _i * 8192), 16, 0, 0); } while (0)
; #define PG8_LDA(dst, b, h) do { _Pragma("unroll") for (int m = 0; m < 4; ++m) _Pragma("unroll") for (int k = 0; k < 2; ++k) dst[m][k] = *(const PG8_LAS bf16x8*)(lds + PG8_SA(b, h) + aoff + m * 2048 + k * 1024); } while (0)
; #define PG8_WAIT_V(n) asm volatile("s_waitcnt vmcnt(" #n ")" ::: "memory")
; #define PG8_WAIT_L(n) asm volatile("s_waitcnt lgkmcnt(" #n ")" ::: "memory")
; #define PG8_BAR __builtin_amdgcn_s_barrier()
; #define PG8_SCHED __builtin_amdgcn_sched_barrier(0)
; template <class Epi, class Sched, bool ALIGN_EPI = false, bool SP2 = false, bool I8 = false>
; __device__ __forceinline__ void gemm_phase(PG8_LAS unsigned char* lds, const Gemm g, const Sched& S, const Epi& E) {
;     ...
;             PG8_WAIT_V(8); PG8_WAIT_L(0); PG8_BAR; PG8_MMA(0, 0, At, B0); PG8_MMA(0, 1, At, B1); PG8_BAR; PG8_SCHED;
;             PG8_LDA(At, 0, 1); PG8_STAGE(PG8_SB(0, 0), b2, voffB); PG8_STAGE(PG8_SB(0, 1), b2 + hstep, voffB); PG8_STAGE(PG8_SA(0, 0), a2, voffA);
;             PG8_WAIT_V(8); PG8_WAIT_L(0); PG8_BAR; PG8_MMA(1, 0, At, B0); PG8_MMA(1, 1, At, B1); PG8_BAR; PG8_SCHED;
	s_waitcnt lgkmcnt(0)
	v_mfma_f32_16x16x32_bf16 v[136:139], v[112:115], v[184:187], v[136:139]
	v_mfma_f32_16x16x32_bf16 v[136:139], v[120:123], v[188:191], v[136:139]
	v_mfma_f32_16x16x32_bf16 v[116:119], v[120:123], v[208:211], v[116:119]
	v_mfma_f32_16x16x32_bf16 v[116:119], v[112:115], v[204:207], v[116:119]
	v_mfma_f32_16x16x32_bf16 v[96:99], v[112:115], v[212:215], v[96:99]
	v_mfma_f32_16x16x32_bf16 v[96:99], v[120:123], v[216:219], v[96:99]
	v_mfma_f32_16x16x32_bf16 v[80:83], v[120:123], v[224:227], v[80:83]
	v_mfma_f32_16x16x32_bf16 v[80:83], v[112:115], v[220:223], v[80:83]
	v_mfma_f32_16x16x32_bf16 v[76:79], v[152:155], v[220:223], v[76:79]
	v_mfma_f32_16x16x32_bf16 v[76:79], v[156:159], v[224:227], v[76:79]
	v_mfma_f32_16x16x32_bf16 v[92:95], v[156:159], v[216:219], v[92:95]
	v_mfma_f32_16x16x32_bf16 v[92:95], v[152:155], v[212:215], v[92:95]
	v_mfma_f32_16x16x32_bf16 v[108:111], v[152:155], v[204:207], v[108:111]
	v_mfma_f32_16x16x32_bf16 v[108:111], v[156:159], v[208:211], v[108:111]
	v_mfma_f32_16x16x32_bf16 v[132:135], v[156:159], v[188:191], v[132:135]
	v_mfma_f32_16x16x32_bf16 v[132:135], v[152:155], v[184:187], v[132:135]
	v_mfma_f32_16x16x32_bf16 v[128:131], v[160:163], v[184:187], v[128:131]
	v_mfma_f32_16x16x32_bf16 v[128:131], v[164:167], v[188:191], v[128:131]
	v_mfma_f32_16x16x32_bf16 v[104:107], v[164:167], v[208:211], v[104:107]
	v_mfma_f32_16x16x32_bf16 v[104:107], v[160:163], v[204:207], v[104:107]
	v_mfma_f32_16x16x32_bf16 v[88:91], v[160:163], v[212:215], v[88:91]
	v_mfma_f32_16x16x32_bf16 v[88:91], v[164:167], v[216:219], v[88:91]
	v_mfma_f32_16x16x32_bf16 v[72:75], v[164:167], v[224:227], v[72:75]
	v_mfma_f32_16x16x32_bf16 v[72:75], v[160:163], v[220:223], v[72:75]
	v_mfma_f32_16x16x32_bf16 v[68:71], v[176:179], v[220:223], v[68:71]
	v_mfma_f32_16x16x32_bf16 v[68:71], v[180:183], v[224:227], v[68:71]
	v_mfma_f32_16x16x32_bf16 v[84:87], v[180:183], v[216:219], v[84:87]
	v_mfma_f32_16x16x32_bf16 v[84:87], v[176:179], v[212:215], v[84:87]
	v_mfma_f32_16x16x32_bf16 v[100:103], v[176:179], v[204:207], v[100:103]
	v_mfma_f32_16x16x32_bf16 v[100:103], v[180:183], v[208:211], v[100:103]
	v_mfma_f32_16x16x32_bf16 v[124:127], v[180:183], v[188:191], v[124:127]
	v_mfma_f32_16x16x32_bf16 v[124:127], v[176:179], v[184:187], v[124:127]
	s_barrier
	s_add_i32 s50, s56, s46
	v_lshl_add_u64 v[168:169], s[72:73], 0, v[2:3]
	s_mov_b32 m0, s50
	ds_read_b128 v[184:187], v173 offset:16384
	ds_read_b128 v[188:191], v173 offset:17408
	ds_read_b128 v[204:207], v173 offset:18432
	ds_read_b128 v[208:211], v173 offset:19456
	ds_read_b128 v[212:215], v173 offset:20480
	ds_read_b128 v[216:219], v173 offset:21504
	ds_read_b128 v[220:223], v173 offset:22528
	ds_read_b128 v[224:227], v173 offset:23552
	global_load_lds_dwordx4 v[168:169], off
	s_add_i32 m0, s50, 0x2000
	s_add_u32 s50, s72, 0x100000
	v_lshl_add_u64 v[228:229], s[72:73], 0, v[144:145]
	s_addc_u32 s51, s73, 0
	s_add_i32 s56, s57, s46
	global_load_lds_dwordx4 v[228:229], off
	v_lshl_add_u64 v[240:241], s[50:51], 0, v[2:3]
	s_mov_b32 m0, s56
	v_lshl_add_u64 v[242:243], s[76:77], 0, v[142:143]
	global_load_lds_dwordx4 v[240:241], off
	v_lshl_add_u64 v[240:241], s[50:51], 0, v[144:145]
	s_add_i32 m0, s56, 0x2000
	s_nop 0
	global_load_lds_dwordx4 v[240:241], off
	v_lshl_add_u64 v[240:241], s[76:77], 0, v[140:141]
	s_mov_b32 m0, s47
	s_nop 0
	global_load_lds_dwordx4 v[240:241], off
	s_mov_b32 m0, s52
	s_nop 0
	global_load_lds_dwordx4 v[242:243], off
	s_waitcnt vmcnt(8)
	s_waitcnt lgkmcnt(0)
	s_barrier
	s_waitcnt lgkmcnt(0)
	v_mfma_f32_16x16x32_bf16 v[64:67], v[112:115], v[184:187], v[64:67]
	v_mfma_f32_16x16x32_bf16 v[64:67], v[120:123], v[188:191], v[64:67]
	v_mfma_f32_16x16x32_bf16 v[48:51], v[120:123], v[208:211], v[48:51]
	v_mfma_f32_16x16x32_bf16 v[48:51], v[112:115], v[204:207], v[48:51]
	v_mfma_f32_16x16x32_bf16 v[32:35], v[112:115], v[212:215], v[32:35]
	v_mfma_f32_16x16x32_bf16 v[32:35], v[120:123], v[216:219], v[32:35]
	v_mfma_f32_16x16x32_bf16 v[16:19], v[120:123], v[224:227], v[16:19]
	v_mfma_f32_16x16x32_bf16 v[16:19], v[112:115], v[220:223], v[16:19]
	v_mfma_f32_16x16x32_bf16 v[12:15], v[152:155], v[220:223], v[12:15]
	v_mfma_f32_16x16x32_bf16 v[12:15], v[156:159], v[224:227], v[12:15]
	v_mfma_f32_16x16x32_bf16 v[28:31], v[156:159], v[216:219], v[28:31]
	v_mfma_f32_16x16x32_bf16 v[28:31], v[152:155], v[212:215], v[28:31]
	v_mfma_f32_16x16x32_bf16 v[44:47], v[152:155], v[204:207], v[44:47]
	v_mfma_f32_16x16x32_bf16 v[44:47], v[156:159], v[208:211], v[44:47]
	v_mfma_f32_16x16x32_bf16 v[60:63], v[156:159], v[188:191], v[60:63]
	v_mfma_f32_16x16x32_bf16 v[60:63], v[152:155], v[184:187], v[60:63]
	v_mfma_f32_16x16x32_bf16 v[56:59], v[160:163], v[184:187], v[56:59]
	v_mfma_f32_16x16x32_bf16 v[56:59], v[164:167], v[188:191], v[56:59]
	v_mfma_f32_16x16x32_bf16 v[40:43], v[164:167], v[208:211], v[40:43]
	v_mfma_f32_16x16x32_bf16 v[40:43], v[160:163], v[204:207], v[40:43]
	v_mfma_f32_16x16x32_bf16 v[24:27], v[160:163], v[212:215], v[24:27]
	v_mfma_f32_16x16x32_bf16 v[24:27], v[164:167], v[216:219], v[24:27]
	v_mfma_f32_16x16x32_bf16 v[8:11], v[164:167], v[224:227], v[8:11]
	v_mfma_f32_16x16x32_bf16 v[8:11], v[160:163], v[220:223], v[8:11]
	v_mfma_f32_16x16x32_bf16 v[4:7], v[176:179], v[220:223], v[4:7]
	v_mfma_f32_16x16x32_bf16 v[4:7], v[180:183], v[224:227], v[4:7]
	v_mfma_f32_16x16x32_bf16 v[20:23], v[180:183], v[216:219], v[20:23]
	v_mfma_f32_16x16x32_bf16 v[20:23], v[176:179], v[212:215], v[20:23]
	v_mfma_f32_16x16x32_bf16 v[36:39], v[176:179], v[204:207], v[36:39]
	v_mfma_f32_16x16x32_bf16 v[36:39], v[180:183], v[208:211], v[36:39]
	v_mfma_f32_16x16x32_bf16 v[52:55], v[180:183], v[188:191], v[52:55]
	v_mfma_f32_16x16x32_bf16 v[52:55], v[176:179], v[184:187], v[52:55]
	s_barrier
; #define PG8_STAGE(bufoff, gbase, voff) do { _Pragma("unroll") for (int _i = 0; _i < 2; ++_i) \
;         __builtin_amdgcn_global_load_lds((const unsigned*)((const char*)(gbase) + (voff)[_i]), (PG8_LAS unsigned*)(lds + (bufoff) + ldsw + _i * 8192), 16, 0, 0); } while (0)
; #define PG8_LDA(dst, b, h) do { _Pragma("unroll") for (int m = 0; m < 4; ++m) _Pragma("unroll") for (int k = 0; k < 2; ++k) dst[m][k] = *(const PG8_LAS bf16x8*)(lds + PG8_SA(b, h) + aoff + m * 2048 + k * 1024); } while (0)
; #define PG8_LDB(dst, b, h) do { _Pragma("unroll") for (int n = 0; n < 2; ++n) _Pragma("unroll") for (int k = 0; k < 2; ++k) dst[n][k] = *(const PG8_LAS bf16x8*)(lds + PG8_SB(b, h) + boff + n * 2048 + k * 1024); } while (0)
; #define PG8_WAIT_V(n) asm volatile("s_waitcnt vmcnt(" #n ")" ::: "memory")
; #define PG8_WAIT_L(n) asm volatile("s_waitcnt lgkmcnt(" #n ")" ::: "memory")
; #define PG8_BAR __builtin_amdgcn_s_barrier()
; #define PG8_SCHED __builtin_amdgcn_sched_barrier(0)
; template <class Epi, class Sched, bool ALIGN_EPI = false, bool SP2 = false, bool I8 = false>
; __device__ __forceinline__ void gemm_phase(PG8_LAS unsigned char* lds, const Gemm g, const Sched& S, const Epi& E) {
;     ...
;             PG8_LDB(B0, 1, 0); PG8_LDB(B1, 1, 1); PG8_SCHED; PG8_LDA(At, 1, 0); PG8_STAGE(PG8_SA(0, 1), a2 + hstep, voffA);
;             PG8_WAIT_V(8); PG8_WAIT_L(0); PG8_BAR; PG8_MMA(0, 0, At, B0); PG8_MMA(0, 1, At, B1); PG8_BAR; PG8_SCHED;
	s_add_i32 s56, 0, 0x18000
	s_add_i32 s57, 0, 0x1c000
	v_add_u32_e32 v156, s56, v171
	v_add_u32_e32 v175, s57, v171
	ds_read_b128 v[112:115], v156
	ds_read_b128 v[120:123], v156 offset:1024
	ds_read_b128 v[152:155], v156 offset:2048
	ds_read_b128 v[156:159], v156 offset:3072
	ds_read_b128 v[160:163], v175
	ds_read_b128 v[164:167], v175 offset:1024
	ds_read_b128 v[176:179], v175 offset:2048
	ds_read_b128 v[180:183], v175 offset:3072
	s_add_u32 s50, s76, 0x100000
	s_addc_u32 s51, s77, 0
	s_mov_b32 m0, s53
	v_lshl_add_u64 v[244:245], s[50:51], 0, v[140:141]
	ds_read_b128 v[184:187], v173 offset:32768
	ds_read_b128 v[188:191], v173 offset:33792
	ds_read_b128 v[204:207], v173 offset:34816
	ds_read_b128 v[208:211], v173 offset:35840
	ds_read_b128 v[212:215], v173 offset:36864
	ds_read_b128 v[216:219], v173 offset:37888
	ds_read_b128 v[220:223], v173 offset:38912
	ds_read_b128 v[224:227], v173 offset:39936
	global_load_lds_dwordx4 v[244:245], off
	v_lshl_add_u64 v[244:245], s[50:51], 0, v[142:143]
	s_mov_b32 m0, s64
	s_nop 0
	global_load_lds_dwordx4 v[244:245], off
	s_waitcnt vmcnt(8)
	s_waitcnt lgkmcnt(0)
	s_barrier
	s_waitcnt lgkmcnt(0)
	v_mfma_f32_16x16x32_bf16 v[136:139], v[112:115], v[184:187], v[136:139]
	v_mfma_f32_16x16x32_bf16 v[136:139], v[120:123], v[188:191], v[136:139]
	v_mfma_f32_16x16x32_bf16 v[116:119], v[120:123], v[208:211], v[116:119]
	v_mfma_f32_16x16x32_bf16 v[116:119], v[112:115], v[204:207], v[116:119]
	v_mfma_f32_16x16x32_bf16 v[96:99], v[112:115], v[212:215], v[96:99]
	v_mfma_f32_16x16x32_bf16 v[96:99], v[120:123], v[216:219], v[96:99]
	v_mfma_f32_16x16x32_bf16 v[80:83], v[120:123], v[224:227], v[80:83]
	v_mfma_f32_16x16x32_bf16 v[80:83], v[112:115], v[220:223], v[80:83]
	v_mfma_f32_16x16x32_bf16 v[76:79], v[152:155], v[220:223], v[76:79]
	v_mfma_f32_16x16x32_bf16 v[76:79], v[156:159], v[224:227], v[76:79]
	v_mfma_f32_16x16x32_bf16 v[92:95], v[156:159], v[216:219], v[92:95]
	v_mfma_f32_16x16x32_bf16 v[92:95], v[152:155], v[212:215], v[92:95]
	v_mfma_f32_16x16x32_bf16 v[108:111], v[152:155], v[204:207], v[108:111]
	v_mfma_f32_16x16x32_bf16 v[108:111], v[156:159], v[208:211], v[108:111]
	v_mfma_f32_16x16x32_bf16 v[132:135], v[156:159], v[188:191], v[132:135]
	v_mfma_f32_16x16x32_bf16 v[132:135], v[152:155], v[184:187], v[132:135]
	v_mfma_f32_16x16x32_bf16 v[128:131], v[160:163], v[184:187], v[128:131]
	v_mfma_f32_16x16x32_bf16 v[128:131], v[164:167], v[188:191], v[128:131]
	v_mfma_f32_16x16x32_bf16 v[104:107], v[164:167], v[208:211], v[104:107]
	v_mfma_f32_16x16x32_bf16 v[104:107], v[160:163], v[204:207], v[104:107]
	v_mfma_f32_16x16x32_bf16 v[88:91], v[160:163], v[212:215], v[88:91]
	v_mfma_f32_16x16x32_bf16 v[88:91], v[164:167], v[216:219], v[88:91]
	v_mfma_f32_16x16x32_bf16 v[72:75], v[164:167], v[224:227], v[72:75]
	v_mfma_f32_16x16x32_bf16 v[72:75], v[160:163], v[220:223], v[72:75]
	v_mfma_f32_16x16x32_bf16 v[68:71], v[176:179], v[220:223], v[68:71]
	v_mfma_f32_16x16x32_bf16 v[68:71], v[180:183], v[224:227], v[68:71]
	v_mfma_f32_16x16x32_bf16 v[84:87], v[180:183], v[216:219], v[84:87]
	v_mfma_f32_16x16x32_bf16 v[84:87], v[176:179], v[212:215], v[84:87]
	v_mfma_f32_16x16x32_bf16 v[100:103], v[176:179], v[204:207], v[100:103]
	v_mfma_f32_16x16x32_bf16 v[100:103], v[180:183], v[208:211], v[100:103]
	v_mfma_f32_16x16x32_bf16 v[124:127], v[180:183], v[188:191], v[124:127]
	v_mfma_f32_16x16x32_bf16 v[124:127], v[176:179], v[184:187], v[124:127]
	s_barrier
; #define PG8_STAGE(bufoff, gbase, voff) do { _Pragma("unroll") for (int _i = 0; _i < 2; ++_i) \
;         __builtin_amdgcn_global_load_lds((const unsigned*)((const char*)(gbase) + (voff)[_i]), (PG8_LAS unsigned*)(lds + (bufoff) + ldsw + _i * 8192), 16, 0, 0); } while (0)
; #define PG8_LDA(dst, b, h) do { _Pragma("unroll") for (int m = 0; m < 4; ++m) _Pragma("unroll") for (int k = 0; k < 2; ++k) dst[m][k] = *(const PG8_LAS bf16x8*)(lds + PG8_SA(b, h) + aoff + m * 2048 + k * 1024); } while (0)
; #define PG8_WAIT_V(n) asm volatile("s_waitcnt vmcnt(" #n ")" ::: "memory")
; #define PG8_WAIT_L(n) asm volatile("s_waitcnt lgkmcnt(" #n ")" ::: "memory")
; #define PG8_BAR __builtin_amdgcn_s_barrier()
; #define PG8_SCHED __builtin_amdgcn_sched_barrier(0)
; template <class Epi, class Sched, bool ALIGN_EPI = false, bool SP2 = false, bool I8 = false>
; __device__ __forceinline__ void gemm_phase(PG8_LAS unsigned char* lds, const Gemm g, const Sched& S, const Epi& E) {
;     ...
;             PG8_LDA(At, 1, 1); PG8_STAGE(PG8_SB(1, 0), b3, voffB); PG8_STAGE(PG8_SB(1, 1), b3 + hstep, voffB); PG8_STAGE(PG8_SA(1, 0), a3, voffA);
;             PG8_WAIT_V(8); PG8_WAIT_L(0); PG8_BAR; PG8_MMA(1, 0, At, B0); PG8_MMA(1, 1, At, B1); PG8_BAR; PG8_SCHED;
	s_add_i32 s50, s56, s46
	v_lshl_add_u64 v[168:169], v[168:169], 0, s[84:85]
	s_mov_b32 m0, s50
	ds_read_b128 v[184:187], v173 offset:49152
	ds_read_b128 v[188:191], v173 offset:50176
	ds_read_b128 v[204:207], v173 offset:51200
	ds_read_b128 v[208:211], v173 offset:52224
	ds_read_b128 v[212:215], v173 offset:53248
	ds_read_b128 v[216:219], v173 offset:54272
	ds_read_b128 v[220:223], v173 offset:55296
	ds_read_b128 v[224:227], v173 offset:56320
	global_load_lds_dwordx4 v[168:169], off
	s_add_i32 m0, s50, 0x2000
	s_add_u32 s50, s72, 0x100080
	v_lshl_add_u64 v[168:169], v[228:229], 0, s[84:85]
	s_addc_u32 s51, s73, 0
	s_add_i32 s56, s57, s46
	global_load_lds_dwordx4 v[168:169], off
	v_lshl_add_u64 v[168:169], s[50:51], 0, v[2:3]
	s_mov_b32 m0, s56
	s_nop 0
	global_load_lds_dwordx4 v[168:169], off
	v_lshl_add_u64 v[168:169], s[50:51], 0, v[144:145]
	s_add_i32 m0, s56, 0x2000
	s_nop 0
	global_load_lds_dwordx4 v[168:169], off
	v_lshl_add_u64 v[168:169], v[240:241], 0, s[84:85]
	s_mov_b32 m0, s28
	s_nop 0
	global_load_lds_dwordx4 v[168:169], off
	v_lshl_add_u64 v[168:169], v[242:243], 0, s[84:85]
	s_mov_b32 m0, s65
	s_nop 0
	global_load_lds_dwordx4 v[168:169], off
	s_waitcnt vmcnt(8)
	s_waitcnt lgkmcnt(0)
	s_barrier
	s_waitcnt lgkmcnt(0)
	v_mfma_f32_16x16x32_bf16 v[64:67], v[112:115], v[184:187], v[64:67]
	v_mfma_f32_16x16x32_bf16 v[64:67], v[120:123], v[188:191], v[64:67]
	v_mfma_f32_16x16x32_bf16 v[48:51], v[120:123], v[208:211], v[48:51]
	v_mfma_f32_16x16x32_bf16 v[48:51], v[112:115], v[204:207], v[48:51]
	v_mfma_f32_16x16x32_bf16 v[32:35], v[112:115], v[212:215], v[32:35]
	v_mfma_f32_16x16x32_bf16 v[32:35], v[120:123], v[216:219], v[32:35]
	v_mfma_f32_16x16x32_bf16 v[16:19], v[120:123], v[224:227], v[16:19]
	v_mfma_f32_16x16x32_bf16 v[16:19], v[112:115], v[220:223], v[16:19]
	v_mfma_f32_16x16x32_bf16 v[12:15], v[152:155], v[220:223], v[12:15]
	v_mfma_f32_16x16x32_bf16 v[12:15], v[156:159], v[224:227], v[12:15]
	v_mfma_f32_16x16x32_bf16 v[28:31], v[156:159], v[216:219], v[28:31]
	v_mfma_f32_16x16x32_bf16 v[28:31], v[152:155], v[212:215], v[28:31]
	v_mfma_f32_16x16x32_bf16 v[44:47], v[152:155], v[204:207], v[44:47]
	v_mfma_f32_16x16x32_bf16 v[44:47], v[156:159], v[208:211], v[44:47]
	v_mfma_f32_16x16x32_bf16 v[60:63], v[156:159], v[188:191], v[60:63]
	v_mfma_f32_16x16x32_bf16 v[60:63], v[152:155], v[184:187], v[60:63]
	v_mfma_f32_16x16x32_bf16 v[56:59], v[160:163], v[184:187], v[56:59]
	v_mfma_f32_16x16x32_bf16 v[56:59], v[164:167], v[188:191], v[56:59]
	v_mfma_f32_16x16x32_bf16 v[40:43], v[164:167], v[208:211], v[40:43]
	v_mfma_f32_16x16x32_bf16 v[40:43], v[160:163], v[204:207], v[40:43]
	v_mfma_f32_16x16x32_bf16 v[24:27], v[160:163], v[212:215], v[24:27]
	v_mfma_f32_16x16x32_bf16 v[24:27], v[164:167], v[216:219], v[24:27]
	v_mfma_f32_16x16x32_bf16 v[8:11], v[164:167], v[224:227], v[8:11]
	v_mfma_f32_16x16x32_bf16 v[8:11], v[160:163], v[220:223], v[8:11]
	v_mfma_f32_16x16x32_bf16 v[4:7], v[176:179], v[220:223], v[4:7]
	v_mfma_f32_16x16x32_bf16 v[4:7], v[180:183], v[224:227], v[4:7]
	v_mfma_f32_16x16x32_bf16 v[20:23], v[180:183], v[216:219], v[20:23]
	v_mfma_f32_16x16x32_bf16 v[20:23], v[176:179], v[212:215], v[20:23]
	v_mfma_f32_16x16x32_bf16 v[36:39], v[176:179], v[204:207], v[36:39]
	v_mfma_f32_16x16x32_bf16 v[36:39], v[180:183], v[208:211], v[36:39]
	v_mfma_f32_16x16x32_bf16 v[52:55], v[180:183], v[188:191], v[52:55]
	v_mfma_f32_16x16x32_bf16 v[52:55], v[176:179], v[184:187], v[52:55]
	s_barrier
	s_add_i32 s97, s97, 2
	s_add_u32 s12, s12, 0x100
	s_addc_u32 s13, s13, 0
	s_add_u32 s37, s37, 0x100
	s_addc_u32 s61, s61, 0
	s_cmp_gt_u32 s97, 61
	s_cbranch_scc0 .LBB0_230

; #define PG8_STAGE(bufoff, gbase, voff) do { _Pragma("unroll") for (int _i = 0; _i < 2; ++_i) \
;         __builtin_amdgcn_global_load_lds((const unsigned*)((const char*)(gbase) + (voff)[_i]), (PG8_LAS unsigned*)(lds + (bufoff) + ldsw + _i * 8192), 16, 0, 0); } while (0)
; #define PG8_LDA(dst, b, h) do { _Pragma("unroll") for (int m = 0; m < 4; ++m) _Pragma("unroll") for (int k = 0; k < 2; ++k) dst[m][k] = *(const PG8_LAS bf16x8*)(lds + PG8_SA(b, h) + aoff + m * 2048 + k * 1024); } while (0)
; #define PG8_LDB(dst, b, h) do { _Pragma("unroll") for (int n = 0; n < 2; ++n) _Pragma("unroll") for (int k = 0; k < 2; ++k) dst[n][k] = *(const PG8_LAS bf16x8*)(lds + PG8_SB(b, h) + boff + n * 2048 + k * 1024); } while (0)
; #define PG8_WAIT_V(n) asm volatile("s_waitcnt vmcnt(" #n ")" ::: "memory")
; #define PG8_WAIT_L(n) asm volatile("s_waitcnt lgkmcnt(" #n ")" ::: "memory")
; #define PG8_BAR __builtin_amdgcn_s_barrier()
; #define PG8_SCHED __builtin_amdgcn_sched_barrier(0)
; template <class Epi, class Sched, bool ALIGN_EPI = false, bool SP2 = false, bool I8 = false>
; __device__ __forceinline__ void gemm_phase(PG8_LAS unsigned char* lds, const Gemm g, const Sched& S, const Epi& E) {
;     ...
;         const char* nA = has_next ? (const char*)g.A + (size_t)nxt.pm * tstep : cA; const char* nB = has_next ? (const char*)g.Bt + (size_t)nxt.pn * tstep : cB;
;         for (int t = 0; t < nt; t += 2) {
;             const bool last = (t == nt - 2);
;             const char* a1 = cA + (size_t)(t + 1) * kstep;
;             const char* a2 = last ? nA : cA + (size_t)(t + 2) * kstep; const char* b2 = last ? nB : cB + (size_t)(t + 2) * kstep;
;             const char* a3 = a2 + kstep; const char* b3 = b2 + kstep;
;             if (last && has_next) S.a_ready(nxt);
;             if constexpr (SP2) {
;             PG8_LDB(B0, 0, 0); PG8_LDB(B1, 0, 1); PG8_SCHED; PG8_LDA(At, 0, 0); PG8_STAGE(PG8_SA(1, 1), a1 + hstep, voffA);
;             PG8_WAIT_V(8); PG8_WAIT_L(0); PG8_BAR; PG8_MMA(0, 0, At, B0); PG8_MMA(0, 1, At, B1); PG8_BAR; PG8_SCHED;
;             PG8_LDA(At, 0, 1); PG8_STAGE(PG8_SB(0, 0), b2, voffB); PG8_STAGE(PG8_SB(0, 1), b2 + hstep, voffB); PG8_STAGE(PG8_SA(0, 0), a2, voffA);
;             PG8_WAIT_V(8); PG8_WAIT_L(0); PG8_BAR; PG8_MMA(1, 0, At, B0); PG8_MMA(1, 1, At, B1); PG8_BAR; PG8_SCHED;
.LBB0_1455:
	s_ashr_i32 s17, s16, 31
	s_lshl_b64 s[20:21], s[16:17], 21
	s_add_u32 s20, s28, s20
	s_addc_u32 s21, s34, s21
	s_and_b64 s[22:23], s[8:9], exec
	s_cselect_b32 s17, s21, s25
	s_cselect_b32 s51, s20, s24
	s_ashr_i32 s19, s18, 31
	s_lshl_b64 s[22:23], s[18:19], 21
	s_add_u32 s22, s35, s22
	s_addc_u32 s23, s39, s23
	s_and_b64 s[36:37], s[8:9], exec
	s_cselect_b32 s19, s23, s27
	s_cselect_b32 s52, s22, s26
	s_add_u32 s24, s24, 0x100080
	s_addc_u32 s25, s25, 0
	s_add_u32 s53, s26, 0x100
	s_addc_u32 s54, s27, 0
	s_mov_b32 s55, -2
	s_waitcnt vmcnt(0)
	s_add_u32 s26, s24, 0xfff00080
	s_addc_u32 s27, s25, -1
	s_add_i32 s56, 0, 0x10000
	s_cmp_eq_u32 s55, 60
	s_cselect_b32 s37, s17, s27
	s_cselect_b32 s36, s51, s26
	s_cselect_b32 s27, s19, s54
	s_cselect_b32 s26, s52, s53
	s_add_i32 s58, 0, 0x14000
	v_add_u32_e32 v144, s56, v240
	v_add_u32_e32 v160, s58, v240
	ds_read_b128 v[124:127], v144
	ds_read_b128 v[128:131], v144 offset:1024
	ds_read_b128 v[132:135], v144 offset:2048
	ds_read_b128 v[144:147], v144 offset:3072
	ds_read_b128 v[148:151], v160
	ds_read_b128 v[152:155], v160 offset:1024
	ds_read_b128 v[156:159], v160 offset:2048
	ds_read_b128 v[160:163], v160 offset:3072
	v_lshl_add_u64 v[218:219], s[24:25], 0, v[210:211]
	s_add_i32 m0, s41, 0xc000
	ds_read_b128 v[164:167], v242
	ds_read_b128 v[168:171], v242 offset:1024
	ds_read_b128 v[172:175], v242 offset:2048
	ds_read_b128 v[176:179], v242 offset:3072
	ds_read_b128 v[180:183], v242 offset:4096
	ds_read_b128 v[184:187], v242 offset:5120
	ds_read_b128 v[188:191], v242 offset:6144
	ds_read_b128 v[214:217], v242 offset:7168
	global_load_lds_dwordx4 v[218:219], off
	v_lshl_add_u64 v[218:219], s[24:25], 0, v[212:213]
	s_add_i32 m0, s41, 0xe000
	s_nop 0
	global_load_lds_dwordx4 v[218:219], off
	s_waitcnt vmcnt(8)
	s_waitcnt lgkmcnt(0)
	s_barrier
	s_waitcnt lgkmcnt(0)
	v_mfma_f32_16x16x32_bf16 v[140:143], v[124:127], v[164:167], 0
	v_mfma_f32_16x16x32_bf16 v[140:143], v[128:131], v[168:171], v[140:143]
	v_mfma_f32_16x16x32_bf16 v[112:115], v[128:131], v[176:179], 0
	v_mfma_f32_16x16x32_bf16 v[112:115], v[124:127], v[172:175], v[112:115]
	v_mfma_f32_16x16x32_bf16 v[96:99], v[124:127], v[180:183], 0
	v_mfma_f32_16x16x32_bf16 v[96:99], v[128:131], v[184:187], v[96:99]
	v_mfma_f32_16x16x32_bf16 v[80:83], v[128:131], v[214:217], 0
	v_mfma_f32_16x16x32_bf16 v[80:83], v[124:127], v[188:191], v[80:83]
	v_mfma_f32_16x16x32_bf16 v[76:79], v[132:135], v[188:191], 0
	v_mfma_f32_16x16x32_bf16 v[76:79], v[144:147], v[214:217], v[76:79]
	v_mfma_f32_16x16x32_bf16 v[92:95], v[144:147], v[184:187], 0
	v_mfma_f32_16x16x32_bf16 v[92:95], v[132:135], v[180:183], v[92:95]
	v_mfma_f32_16x16x32_bf16 v[108:111], v[132:135], v[172:175], 0
	v_mfma_f32_16x16x32_bf16 v[108:111], v[144:147], v[176:179], v[108:111]
	v_mfma_f32_16x16x32_bf16 v[136:139], v[144:147], v[168:171], 0
	v_mfma_f32_16x16x32_bf16 v[136:139], v[132:135], v[164:167], v[136:139]
	v_mfma_f32_16x16x32_bf16 v[120:123], v[148:151], v[164:167], 0
	v_mfma_f32_16x16x32_bf16 v[120:123], v[152:155], v[168:171], v[120:123]
	v_mfma_f32_16x16x32_bf16 v[104:107], v[152:155], v[176:179], 0
	v_mfma_f32_16x16x32_bf16 v[104:107], v[148:151], v[172:175], v[104:107]
	v_mfma_f32_16x16x32_bf16 v[88:91], v[148:151], v[180:183], 0
	v_mfma_f32_16x16x32_bf16 v[88:91], v[152:155], v[184:187], v[88:91]
	v_mfma_f32_16x16x32_bf16 v[72:75], v[152:155], v[214:217], 0
	v_mfma_f32_16x16x32_bf16 v[72:75], v[148:151], v[188:191], v[72:75]
	v_mfma_f32_16x16x32_bf16 v[68:71], v[156:159], v[188:191], 0
	v_mfma_f32_16x16x32_bf16 v[68:71], v[160:163], v[214:217], v[68:71]
	v_mfma_f32_16x16x32_bf16 v[84:87], v[160:163], v[184:187], 0
	v_mfma_f32_16x16x32_bf16 v[84:87], v[156:159], v[180:183], v[84:87]
	v_mfma_f32_16x16x32_bf16 v[100:103], v[156:159], v[172:175], 0
	v_mfma_f32_16x16x32_bf16 v[100:103], v[160:163], v[176:179], v[100:103]
	v_mfma_f32_16x16x32_bf16 v[116:119], v[160:163], v[168:171], 0
	v_mfma_f32_16x16x32_bf16 v[116:119], v[156:159], v[164:167], v[116:119]
	s_barrier
	s_add_i32 s56, s56, s40
	v_lshl_add_u64 v[218:219], s[26:27], 0, v[2:3]
	s_mov_b32 m0, s56
	ds_read_b128 v[164:167], v242 offset:16384
	ds_read_b128 v[168:171], v242 offset:17408
	ds_read_b128 v[172:175], v242 offset:18432
	ds_read_b128 v[176:179], v242 offset:19456
	ds_read_b128 v[180:183], v242 offset:20480
	ds_read_b128 v[184:187], v242 offset:21504
	ds_read_b128 v[188:191], v242 offset:22528
	ds_read_b128 v[214:217], v242 offset:23552
	global_load_lds_dwordx4 v[218:219], off
	s_add_i32 m0, s56, 0x2000
	s_add_u32 s56, s26, 0x100000
	v_lshl_add_u64 v[220:221], s[26:27], 0, v[204:205]
	s_addc_u32 s57, s27, 0
	s_add_i32 s58, s58, s40
	global_load_lds_dwordx4 v[220:221], off
	v_lshl_add_u64 v[222:223], s[56:57], 0, v[2:3]
	s_mov_b32 m0, s58
	v_lshl_add_u64 v[224:225], s[36:37], 0, v[206:207]
	global_load_lds_dwordx4 v[222:223], off
	v_lshl_add_u64 v[222:223], s[56:57], 0, v[204:205]
	s_add_i32 m0, s58, 0x2000
	s_nop 0
	global_load_lds_dwordx4 v[222:223], off
	v_lshl_add_u64 v[222:223], s[36:37], 0, v[208:209]
	s_mov_b32 m0, s41
	s_nop 0
	global_load_lds_dwordx4 v[222:223], off
	s_mov_b32 m0, s42
	s_nop 0
	global_load_lds_dwordx4 v[224:225], off
	s_waitcnt vmcnt(8)
	s_waitcnt lgkmcnt(0)
	s_barrier
; #define PG8_STAGE(bufoff, gbase, voff) do { _Pragma("unroll") for (int _i = 0; _i < 2; ++_i) \
;         __builtin_amdgcn_global_load_lds((const unsigned*)((const char*)(gbase) + (voff)[_i]), (PG8_LAS unsigned*)(lds + (bufoff) + ldsw + _i * 8192), 16, 0, 0); } while (0)
; #define PG8_LDA(dst, b, h) do { _Pragma("unroll") for (int m = 0; m < 4; ++m) _Pragma("unroll") for (int k = 0; k < 2; ++k) dst[m][k] = *(const PG8_LAS bf16x8*)(lds + PG8_SA(b, h) + aoff + m * 2048 + k * 1024); } while (0)
; #define PG8_LDB(dst, b, h) do { _Pragma("unroll") for (int n = 0; n < 2; ++n) _Pragma("unroll") for (int k = 0; k < 2; ++k) dst[n][k] = *(const PG8_LAS bf16x8*)(lds + PG8_SB(b, h) + boff + n * 2048 + k * 1024); } while (0)
; #define PG8_WAIT_V(n) asm volatile("s_waitcnt vmcnt(" #n ")" ::: "memory")
; #define PG8_WAIT_L(n) asm volatile("s_waitcnt lgkmcnt(" #n ")" ::: "memory")
; #define PG8_BAR __builtin_amdgcn_s_barrier()
; #define PG8_SCHED __builtin_amdgcn_sched_barrier(0)
; template <class Epi, class Sched, bool ALIGN_EPI = false, bool SP2 = false, bool I8 = false>
; __device__ __forceinline__ void gemm_phase(PG8_LAS unsigned char* lds, const Gemm g, const Sched& S, const Epi& E) {
;     ...
;             PG8_WAIT_V(8); PG8_WAIT_L(0); PG8_BAR; PG8_MMA(1, 0, At, B0); PG8_MMA(1, 1, At, B1); PG8_BAR; PG8_SCHED;
;             PG8_LDB(B0, 1, 0); PG8_LDB(B1, 1, 1); PG8_SCHED; PG8_LDA(At, 1, 0); PG8_STAGE(PG8_SA(0, 1), a2 + hstep, voffA);
;             PG8_WAIT_V(8); PG8_WAIT_L(0); PG8_BAR; PG8_MMA(0, 0, At, B0); PG8_MMA(0, 1, At, B1); PG8_BAR; PG8_SCHED;
	s_waitcnt lgkmcnt(0)
	v_mfma_f32_16x16x32_bf16 v[64:67], v[124:127], v[164:167], 0
	v_mfma_f32_16x16x32_bf16 v[64:67], v[128:131], v[168:171], v[64:67]
	v_mfma_f32_16x16x32_bf16 v[48:51], v[128:131], v[176:179], 0
	v_mfma_f32_16x16x32_bf16 v[48:51], v[124:127], v[172:175], v[48:51]
	v_mfma_f32_16x16x32_bf16 v[32:35], v[124:127], v[180:183], 0
	v_mfma_f32_16x16x32_bf16 v[32:35], v[128:131], v[184:187], v[32:35]
	v_mfma_f32_16x16x32_bf16 v[16:19], v[128:131], v[214:217], 0
	v_mfma_f32_16x16x32_bf16 v[16:19], v[124:127], v[188:191], v[16:19]
	v_mfma_f32_16x16x32_bf16 v[12:15], v[132:135], v[188:191], 0
	v_mfma_f32_16x16x32_bf16 v[12:15], v[144:147], v[214:217], v[12:15]
	v_mfma_f32_16x16x32_bf16 v[28:31], v[144:147], v[184:187], 0
	v_mfma_f32_16x16x32_bf16 v[28:31], v[132:135], v[180:183], v[28:31]
	v_mfma_f32_16x16x32_bf16 v[44:47], v[132:135], v[172:175], 0
	v_mfma_f32_16x16x32_bf16 v[44:47], v[144:147], v[176:179], v[44:47]
	v_mfma_f32_16x16x32_bf16 v[60:63], v[144:147], v[168:171], 0
	v_mfma_f32_16x16x32_bf16 v[60:63], v[132:135], v[164:167], v[60:63]
	v_mfma_f32_16x16x32_bf16 v[56:59], v[148:151], v[164:167], 0
	v_mfma_f32_16x16x32_bf16 v[56:59], v[152:155], v[168:171], v[56:59]
	v_mfma_f32_16x16x32_bf16 v[40:43], v[152:155], v[176:179], 0
	v_mfma_f32_16x16x32_bf16 v[40:43], v[148:151], v[172:175], v[40:43]
	v_mfma_f32_16x16x32_bf16 v[24:27], v[148:151], v[180:183], 0
	v_mfma_f32_16x16x32_bf16 v[24:27], v[152:155], v[184:187], v[24:27]
	v_mfma_f32_16x16x32_bf16 v[8:11], v[152:155], v[214:217], 0
	v_mfma_f32_16x16x32_bf16 v[8:11], v[148:151], v[188:191], v[8:11]
	v_mfma_f32_16x16x32_bf16 v[4:7], v[156:159], v[188:191], 0
	v_mfma_f32_16x16x32_bf16 v[4:7], v[160:163], v[214:217], v[4:7]
	v_mfma_f32_16x16x32_bf16 v[20:23], v[160:163], v[184:187], 0
	v_mfma_f32_16x16x32_bf16 v[20:23], v[156:159], v[180:183], v[20:23]
	v_mfma_f32_16x16x32_bf16 v[36:39], v[156:159], v[172:175], 0
	v_mfma_f32_16x16x32_bf16 v[36:39], v[160:163], v[176:179], v[36:39]
	v_mfma_f32_16x16x32_bf16 v[52:55], v[160:163], v[168:171], 0
	v_mfma_f32_16x16x32_bf16 v[52:55], v[156:159], v[164:167], v[52:55]
	s_barrier
	s_add_i32 s56, 0, 0x18000
	s_add_i32 s57, 0, 0x1c000
	v_add_u32_e32 v144, s56, v240
	v_add_u32_e32 v160, s57, v240
	ds_read_b128 v[124:127], v144
	ds_read_b128 v[128:131], v144 offset:1024
	ds_read_b128 v[132:135], v144 offset:2048
	ds_read_b128 v[144:147], v144 offset:3072
	ds_read_b128 v[148:151], v160
	ds_read_b128 v[152:155], v160 offset:1024
	ds_read_b128 v[156:159], v160 offset:2048
	ds_read_b128 v[160:163], v160 offset:3072
	s_add_u32 s36, s36, 0x100000
	s_addc_u32 s37, s37, 0
	s_mov_b32 m0, s43
	v_lshl_add_u64 v[226:227], s[36:37], 0, v[208:209]
	ds_read_b128 v[164:167], v242 offset:32768
	ds_read_b128 v[168:171], v242 offset:33792
	ds_read_b128 v[172:175], v242 offset:34816
	ds_read_b128 v[176:179], v242 offset:35840
	ds_read_b128 v[180:183], v242 offset:36864
	ds_read_b128 v[184:187], v242 offset:37888
	ds_read_b128 v[188:191], v242 offset:38912
	ds_read_b128 v[214:217], v242 offset:39936
	global_load_lds_dwordx4 v[226:227], off
	v_lshl_add_u64 v[226:227], s[36:37], 0, v[206:207]
	s_mov_b32 m0, s44
	s_nop 0
	global_load_lds_dwordx4 v[226:227], off
	s_waitcnt vmcnt(8)
	s_waitcnt lgkmcnt(0)
	s_barrier
	s_waitcnt lgkmcnt(0)
	v_mfma_f32_16x16x32_bf16 v[140:143], v[124:127], v[164:167], v[140:143]
	v_mfma_f32_16x16x32_bf16 v[140:143], v[128:131], v[168:171], v[140:143]
	v_mfma_f32_16x16x32_bf16 v[112:115], v[128:131], v[176:179], v[112:115]
	v_mfma_f32_16x16x32_bf16 v[112:115], v[124:127], v[172:175], v[112:115]
	v_mfma_f32_16x16x32_bf16 v[96:99], v[124:127], v[180:183], v[96:99]
	v_mfma_f32_16x16x32_bf16 v[96:99], v[128:131], v[184:187], v[96:99]
	v_mfma_f32_16x16x32_bf16 v[80:83], v[128:131], v[214:217], v[80:83]
	v_mfma_f32_16x16x32_bf16 v[80:83], v[124:127], v[188:191], v[80:83]
	v_mfma_f32_16x16x32_bf16 v[76:79], v[132:135], v[188:191], v[76:79]
	v_mfma_f32_16x16x32_bf16 v[76:79], v[144:147], v[214:217], v[76:79]
	v_mfma_f32_16x16x32_bf16 v[92:95], v[144:147], v[184:187], v[92:95]
	v_mfma_f32_16x16x32_bf16 v[92:95], v[132:135], v[180:183], v[92:95]
	v_mfma_f32_16x16x32_bf16 v[108:111], v[132:135], v[172:175], v[108:111]
	v_mfma_f32_16x16x32_bf16 v[108:111], v[144:147], v[176:179], v[108:111]
	v_mfma_f32_16x16x32_bf16 v[136:139], v[144:147], v[168:171], v[136:139]
	v_mfma_f32_16x16x32_bf16 v[136:139], v[132:135], v[164:167], v[136:139]
	v_mfma_f32_16x16x32_bf16 v[120:123], v[148:151], v[164:167], v[120:123]
	v_mfma_f32_16x16x32_bf16 v[120:123], v[152:155], v[168:171], v[120:123]
	v_mfma_f32_16x16x32_bf16 v[104:107], v[152:155], v[176:179], v[104:107]
	v_mfma_f32_16x16x32_bf16 v[104:107], v[148:151], v[172:175], v[104:107]
	v_mfma_f32_16x16x32_bf16 v[88:91], v[148:151], v[180:183], v[88:91]
	v_mfma_f32_16x16x32_bf16 v[88:91], v[152:155], v[184:187], v[88:91]
	v_mfma_f32_16x16x32_bf16 v[72:75], v[152:155], v[214:217], v[72:75]
	v_mfma_f32_16x16x32_bf16 v[72:75], v[148:151], v[188:191], v[72:75]
	v_mfma_f32_16x16x32_bf16 v[68:71], v[156:159], v[188:191], v[68:71]
	v_mfma_f32_16x16x32_bf16 v[68:71], v[160:163], v[214:217], v[68:71]
	v_mfma_f32_16x16x32_bf16 v[84:87], v[160:163], v[184:187], v[84:87]
	v_mfma_f32_16x16x32_bf16 v[84:87], v[156:159], v[180:183], v[84:87]
	v_mfma_f32_16x16x32_bf16 v[100:103], v[156:159], v[172:175], v[100:103]
	v_mfma_f32_16x16x32_bf16 v[100:103], v[160:163], v[176:179], v[100:103]
	v_mfma_f32_16x16x32_bf16 v[116:119], v[160:163], v[168:171], v[116:119]
	v_mfma_f32_16x16x32_bf16 v[116:119], v[156:159], v[164:167], v[116:119]
	s_barrier
; #define PG8_STAGE(bufoff, gbase, voff) do { _Pragma("unroll") for (int _i = 0; _i < 2; ++_i) \
;         __builtin_amdgcn_global_load_lds((const unsigned*)((const char*)(gbase) + (voff)[_i]), (PG8_LAS unsigned*)(lds + (bufoff) + ldsw + _i * 8192), 16, 0, 0); } while (0)
; #define PG8_LDA(dst, b, h) do { _Pragma("unroll") for (int m = 0; m < 4; ++m) _Pragma("unroll") for (int k = 0; k < 2; ++k) dst[m][k] = *(const PG8_LAS bf16x8*)(lds + PG8_SA(b, h) + aoff + m * 2048 + k * 1024); } while (0)
; #define PG8_LDB(dst, b, h) do { _Pragma("unroll") for (int n = 0; n < 2; ++n) _Pragma("unroll") for (int k = 0; k < 2; ++k) dst[n][k] = *(const PG8_LAS bf16x8*)(lds + PG8_SB(b, h) + boff + n * 2048 + k * 1024); } while (0)
; #define PG8_WAIT_V(n) asm volatile("s_waitcnt vmcnt(" #n ")" ::: "memory")
; #define PG8_WAIT_L(n) asm volatile("s_waitcnt lgkmcnt(" #n ")" ::: "memory")
; #define PG8_BAR __builtin_amdgcn_s_barrier()
; #define PG8_SCHED __builtin_amdgcn_sched_barrier(0)
; template <class Epi, class Sched, bool ALIGN_EPI = false, bool SP2 = false, bool I8 = false>
; __device__ __forceinline__ void gemm_phase(PG8_LAS unsigned char* lds, const Gemm g, const Sched& S, const Epi& E) {
;     ...
;             const bool last = (t == nt - 2);
;             const char* a1 = cA + (size_t)(t + 1) * kstep;
;             const char* a2 = last ? nA : cA + (size_t)(t + 2) * kstep; const char* b2 = last ? nB : cB + (size_t)(t + 2) * kstep;
;             const char* a3 = a2 + kstep; const char* b3 = b2 + kstep;
;             if (last && has_next) S.a_ready(nxt);
;             if constexpr (SP2) {
;             PG8_LDB(B0, 0, 0); PG8_LDB(B1, 0, 1); PG8_SCHED; PG8_LDA(At, 0, 0); PG8_STAGE(PG8_SA(1, 1), a1 + hstep, voffA);
;             PG8_WAIT_V(8); PG8_WAIT_L(0); PG8_BAR; PG8_MMA(0, 0, At, B0); PG8_MMA(0, 1, At, B1); PG8_BAR; PG8_SCHED;
;     ...
;             PG8_LDA(At, 1, 1); PG8_STAGE(PG8_SB(1, 0), b3, voffB); PG8_STAGE(PG8_SB(1, 1), b3 + hstep, voffB); PG8_STAGE(PG8_SA(1, 0), a3, voffA);
;             PG8_WAIT_V(8); PG8_WAIT_L(0); PG8_BAR; PG8_MMA(1, 0, At, B0); PG8_MMA(1, 1, At, B1); PG8_BAR; PG8_SCHED;
	s_add_i32 s36, s56, s40
	v_lshl_add_u64 v[218:219], v[218:219], 0, s[84:85]
	s_mov_b32 m0, s36
	ds_read_b128 v[164:167], v242 offset:49152
	ds_read_b128 v[168:171], v242 offset:50176
	ds_read_b128 v[172:175], v242 offset:51200
	ds_read_b128 v[176:179], v242 offset:52224
	ds_read_b128 v[180:183], v242 offset:53248
	ds_read_b128 v[184:187], v242 offset:54272
	ds_read_b128 v[188:191], v242 offset:55296
	ds_read_b128 v[214:217], v242 offset:56320
	global_load_lds_dwordx4 v[218:219], off
	s_add_i32 m0, s36, 0x2000
	s_add_u32 s26, s26, 0x100080
	v_lshl_add_u64 v[218:219], v[220:221], 0, s[84:85]
	s_addc_u32 s27, s27, 0
	s_add_i32 s36, s57, s40
	global_load_lds_dwordx4 v[218:219], off
	v_lshl_add_u64 v[218:219], s[26:27], 0, v[2:3]
	s_mov_b32 m0, s36
	s_nop 0
	global_load_lds_dwordx4 v[218:219], off
	v_lshl_add_u64 v[218:219], s[26:27], 0, v[204:205]
	s_add_i32 m0, s36, 0x2000
	s_nop 0
	global_load_lds_dwordx4 v[218:219], off
	v_lshl_add_u64 v[218:219], v[222:223], 0, s[84:85]
	s_mov_b32 m0, s45
	s_nop 0
	global_load_lds_dwordx4 v[218:219], off
	v_lshl_add_u64 v[218:219], v[224:225], 0, s[84:85]
	s_mov_b32 m0, s46
	s_nop 0
	global_load_lds_dwordx4 v[218:219], off
	s_waitcnt vmcnt(8)
	s_waitcnt lgkmcnt(0)
	s_barrier
	s_waitcnt lgkmcnt(0)
	v_mfma_f32_16x16x32_bf16 v[64:67], v[124:127], v[164:167], v[64:67]
	v_mfma_f32_16x16x32_bf16 v[64:67], v[128:131], v[168:171], v[64:67]
	v_mfma_f32_16x16x32_bf16 v[48:51], v[128:131], v[176:179], v[48:51]
	v_mfma_f32_16x16x32_bf16 v[48:51], v[124:127], v[172:175], v[48:51]
	v_mfma_f32_16x16x32_bf16 v[32:35], v[124:127], v[180:183], v[32:35]
	v_mfma_f32_16x16x32_bf16 v[32:35], v[128:131], v[184:187], v[32:35]
	v_mfma_f32_16x16x32_bf16 v[16:19], v[128:131], v[214:217], v[16:19]
	v_mfma_f32_16x16x32_bf16 v[16:19], v[124:127], v[188:191], v[16:19]
	v_mfma_f32_16x16x32_bf16 v[12:15], v[132:135], v[188:191], v[12:15]
	v_mfma_f32_16x16x32_bf16 v[12:15], v[144:147], v[214:217], v[12:15]
	v_mfma_f32_16x16x32_bf16 v[28:31], v[144:147], v[184:187], v[28:31]
	v_mfma_f32_16x16x32_bf16 v[28:31], v[132:135], v[180:183], v[28:31]
	v_mfma_f32_16x16x32_bf16 v[44:47], v[132:135], v[172:175], v[44:47]
	v_mfma_f32_16x16x32_bf16 v[44:47], v[144:147], v[176:179], v[44:47]
	v_mfma_f32_16x16x32_bf16 v[60:63], v[144:147], v[168:171], v[60:63]
	v_mfma_f32_16x16x32_bf16 v[60:63], v[132:135], v[164:167], v[60:63]
	v_mfma_f32_16x16x32_bf16 v[56:59], v[148:151], v[164:167], v[56:59]
	v_mfma_f32_16x16x32_bf16 v[56:59], v[152:155], v[168:171], v[56:59]
	v_mfma_f32_16x16x32_bf16 v[40:43], v[152:155], v[176:179], v[40:43]
	v_mfma_f32_16x16x32_bf16 v[40:43], v[148:151], v[172:175], v[40:43]
	v_mfma_f32_16x16x32_bf16 v[24:27], v[148:151], v[180:183], v[24:27]
	v_mfma_f32_16x16x32_bf16 v[24:27], v[152:155], v[184:187], v[24:27]
	v_mfma_f32_16x16x32_bf16 v[8:11], v[152:155], v[214:217], v[8:11]
	v_mfma_f32_16x16x32_bf16 v[8:11], v[148:151], v[188:191], v[8:11]
	v_mfma_f32_16x16x32_bf16 v[4:7], v[156:159], v[188:191], v[4:7]
	v_mfma_f32_16x16x32_bf16 v[4:7], v[160:163], v[214:217], v[4:7]
	v_mfma_f32_16x16x32_bf16 v[20:23], v[160:163], v[184:187], v[20:23]
	v_mfma_f32_16x16x32_bf16 v[20:23], v[156:159], v[180:183], v[20:23]
	v_mfma_f32_16x16x32_bf16 v[36:39], v[156:159], v[172:175], v[36:39]
	v_mfma_f32_16x16x32_bf16 v[36:39], v[160:163], v[176:179], v[36:39]
	v_mfma_f32_16x16x32_bf16 v[52:55], v[160:163], v[168:171], v[52:55]
	v_mfma_f32_16x16x32_bf16 v[52:55], v[156:159], v[164:167], v[52:55]
	s_barrier
	s_add_i32 s55, s55, 2
	s_add_u32 s24, s24, 0x100
	s_addc_u32 s25, s25, 0
	s_add_u32 s53, s53, 0x100
	s_addc_u32 s54, s54, 0
	s_cmp_gt_u32 s55, 61
	s_cbranch_scc1 .Lkloop_exit_2
.LBB0_1456:
	s_add_u32 s26, s24, 0xfff00080
	s_addc_u32 s27, s25, -1
	s_add_i32 s56, 0, 0x10000
	s_cmp_eq_u32 s55, 60
	s_cselect_b32 s37, s17, s27
	s_cselect_b32 s36, s51, s26
	s_cselect_b32 s27, s19, s54
	s_cselect_b32 s26, s52, s53
	s_add_i32 s58, 0, 0x14000
	v_add_u32_e32 v144, s56, v240
	v_add_u32_e32 v160, s58, v240
	ds_read_b128 v[124:127], v144
	ds_read_b128 v[128:131], v144 offset:1024
	ds_read_b128 v[132:135], v144 offset:2048
	ds_read_b128 v[144:147], v144 offset:3072
	ds_read_b128 v[148:151], v160
	ds_read_b128 v[152:155], v160 offset:1024
	ds_read_b128 v[156:159], v160 offset:2048
	ds_read_b128 v[160:163], v160 offset:3072
	v_lshl_add_u64 v[218:219], s[24:25], 0, v[210:211]
	s_add_i32 m0, s41, 0xc000
	ds_read_b128 v[164:167], v242
	ds_read_b128 v[168:171], v242 offset:1024
	ds_read_b128 v[172:175], v242 offset:2048
	ds_read_b128 v[176:179], v242 offset:3072
	ds_read_b128 v[180:183], v242 offset:4096
	ds_read_b128 v[184:187], v242 offset:5120
	ds_read_b128 v[188:191], v242 offset:6144
	ds_read_b128 v[214:217], v242 offset:7168
	global_load_lds_dwordx4 v[218:219], off
	v_lshl_add_u64 v[218:219], s[24:25], 0, v[212:213]
	s_add_i32 m0, s41, 0xe000
	s_nop 0
	global_load_lds_dwordx4 v[218:219], off
	s_waitcnt vmcnt(8)
	s_waitcnt lgkmcnt(0)
	s_barrier
; #define PG8_STAGE(bufoff, gbase, voff) do { _Pragma("unroll") for (int _i = 0; _i < 2; ++_i) \
;         __builtin_amdgcn_global_load_lds((const unsigned*)((const char*)(gbase) + (voff)[_i]), (PG8_LAS unsigned*)(lds + (bufoff) + ldsw + _i * 8192), 16, 0, 0); } while (0)
; #define PG8_LDA(dst, b, h) do { _Pragma("unroll") for (int m = 0; m < 4; ++m) _Pragma("unroll") for (int k = 0; k < 2; ++k) dst[m][k] = *(const PG8_LAS bf16x8*)(lds + PG8_SA(b, h) + aoff + m * 2048 + k * 1024); } while (0)
; #define PG8_WAIT_V(n) asm volatile("s_waitcnt vmcnt(" #n ")" ::: "memory")
; #define PG8_WAIT_L(n) asm volatile("s_waitcnt lgkmcnt(" #n ")" ::: "memory")
; #define PG8_BAR __builtin_amdgcn_s_barrier()
; #define PG8_SCHED __builtin_amdgcn_sched_barrier(0)
; template <class Epi, class Sched, bool ALIGN_EPI = false, bool SP2 = false, bool I8 = false>
; __device__ __forceinline__ void gemm_phase(PG8_LAS unsigned char* lds, const Gemm g, const Sched& S, const Epi& E) {
;     ...
;             PG8_WAIT_V(8); PG8_WAIT_L(0); PG8_BAR; PG8_MMA(0, 0, At, B0); PG8_MMA(0, 1, At, B1); PG8_BAR; PG8_SCHED;
;             PG8_LDA(At, 0, 1); PG8_STAGE(PG8_SB(0, 0), b2, voffB); PG8_STAGE(PG8_SB(0, 1), b2 + hstep, voffB); PG8_STAGE(PG8_SA(0, 0), a2, voffA);
;             PG8_WAIT_V(8); PG8_WAIT_L(0); PG8_BAR; PG8_MMA(1, 0, At, B0); PG8_MMA(1, 1, At, B1); PG8_BAR; PG8_SCHED;
	s_waitcnt lgkmcnt(0)
	v_mfma_f32_16x16x32_bf16 v[140:143], v[124:127], v[164:167], v[140:143]
	v_mfma_f32_16x16x32_bf16 v[140:143], v[128:131], v[168:171], v[140:143]
	v_mfma_f32_16x16x32_bf16 v[112:115], v[128:131], v[176:179], v[112:115]
	v_mfma_f32_16x16x32_bf16 v[112:115], v[124:127], v[172:175], v[112:115]
	v_mfma_f32_16x16x32_bf16 v[96:99], v[124:127], v[180:183], v[96:99]
	v_mfma_f32_16x16x32_bf16 v[96:99], v[128:131], v[184:187], v[96:99]
	v_mfma_f32_16x16x32_bf16 v[80:83], v[128:131], v[214:217], v[80:83]
	v_mfma_f32_16x16x32_bf16 v[80:83], v[124:127], v[188:191], v[80:83]
	v_mfma_f32_16x16x32_bf16 v[76:79], v[132:135], v[188:191], v[76:79]
	v_mfma_f32_16x16x32_bf16 v[76:79], v[144:147], v[214:217], v[76:79]
	v_mfma_f32_16x16x32_bf16 v[92:95], v[144:147], v[184:187], v[92:95]
	v_mfma_f32_16x16x32_bf16 v[92:95], v[132:135], v[180:183], v[92:95]
	v_mfma_f32_16x16x32_bf16 v[108:111], v[132:135], v[172:175], v[108:111]
	v_mfma_f32_16x16x32_bf16 v[108:111], v[144:147], v[176:179], v[108:111]
	v_mfma_f32_16x16x32_bf16 v[136:139], v[144:147], v[168:171], v[136:139]
	v_mfma_f32_16x16x32_bf16 v[136:139], v[132:135], v[164:167], v[136:139]
	v_mfma_f32_16x16x32_bf16 v[120:123], v[148:151], v[164:167], v[120:123]
	v_mfma_f32_16x16x32_bf16 v[120:123], v[152:155], v[168:171], v[120:123]
	v_mfma_f32_16x16x32_bf16 v[104:107], v[152:155], v[176:179], v[104:107]
	v_mfma_f32_16x16x32_bf16 v[104:107], v[148:151], v[172:175], v[104:107]
	v_mfma_f32_16x16x32_bf16 v[88:91], v[148:151], v[180:183], v[88:91]
	v_mfma_f32_16x16x32_bf16 v[88:91], v[152:155], v[184:187], v[88:91]
	v_mfma_f32_16x16x32_bf16 v[72:75], v[152:155], v[214:217], v[72:75]
	v_mfma_f32_16x16x32_bf16 v[72:75], v[148:151], v[188:191], v[72:75]
	v_mfma_f32_16x16x32_bf16 v[68:71], v[156:159], v[188:191], v[68:71]
	v_mfma_f32_16x16x32_bf16 v[68:71], v[160:163], v[214:217], v[68:71]
	v_mfma_f32_16x16x32_bf16 v[84:87], v[160:163], v[184:187], v[84:87]
	v_mfma_f32_16x16x32_bf16 v[84:87], v[156:159], v[180:183], v[84:87]
	v_mfma_f32_16x16x32_bf16 v[100:103], v[156:159], v[172:175], v[100:103]
	v_mfma_f32_16x16x32_bf16 v[100:103], v[160:163], v[176:179], v[100:103]
	v_mfma_f32_16x16x32_bf16 v[116:119], v[160:163], v[168:171], v[116:119]
	v_mfma_f32_16x16x32_bf16 v[116:119], v[156:159], v[164:167], v[116:119]
	s_barrier
	s_add_i32 s56, s56, s40
	v_lshl_add_u64 v[218:219], s[26:27], 0, v[2:3]
	s_mov_b32 m0, s56
	ds_read_b128 v[164:167], v242 offset:16384
	ds_read_b128 v[168:171], v242 offset:17408
	ds_read_b128 v[172:175], v242 offset:18432
	ds_read_b128 v[176:179], v242 offset:19456
	ds_read_b128 v[180:183], v242 offset:20480
	ds_read_b128 v[184:187], v242 offset:21504
	ds_read_b128 v[188:191], v242 offset:22528
	ds_read_b128 v[214:217], v242 offset:23552
	global_load_lds_dwordx4 v[218:219], off
	s_add_i32 m0, s56, 0x2000
	s_add_u32 s56, s26, 0x100000
	v_lshl_add_u64 v[220:221], s[26:27], 0, v[204:205]
	s_addc_u32 s57, s27, 0
	s_add_i32 s58, s58, s40
	global_load_lds_dwordx4 v[220:221], off
	v_lshl_add_u64 v[222:223], s[56:57], 0, v[2:3]
	s_mov_b32 m0, s58
	v_lshl_add_u64 v[224:225], s[36:37], 0, v[206:207]
	global_load_lds_dwordx4 v[222:223], off
	v_lshl_add_u64 v[222:223], s[56:57], 0, v[204:205]
	s_add_i32 m0, s58, 0x2000
	s_nop 0
	global_load_lds_dwordx4 v[222:223], off
	v_lshl_add_u64 v[222:223], s[36:37], 0, v[208:209]
	s_mov_b32 m0, s41
	s_nop 0
	global_load_lds_dwordx4 v[222:223], off
	s_mov_b32 m0, s42
	s_nop 0
	global_load_lds_dwordx4 v[224:225], off
	s_waitcnt vmcnt(8)
	s_waitcnt lgkmcnt(0)
	s_barrier
	s_waitcnt lgkmcnt(0)
	v_mfma_f32_16x16x32_bf16 v[64:67], v[124:127], v[164:167], v[64:67]
	v_mfma_f32_16x16x32_bf16 v[64:67], v[128:131], v[168:171], v[64:67]
	v_mfma_f32_16x16x32_bf16 v[48:51], v[128:131], v[176:179], v[48:51]
	v_mfma_f32_16x16x32_bf16 v[48:51], v[124:127], v[172:175], v[48:51]
	v_mfma_f32_16x16x32_bf16 v[32:35], v[124:127], v[180:183], v[32:35]
	v_mfma_f32_16x16x32_bf16 v[32:35], v[128:131], v[184:187], v[32:35]
	v_mfma_f32_16x16x32_bf16 v[16:19], v[128:131], v[214:217], v[16:19]
	v_mfma_f32_16x16x32_bf16 v[16:19], v[124:127], v[188:191], v[16:19]
	v_mfma_f32_16x16x32_bf16 v[12:15], v[132:135], v[188:191], v[12:15]
	v_mfma_f32_16x16x32_bf16 v[12:15], v[144:147], v[214:217], v[12:15]
	v_mfma_f32_16x16x32_bf16 v[28:31], v[144:147], v[184:187], v[28:31]
	v_mfma_f32_16x16x32_bf16 v[28:31], v[132:135], v[180:183], v[28:31]
	v_mfma_f32_16x16x32_bf16 v[44:47], v[132:135], v[172:175], v[44:47]
	v_mfma_f32_16x16x32_bf16 v[44:47], v[144:147], v[176:179], v[44:47]
	v_mfma_f32_16x16x32_bf16 v[60:63], v[144:147], v[168:171], v[60:63]
	v_mfma_f32_16x16x32_bf16 v[60:63], v[132:135], v[164:167], v[60:63]
	v_mfma_f32_16x16x32_bf16 v[56:59], v[148:151], v[164:167], v[56:59]
	v_mfma_f32_16x16x32_bf16 v[56:59], v[152:155], v[168:171], v[56:59]
	v_mfma_f32_16x16x32_bf16 v[40:43], v[152:155], v[176:179], v[40:43]
	v_mfma_f32_16x16x32_bf16 v[40:43], v[148:151], v[172:175], v[40:43]
	v_mfma_f32_16x16x32_bf16 v[24:27], v[148:151], v[180:183], v[24:27]
	v_mfma_f32_16x16x32_bf16 v[24:27], v[152:155], v[184:187], v[24:27]
	v_mfma_f32_16x16x32_bf16 v[8:11], v[152:155], v[214:217], v[8:11]
	v_mfma_f32_16x16x32_bf16 v[8:11], v[148:151], v[188:191], v[8:11]
	v_mfma_f32_16x16x32_bf16 v[4:7], v[156:159], v[188:191], v[4:7]
	v_mfma_f32_16x16x32_bf16 v[4:7], v[160:163], v[214:217], v[4:7]
	v_mfma_f32_16x16x32_bf16 v[20:23], v[160:163], v[184:187], v[20:23]
	v_mfma_f32_16x16x32_bf16 v[20:23], v[156:159], v[180:183], v[20:23]
	v_mfma_f32_16x16x32_bf16 v[36:39], v[156:159], v[172:175], v[36:39]
	v_mfma_f32_16x16x32_bf16 v[36:39], v[160:163], v[176:179], v[36:39]
	v_mfma_f32_16x16x32_bf16 v[52:55], v[160:163], v[168:171], v[52:55]
	v_mfma_f32_16x16x32_bf16 v[52:55], v[156:159], v[164:167], v[52:55]
	s_barrier
; #define PG8_STAGE(bufoff, gbase, voff) do { _Pragma("unroll") for (int _i = 0; _i < 2; ++_i) \
;         __builtin_amdgcn_global_load_lds((const unsigned*)((const char*)(gbase) + (voff)[_i]), (PG8_LAS unsigned*)(lds + (bufoff) + ldsw + _i * 8192), 16, 0, 0); } while (0)
; #define PG8_LDA(dst, b, h) do { _Pragma("unroll") for (int m = 0; m < 4; ++m) _Pragma("unroll") for (int k = 0; k < 2; ++k) dst[m][k] = *(const PG8_LAS bf16x8*)(lds + PG8_SA(b, h) + aoff + m * 2048 + k * 1024); } while (0)
; #define PG8_LDB(dst, b, h) do { _Pragma("unroll") for (int n = 0; n < 2; ++n) _Pragma("unroll") for (int k = 0; k < 2; ++k) dst[n][k] = *(const PG8_LAS bf16x8*)(lds + PG8_SB(b, h) + boff + n * 2048 + k * 1024); } while (0)
; #define PG8_WAIT_V(n) asm volatile("s_waitcnt vmcnt(" #n ")" ::: "memory")
; #define PG8_WAIT_L(n) asm volatile("s_waitcnt lgkmcnt(" #n ")" ::: "memory")
; #define PG8_BAR __builtin_amdgcn_s_barrier()
; #define PG8_SCHED __builtin_amdgcn_sched_barrier(0)
; template <class Epi, class Sched, bool ALIGN_EPI = false, bool SP2 = false, bool I8 = false>
; __device__ __forceinline__ void gemm_phase(PG8_LAS unsigned char* lds, const Gemm g, const Sched& S, const Epi& E) {
;     ...
;             PG8_LDB(B0, 1, 0); PG8_LDB(B1, 1, 1); PG8_SCHED; PG8_LDA(At, 1, 0); PG8_STAGE(PG8_SA(0, 1), a2 + hstep, voffA);
;             PG8_WAIT_V(8); PG8_WAIT_L(0); PG8_BAR; PG8_MMA(0, 0, At, B0); PG8_MMA(0, 1, At, B1); PG8_BAR; PG8_SCHED;
	s_add_i32 s56, 0, 0x18000
	s_add_i32 s57, 0, 0x1c000
	v_add_u32_e32 v144, s56, v240
	v_add_u32_e32 v160, s57, v240
	ds_read_b128 v[124:127], v144
	ds_read_b128 v[128:131], v144 offset:1024
	ds_read_b128 v[132:135], v144 offset:2048
	ds_read_b128 v[144:147], v144 offset:3072
	ds_read_b128 v[148:151], v160
	ds_read_b128 v[152:155], v160 offset:1024
	ds_read_b128 v[156:159], v160 offset:2048
	ds_read_b128 v[160:163], v160 offset:3072
	s_add_u32 s36, s36, 0x100000
	s_addc_u32 s37, s37, 0
	s_mov_b32 m0, s43
	v_lshl_add_u64 v[226:227], s[36:37], 0, v[208:209]
	ds_read_b128 v[164:167], v242 offset:32768
	ds_read_b128 v[168:171], v242 offset:33792
	ds_read_b128 v[172:175], v242 offset:34816
	ds_read_b128 v[176:179], v242 offset:35840
	ds_read_b128 v[180:183], v242 offset:36864
	ds_read_b128 v[184:187], v242 offset:37888
	ds_read_b128 v[188:191], v242 offset:38912
	ds_read_b128 v[214:217], v242 offset:39936
	global_load_lds_dwordx4 v[226:227], off
	v_lshl_add_u64 v[226:227], s[36:37], 0, v[206:207]
	s_mov_b32 m0, s44
	s_nop 0
	global_load_lds_dwordx4 v[226:227], off
	s_waitcnt vmcnt(8)
	s_waitcnt lgkmcnt(0)
	s_barrier
	s_waitcnt lgkmcnt(0)
	v_mfma_f32_16x16x32_bf16 v[140:143], v[124:127], v[164:167], v[140:143]
	v_mfma_f32_16x16x32_bf16 v[140:143], v[128:131], v[168:171], v[140:143]
	v_mfma_f32_16x16x32_bf16 v[112:115], v[128:131], v[176:179], v[112:115]
	v_mfma_f32_16x16x32_bf16 v[112:115], v[124:127], v[172:175], v[112:115]
	v_mfma_f32_16x16x32_bf16 v[96:99], v[124:127], v[180:183], v[96:99]
	v_mfma_f32_16x16x32_bf16 v[96:99], v[128:131], v[184:187], v[96:99]
	v_mfma_f32_16x16x32_bf16 v[80:83], v[128:131], v[214:217], v[80:83]
	v_mfma_f32_16x16x32_bf16 v[80:83], v[124:127], v[188:191], v[80:83]
	v_mfma_f32_16x16x32_bf16 v[76:79], v[132:135], v[188:191], v[76:79]
	v_mfma_f32_16x16x32_bf16 v[76:79], v[144:147], v[214:217], v[76:79]
	v_mfma_f32_16x16x32_bf16 v[92:95], v[144:147], v[184:187], v[92:95]
	v_mfma_f32_16x16x32_bf16 v[92:95], v[132:135], v[180:183], v[92:95]
	v_mfma_f32_16x16x32_bf16 v[108:111], v[132:135], v[172:175], v[108:111]
	v_mfma_f32_16x16x32_bf16 v[108:111], v[144:147], v[176:179], v[108:111]
	v_mfma_f32_16x16x32_bf16 v[136:139], v[144:147], v[168:171], v[136:139]
	v_mfma_f32_16x16x32_bf16 v[136:139], v[132:135], v[164:167], v[136:139]
	v_mfma_f32_16x16x32_bf16 v[120:123], v[148:151], v[164:167], v[120:123]
	v_mfma_f32_16x16x32_bf16 v[120:123], v[152:155], v[168:171], v[120:123]
	v_mfma_f32_16x16x32_bf16 v[104:107], v[152:155], v[176:179], v[104:107]
	v_mfma_f32_16x16x32_bf16 v[104:107], v[148:151], v[172:175], v[104:107]
	v_mfma_f32_16x16x32_bf16 v[88:91], v[148:151], v[180:183], v[88:91]
	v_mfma_f32_16x16x32_bf16 v[88:91], v[152:155], v[184:187], v[88:91]
	v_mfma_f32_16x16x32_bf16 v[72:75], v[152:155], v[214:217], v[72:75]
	v_mfma_f32_16x16x32_bf16 v[72:75], v[148:151], v[188:191], v[72:75]
	v_mfma_f32_16x16x32_bf16 v[68:71], v[156:159], v[188:191], v[68:71]
	v_mfma_f32_16x16x32_bf16 v[68:71], v[160:163], v[214:217], v[68:71]
	v_mfma_f32_16x16x32_bf16 v[84:87], v[160:163], v[184:187], v[84:87]
	v_mfma_f32_16x16x32_bf16 v[84:87], v[156:159], v[180:183], v[84:87]
	v_mfma_f32_16x16x32_bf16 v[100:103], v[156:159], v[172:175], v[100:103]
	v_mfma_f32_16x16x32_bf16 v[100:103], v[160:163], v[176:179], v[100:103]
	v_mfma_f32_16x16x32_bf16 v[116:119], v[160:163], v[168:171], v[116:119]
	v_mfma_f32_16x16x32_bf16 v[116:119], v[156:159], v[164:167], v[116:119]
	s_barrier
; #define PG8_STAGE(bufoff, gbase, voff) do { _Pragma("unroll") for (int _i = 0; _i < 2; ++_i) \
;         __builtin_amdgcn_global_load_lds((const unsigned*)((const char*)(gbase) + (voff)[_i]), (PG8_LAS unsigned*)(lds + (bufoff) + ldsw + _i * 8192), 16, 0, 0); } while (0)
; #define PG8_LDA(dst, b, h) do { _Pragma("unroll") for (int m = 0; m < 4; ++m) _Pragma("unroll") for (int k = 0; k < 2; ++k) dst[m][k] = *(const PG8_LAS bf16x8*)(lds + PG8_SA(b, h) + aoff + m * 2048 + k * 1024); } while (0)
; #define PG8_WAIT_V(n) asm volatile("s_waitcnt vmcnt(" #n ")" ::: "memory")
; #define PG8_WAIT_L(n) asm volatile("s_waitcnt lgkmcnt(" #n ")" ::: "memory")
; #define PG8_BAR __builtin_amdgcn_s_barrier()
; #define PG8_SCHED __builtin_amdgcn_sched_barrier(0)
; template <class Epi, class Sched, bool ALIGN_EPI = false, bool SP2 = false, bool I8 = false>
; __device__ __forceinline__ void gemm_phase(PG8_LAS unsigned char* lds, const Gemm g, const Sched& S, const Epi& E) {
;     ...
;             PG8_LDA(At, 1, 1); PG8_STAGE(PG8_SB(1, 0), b3, voffB); PG8_STAGE(PG8_SB(1, 1), b3 + hstep, voffB); PG8_STAGE(PG8_SA(1, 0), a3, voffA);
;             PG8_WAIT_V(8); PG8_WAIT_L(0); PG8_BAR; PG8_MMA(1, 0, At, B0); PG8_MMA(1, 1, At, B1); PG8_BAR; PG8_SCHED;
	s_add_i32 s36, s56, s40
	v_lshl_add_u64 v[218:219], v[218:219], 0, s[84:85]
	s_mov_b32 m0, s36
	ds_read_b128 v[164:167], v242 offset:49152
	ds_read_b128 v[168:171], v242 offset:50176
	ds_read_b128 v[172:175], v242 offset:51200
	ds_read_b128 v[176:179], v242 offset:52224
	ds_read_b128 v[180:183], v242 offset:53248
	ds_read_b128 v[184:187], v242 offset:54272
	ds_read_b128 v[188:191], v242 offset:55296
	ds_read_b128 v[214:217], v242 offset:56320
	global_load_lds_dwordx4 v[218:219], off
	s_add_i32 m0, s36, 0x2000
	s_add_u32 s26, s26, 0x100080
	v_lshl_add_u64 v[218:219], v[220:221], 0, s[84:85]
	s_addc_u32 s27, s27, 0
	s_add_i32 s36, s57, s40
	global_load_lds_dwordx4 v[218:219], off
	v_lshl_add_u64 v[218:219], s[26:27], 0, v[2:3]
	s_mov_b32 m0, s36
	s_nop 0
	global_load_lds_dwordx4 v[218:219], off
	v_lshl_add_u64 v[218:219], s[26:27], 0, v[204:205]
	s_add_i32 m0, s36, 0x2000
	s_nop 0
	global_load_lds_dwordx4 v[218:219], off
	v_lshl_add_u64 v[218:219], v[222:223], 0, s[84:85]
	s_mov_b32 m0, s45
	s_nop 0
	global_load_lds_dwordx4 v[218:219], off
	v_lshl_add_u64 v[218:219], v[224:225], 0, s[84:85]
	s_mov_b32 m0, s46
	s_nop 0
	global_load_lds_dwordx4 v[218:219], off
	s_waitcnt vmcnt(8)
	s_waitcnt lgkmcnt(0)
	s_barrier
	s_waitcnt lgkmcnt(0)
	v_mfma_f32_16x16x32_bf16 v[64:67], v[124:127], v[164:167], v[64:67]
	v_mfma_f32_16x16x32_bf16 v[64:67], v[128:131], v[168:171], v[64:67]
	v_mfma_f32_16x16x32_bf16 v[48:51], v[128:131], v[176:179], v[48:51]
	v_mfma_f32_16x16x32_bf16 v[48:51], v[124:127], v[172:175], v[48:51]
	v_mfma_f32_16x16x32_bf16 v[32:35], v[124:127], v[180:183], v[32:35]
	v_mfma_f32_16x16x32_bf16 v[32:35], v[128:131], v[184:187], v[32:35]
	v_mfma_f32_16x16x32_bf16 v[16:19], v[128:131], v[214:217], v[16:19]
	v_mfma_f32_16x16x32_bf16 v[16:19], v[124:127], v[188:191], v[16:19]
	v_mfma_f32_16x16x32_bf16 v[12:15], v[132:135], v[188:191], v[12:15]
	v_mfma_f32_16x16x32_bf16 v[12:15], v[144:147], v[214:217], v[12:15]
	v_mfma_f32_16x16x32_bf16 v[28:31], v[144:147], v[184:187], v[28:31]
	v_mfma_f32_16x16x32_bf16 v[28:31], v[132:135], v[180:183], v[28:31]
	v_mfma_f32_16x16x32_bf16 v[44:47], v[132:135], v[172:175], v[44:47]
	v_mfma_f32_16x16x32_bf16 v[44:47], v[144:147], v[176:179], v[44:47]
	v_mfma_f32_16x16x32_bf16 v[60:63], v[144:147], v[168:171], v[60:63]
	v_mfma_f32_16x16x32_bf16 v[60:63], v[132:135], v[164:167], v[60:63]
	v_mfma_f32_16x16x32_bf16 v[56:59], v[148:151], v[164:167], v[56:59]
	v_mfma_f32_16x16x32_bf16 v[56:59], v[152:155], v[168:171], v[56:59]
	v_mfma_f32_16x16x32_bf16 v[40:43], v[152:155], v[176:179], v[40:43]
	v_mfma_f32_16x16x32_bf16 v[40:43], v[148:151], v[172:175], v[40:43]
	v_mfma_f32_16x16x32_bf16 v[24:27], v[148:151], v[180:183], v[24:27]
	v_mfma_f32_16x16x32_bf16 v[24:27], v[152:155], v[184:187], v[24:27]
	v_mfma_f32_16x16x32_bf16 v[8:11], v[152:155], v[214:217], v[8:11]
	v_mfma_f32_16x16x32_bf16 v[8:11], v[148:151], v[188:191], v[8:11]
	v_mfma_f32_16x16x32_bf16 v[4:7], v[156:159], v[188:191], v[4:7]
	v_mfma_f32_16x16x32_bf16 v[4:7], v[160:163], v[214:217], v[4:7]
	v_mfma_f32_16x16x32_bf16 v[20:23], v[160:163], v[184:187], v[20:23]
	v_mfma_f32_16x16x32_bf16 v[20:23], v[156:159], v[180:183], v[20:23]
	v_mfma_f32_16x16x32_bf16 v[36:39], v[156:159], v[172:175], v[36:39]
	v_mfma_f32_16x16x32_bf16 v[36:39], v[160:163], v[176:179], v[36:39]
	v_mfma_f32_16x16x32_bf16 v[52:55], v[160:163], v[168:171], v[52:55]
	v_mfma_f32_16x16x32_bf16 v[52:55], v[156:159], v[164:167], v[52:55]
	s_barrier
	s_add_i32 s55, s55, 2
	s_add_u32 s24, s24, 0x100
	s_addc_u32 s25, s25, 0
	s_add_u32 s53, s53, 0x100
	s_addc_u32 s54, s54, 0
	s_cmp_gt_u32 s55, 61
	s_cbranch_scc0 .LBB0_1456

; #define PG8_STAGE(bufoff, gbase, voff) do { _Pragma("unroll") for (int _i = 0; _i < 2; ++_i) \
;         __builtin_amdgcn_global_load_lds((const unsigned*)((const char*)(gbase) + (voff)[_i]), (PG8_LAS unsigned*)(lds + (bufoff) + ldsw + _i * 8192), 16, 0, 0); } while (0)
; #define PG8_LDA(dst, b, h) do { _Pragma("unroll") for (int m = 0; m < 4; ++m) _Pragma("unroll") for (int k = 0; k < 2; ++k) dst[m][k] = *(const PG8_LAS bf16x8*)(lds + PG8_SA(b, h) + aoff + m * 2048 + k * 1024); } while (0)
; #define PG8_LDB(dst, b, h) do { _Pragma("unroll") for (int n = 0; n < 2; ++n) _Pragma("unroll") for (int k = 0; k < 2; ++k) dst[n][k] = *(const PG8_LAS bf16x8*)(lds + PG8_SB(b, h) + boff + n * 2048 + k * 1024); } while (0)
; #define PG8_WAIT_V(n) asm volatile("s_waitcnt vmcnt(" #n ")" ::: "memory")
; #define PG8_WAIT_L(n) asm volatile("s_waitcnt lgkmcnt(" #n ")" ::: "memory")
; #define PG8_BAR __builtin_amdgcn_s_barrier()
; #define PG8_SCHED __builtin_amdgcn_sched_barrier(0)
; template <class Epi, class Sched, bool ALIGN_EPI = false, bool SP2 = false, bool I8 = false>
; __device__ __forceinline__ void gemm_phase(PG8_LAS unsigned char* lds, const Gemm g, const Sched& S, const Epi& E) {
;     ...
;         const char* nA = has_next ? (const char*)g.A + (size_t)nxt.pm * tstep : cA; const char* nB = has_next ? (const char*)g.Bt + (size_t)nxt.pn * tstep : cB;
;         for (int t = 0; t < nt; t += 2) {
;             const bool last = (t == nt - 2);
;             const char* a1 = cA + (size_t)(t + 1) * kstep;
;             const char* a2 = last ? nA : cA + (size_t)(t + 2) * kstep; const char* b2 = last ? nB : cB + (size_t)(t + 2) * kstep;
;             const char* a3 = a2 + kstep; const char* b3 = b2 + kstep;
;             if (last && has_next) S.a_ready(nxt);
;             if constexpr (SP2) {
;             PG8_LDB(B0, 0, 0); PG8_LDB(B1, 0, 1); PG8_SCHED; PG8_LDA(At, 0, 0); PG8_STAGE(PG8_SA(1, 1), a1 + hstep, voffA);
;             PG8_WAIT_V(8); PG8_WAIT_L(0); PG8_BAR; PG8_MMA(0, 0, At, B0); PG8_MMA(0, 1, At, B1); PG8_BAR; PG8_SCHED;
;             PG8_LDA(At, 0, 1); PG8_STAGE(PG8_SB(0, 0), b2, voffB); PG8_STAGE(PG8_SB(0, 1), b2 + hstep, voffB); PG8_STAGE(PG8_SA(0, 0), a2, voffA);
;             PG8_WAIT_V(8); PG8_WAIT_L(0); PG8_BAR; PG8_MMA(1, 0, At, B0); PG8_MMA(1, 1, At, B1); PG8_BAR; PG8_SCHED;
.LBB0_1590:
	s_ashr_i32 s25, s24, 31
	s_lshl_b64 s[26:27], s[24:25], 20
	s_add_u32 s26, s28, s26
	s_addc_u32 s27, s42, s27
	s_and_b64 s[36:37], s[10:11], exec
	s_cselect_b32 s25, s27, s41
	s_cselect_b32 s57, s26, s40
	s_ashr_i32 s23, s22, 31
	s_lshl_b64 s[36:37], s[22:23], 20
	s_add_u32 s36, s43, s36
	s_addc_u32 s37, s46, s37
	s_and_b64 s[48:49], s[10:11], exec
	s_cselect_b32 s23, s37, s45
	s_cselect_b32 s58, s36, s44
	s_add_u32 s40, s40, 0x80080
	s_addc_u32 s41, s41, 0
	s_add_u32 s59, s44, 0x100
	s_addc_u32 s60, s45, 0
	s_mov_b32 s61, -2
	s_add_u32 s44, s40, 0xfff80080
	s_addc_u32 s45, s41, -1
	s_add_i32 s64, 0, 0x10000
	s_cmp_eq_u32 s61, 28
	s_cselect_b32 s49, s25, s45
	s_cselect_b32 s48, s57, s44
	s_cselect_b32 s45, s23, s60
	s_cselect_b32 s44, s58, s59
	s_add_i32 s67, 0, 0x14000
	v_add_u32_e32 v144, s64, v167
	v_add_u32_e32 v158, s67, v167
	ds_read_b128 v[36:39], v144
	ds_read_b128 v[44:47], v144 offset:1024
	ds_read_b128 v[140:143], v144 offset:2048
	ds_read_b128 v[144:147], v144 offset:3072
	ds_read_b128 v[160:163], v158
	ds_read_b128 v[172:175], v158 offset:1024
	ds_read_b128 v[176:179], v158 offset:2048
	ds_read_b128 v[180:183], v158 offset:3072
	v_lshl_add_u64 v[164:165], s[40:41], 0, v[154:155]
	s_add_i32 m0, s50, 0xc000
	ds_read_b128 v[184:187], v171
	ds_read_b128 v[188:191], v171 offset:1024
	ds_read_b128 v[204:207], v171 offset:2048
	ds_read_b128 v[208:211], v171 offset:3072
	ds_read_b128 v[212:215], v171 offset:4096
	ds_read_b128 v[216:219], v171 offset:5120
	ds_read_b128 v[220:223], v171 offset:6144
	ds_read_b128 v[224:227], v171 offset:7168
	global_load_lds_dwordx4 v[164:165], off
	v_lshl_add_u64 v[164:165], s[40:41], 0, v[156:157]
	s_add_i32 m0, s50, 0xe000
	s_nop 0
	global_load_lds_dwordx4 v[164:165], off
	s_waitcnt vmcnt(8)
	s_waitcnt lgkmcnt(0)
	s_barrier
	s_waitcnt lgkmcnt(0)
	v_mfma_i32_16x16x64_i8 v[136:139], v[36:39], v[184:187], 0
	v_mfma_i32_16x16x64_i8 v[136:139], v[44:47], v[188:191], v[136:139]
	v_mfma_i32_16x16x64_i8 v[120:123], v[44:47], v[208:211], 0
	v_mfma_i32_16x16x64_i8 v[120:123], v[36:39], v[204:207], v[120:123]
	v_mfma_i32_16x16x64_i8 v[104:107], v[36:39], v[212:215], 0
	v_mfma_i32_16x16x64_i8 v[104:107], v[44:47], v[216:219], v[104:107]
	v_mfma_i32_16x16x64_i8 v[88:91], v[44:47], v[224:227], 0
	v_mfma_i32_16x16x64_i8 v[88:91], v[36:39], v[220:223], v[88:91]
	v_mfma_i32_16x16x64_i8 v[80:83], v[140:143], v[220:223], 0
	v_mfma_i32_16x16x64_i8 v[80:83], v[144:147], v[224:227], v[80:83]
	v_mfma_i32_16x16x64_i8 v[96:99], v[144:147], v[216:219], 0
	v_mfma_i32_16x16x64_i8 v[96:99], v[140:143], v[212:215], v[96:99]
	v_mfma_i32_16x16x64_i8 v[112:115], v[140:143], v[204:207], 0
	v_mfma_i32_16x16x64_i8 v[112:115], v[144:147], v[208:211], v[112:115]
	v_mfma_i32_16x16x64_i8 v[128:131], v[144:147], v[188:191], 0
	v_mfma_i32_16x16x64_i8 v[128:131], v[140:143], v[184:187], v[128:131]
	v_mfma_i32_16x16x64_i8 v[132:135], v[160:163], v[184:187], 0
	v_mfma_i32_16x16x64_i8 v[132:135], v[172:175], v[188:191], v[132:135]
	v_mfma_i32_16x16x64_i8 v[116:119], v[172:175], v[208:211], 0
	v_mfma_i32_16x16x64_i8 v[116:119], v[160:163], v[204:207], v[116:119]
	v_mfma_i32_16x16x64_i8 v[100:103], v[160:163], v[212:215], 0
	v_mfma_i32_16x16x64_i8 v[100:103], v[172:175], v[216:219], v[100:103]
	v_mfma_i32_16x16x64_i8 v[84:87], v[172:175], v[224:227], 0
	v_mfma_i32_16x16x64_i8 v[84:87], v[160:163], v[220:223], v[84:87]
	v_mfma_i32_16x16x64_i8 v[76:79], v[176:179], v[220:223], 0
	v_mfma_i32_16x16x64_i8 v[76:79], v[180:183], v[224:227], v[76:79]
	v_mfma_i32_16x16x64_i8 v[92:95], v[180:183], v[216:219], 0
	v_mfma_i32_16x16x64_i8 v[92:95], v[176:179], v[212:215], v[92:95]
	v_mfma_i32_16x16x64_i8 v[108:111], v[176:179], v[204:207], 0
	v_mfma_i32_16x16x64_i8 v[108:111], v[180:183], v[208:211], v[108:111]
	v_mfma_i32_16x16x64_i8 v[124:127], v[180:183], v[188:191], 0
	v_mfma_i32_16x16x64_i8 v[124:127], v[176:179], v[184:187], v[124:127]
	s_barrier
	s_add_i32 s64, s64, s47
	v_lshl_add_u64 v[164:165], s[44:45], 0, v[2:3]
	s_mov_b32 m0, s64
	ds_read_b128 v[184:187], v171 offset:16384
	ds_read_b128 v[188:191], v171 offset:17408
	ds_read_b128 v[204:207], v171 offset:18432
	ds_read_b128 v[208:211], v171 offset:19456
	ds_read_b128 v[212:215], v171 offset:20480
	ds_read_b128 v[216:219], v171 offset:21504
	ds_read_b128 v[220:223], v171 offset:22528
	ds_read_b128 v[224:227], v171 offset:23552
	global_load_lds_dwordx4 v[164:165], off
	s_add_i32 m0, s64, 0x2000
	s_add_u32 s64, s44, 0x80000
	v_lshl_add_u64 v[228:229], s[44:45], 0, v[148:149]
	s_addc_u32 s65, s45, 0
	s_add_i32 s67, s67, s47
	global_load_lds_dwordx4 v[228:229], off
	v_lshl_add_u64 v[240:241], s[64:65], 0, v[2:3]
	s_mov_b32 m0, s67
	v_lshl_add_u64 v[242:243], s[48:49], 0, v[150:151]
	global_load_lds_dwordx4 v[240:241], off
	v_lshl_add_u64 v[240:241], s[64:65], 0, v[148:149]
	s_add_i32 m0, s67, 0x2000
	s_nop 0
	global_load_lds_dwordx4 v[240:241], off
	v_lshl_add_u64 v[240:241], s[48:49], 0, v[152:153]
	s_mov_b32 m0, s50
	s_nop 0
	global_load_lds_dwordx4 v[240:241], off
	s_mov_b32 m0, s51
	s_nop 0
	global_load_lds_dwordx4 v[242:243], off
	s_waitcnt vmcnt(8)
	s_waitcnt lgkmcnt(0)
	s_barrier
; #define PG8_STAGE(bufoff, gbase, voff) do { _Pragma("unroll") for (int _i = 0; _i < 2; ++_i) \
;         __builtin_amdgcn_global_load_lds((const unsigned*)((const char*)(gbase) + (voff)[_i]), (PG8_LAS unsigned*)(lds + (bufoff) + ldsw + _i * 8192), 16, 0, 0); } while (0)
; #define PG8_LDA(dst, b, h) do { _Pragma("unroll") for (int m = 0; m < 4; ++m) _Pragma("unroll") for (int k = 0; k < 2; ++k) dst[m][k] = *(const PG8_LAS bf16x8*)(lds + PG8_SA(b, h) + aoff + m * 2048 + k * 1024); } while (0)
; #define PG8_LDB(dst, b, h) do { _Pragma("unroll") for (int n = 0; n < 2; ++n) _Pragma("unroll") for (int k = 0; k < 2; ++k) dst[n][k] = *(const PG8_LAS bf16x8*)(lds + PG8_SB(b, h) + boff + n * 2048 + k * 1024); } while (0)
; #define PG8_WAIT_V(n) asm volatile("s_waitcnt vmcnt(" #n ")" ::: "memory")
; #define PG8_WAIT_L(n) asm volatile("s_waitcnt lgkmcnt(" #n ")" ::: "memory")
; #define PG8_BAR __builtin_amdgcn_s_barrier()
; #define PG8_SCHED __builtin_amdgcn_sched_barrier(0)
; template <class Epi, class Sched, bool ALIGN_EPI = false, bool SP2 = false, bool I8 = false>
; __device__ __forceinline__ void gemm_phase(PG8_LAS unsigned char* lds, const Gemm g, const Sched& S, const Epi& E) {
;     ...
;             PG8_WAIT_V(8); PG8_WAIT_L(0); PG8_BAR; PG8_MMA(0, 0, At, B0); PG8_MMA(0, 1, At, B1); PG8_BAR; PG8_SCHED;
;             PG8_LDA(At, 0, 1); PG8_STAGE(PG8_SB(0, 0), b2, voffB); PG8_STAGE(PG8_SB(0, 1), b2 + hstep, voffB); PG8_STAGE(PG8_SA(0, 0), a2, voffA);
;             PG8_WAIT_V(8); PG8_WAIT_L(0); PG8_BAR; PG8_MMA(1, 0, At, B0); PG8_MMA(1, 1, At, B1); PG8_BAR; PG8_SCHED;
;             PG8_LDB(B0, 1, 0); PG8_LDB(B1, 1, 1); PG8_SCHED; PG8_LDA(At, 1, 0); PG8_STAGE(PG8_SA(0, 1), a2 + hstep, voffA);
;             PG8_WAIT_V(8); PG8_WAIT_L(0); PG8_BAR; PG8_MMA(0, 0, At, B0); PG8_MMA(0, 1, At, B1); PG8_BAR; PG8_SCHED;
	s_waitcnt lgkmcnt(0)
	v_mfma_i32_16x16x64_i8 v[72:75], v[36:39], v[184:187], 0
	v_mfma_i32_16x16x64_i8 v[72:75], v[44:47], v[188:191], v[72:75]
	v_mfma_i32_16x16x64_i8 v[56:59], v[44:47], v[208:211], 0
	v_mfma_i32_16x16x64_i8 v[56:59], v[36:39], v[204:207], v[56:59]
	v_mfma_i32_16x16x64_i8 v[32:35], v[36:39], v[212:215], 0
	v_mfma_i32_16x16x64_i8 v[32:35], v[44:47], v[216:219], v[32:35]
	v_mfma_i32_16x16x64_i8 v[16:19], v[44:47], v[224:227], 0
	v_mfma_i32_16x16x64_i8 v[16:19], v[36:39], v[220:223], v[16:19]
	v_mfma_i32_16x16x64_i8 v[8:11], v[140:143], v[220:223], 0
	v_mfma_i32_16x16x64_i8 v[8:11], v[144:147], v[224:227], v[8:11]
	v_mfma_i32_16x16x64_i8 v[24:27], v[144:147], v[216:219], 0
	v_mfma_i32_16x16x64_i8 v[24:27], v[140:143], v[212:215], v[24:27]
	v_mfma_i32_16x16x64_i8 v[48:51], v[140:143], v[204:207], 0
	v_mfma_i32_16x16x64_i8 v[48:51], v[144:147], v[208:211], v[48:51]
	v_mfma_i32_16x16x64_i8 v[64:67], v[144:147], v[188:191], 0
	v_mfma_i32_16x16x64_i8 v[64:67], v[140:143], v[184:187], v[64:67]
	v_mfma_i32_16x16x64_i8 v[36:39], v[160:163], v[184:187], 0
	v_mfma_i32_16x16x64_i8 v[36:39], v[172:175], v[188:191], v[36:39]
	v_mfma_i32_16x16x64_i8 v[52:55], v[172:175], v[208:211], 0
	v_mfma_i32_16x16x64_i8 v[52:55], v[160:163], v[204:207], v[52:55]
	v_mfma_i32_16x16x64_i8 v[28:31], v[160:163], v[212:215], 0
	v_mfma_i32_16x16x64_i8 v[28:31], v[172:175], v[216:219], v[28:31]
	v_mfma_i32_16x16x64_i8 v[12:15], v[172:175], v[224:227], 0
	v_mfma_i32_16x16x64_i8 v[12:15], v[160:163], v[220:223], v[12:15]
	v_mfma_i32_16x16x64_i8 v[4:7], v[176:179], v[220:223], 0
	v_mfma_i32_16x16x64_i8 v[4:7], v[180:183], v[224:227], v[4:7]
	v_mfma_i32_16x16x64_i8 v[20:23], v[180:183], v[216:219], 0
	v_mfma_i32_16x16x64_i8 v[20:23], v[176:179], v[212:215], v[20:23]
	v_mfma_i32_16x16x64_i8 v[40:43], v[176:179], v[204:207], 0
	v_mfma_i32_16x16x64_i8 v[40:43], v[180:183], v[208:211], v[40:43]
	v_mfma_i32_16x16x64_i8 v[44:47], v[180:183], v[188:191], 0
	v_mfma_i32_16x16x64_i8 v[44:47], v[176:179], v[184:187], v[44:47]
	s_barrier
	s_add_i32 s64, 0, 0x18000
	s_add_i32 s65, 0, 0x1c000
	v_add_u32_e32 v144, s64, v167
	v_add_u32_e32 v158, s65, v167
	ds_read_b128 v[60:63], v144
	ds_read_b128 v[68:71], v144 offset:1024
	ds_read_b128 v[140:143], v144 offset:2048
	ds_read_b128 v[144:147], v144 offset:3072
	ds_read_b128 v[160:163], v158
	ds_read_b128 v[172:175], v158 offset:1024
	ds_read_b128 v[176:179], v158 offset:2048
	ds_read_b128 v[180:183], v158 offset:3072
	s_add_u32 s48, s48, 0x80000
	s_addc_u32 s49, s49, 0
	s_mov_b32 m0, s52
	v_lshl_add_u64 v[244:245], s[48:49], 0, v[152:153]
	ds_read_b128 v[184:187], v171 offset:32768
	ds_read_b128 v[188:191], v171 offset:33792
	ds_read_b128 v[204:207], v171 offset:34816
	ds_read_b128 v[208:211], v171 offset:35840
	ds_read_b128 v[212:215], v171 offset:36864
	ds_read_b128 v[216:219], v171 offset:37888
	ds_read_b128 v[220:223], v171 offset:38912
	ds_read_b128 v[224:227], v171 offset:39936
	global_load_lds_dwordx4 v[244:245], off
	v_lshl_add_u64 v[244:245], s[48:49], 0, v[150:151]
	s_mov_b32 m0, s53
	s_nop 0
	global_load_lds_dwordx4 v[244:245], off
	s_waitcnt vmcnt(8)
	s_waitcnt lgkmcnt(0)
	s_barrier
	s_waitcnt lgkmcnt(0)
	v_mfma_i32_16x16x64_i8 v[136:139], v[60:63], v[184:187], v[136:139]
	v_mfma_i32_16x16x64_i8 v[136:139], v[68:71], v[188:191], v[136:139]
	v_mfma_i32_16x16x64_i8 v[120:123], v[68:71], v[208:211], v[120:123]
	v_mfma_i32_16x16x64_i8 v[120:123], v[60:63], v[204:207], v[120:123]
	v_mfma_i32_16x16x64_i8 v[104:107], v[60:63], v[212:215], v[104:107]
	v_mfma_i32_16x16x64_i8 v[104:107], v[68:71], v[216:219], v[104:107]
	v_mfma_i32_16x16x64_i8 v[88:91], v[68:71], v[224:227], v[88:91]
	v_mfma_i32_16x16x64_i8 v[88:91], v[60:63], v[220:223], v[88:91]
	v_mfma_i32_16x16x64_i8 v[80:83], v[140:143], v[220:223], v[80:83]
	v_mfma_i32_16x16x64_i8 v[80:83], v[144:147], v[224:227], v[80:83]
	v_mfma_i32_16x16x64_i8 v[96:99], v[144:147], v[216:219], v[96:99]
	v_mfma_i32_16x16x64_i8 v[96:99], v[140:143], v[212:215], v[96:99]
	v_mfma_i32_16x16x64_i8 v[112:115], v[140:143], v[204:207], v[112:115]
	v_mfma_i32_16x16x64_i8 v[112:115], v[144:147], v[208:211], v[112:115]
	v_mfma_i32_16x16x64_i8 v[128:131], v[144:147], v[188:191], v[128:131]
	v_mfma_i32_16x16x64_i8 v[128:131], v[140:143], v[184:187], v[128:131]
	v_mfma_i32_16x16x64_i8 v[132:135], v[160:163], v[184:187], v[132:135]
	v_mfma_i32_16x16x64_i8 v[132:135], v[172:175], v[188:191], v[132:135]
	v_mfma_i32_16x16x64_i8 v[116:119], v[172:175], v[208:211], v[116:119]
	v_mfma_i32_16x16x64_i8 v[116:119], v[160:163], v[204:207], v[116:119]
	v_mfma_i32_16x16x64_i8 v[100:103], v[160:163], v[212:215], v[100:103]
	v_mfma_i32_16x16x64_i8 v[100:103], v[172:175], v[216:219], v[100:103]
	v_mfma_i32_16x16x64_i8 v[84:87], v[172:175], v[224:227], v[84:87]
	v_mfma_i32_16x16x64_i8 v[84:87], v[160:163], v[220:223], v[84:87]
	v_mfma_i32_16x16x64_i8 v[76:79], v[176:179], v[220:223], v[76:79]
	v_mfma_i32_16x16x64_i8 v[76:79], v[180:183], v[224:227], v[76:79]
	v_mfma_i32_16x16x64_i8 v[92:95], v[180:183], v[216:219], v[92:95]
	v_mfma_i32_16x16x64_i8 v[92:95], v[176:179], v[212:215], v[92:95]
	v_mfma_i32_16x16x64_i8 v[108:111], v[176:179], v[204:207], v[108:111]
	v_mfma_i32_16x16x64_i8 v[108:111], v[180:183], v[208:211], v[108:111]
	v_mfma_i32_16x16x64_i8 v[124:127], v[180:183], v[188:191], v[124:127]
	v_mfma_i32_16x16x64_i8 v[124:127], v[176:179], v[184:187], v[124:127]
	s_barrier
; #define PG8_STAGE(bufoff, gbase, voff) do { _Pragma("unroll") for (int _i = 0; _i < 2; ++_i) \
;         __builtin_amdgcn_global_load_lds((const unsigned*)((const char*)(gbase) + (voff)[_i]), (PG8_LAS unsigned*)(lds + (bufoff) + ldsw + _i * 8192), 16, 0, 0); } while (0)
; #define PG8_LDA(dst, b, h) do { _Pragma("unroll") for (int m = 0; m < 4; ++m) _Pragma("unroll") for (int k = 0; k < 2; ++k) dst[m][k] = *(const PG8_LAS bf16x8*)(lds + PG8_SA(b, h) + aoff + m * 2048 + k * 1024); } while (0)
; #define PG8_LDB(dst, b, h) do { _Pragma("unroll") for (int n = 0; n < 2; ++n) _Pragma("unroll") for (int k = 0; k < 2; ++k) dst[n][k] = *(const PG8_LAS bf16x8*)(lds + PG8_SB(b, h) + boff + n * 2048 + k * 1024); } while (0)
; #define PG8_WAIT_V(n) asm volatile("s_waitcnt vmcnt(" #n ")" ::: "memory")
; #define PG8_WAIT_L(n) asm volatile("s_waitcnt lgkmcnt(" #n ")" ::: "memory")
; #define PG8_BAR __builtin_amdgcn_s_barrier()
; #define PG8_SCHED __builtin_amdgcn_sched_barrier(0)
; template <class Epi, class Sched, bool ALIGN_EPI = false, bool SP2 = false, bool I8 = false>
; __device__ __forceinline__ void gemm_phase(PG8_LAS unsigned char* lds, const Gemm g, const Sched& S, const Epi& E) {
;     ...
;             const bool last = (t == nt - 2);
;             const char* a1 = cA + (size_t)(t + 1) * kstep;
;             const char* a2 = last ? nA : cA + (size_t)(t + 2) * kstep; const char* b2 = last ? nB : cB + (size_t)(t + 2) * kstep;
;             const char* a3 = a2 + kstep; const char* b3 = b2 + kstep;
;             if (last && has_next) S.a_ready(nxt);
;             if constexpr (SP2) {
;             PG8_LDB(B0, 0, 0); PG8_LDB(B1, 0, 1); PG8_SCHED; PG8_LDA(At, 0, 0); PG8_STAGE(PG8_SA(1, 1), a1 + hstep, voffA);
;             PG8_WAIT_V(8); PG8_WAIT_L(0); PG8_BAR; PG8_MMA(0, 0, At, B0); PG8_MMA(0, 1, At, B1); PG8_BAR; PG8_SCHED;
;     ...
;             PG8_LDA(At, 1, 1); PG8_STAGE(PG8_SB(1, 0), b3, voffB); PG8_STAGE(PG8_SB(1, 1), b3 + hstep, voffB); PG8_STAGE(PG8_SA(1, 0), a3, voffA);
;             PG8_WAIT_V(8); PG8_WAIT_L(0); PG8_BAR; PG8_MMA(1, 0, At, B0); PG8_MMA(1, 1, At, B1); PG8_BAR; PG8_SCHED;
	s_add_i32 s48, s64, s47
	v_lshl_add_u64 v[164:165], v[164:165], 0, s[84:85]
	s_mov_b32 m0, s48
	ds_read_b128 v[184:187], v171 offset:49152
	ds_read_b128 v[188:191], v171 offset:50176
	ds_read_b128 v[204:207], v171 offset:51200
	ds_read_b128 v[208:211], v171 offset:52224
	ds_read_b128 v[212:215], v171 offset:53248
	ds_read_b128 v[216:219], v171 offset:54272
	ds_read_b128 v[220:223], v171 offset:55296
	ds_read_b128 v[224:227], v171 offset:56320
	global_load_lds_dwordx4 v[164:165], off
	s_add_i32 m0, s48, 0x2000
	s_add_u32 s44, s44, 0x80080
	v_lshl_add_u64 v[164:165], v[228:229], 0, s[84:85]
	s_addc_u32 s45, s45, 0
	s_add_i32 s48, s65, s47
	global_load_lds_dwordx4 v[164:165], off
	v_lshl_add_u64 v[164:165], s[44:45], 0, v[2:3]
	s_mov_b32 m0, s48
	s_nop 0
	global_load_lds_dwordx4 v[164:165], off
	v_lshl_add_u64 v[164:165], s[44:45], 0, v[148:149]
	s_add_i32 m0, s48, 0x2000
	s_nop 0
	global_load_lds_dwordx4 v[164:165], off
	v_lshl_add_u64 v[164:165], v[240:241], 0, s[84:85]
	s_mov_b32 m0, s54
	s_nop 0
	global_load_lds_dwordx4 v[164:165], off
	v_lshl_add_u64 v[164:165], v[242:243], 0, s[84:85]
	s_mov_b32 m0, s55
	s_nop 0
	global_load_lds_dwordx4 v[164:165], off
	s_waitcnt vmcnt(8)
	s_waitcnt lgkmcnt(0)
	s_barrier
	s_waitcnt lgkmcnt(0)
	v_mfma_i32_16x16x64_i8 v[72:75], v[60:63], v[184:187], v[72:75]
	v_mfma_i32_16x16x64_i8 v[72:75], v[68:71], v[188:191], v[72:75]
	v_mfma_i32_16x16x64_i8 v[56:59], v[68:71], v[208:211], v[56:59]
	v_mfma_i32_16x16x64_i8 v[56:59], v[60:63], v[204:207], v[56:59]
	v_mfma_i32_16x16x64_i8 v[32:35], v[60:63], v[212:215], v[32:35]
	v_mfma_i32_16x16x64_i8 v[32:35], v[68:71], v[216:219], v[32:35]
	v_mfma_i32_16x16x64_i8 v[16:19], v[68:71], v[224:227], v[16:19]
	v_mfma_i32_16x16x64_i8 v[16:19], v[60:63], v[220:223], v[16:19]
	v_mfma_i32_16x16x64_i8 v[8:11], v[140:143], v[220:223], v[8:11]
	v_mfma_i32_16x16x64_i8 v[8:11], v[144:147], v[224:227], v[8:11]
	v_mfma_i32_16x16x64_i8 v[24:27], v[144:147], v[216:219], v[24:27]
	v_mfma_i32_16x16x64_i8 v[24:27], v[140:143], v[212:215], v[24:27]
	v_mfma_i32_16x16x64_i8 v[48:51], v[140:143], v[204:207], v[48:51]
	v_mfma_i32_16x16x64_i8 v[48:51], v[144:147], v[208:211], v[48:51]
	v_mfma_i32_16x16x64_i8 v[64:67], v[144:147], v[188:191], v[64:67]
	v_mfma_i32_16x16x64_i8 v[64:67], v[140:143], v[184:187], v[64:67]
	v_mfma_i32_16x16x64_i8 v[36:39], v[160:163], v[184:187], v[36:39]
	v_mfma_i32_16x16x64_i8 v[68:71], v[172:175], v[188:191], v[36:39]
	v_mfma_i32_16x16x64_i8 v[36:39], v[172:175], v[208:211], v[52:55]
	v_mfma_i32_16x16x64_i8 v[52:55], v[160:163], v[204:207], v[36:39]
	v_mfma_i32_16x16x64_i8 v[28:31], v[160:163], v[212:215], v[28:31]
	v_mfma_i32_16x16x64_i8 v[28:31], v[172:175], v[216:219], v[28:31]
	v_mfma_i32_16x16x64_i8 v[12:15], v[172:175], v[224:227], v[12:15]
	v_mfma_i32_16x16x64_i8 v[12:15], v[160:163], v[220:223], v[12:15]
	v_mfma_i32_16x16x64_i8 v[4:7], v[176:179], v[220:223], v[4:7]
	v_mfma_i32_16x16x64_i8 v[4:7], v[180:183], v[224:227], v[4:7]
	v_mfma_i32_16x16x64_i8 v[20:23], v[180:183], v[216:219], v[20:23]
	v_mfma_i32_16x16x64_i8 v[20:23], v[176:179], v[212:215], v[20:23]
	v_mfma_i32_16x16x64_i8 v[36:39], v[176:179], v[204:207], v[40:43]
	v_mfma_i32_16x16x64_i8 v[40:43], v[180:183], v[208:211], v[36:39]
	v_mfma_i32_16x16x64_i8 v[36:39], v[180:183], v[188:191], v[44:47]
	v_mfma_i32_16x16x64_i8 v[60:63], v[176:179], v[184:187], v[36:39]
	s_barrier
	s_add_i32 s61, s61, 2
	s_add_u32 s40, s40, 0x100
	s_addc_u32 s41, s41, 0
	s_add_u32 s59, s59, 0x100
	s_addc_u32 s60, s60, 0
	s_cmp_gt_u32 s61, 29
	s_cbranch_scc1 .Lkloop_exit_3
.LBB0_1591:
	s_add_u32 s44, s40, 0xfff80080
	s_addc_u32 s45, s41, -1
	s_add_i32 s64, 0, 0x10000
	s_cmp_eq_u32 s61, 28
	s_cselect_b32 s49, s25, s45
	s_cselect_b32 s48, s57, s44
	s_cselect_b32 s45, s23, s60
	s_cselect_b32 s44, s58, s59
	s_add_i32 s67, 0, 0x14000
	v_add_u32_e32 v144, s64, v167
	v_add_u32_e32 v158, s67, v167
	ds_read_b128 v[36:39], v144
	ds_read_b128 v[44:47], v144 offset:1024
	ds_read_b128 v[140:143], v144 offset:2048
	ds_read_b128 v[144:147], v144 offset:3072
	ds_read_b128 v[160:163], v158
	ds_read_b128 v[172:175], v158 offset:1024
	ds_read_b128 v[176:179], v158 offset:2048
	ds_read_b128 v[180:183], v158 offset:3072
	v_lshl_add_u64 v[164:165], s[40:41], 0, v[154:155]
	s_add_i32 m0, s50, 0xc000
	ds_read_b128 v[184:187], v171
	ds_read_b128 v[188:191], v171 offset:1024
	ds_read_b128 v[204:207], v171 offset:2048
	ds_read_b128 v[208:211], v171 offset:3072
	ds_read_b128 v[212:215], v171 offset:4096
	ds_read_b128 v[216:219], v171 offset:5120
	ds_read_b128 v[220:223], v171 offset:6144
	ds_read_b128 v[224:227], v171 offset:7168
	global_load_lds_dwordx4 v[164:165], off
	v_lshl_add_u64 v[164:165], s[40:41], 0, v[156:157]
	s_add_i32 m0, s50, 0xe000
	s_nop 0
	global_load_lds_dwordx4 v[164:165], off
	s_waitcnt vmcnt(8)
	s_waitcnt lgkmcnt(0)
	s_barrier
; #define PG8_STAGE(bufoff, gbase, voff) do { _Pragma("unroll") for (int _i = 0; _i < 2; ++_i) \
;         __builtin_amdgcn_global_load_lds((const unsigned*)((const char*)(gbase) + (voff)[_i]), (PG8_LAS unsigned*)(lds + (bufoff) + ldsw + _i * 8192), 16, 0, 0); } while (0)
; #define PG8_LDA(dst, b, h) do { _Pragma("unroll") for (int m = 0; m < 4; ++m) _Pragma("unroll") for (int k = 0; k < 2; ++k) dst[m][k] = *(const PG8_LAS bf16x8*)(lds + PG8_SA(b, h) + aoff + m * 2048 + k * 1024); } while (0)
; #define PG8_WAIT_V(n) asm volatile("s_waitcnt vmcnt(" #n ")" ::: "memory")
; #define PG8_WAIT_L(n) asm volatile("s_waitcnt lgkmcnt(" #n ")" ::: "memory")
; #define PG8_BAR __builtin_amdgcn_s_barrier()
; #define PG8_SCHED __builtin_amdgcn_sched_barrier(0)
; template <class Epi, class Sched, bool ALIGN_EPI = false, bool SP2 = false, bool I8 = false>
; __device__ __forceinline__ void gemm_phase(PG8_LAS unsigned char* lds, const Gemm g, const Sched& S, const Epi& E) {
;     ...
;             PG8_WAIT_V(8); PG8_WAIT_L(0); PG8_BAR; PG8_MMA(0, 0, At, B0); PG8_MMA(0, 1, At, B1); PG8_BAR; PG8_SCHED;
;             PG8_LDA(At, 0, 1); PG8_STAGE(PG8_SB(0, 0), b2, voffB); PG8_STAGE(PG8_SB(0, 1), b2 + hstep, voffB); PG8_STAGE(PG8_SA(0, 0), a2, voffA);
;             PG8_WAIT_V(8); PG8_WAIT_L(0); PG8_BAR; PG8_MMA(1, 0, At, B0); PG8_MMA(1, 1, At, B1); PG8_BAR; PG8_SCHED;
	s_waitcnt lgkmcnt(0)
	v_mfma_i32_16x16x64_i8 v[136:139], v[36:39], v[184:187], v[136:139]
	v_mfma_i32_16x16x64_i8 v[136:139], v[44:47], v[188:191], v[136:139]
	v_mfma_i32_16x16x64_i8 v[120:123], v[44:47], v[208:211], v[120:123]
	v_mfma_i32_16x16x64_i8 v[120:123], v[36:39], v[204:207], v[120:123]
	v_mfma_i32_16x16x64_i8 v[104:107], v[36:39], v[212:215], v[104:107]
	v_mfma_i32_16x16x64_i8 v[104:107], v[44:47], v[216:219], v[104:107]
	v_mfma_i32_16x16x64_i8 v[88:91], v[44:47], v[224:227], v[88:91]
	v_mfma_i32_16x16x64_i8 v[88:91], v[36:39], v[220:223], v[88:91]
	v_mfma_i32_16x16x64_i8 v[80:83], v[140:143], v[220:223], v[80:83]
	v_mfma_i32_16x16x64_i8 v[80:83], v[144:147], v[224:227], v[80:83]
	v_mfma_i32_16x16x64_i8 v[96:99], v[144:147], v[216:219], v[96:99]
	v_mfma_i32_16x16x64_i8 v[96:99], v[140:143], v[212:215], v[96:99]
	v_mfma_i32_16x16x64_i8 v[112:115], v[140:143], v[204:207], v[112:115]
	v_mfma_i32_16x16x64_i8 v[112:115], v[144:147], v[208:211], v[112:115]
	v_mfma_i32_16x16x64_i8 v[128:131], v[144:147], v[188:191], v[128:131]
	v_mfma_i32_16x16x64_i8 v[128:131], v[140:143], v[184:187], v[128:131]
	v_mfma_i32_16x16x64_i8 v[132:135], v[160:163], v[184:187], v[132:135]
	v_mfma_i32_16x16x64_i8 v[132:135], v[172:175], v[188:191], v[132:135]
	v_mfma_i32_16x16x64_i8 v[116:119], v[172:175], v[208:211], v[116:119]
	v_mfma_i32_16x16x64_i8 v[116:119], v[160:163], v[204:207], v[116:119]
	v_mfma_i32_16x16x64_i8 v[100:103], v[160:163], v[212:215], v[100:103]
	v_mfma_i32_16x16x64_i8 v[100:103], v[172:175], v[216:219], v[100:103]
	v_mfma_i32_16x16x64_i8 v[84:87], v[172:175], v[224:227], v[84:87]
	v_mfma_i32_16x16x64_i8 v[84:87], v[160:163], v[220:223], v[84:87]
	v_mfma_i32_16x16x64_i8 v[76:79], v[176:179], v[220:223], v[76:79]
	v_mfma_i32_16x16x64_i8 v[76:79], v[180:183], v[224:227], v[76:79]
	v_mfma_i32_16x16x64_i8 v[92:95], v[180:183], v[216:219], v[92:95]
	v_mfma_i32_16x16x64_i8 v[92:95], v[176:179], v[212:215], v[92:95]
	v_mfma_i32_16x16x64_i8 v[108:111], v[176:179], v[204:207], v[108:111]
	v_mfma_i32_16x16x64_i8 v[108:111], v[180:183], v[208:211], v[108:111]
	v_mfma_i32_16x16x64_i8 v[124:127], v[180:183], v[188:191], v[124:127]
	v_mfma_i32_16x16x64_i8 v[124:127], v[176:179], v[184:187], v[124:127]
	s_barrier
	s_add_i32 s64, s64, s47
	v_lshl_add_u64 v[164:165], s[44:45], 0, v[2:3]
	s_mov_b32 m0, s64
	ds_read_b128 v[184:187], v171 offset:16384
	ds_read_b128 v[188:191], v171 offset:17408
	ds_read_b128 v[204:207], v171 offset:18432
	ds_read_b128 v[208:211], v171 offset:19456
	ds_read_b128 v[212:215], v171 offset:20480
	ds_read_b128 v[216:219], v171 offset:21504
	ds_read_b128 v[220:223], v171 offset:22528
	ds_read_b128 v[224:227], v171 offset:23552
	global_load_lds_dwordx4 v[164:165], off
	s_add_i32 m0, s64, 0x2000
	s_add_u32 s64, s44, 0x80000
	v_lshl_add_u64 v[228:229], s[44:45], 0, v[148:149]
	s_addc_u32 s65, s45, 0
	s_add_i32 s67, s67, s47
	global_load_lds_dwordx4 v[228:229], off
	v_lshl_add_u64 v[240:241], s[64:65], 0, v[2:3]
	s_mov_b32 m0, s67
	v_lshl_add_u64 v[242:243], s[48:49], 0, v[150:151]
	global_load_lds_dwordx4 v[240:241], off
	v_lshl_add_u64 v[240:241], s[64:65], 0, v[148:149]
	s_add_i32 m0, s67, 0x2000
	s_nop 0
	global_load_lds_dwordx4 v[240:241], off
	v_lshl_add_u64 v[240:241], s[48:49], 0, v[152:153]
	s_mov_b32 m0, s50
	s_nop 0
	global_load_lds_dwordx4 v[240:241], off
	s_mov_b32 m0, s51
	s_nop 0
	global_load_lds_dwordx4 v[242:243], off
	s_waitcnt vmcnt(8)
	s_waitcnt lgkmcnt(0)
	s_barrier
	s_waitcnt lgkmcnt(0)
	v_mfma_i32_16x16x64_i8 v[72:75], v[36:39], v[184:187], v[72:75]
	v_mfma_i32_16x16x64_i8 v[72:75], v[44:47], v[188:191], v[72:75]
	v_mfma_i32_16x16x64_i8 v[56:59], v[44:47], v[208:211], v[56:59]
	v_mfma_i32_16x16x64_i8 v[56:59], v[36:39], v[204:207], v[56:59]
	v_mfma_i32_16x16x64_i8 v[32:35], v[36:39], v[212:215], v[32:35]
	v_mfma_i32_16x16x64_i8 v[32:35], v[44:47], v[216:219], v[32:35]
	v_mfma_i32_16x16x64_i8 v[16:19], v[44:47], v[224:227], v[16:19]
	v_mfma_i32_16x16x64_i8 v[16:19], v[36:39], v[220:223], v[16:19]
	v_mfma_i32_16x16x64_i8 v[8:11], v[140:143], v[220:223], v[8:11]
	v_mfma_i32_16x16x64_i8 v[8:11], v[144:147], v[224:227], v[8:11]
	v_mfma_i32_16x16x64_i8 v[24:27], v[144:147], v[216:219], v[24:27]
	v_mfma_i32_16x16x64_i8 v[24:27], v[140:143], v[212:215], v[24:27]
	v_mfma_i32_16x16x64_i8 v[48:51], v[140:143], v[204:207], v[48:51]
	v_mfma_i32_16x16x64_i8 v[48:51], v[144:147], v[208:211], v[48:51]
	v_mfma_i32_16x16x64_i8 v[64:67], v[144:147], v[188:191], v[64:67]
	v_mfma_i32_16x16x64_i8 v[64:67], v[140:143], v[184:187], v[64:67]
	v_mfma_i32_16x16x64_i8 v[36:39], v[160:163], v[184:187], v[68:71]
	v_mfma_i32_16x16x64_i8 v[36:39], v[172:175], v[188:191], v[36:39]
	v_mfma_i32_16x16x64_i8 v[52:55], v[172:175], v[208:211], v[52:55]
	v_mfma_i32_16x16x64_i8 v[52:55], v[160:163], v[204:207], v[52:55]
	v_mfma_i32_16x16x64_i8 v[28:31], v[160:163], v[212:215], v[28:31]
	v_mfma_i32_16x16x64_i8 v[28:31], v[172:175], v[216:219], v[28:31]
	v_mfma_i32_16x16x64_i8 v[12:15], v[172:175], v[224:227], v[12:15]
	v_mfma_i32_16x16x64_i8 v[12:15], v[160:163], v[220:223], v[12:15]
	v_mfma_i32_16x16x64_i8 v[4:7], v[176:179], v[220:223], v[4:7]
	v_mfma_i32_16x16x64_i8 v[4:7], v[180:183], v[224:227], v[4:7]
	v_mfma_i32_16x16x64_i8 v[20:23], v[180:183], v[216:219], v[20:23]
	v_mfma_i32_16x16x64_i8 v[20:23], v[176:179], v[212:215], v[20:23]
	v_mfma_i32_16x16x64_i8 v[40:43], v[176:179], v[204:207], v[40:43]
	v_mfma_i32_16x16x64_i8 v[40:43], v[180:183], v[208:211], v[40:43]
	v_mfma_i32_16x16x64_i8 v[44:47], v[180:183], v[188:191], v[60:63]
	v_mfma_i32_16x16x64_i8 v[44:47], v[176:179], v[184:187], v[44:47]
	s_barrier
; #define PG8_STAGE(bufoff, gbase, voff) do { _Pragma("unroll") for (int _i = 0; _i < 2; ++_i) \
;         __builtin_amdgcn_global_load_lds((const unsigned*)((const char*)(gbase) + (voff)[_i]), (PG8_LAS unsigned*)(lds + (bufoff) + ldsw + _i * 8192), 16, 0, 0); } while (0)
; #define PG8_LDA(dst, b, h) do { _Pragma("unroll") for (int m = 0; m < 4; ++m) _Pragma("unroll") for (int k = 0; k < 2; ++k) dst[m][k] = *(const PG8_LAS bf16x8*)(lds + PG8_SA(b, h) + aoff + m * 2048 + k * 1024); } while (0)
; #define PG8_LDB(dst, b, h) do { _Pragma("unroll") for (int n = 0; n < 2; ++n) _Pragma("unroll") for (int k = 0; k < 2; ++k) dst[n][k] = *(const PG8_LAS bf16x8*)(lds + PG8_SB(b, h) + boff + n * 2048 + k * 1024); } while (0)
; #define PG8_WAIT_V(n) asm volatile("s_waitcnt vmcnt(" #n ")" ::: "memory")
; #define PG8_WAIT_L(n) asm volatile("s_waitcnt lgkmcnt(" #n ")" ::: "memory")
; #define PG8_BAR __builtin_amdgcn_s_barrier()
; #define PG8_SCHED __builtin_amdgcn_sched_barrier(0)
; template <class Epi, class Sched, bool ALIGN_EPI = false, bool SP2 = false, bool I8 = false>
; __device__ __forceinline__ void gemm_phase(PG8_LAS unsigned char* lds, const Gemm g, const Sched& S, const Epi& E) {
;     ...
;             PG8_LDB(B0, 1, 0); PG8_LDB(B1, 1, 1); PG8_SCHED; PG8_LDA(At, 1, 0); PG8_STAGE(PG8_SA(0, 1), a2 + hstep, voffA);
;             PG8_WAIT_V(8); PG8_WAIT_L(0); PG8_BAR; PG8_MMA(0, 0, At, B0); PG8_MMA(0, 1, At, B1); PG8_BAR; PG8_SCHED;
;             PG8_LDA(At, 1, 1); PG8_STAGE(PG8_SB(1, 0), b3, voffB); PG8_STAGE(PG8_SB(1, 1), b3 + hstep, voffB); PG8_STAGE(PG8_SA(1, 0), a3, voffA);
;             PG8_WAIT_V(8); PG8_WAIT_L(0); PG8_BAR; PG8_MMA(1, 0, At, B0); PG8_MMA(1, 1, At, B1); PG8_BAR; PG8_SCHED;
	s_add_i32 s64, 0, 0x18000
	s_add_i32 s65, 0, 0x1c000
	v_add_u32_e32 v144, s64, v167
	v_add_u32_e32 v158, s65, v167
	ds_read_b128 v[60:63], v144
	ds_read_b128 v[68:71], v144 offset:1024
	ds_read_b128 v[140:143], v144 offset:2048
	ds_read_b128 v[144:147], v144 offset:3072
	ds_read_b128 v[160:163], v158
	ds_read_b128 v[172:175], v158 offset:1024
	ds_read_b128 v[176:179], v158 offset:2048
	ds_read_b128 v[180:183], v158 offset:3072
	s_add_u32 s48, s48, 0x80000
	s_addc_u32 s49, s49, 0
	s_mov_b32 m0, s52
	v_lshl_add_u64 v[244:245], s[48:49], 0, v[152:153]
	ds_read_b128 v[184:187], v171 offset:32768
	ds_read_b128 v[188:191], v171 offset:33792
	ds_read_b128 v[204:207], v171 offset:34816
	ds_read_b128 v[208:211], v171 offset:35840
	ds_read_b128 v[212:215], v171 offset:36864
	ds_read_b128 v[216:219], v171 offset:37888
	ds_read_b128 v[220:223], v171 offset:38912
	ds_read_b128 v[224:227], v171 offset:39936
	global_load_lds_dwordx4 v[244:245], off
	v_lshl_add_u64 v[244:245], s[48:49], 0, v[150:151]
	s_mov_b32 m0, s53
	s_nop 0
	global_load_lds_dwordx4 v[244:245], off
	s_waitcnt vmcnt(8)
	s_waitcnt lgkmcnt(0)
	s_barrier
	s_waitcnt lgkmcnt(0)
	v_mfma_i32_16x16x64_i8 v[136:139], v[60:63], v[184:187], v[136:139]
	v_mfma_i32_16x16x64_i8 v[136:139], v[68:71], v[188:191], v[136:139]
	v_mfma_i32_16x16x64_i8 v[120:123], v[68:71], v[208:211], v[120:123]
	v_mfma_i32_16x16x64_i8 v[120:123], v[60:63], v[204:207], v[120:123]
	v_mfma_i32_16x16x64_i8 v[104:107], v[60:63], v[212:215], v[104:107]
	v_mfma_i32_16x16x64_i8 v[104:107], v[68:71], v[216:219], v[104:107]
	v_mfma_i32_16x16x64_i8 v[88:91], v[68:71], v[224:227], v[88:91]
	v_mfma_i32_16x16x64_i8 v[88:91], v[60:63], v[220:223], v[88:91]
	v_mfma_i32_16x16x64_i8 v[80:83], v[140:143], v[220:223], v[80:83]
	v_mfma_i32_16x16x64_i8 v[80:83], v[144:147], v[224:227], v[80:83]
	v_mfma_i32_16x16x64_i8 v[96:99], v[144:147], v[216:219], v[96:99]
	v_mfma_i32_16x16x64_i8 v[96:99], v[140:143], v[212:215], v[96:99]
	v_mfma_i32_16x16x64_i8 v[112:115], v[140:143], v[204:207], v[112:115]
	v_mfma_i32_16x16x64_i8 v[112:115], v[144:147], v[208:211], v[112:115]
	v_mfma_i32_16x16x64_i8 v[128:131], v[144:147], v[188:191], v[128:131]
	v_mfma_i32_16x16x64_i8 v[128:131], v[140:143], v[184:187], v[128:131]
	v_mfma_i32_16x16x64_i8 v[132:135], v[160:163], v[184:187], v[132:135]
	v_mfma_i32_16x16x64_i8 v[132:135], v[172:175], v[188:191], v[132:135]
	v_mfma_i32_16x16x64_i8 v[116:119], v[172:175], v[208:211], v[116:119]
	v_mfma_i32_16x16x64_i8 v[116:119], v[160:163], v[204:207], v[116:119]
	v_mfma_i32_16x16x64_i8 v[100:103], v[160:163], v[212:215], v[100:103]
	v_mfma_i32_16x16x64_i8 v[100:103], v[172:175], v[216:219], v[100:103]
	v_mfma_i32_16x16x64_i8 v[84:87], v[172:175], v[224:227], v[84:87]
	v_mfma_i32_16x16x64_i8 v[84:87], v[160:163], v[220:223], v[84:87]
	v_mfma_i32_16x16x64_i8 v[76:79], v[176:179], v[220:223], v[76:79]
	v_mfma_i32_16x16x64_i8 v[76:79], v[180:183], v[224:227], v[76:79]
	v_mfma_i32_16x16x64_i8 v[92:95], v[180:183], v[216:219], v[92:95]
	v_mfma_i32_16x16x64_i8 v[92:95], v[176:179], v[212:215], v[92:95]
	v_mfma_i32_16x16x64_i8 v[108:111], v[176:179], v[204:207], v[108:111]
	v_mfma_i32_16x16x64_i8 v[108:111], v[180:183], v[208:211], v[108:111]
	v_mfma_i32_16x16x64_i8 v[124:127], v[180:183], v[188:191], v[124:127]
	v_mfma_i32_16x16x64_i8 v[124:127], v[176:179], v[184:187], v[124:127]
	s_barrier
	s_add_i32 s48, s64, s47
	v_lshl_add_u64 v[164:165], v[164:165], 0, s[84:85]
	s_mov_b32 m0, s48
	ds_read_b128 v[184:187], v171 offset:49152
	ds_read_b128 v[188:191], v171 offset:50176
	ds_read_b128 v[204:207], v171 offset:51200
	ds_read_b128 v[208:211], v171 offset:52224
	ds_read_b128 v[212:215], v171 offset:53248
	ds_read_b128 v[216:219], v171 offset:54272
	ds_read_b128 v[220:223], v171 offset:55296
	ds_read_b128 v[224:227], v171 offset:56320
	global_load_lds_dwordx4 v[164:165], off
	s_add_i32 m0, s48, 0x2000
	s_add_u32 s44, s44, 0x80080
	v_lshl_add_u64 v[164:165], v[228:229], 0, s[84:85]
	s_addc_u32 s45, s45, 0
	s_add_i32 s48, s65, s47
	global_load_lds_dwordx4 v[164:165], off
	v_lshl_add_u64 v[164:165], s[44:45], 0, v[2:3]
	s_mov_b32 m0, s48
	s_nop 0
	global_load_lds_dwordx4 v[164:165], off
	v_lshl_add_u64 v[164:165], s[44:45], 0, v[148:149]
	s_add_i32 m0, s48, 0x2000
	s_nop 0
	global_load_lds_dwordx4 v[164:165], off
	v_lshl_add_u64 v[164:165], v[240:241], 0, s[84:85]
	s_mov_b32 m0, s54
	s_nop 0
	global_load_lds_dwordx4 v[164:165], off
	v_lshl_add_u64 v[164:165], v[242:243], 0, s[84:85]
	s_mov_b32 m0, s55
	s_nop 0
	global_load_lds_dwordx4 v[164:165], off
	s_waitcnt vmcnt(8)
	s_waitcnt lgkmcnt(0)
	s_barrier
	s_waitcnt lgkmcnt(0)
	v_mfma_i32_16x16x64_i8 v[72:75], v[60:63], v[184:187], v[72:75]
	v_mfma_i32_16x16x64_i8 v[72:75], v[68:71], v[188:191], v[72:75]
	v_mfma_i32_16x16x64_i8 v[56:59], v[68:71], v[208:211], v[56:59]
	v_mfma_i32_16x16x64_i8 v[56:59], v[60:63], v[204:207], v[56:59]
	v_mfma_i32_16x16x64_i8 v[32:35], v[60:63], v[212:215], v[32:35]
	v_mfma_i32_16x16x64_i8 v[32:35], v[68:71], v[216:219], v[32:35]
	v_mfma_i32_16x16x64_i8 v[16:19], v[68:71], v[224:227], v[16:19]
	v_mfma_i32_16x16x64_i8 v[16:19], v[60:63], v[220:223], v[16:19]
	v_mfma_i32_16x16x64_i8 v[8:11], v[140:143], v[220:223], v[8:11]
	v_mfma_i32_16x16x64_i8 v[8:11], v[144:147], v[224:227], v[8:11]
	v_mfma_i32_16x16x64_i8 v[24:27], v[144:147], v[216:219], v[24:27]
	v_mfma_i32_16x16x64_i8 v[24:27], v[140:143], v[212:215], v[24:27]
	v_mfma_i32_16x16x64_i8 v[48:51], v[140:143], v[204:207], v[48:51]
	v_mfma_i32_16x16x64_i8 v[48:51], v[144:147], v[208:211], v[48:51]
	v_mfma_i32_16x16x64_i8 v[64:67], v[144:147], v[188:191], v[64:67]
	v_mfma_i32_16x16x64_i8 v[64:67], v[140:143], v[184:187], v[64:67]
	v_mfma_i32_16x16x64_i8 v[36:39], v[160:163], v[184:187], v[36:39]
	v_mfma_i32_16x16x64_i8 v[68:71], v[172:175], v[188:191], v[36:39]
	v_mfma_i32_16x16x64_i8 v[36:39], v[172:175], v[208:211], v[52:55]
	v_mfma_i32_16x16x64_i8 v[52:55], v[160:163], v[204:207], v[36:39]
	v_mfma_i32_16x16x64_i8 v[28:31], v[160:163], v[212:215], v[28:31]
	v_mfma_i32_16x16x64_i8 v[28:31], v[172:175], v[216:219], v[28:31]
	v_mfma_i32_16x16x64_i8 v[12:15], v[172:175], v[224:227], v[12:15]
	v_mfma_i32_16x16x64_i8 v[12:15], v[160:163], v[220:223], v[12:15]
	v_mfma_i32_16x16x64_i8 v[4:7], v[176:179], v[220:223], v[4:7]
	v_mfma_i32_16x16x64_i8 v[4:7], v[180:183], v[224:227], v[4:7]
	v_mfma_i32_16x16x64_i8 v[20:23], v[180:183], v[216:219], v[20:23]
	v_mfma_i32_16x16x64_i8 v[20:23], v[176:179], v[212:215], v[20:23]
	v_mfma_i32_16x16x64_i8 v[36:39], v[176:179], v[204:207], v[40:43]
	v_mfma_i32_16x16x64_i8 v[40:43], v[180:183], v[208:211], v[36:39]
	v_mfma_i32_16x16x64_i8 v[36:39], v[180:183], v[188:191], v[44:47]
	v_mfma_i32_16x16x64_i8 v[60:63], v[176:179], v[184:187], v[36:39]
	s_barrier
	s_add_i32 s61, s61, 2
	s_add_u32 s40, s40, 0x100
	s_addc_u32 s41, s41, 0
	s_add_u32 s59, s59, 0x100
	s_addc_u32 s60, s60, 0
	s_cmp_gt_u32 s61, 29
	s_cbranch_scc0 .LBB0_1591

; #define PG8_STAGE(bufoff, gbase, voff) do { _Pragma("unroll") for (int _i = 0; _i < 2; ++_i) \
;         __builtin_amdgcn_global_load_lds((const unsigned*)((const char*)(gbase) + (voff)[_i]), (PG8_LAS unsigned*)(lds + (bufoff) + ldsw + _i * 8192), 16, 0, 0); } while (0)
; #define PG8_LDA(dst, b, h) do { _Pragma("unroll") for (int m = 0; m < 4; ++m) _Pragma("unroll") for (int k = 0; k < 2; ++k) dst[m][k] = *(const PG8_LAS bf16x8*)(lds + PG8_SA(b, h) + aoff + m * 2048 + k * 1024); } while (0)
; #define PG8_LDB(dst, b, h) do { _Pragma("unroll") for (int n = 0; n < 2; ++n) _Pragma("unroll") for (int k = 0; k < 2; ++k) dst[n][k] = *(const PG8_LAS bf16x8*)(lds + PG8_SB(b, h) + boff + n * 2048 + k * 1024); } while (0)
; #define PG8_SCHED __builtin_amdgcn_sched_barrier(0)
; template <class Epi, class Sched, bool ALIGN_EPI = false, bool SP2 = false, bool I8 = false>
; __device__ __forceinline__ void gemm_phase(PG8_LAS unsigned char* lds, const Gemm g, const Sched& S, const Epi& E) {
;     ...
;     typedef typename AccT<I8>::type acc_t;
;     acc_t acc[2][2][4][2];
; #pragma unroll
;     for (int a = 0; a < 2; ++a)
; #pragma unroll
;         for (int b = 0; b < 2; ++b)
; #pragma unroll
;             for (int m = 0; m < 4; ++m)
; #pragma unroll
;                 for (int n = 0; n < 2; ++n) acc[a][b][m][n] = (acc_t){0, 0, 0, 0};
;     ...
;         const char* nA = has_next ? (const char*)g.A + (size_t)nxt.pm * tstep : cA; const char* nB = has_next ? (const char*)g.Bt + (size_t)nxt.pn * tstep : cB;
;         for (int t = 0; t < nt; t += 2) {
;             const bool last = (t == nt - 2);
;             const char* a1 = cA + (size_t)(t + 1) * kstep;
;             const char* a2 = last ? nA : cA + (size_t)(t + 2) * kstep; const char* b2 = last ? nB : cB + (size_t)(t + 2) * kstep;
;             const char* a3 = a2 + kstep; const char* b3 = b2 + kstep;
;             if (last && has_next) S.a_ready(nxt);
;             if constexpr (SP2) {
;             PG8_LDB(B0, 0, 0); PG8_LDB(B1, 0, 1); PG8_SCHED; PG8_LDA(At, 0, 0); PG8_STAGE(PG8_SA(1, 1), a1 + hstep, voffA);
.LBB0_1621:
	v_mov_b32_e32 v127, 0
	s_andn2_b64 vcc, exec, s[26:27]
	v_mov_b32_e32 v126, v127
	v_mov_b32_e32 v125, v127
	v_mov_b32_e32 v124, v127
	v_mov_b32_e32 v131, v127
	v_mov_b32_e32 v130, v127
	v_mov_b32_e32 v129, v127
	v_mov_b32_e32 v128, v127
	v_mov_b32_e32 v115, v127
	v_mov_b32_e32 v114, v127
	v_mov_b32_e32 v113, v127
	v_mov_b32_e32 v112, v127
	v_mov_b32_e32 v111, v127
	v_mov_b32_e32 v110, v127
	v_mov_b32_e32 v109, v127
	v_mov_b32_e32 v108, v127
	v_mov_b32_e32 v99, v127
	v_mov_b32_e32 v98, v127
	v_mov_b32_e32 v97, v127
	v_mov_b32_e32 v96, v127
	v_mov_b32_e32 v95, v127
	v_mov_b32_e32 v94, v127
	v_mov_b32_e32 v93, v127
	v_mov_b32_e32 v92, v127
	v_mov_b32_e32 v83, v127
	v_mov_b32_e32 v82, v127
	v_mov_b32_e32 v81, v127
	v_mov_b32_e32 v80, v127
	v_mov_b32_e32 v79, v127
	v_mov_b32_e32 v78, v127
	v_mov_b32_e32 v77, v127
	v_mov_b32_e32 v76, v127
	v_mov_b32_e32 v123, v127
	v_mov_b32_e32 v122, v127
	v_mov_b32_e32 v121, v127
	v_mov_b32_e32 v120, v127
	v_mov_b32_e32 v119, v127
	v_mov_b32_e32 v118, v127
	v_mov_b32_e32 v117, v127
	v_mov_b32_e32 v116, v127
	v_mov_b32_e32 v107, v127
	v_mov_b32_e32 v106, v127
	v_mov_b32_e32 v105, v127
	v_mov_b32_e32 v104, v127
	v_mov_b32_e32 v103, v127
	v_mov_b32_e32 v102, v127
	v_mov_b32_e32 v101, v127
	v_mov_b32_e32 v100, v127
	v_mov_b32_e32 v91, v127
	v_mov_b32_e32 v90, v127
	v_mov_b32_e32 v89, v127
	v_mov_b32_e32 v88, v127
	v_mov_b32_e32 v87, v127
	v_mov_b32_e32 v86, v127
	v_mov_b32_e32 v85, v127
	v_mov_b32_e32 v84, v127
	v_mov_b32_e32 v75, v127
	v_mov_b32_e32 v74, v127
	v_mov_b32_e32 v73, v127
	v_mov_b32_e32 v72, v127
	v_mov_b32_e32 v71, v127
	v_mov_b32_e32 v70, v127
	v_mov_b32_e32 v69, v127
	v_mov_b32_e32 v68, v127
	v_mov_b32_e32 v67, v127
	v_mov_b32_e32 v66, v127
	v_mov_b32_e32 v65, v127
	v_mov_b32_e32 v64, v127
	v_mov_b32_e32 v63, v127
	v_mov_b32_e32 v62, v127
	v_mov_b32_e32 v61, v127
	v_mov_b32_e32 v60, v127
	v_mov_b32_e32 v51, v127
	v_mov_b32_e32 v50, v127
	v_mov_b32_e32 v49, v127
	v_mov_b32_e32 v48, v127
	v_mov_b32_e32 v47, v127
	v_mov_b32_e32 v46, v127
	v_mov_b32_e32 v45, v127
	v_mov_b32_e32 v44, v127
	v_mov_b32_e32 v35, v127
	v_mov_b32_e32 v34, v127
	v_mov_b32_e32 v33, v127
	v_mov_b32_e32 v32, v127
	v_mov_b32_e32 v31, v127
	v_mov_b32_e32 v30, v127
	v_mov_b32_e32 v29, v127
	v_mov_b32_e32 v28, v127
	v_mov_b32_e32 v19, v127
	v_mov_b32_e32 v18, v127
	v_mov_b32_e32 v17, v127
	v_mov_b32_e32 v16, v127
	v_mov_b32_e32 v15, v127
	v_mov_b32_e32 v14, v127
	v_mov_b32_e32 v13, v127
	v_mov_b32_e32 v12, v127
	v_mov_b32_e32 v59, v127
	v_mov_b32_e32 v58, v127
	v_mov_b32_e32 v57, v127
	v_mov_b32_e32 v56, v127
	v_mov_b32_e32 v55, v127
	v_mov_b32_e32 v54, v127
	v_mov_b32_e32 v53, v127
	v_mov_b32_e32 v52, v127
	v_mov_b32_e32 v43, v127
	v_mov_b32_e32 v42, v127
	v_mov_b32_e32 v41, v127
	v_mov_b32_e32 v40, v127
	v_mov_b32_e32 v39, v127
	v_mov_b32_e32 v38, v127
	v_mov_b32_e32 v37, v127
	v_mov_b32_e32 v36, v127
	v_mov_b32_e32 v27, v127
	v_mov_b32_e32 v26, v127
	v_mov_b32_e32 v25, v127
	v_mov_b32_e32 v24, v127
	v_mov_b32_e32 v23, v127
	v_mov_b32_e32 v22, v127
	v_mov_b32_e32 v21, v127
	v_mov_b32_e32 v20, v127
	v_mov_b32_e32 v11, v127
	v_mov_b32_e32 v10, v127
	v_mov_b32_e32 v9, v127
	v_mov_b32_e32 v8, v127
	v_mov_b32_e32 v7, v127
	v_mov_b32_e32 v6, v127
	v_mov_b32_e32 v5, v127
	v_mov_b32_e32 v4, v127
	s_cbranch_vccnz .LBB0_1625
	s_add_u32 s44, s44, 0x80
	s_addc_u32 s45, s45, 0
	s_add_u32 s65, s48, 0x100
	s_addc_u32 s67, s49, 0
	s_mov_b32 s48, 0
	s_add_i32 s72, s48, 2
	s_add_u32 s73, s44, 0x80
	s_addc_u32 s49, s45, 0
	s_add_i32 s86, 0, 0x10000
	s_cmp_eq_u32 s57, s48
	s_cselect_b32 s49, s13, s49
	s_cselect_b32 s48, s12, s73
	s_cselect_b32 s77, s41, s67
	s_cselect_b32 s76, s40, s65
	s_add_i32 s73, 0, 0x14000
	v_add_u32_e32 v158, s86, v143
	v_add_u32_e32 v174, s73, v143
	ds_read_b128 v[146:149], v158
	ds_read_b128 v[150:153], v158 offset:1024
	ds_read_b128 v[154:157], v158 offset:2048
	ds_read_b128 v[158:161], v158 offset:3072
	ds_read_b128 v[162:165], v174
	ds_read_b128 v[166:169], v174 offset:1024
	ds_read_b128 v[170:173], v174 offset:2048
	ds_read_b128 v[174:177], v174 offset:3072
	v_lshl_add_u64 v[190:191], s[44:45], 0, v[138:139]
	s_add_i32 m0, s47, 0xc000
	ds_read_b128 v[178:181], v145
	ds_read_b128 v[182:185], v145 offset:1024
	ds_read_b128 v[186:189], v145 offset:2048
	ds_read_b128 v[204:207], v145 offset:3072
	ds_read_b128 v[208:211], v145 offset:4096
	ds_read_b128 v[212:215], v145 offset:5120
	ds_read_b128 v[216:219], v145 offset:6144
	ds_read_b128 v[220:223], v145 offset:7168
	global_load_lds_dwordx4 v[190:191], off
	v_lshl_add_u64 v[190:191], s[44:45], 0, v[140:141]
	s_add_i32 m0, s47, 0xe000
	s_nop 0
	global_load_lds_dwordx4 v[190:191], off
	s_waitcnt vmcnt(8)
	s_waitcnt lgkmcnt(0)
	s_barrier
; #define PG8_STAGE(bufoff, gbase, voff) do { _Pragma("unroll") for (int _i = 0; _i < 2; ++_i) \
;         __builtin_amdgcn_global_load_lds((const unsigned*)((const char*)(gbase) + (voff)[_i]), (PG8_LAS unsigned*)(lds + (bufoff) + ldsw + _i * 8192), 16, 0, 0); } while (0)
; #define PG8_LDA(dst, b, h) do { _Pragma("unroll") for (int m = 0; m < 4; ++m) _Pragma("unroll") for (int k = 0; k < 2; ++k) dst[m][k] = *(const PG8_LAS bf16x8*)(lds + PG8_SA(b, h) + aoff + m * 2048 + k * 1024); } while (0)
; #define PG8_LDB(dst, b, h) do { _Pragma("unroll") for (int n = 0; n < 2; ++n) _Pragma("unroll") for (int k = 0; k < 2; ++k) dst[n][k] = *(const PG8_LAS bf16x8*)(lds + PG8_SB(b, h) + boff + n * 2048 + k * 1024); } while (0)
; #define PG8_WAIT_V(n) asm volatile("s_waitcnt vmcnt(" #n ")" ::: "memory")
; #define PG8_WAIT_L(n) asm volatile("s_waitcnt lgkmcnt(" #n ")" ::: "memory")
; #define PG8_BAR __builtin_amdgcn_s_barrier()
; #define PG8_SCHED __builtin_amdgcn_sched_barrier(0)
; template <class Epi, class Sched, bool ALIGN_EPI = false, bool SP2 = false, bool I8 = false>
; __device__ __forceinline__ void gemm_phase(PG8_LAS unsigned char* lds, const Gemm g, const Sched& S, const Epi& E) {
;     ...
;             PG8_WAIT_V(8); PG8_WAIT_L(0); PG8_BAR; PG8_MMA(0, 0, At, B0); PG8_MMA(0, 1, At, B1); PG8_BAR; PG8_SCHED;
;             PG8_LDA(At, 0, 1); PG8_STAGE(PG8_SB(0, 0), b2, voffB); PG8_STAGE(PG8_SB(0, 1), b2 + hstep, voffB); PG8_STAGE(PG8_SA(0, 0), a2, voffA);
;             PG8_WAIT_V(8); PG8_WAIT_L(0); PG8_BAR; PG8_MMA(1, 0, At, B0); PG8_MMA(1, 1, At, B1); PG8_BAR; PG8_SCHED;
;             PG8_LDB(B0, 1, 0); PG8_LDB(B1, 1, 1); PG8_SCHED; PG8_LDA(At, 1, 0); PG8_STAGE(PG8_SA(0, 1), a2 + hstep, voffA);
;             PG8_WAIT_V(8); PG8_WAIT_L(0); PG8_BAR; PG8_MMA(0, 0, At, B0); PG8_MMA(0, 1, At, B1); PG8_BAR; PG8_SCHED;
	s_waitcnt lgkmcnt(0)
	v_mfma_f32_16x16x32_bf16 v[124:127], v[146:149], v[178:181], 0
	v_mfma_f32_16x16x32_bf16 v[124:127], v[150:153], v[182:185], v[124:127]
	v_mfma_f32_16x16x32_bf16 v[112:115], v[150:153], v[204:207], 0
	v_mfma_f32_16x16x32_bf16 v[112:115], v[146:149], v[186:189], v[112:115]
	v_mfma_f32_16x16x32_bf16 v[96:99], v[146:149], v[208:211], 0
	v_mfma_f32_16x16x32_bf16 v[96:99], v[150:153], v[212:215], v[96:99]
	v_mfma_f32_16x16x32_bf16 v[80:83], v[150:153], v[220:223], 0
	v_mfma_f32_16x16x32_bf16 v[80:83], v[146:149], v[216:219], v[80:83]
	v_mfma_f32_16x16x32_bf16 v[76:79], v[154:157], v[216:219], 0
	v_mfma_f32_16x16x32_bf16 v[76:79], v[158:161], v[220:223], v[76:79]
	v_mfma_f32_16x16x32_bf16 v[92:95], v[158:161], v[212:215], 0
	v_mfma_f32_16x16x32_bf16 v[92:95], v[154:157], v[208:211], v[92:95]
	v_mfma_f32_16x16x32_bf16 v[108:111], v[154:157], v[186:189], 0
	v_mfma_f32_16x16x32_bf16 v[108:111], v[158:161], v[204:207], v[108:111]
	v_mfma_f32_16x16x32_bf16 v[128:131], v[158:161], v[182:185], 0
	v_mfma_f32_16x16x32_bf16 v[128:131], v[154:157], v[178:181], v[128:131]
	v_mfma_f32_16x16x32_bf16 v[120:123], v[162:165], v[178:181], 0
	v_mfma_f32_16x16x32_bf16 v[120:123], v[166:169], v[182:185], v[120:123]
	v_mfma_f32_16x16x32_bf16 v[104:107], v[166:169], v[204:207], 0
	v_mfma_f32_16x16x32_bf16 v[104:107], v[162:165], v[186:189], v[104:107]
	v_mfma_f32_16x16x32_bf16 v[88:91], v[162:165], v[208:211], 0
	v_mfma_f32_16x16x32_bf16 v[88:91], v[166:169], v[212:215], v[88:91]
	v_mfma_f32_16x16x32_bf16 v[72:75], v[166:169], v[220:223], 0
	v_mfma_f32_16x16x32_bf16 v[72:75], v[162:165], v[216:219], v[72:75]
	v_mfma_f32_16x16x32_bf16 v[68:71], v[170:173], v[216:219], 0
	v_mfma_f32_16x16x32_bf16 v[68:71], v[174:177], v[220:223], v[68:71]
	v_mfma_f32_16x16x32_bf16 v[84:87], v[174:177], v[212:215], 0
	v_mfma_f32_16x16x32_bf16 v[84:87], v[170:173], v[208:211], v[84:87]
	v_mfma_f32_16x16x32_bf16 v[100:103], v[170:173], v[186:189], 0
	v_mfma_f32_16x16x32_bf16 v[100:103], v[174:177], v[204:207], v[100:103]
	v_mfma_f32_16x16x32_bf16 v[116:119], v[174:177], v[182:185], 0
	v_mfma_f32_16x16x32_bf16 v[116:119], v[170:173], v[178:181], v[116:119]
	s_barrier
	s_add_i32 s86, s86, s28
	v_lshl_add_u64 v[190:191], s[76:77], 0, v[2:3]
	s_mov_b32 m0, s86
	ds_read_b128 v[178:181], v145 offset:16384
	ds_read_b128 v[182:185], v145 offset:17408
	ds_read_b128 v[186:189], v145 offset:18432
	ds_read_b128 v[204:207], v145 offset:19456
	ds_read_b128 v[208:211], v145 offset:20480
	ds_read_b128 v[212:215], v145 offset:21504
	ds_read_b128 v[216:219], v145 offset:22528
	ds_read_b128 v[220:223], v145 offset:23552
	global_load_lds_dwordx4 v[190:191], off
	s_add_i32 m0, s86, 0x2000
	v_lshl_add_u64 v[224:225], s[76:77], 0, v[136:137]
	s_add_u32 s76, s76, s18
	s_addc_u32 s77, s77, s19
	s_add_i32 s73, s73, s28
	global_load_lds_dwordx4 v[224:225], off
	v_lshl_add_u64 v[226:227], s[76:77], 0, v[2:3]
	s_mov_b32 m0, s73
	v_lshl_add_u64 v[228:229], s[76:77], 0, v[136:137]
	global_load_lds_dwordx4 v[226:227], off
	s_add_i32 m0, s73, 0x2000
	v_lshl_add_u64 v[240:241], s[48:49], 0, v[132:133]
	global_load_lds_dwordx4 v[228:229], off
	s_mov_b32 m0, s47
	v_lshl_add_u64 v[242:243], s[48:49], 0, v[134:135]
	global_load_lds_dwordx4 v[240:241], off
	s_mov_b32 m0, s50
	s_nop 0
	global_load_lds_dwordx4 v[242:243], off
	s_waitcnt vmcnt(8)
	s_waitcnt lgkmcnt(0)
	s_barrier
	s_waitcnt lgkmcnt(0)
	v_mfma_f32_16x16x32_bf16 v[64:67], v[146:149], v[178:181], 0
	v_mfma_f32_16x16x32_bf16 v[64:67], v[150:153], v[182:185], v[64:67]
	v_mfma_f32_16x16x32_bf16 v[48:51], v[150:153], v[204:207], 0
	v_mfma_f32_16x16x32_bf16 v[48:51], v[146:149], v[186:189], v[48:51]
	v_mfma_f32_16x16x32_bf16 v[32:35], v[146:149], v[208:211], 0
	v_mfma_f32_16x16x32_bf16 v[32:35], v[150:153], v[212:215], v[32:35]
	v_mfma_f32_16x16x32_bf16 v[16:19], v[150:153], v[220:223], 0
	v_mfma_f32_16x16x32_bf16 v[16:19], v[146:149], v[216:219], v[16:19]
	v_mfma_f32_16x16x32_bf16 v[12:15], v[154:157], v[216:219], 0
	v_mfma_f32_16x16x32_bf16 v[12:15], v[158:161], v[220:223], v[12:15]
	v_mfma_f32_16x16x32_bf16 v[28:31], v[158:161], v[212:215], 0
	v_mfma_f32_16x16x32_bf16 v[28:31], v[154:157], v[208:211], v[28:31]
	v_mfma_f32_16x16x32_bf16 v[44:47], v[154:157], v[186:189], 0
	v_mfma_f32_16x16x32_bf16 v[44:47], v[158:161], v[204:207], v[44:47]
	v_mfma_f32_16x16x32_bf16 v[60:63], v[158:161], v[182:185], 0
	v_mfma_f32_16x16x32_bf16 v[60:63], v[154:157], v[178:181], v[60:63]
	v_mfma_f32_16x16x32_bf16 v[56:59], v[162:165], v[178:181], 0
	v_mfma_f32_16x16x32_bf16 v[56:59], v[166:169], v[182:185], v[56:59]
	v_mfma_f32_16x16x32_bf16 v[40:43], v[166:169], v[204:207], 0
	v_mfma_f32_16x16x32_bf16 v[40:43], v[162:165], v[186:189], v[40:43]
	v_mfma_f32_16x16x32_bf16 v[24:27], v[162:165], v[208:211], 0
	v_mfma_f32_16x16x32_bf16 v[24:27], v[166:169], v[212:215], v[24:27]
	v_mfma_f32_16x16x32_bf16 v[8:11], v[166:169], v[220:223], 0
	v_mfma_f32_16x16x32_bf16 v[8:11], v[162:165], v[216:219], v[8:11]
	v_mfma_f32_16x16x32_bf16 v[4:7], v[170:173], v[216:219], 0
	v_mfma_f32_16x16x32_bf16 v[4:7], v[174:177], v[220:223], v[4:7]
	v_mfma_f32_16x16x32_bf16 v[20:23], v[174:177], v[212:215], 0
	v_mfma_f32_16x16x32_bf16 v[20:23], v[170:173], v[208:211], v[20:23]
	v_mfma_f32_16x16x32_bf16 v[36:39], v[170:173], v[186:189], 0
	v_mfma_f32_16x16x32_bf16 v[36:39], v[174:177], v[204:207], v[36:39]
	v_mfma_f32_16x16x32_bf16 v[52:55], v[174:177], v[182:185], 0
	v_mfma_f32_16x16x32_bf16 v[52:55], v[170:173], v[178:181], v[52:55]
	s_barrier
; #define PG8_STAGE(bufoff, gbase, voff) do { _Pragma("unroll") for (int _i = 0; _i < 2; ++_i) \
;         __builtin_amdgcn_global_load_lds((const unsigned*)((const char*)(gbase) + (voff)[_i]), (PG8_LAS unsigned*)(lds + (bufoff) + ldsw + _i * 8192), 16, 0, 0); } while (0)
; #define PG8_LDA(dst, b, h) do { _Pragma("unroll") for (int m = 0; m < 4; ++m) _Pragma("unroll") for (int k = 0; k < 2; ++k) dst[m][k] = *(const PG8_LAS bf16x8*)(lds + PG8_SA(b, h) + aoff + m * 2048 + k * 1024); } while (0)
; #define PG8_LDB(dst, b, h) do { _Pragma("unroll") for (int n = 0; n < 2; ++n) _Pragma("unroll") for (int k = 0; k < 2; ++k) dst[n][k] = *(const PG8_LAS bf16x8*)(lds + PG8_SB(b, h) + boff + n * 2048 + k * 1024); } while (0)
; #define PG8_WAIT_V(n) asm volatile("s_waitcnt vmcnt(" #n ")" ::: "memory")
; #define PG8_WAIT_L(n) asm volatile("s_waitcnt lgkmcnt(" #n ")" ::: "memory")
; #define PG8_BAR __builtin_amdgcn_s_barrier()
; #define PG8_SCHED __builtin_amdgcn_sched_barrier(0)
; template <class Epi, class Sched, bool ALIGN_EPI = false, bool SP2 = false, bool I8 = false>
; __device__ __forceinline__ void gemm_phase(PG8_LAS unsigned char* lds, const Gemm g, const Sched& S, const Epi& E) {
;     ...
;             PG8_LDB(B0, 1, 0); PG8_LDB(B1, 1, 1); PG8_SCHED; PG8_LDA(At, 1, 0); PG8_STAGE(PG8_SA(0, 1), a2 + hstep, voffA);
;             PG8_WAIT_V(8); PG8_WAIT_L(0); PG8_BAR; PG8_MMA(0, 0, At, B0); PG8_MMA(0, 1, At, B1); PG8_BAR; PG8_SCHED;
;             PG8_LDA(At, 1, 1); PG8_STAGE(PG8_SB(1, 0), b3, voffB); PG8_STAGE(PG8_SB(1, 1), b3 + hstep, voffB); PG8_STAGE(PG8_SA(1, 0), a3, voffA);
;             PG8_WAIT_V(8); PG8_WAIT_L(0); PG8_BAR; PG8_MMA(1, 0, At, B0); PG8_MMA(1, 1, At, B1); PG8_BAR; PG8_SCHED;
	s_add_i32 s73, 0, 0x18000
	s_add_i32 s76, 0, 0x1c000
	v_add_u32_e32 v158, s73, v143
	v_add_u32_e32 v174, s76, v143
	ds_read_b128 v[146:149], v158
	ds_read_b128 v[150:153], v158 offset:1024
	ds_read_b128 v[154:157], v158 offset:2048
	ds_read_b128 v[158:161], v158 offset:3072
	ds_read_b128 v[162:165], v174
	ds_read_b128 v[166:169], v174 offset:1024
	ds_read_b128 v[170:173], v174 offset:2048
	ds_read_b128 v[174:177], v174 offset:3072
	s_add_u32 s48, s48, s18
	s_addc_u32 s49, s49, s19
	s_mov_b32 m0, s51
	v_lshl_add_u64 v[244:245], s[48:49], 0, v[132:133]
	ds_read_b128 v[178:181], v145 offset:32768
	ds_read_b128 v[182:185], v145 offset:33792
	ds_read_b128 v[186:189], v145 offset:34816
	ds_read_b128 v[204:207], v145 offset:35840
	ds_read_b128 v[208:211], v145 offset:36864
	ds_read_b128 v[212:215], v145 offset:37888
	ds_read_b128 v[216:219], v145 offset:38912
	ds_read_b128 v[220:223], v145 offset:39936
	global_load_lds_dwordx4 v[244:245], off
	v_lshl_add_u64 v[244:245], s[48:49], 0, v[134:135]
	s_mov_b32 m0, s52
	s_nop 0
	global_load_lds_dwordx4 v[244:245], off
	s_waitcnt vmcnt(8)
	s_waitcnt lgkmcnt(0)
	s_barrier
	s_waitcnt lgkmcnt(0)
	v_mfma_f32_16x16x32_bf16 v[124:127], v[146:149], v[178:181], v[124:127]
	v_mfma_f32_16x16x32_bf16 v[124:127], v[150:153], v[182:185], v[124:127]
	v_mfma_f32_16x16x32_bf16 v[112:115], v[150:153], v[204:207], v[112:115]
	v_mfma_f32_16x16x32_bf16 v[112:115], v[146:149], v[186:189], v[112:115]
	v_mfma_f32_16x16x32_bf16 v[96:99], v[146:149], v[208:211], v[96:99]
	v_mfma_f32_16x16x32_bf16 v[96:99], v[150:153], v[212:215], v[96:99]
	v_mfma_f32_16x16x32_bf16 v[80:83], v[150:153], v[220:223], v[80:83]
	v_mfma_f32_16x16x32_bf16 v[80:83], v[146:149], v[216:219], v[80:83]
	v_mfma_f32_16x16x32_bf16 v[76:79], v[154:157], v[216:219], v[76:79]
	v_mfma_f32_16x16x32_bf16 v[76:79], v[158:161], v[220:223], v[76:79]
	v_mfma_f32_16x16x32_bf16 v[92:95], v[158:161], v[212:215], v[92:95]
	v_mfma_f32_16x16x32_bf16 v[92:95], v[154:157], v[208:211], v[92:95]
	v_mfma_f32_16x16x32_bf16 v[108:111], v[154:157], v[186:189], v[108:111]
	v_mfma_f32_16x16x32_bf16 v[108:111], v[158:161], v[204:207], v[108:111]
	v_mfma_f32_16x16x32_bf16 v[128:131], v[158:161], v[182:185], v[128:131]
	v_mfma_f32_16x16x32_bf16 v[128:131], v[154:157], v[178:181], v[128:131]
	v_mfma_f32_16x16x32_bf16 v[120:123], v[162:165], v[178:181], v[120:123]
	v_mfma_f32_16x16x32_bf16 v[120:123], v[166:169], v[182:185], v[120:123]
	v_mfma_f32_16x16x32_bf16 v[104:107], v[166:169], v[204:207], v[104:107]
	v_mfma_f32_16x16x32_bf16 v[104:107], v[162:165], v[186:189], v[104:107]
	v_mfma_f32_16x16x32_bf16 v[88:91], v[162:165], v[208:211], v[88:91]
	v_mfma_f32_16x16x32_bf16 v[88:91], v[166:169], v[212:215], v[88:91]
	v_mfma_f32_16x16x32_bf16 v[72:75], v[166:169], v[220:223], v[72:75]
	v_mfma_f32_16x16x32_bf16 v[72:75], v[162:165], v[216:219], v[72:75]
	v_mfma_f32_16x16x32_bf16 v[68:71], v[170:173], v[216:219], v[68:71]
	v_mfma_f32_16x16x32_bf16 v[68:71], v[174:177], v[220:223], v[68:71]
	v_mfma_f32_16x16x32_bf16 v[84:87], v[174:177], v[212:215], v[84:87]
	v_mfma_f32_16x16x32_bf16 v[84:87], v[170:173], v[208:211], v[84:87]
	v_mfma_f32_16x16x32_bf16 v[100:103], v[170:173], v[186:189], v[100:103]
	v_mfma_f32_16x16x32_bf16 v[100:103], v[174:177], v[204:207], v[100:103]
	v_mfma_f32_16x16x32_bf16 v[116:119], v[174:177], v[182:185], v[116:119]
	v_mfma_f32_16x16x32_bf16 v[116:119], v[170:173], v[178:181], v[116:119]
	s_barrier
	s_add_i32 s48, s73, s28
	v_lshl_add_u64 v[190:191], v[190:191], 0, s[84:85]
	s_mov_b32 m0, s48
	ds_read_b128 v[178:181], v145 offset:49152
	ds_read_b128 v[182:185], v145 offset:50176
	ds_read_b128 v[186:189], v145 offset:51200
	ds_read_b128 v[204:207], v145 offset:52224
	ds_read_b128 v[208:211], v145 offset:53248
	ds_read_b128 v[212:215], v145 offset:54272
	ds_read_b128 v[216:219], v145 offset:55296
	ds_read_b128 v[220:223], v145 offset:56320
	global_load_lds_dwordx4 v[190:191], off
	v_lshl_add_u64 v[190:191], v[224:225], 0, s[84:85]
	s_add_i32 m0, s48, 0x2000
	s_add_i32 s48, s76, s28
	global_load_lds_dwordx4 v[190:191], off
	v_lshl_add_u64 v[190:191], v[226:227], 0, s[84:85]
	s_mov_b32 m0, s48
	s_nop 0
	global_load_lds_dwordx4 v[190:191], off
	v_lshl_add_u64 v[190:191], v[228:229], 0, s[84:85]
	s_add_i32 m0, s48, 0x2000
	s_nop 0
	global_load_lds_dwordx4 v[190:191], off
	v_lshl_add_u64 v[190:191], v[240:241], 0, s[84:85]
	s_mov_b32 m0, s55
	s_nop 0
	global_load_lds_dwordx4 v[190:191], off
	v_lshl_add_u64 v[190:191], v[242:243], 0, s[84:85]
	s_mov_b32 m0, s56
	s_nop 0
	global_load_lds_dwordx4 v[190:191], off
	s_waitcnt vmcnt(8)
	s_waitcnt lgkmcnt(0)
	s_barrier
	s_waitcnt lgkmcnt(0)
	v_mfma_f32_16x16x32_bf16 v[64:67], v[146:149], v[178:181], v[64:67]
	v_mfma_f32_16x16x32_bf16 v[64:67], v[150:153], v[182:185], v[64:67]
	v_mfma_f32_16x16x32_bf16 v[48:51], v[150:153], v[204:207], v[48:51]
	v_mfma_f32_16x16x32_bf16 v[48:51], v[146:149], v[186:189], v[48:51]
	v_mfma_f32_16x16x32_bf16 v[32:35], v[146:149], v[208:211], v[32:35]
	v_mfma_f32_16x16x32_bf16 v[32:35], v[150:153], v[212:215], v[32:35]
	v_mfma_f32_16x16x32_bf16 v[16:19], v[150:153], v[220:223], v[16:19]
	v_mfma_f32_16x16x32_bf16 v[16:19], v[146:149], v[216:219], v[16:19]
	v_mfma_f32_16x16x32_bf16 v[12:15], v[154:157], v[216:219], v[12:15]
	v_mfma_f32_16x16x32_bf16 v[12:15], v[158:161], v[220:223], v[12:15]
	v_mfma_f32_16x16x32_bf16 v[28:31], v[158:161], v[212:215], v[28:31]
	v_mfma_f32_16x16x32_bf16 v[28:31], v[154:157], v[208:211], v[28:31]
	v_mfma_f32_16x16x32_bf16 v[44:47], v[154:157], v[186:189], v[44:47]
	v_mfma_f32_16x16x32_bf16 v[44:47], v[158:161], v[204:207], v[44:47]
	v_mfma_f32_16x16x32_bf16 v[60:63], v[158:161], v[182:185], v[60:63]
	v_mfma_f32_16x16x32_bf16 v[60:63], v[154:157], v[178:181], v[60:63]
	v_mfma_f32_16x16x32_bf16 v[56:59], v[162:165], v[178:181], v[56:59]
	v_mfma_f32_16x16x32_bf16 v[56:59], v[166:169], v[182:185], v[56:59]
	v_mfma_f32_16x16x32_bf16 v[40:43], v[166:169], v[204:207], v[40:43]
	v_mfma_f32_16x16x32_bf16 v[40:43], v[162:165], v[186:189], v[40:43]
	v_mfma_f32_16x16x32_bf16 v[24:27], v[162:165], v[208:211], v[24:27]
	v_mfma_f32_16x16x32_bf16 v[24:27], v[166:169], v[212:215], v[24:27]
	v_mfma_f32_16x16x32_bf16 v[8:11], v[166:169], v[220:223], v[8:11]
	v_mfma_f32_16x16x32_bf16 v[8:11], v[162:165], v[216:219], v[8:11]
	v_mfma_f32_16x16x32_bf16 v[4:7], v[170:173], v[216:219], v[4:7]
	v_mfma_f32_16x16x32_bf16 v[4:7], v[174:177], v[220:223], v[4:7]
	v_mfma_f32_16x16x32_bf16 v[20:23], v[174:177], v[212:215], v[20:23]
	v_mfma_f32_16x16x32_bf16 v[20:23], v[170:173], v[208:211], v[20:23]
	v_mfma_f32_16x16x32_bf16 v[36:39], v[170:173], v[186:189], v[36:39]
	v_mfma_f32_16x16x32_bf16 v[36:39], v[174:177], v[204:207], v[36:39]
	v_mfma_f32_16x16x32_bf16 v[52:55], v[174:177], v[182:185], v[52:55]
	v_mfma_f32_16x16x32_bf16 v[52:55], v[170:173], v[178:181], v[52:55]
	s_barrier
	s_add_u32 s44, s44, 0x100
	s_addc_u32 s45, s45, 0
	s_add_u32 s65, s65, 0x100
	s_addc_u32 s67, s67, 0
	s_cmp_ge_i32 s72, s53
	s_mov_b32 s48, s72
	s_cbranch_scc1 .Lkloop_exit_4
; #define PG8_STAGE(bufoff, gbase, voff) do { _Pragma("unroll") for (int _i = 0; _i < 2; ++_i) \
;         __builtin_amdgcn_global_load_lds((const unsigned*)((const char*)(gbase) + (voff)[_i]), (PG8_LAS unsigned*)(lds + (bufoff) + ldsw + _i * 8192), 16, 0, 0); } while (0)
; #define PG8_LDA(dst, b, h) do { _Pragma("unroll") for (int m = 0; m < 4; ++m) _Pragma("unroll") for (int k = 0; k < 2; ++k) dst[m][k] = *(const PG8_LAS bf16x8*)(lds + PG8_SA(b, h) + aoff + m * 2048 + k * 1024); } while (0)
; #define PG8_LDB(dst, b, h) do { _Pragma("unroll") for (int n = 0; n < 2; ++n) _Pragma("unroll") for (int k = 0; k < 2; ++k) dst[n][k] = *(const PG8_LAS bf16x8*)(lds + PG8_SB(b, h) + boff + n * 2048 + k * 1024); } while (0)
; #define PG8_WAIT_V(n) asm volatile("s_waitcnt vmcnt(" #n ")" ::: "memory")
; #define PG8_WAIT_L(n) asm volatile("s_waitcnt lgkmcnt(" #n ")" ::: "memory")
; #define PG8_BAR __builtin_amdgcn_s_barrier()
; #define PG8_SCHED __builtin_amdgcn_sched_barrier(0)
; template <class Epi, class Sched, bool ALIGN_EPI = false, bool SP2 = false, bool I8 = false>
; __device__ __forceinline__ void gemm_phase(PG8_LAS unsigned char* lds, const Gemm g, const Sched& S, const Epi& E) {
;     ...
;         const bool has_next = S.next(ui + 1, nxt);
;         const char* nA = has_next ? (const char*)g.A + (size_t)nxt.pm * tstep : cA; const char* nB = has_next ? (const char*)g.Bt + (size_t)nxt.pn * tstep : cB;
;         for (int t = 0; t < nt; t += 2) {
;             const bool last = (t == nt - 2);
;             const char* a1 = cA + (size_t)(t + 1) * kstep;
;             const char* a2 = last ? nA : cA + (size_t)(t + 2) * kstep; const char* b2 = last ? nB : cB + (size_t)(t + 2) * kstep;
;             const char* a3 = a2 + kstep; const char* b3 = b2 + kstep;
;             if (last && has_next) S.a_ready(nxt);
;             if constexpr (SP2) {
;             PG8_LDB(B0, 0, 0); PG8_LDB(B1, 0, 1); PG8_SCHED; PG8_LDA(At, 0, 0); PG8_STAGE(PG8_SA(1, 1), a1 + hstep, voffA);
;             PG8_WAIT_V(8); PG8_WAIT_L(0); PG8_BAR; PG8_MMA(0, 0, At, B0); PG8_MMA(0, 1, At, B1); PG8_BAR; PG8_SCHED;
;             PG8_LDA(At, 0, 1); PG8_STAGE(PG8_SB(0, 0), b2, voffB); PG8_STAGE(PG8_SB(0, 1), b2 + hstep, voffB); PG8_STAGE(PG8_SA(0, 0), a2, voffA);
;             PG8_WAIT_V(8); PG8_WAIT_L(0); PG8_BAR; PG8_MMA(1, 0, At, B0); PG8_MMA(1, 1, At, B1); PG8_BAR; PG8_SCHED;
.LBB0_1623:
	s_add_i32 s72, s48, 2
	s_add_u32 s73, s44, 0x80
	s_addc_u32 s49, s45, 0
	s_add_i32 s86, 0, 0x10000
	s_cmp_eq_u32 s57, s48
	s_cselect_b32 s49, s13, s49
	s_cselect_b32 s48, s12, s73
	s_cselect_b32 s77, s41, s67
	s_cselect_b32 s76, s40, s65
	s_add_i32 s73, 0, 0x14000
	v_add_u32_e32 v158, s86, v143
	v_add_u32_e32 v174, s73, v143
	ds_read_b128 v[146:149], v158
	ds_read_b128 v[150:153], v158 offset:1024
	ds_read_b128 v[154:157], v158 offset:2048
	ds_read_b128 v[158:161], v158 offset:3072
	ds_read_b128 v[162:165], v174
	ds_read_b128 v[166:169], v174 offset:1024
	ds_read_b128 v[170:173], v174 offset:2048
	ds_read_b128 v[174:177], v174 offset:3072
	v_lshl_add_u64 v[190:191], s[44:45], 0, v[138:139]
	s_add_i32 m0, s47, 0xc000
	ds_read_b128 v[178:181], v145
	ds_read_b128 v[182:185], v145 offset:1024
	ds_read_b128 v[186:189], v145 offset:2048
	ds_read_b128 v[204:207], v145 offset:3072
	ds_read_b128 v[208:211], v145 offset:4096
	ds_read_b128 v[212:215], v145 offset:5120
	ds_read_b128 v[216:219], v145 offset:6144
	ds_read_b128 v[220:223], v145 offset:7168
	global_load_lds_dwordx4 v[190:191], off
	v_lshl_add_u64 v[190:191], s[44:45], 0, v[140:141]
	s_add_i32 m0, s47, 0xe000
	s_nop 0
	global_load_lds_dwordx4 v[190:191], off
	s_waitcnt vmcnt(8)
	s_waitcnt lgkmcnt(0)
	s_barrier
	s_waitcnt lgkmcnt(0)
	v_mfma_f32_16x16x32_bf16 v[124:127], v[146:149], v[178:181], v[124:127]
	v_mfma_f32_16x16x32_bf16 v[124:127], v[150:153], v[182:185], v[124:127]
	v_mfma_f32_16x16x32_bf16 v[112:115], v[150:153], v[204:207], v[112:115]
	v_mfma_f32_16x16x32_bf16 v[112:115], v[146:149], v[186:189], v[112:115]
	v_mfma_f32_16x16x32_bf16 v[96:99], v[146:149], v[208:211], v[96:99]
	v_mfma_f32_16x16x32_bf16 v[96:99], v[150:153], v[212:215], v[96:99]
	v_mfma_f32_16x16x32_bf16 v[80:83], v[150:153], v[220:223], v[80:83]
	v_mfma_f32_16x16x32_bf16 v[80:83], v[146:149], v[216:219], v[80:83]
	v_mfma_f32_16x16x32_bf16 v[76:79], v[154:157], v[216:219], v[76:79]
	v_mfma_f32_16x16x32_bf16 v[76:79], v[158:161], v[220:223], v[76:79]
	v_mfma_f32_16x16x32_bf16 v[92:95], v[158:161], v[212:215], v[92:95]
	v_mfma_f32_16x16x32_bf16 v[92:95], v[154:157], v[208:211], v[92:95]
	v_mfma_f32_16x16x32_bf16 v[108:111], v[154:157], v[186:189], v[108:111]
	v_mfma_f32_16x16x32_bf16 v[108:111], v[158:161], v[204:207], v[108:111]
	v_mfma_f32_16x16x32_bf16 v[128:131], v[158:161], v[182:185], v[128:131]
	v_mfma_f32_16x16x32_bf16 v[128:131], v[154:157], v[178:181], v[128:131]
	v_mfma_f32_16x16x32_bf16 v[120:123], v[162:165], v[178:181], v[120:123]
	v_mfma_f32_16x16x32_bf16 v[120:123], v[166:169], v[182:185], v[120:123]
	v_mfma_f32_16x16x32_bf16 v[104:107], v[166:169], v[204:207], v[104:107]
	v_mfma_f32_16x16x32_bf16 v[104:107], v[162:165], v[186:189], v[104:107]
	v_mfma_f32_16x16x32_bf16 v[88:91], v[162:165], v[208:211], v[88:91]
	v_mfma_f32_16x16x32_bf16 v[88:91], v[166:169], v[212:215], v[88:91]
	v_mfma_f32_16x16x32_bf16 v[72:75], v[166:169], v[220:223], v[72:75]
	v_mfma_f32_16x16x32_bf16 v[72:75], v[162:165], v[216:219], v[72:75]
	v_mfma_f32_16x16x32_bf16 v[68:71], v[170:173], v[216:219], v[68:71]
	v_mfma_f32_16x16x32_bf16 v[68:71], v[174:177], v[220:223], v[68:71]
	v_mfma_f32_16x16x32_bf16 v[84:87], v[174:177], v[212:215], v[84:87]
	v_mfma_f32_16x16x32_bf16 v[84:87], v[170:173], v[208:211], v[84:87]
	v_mfma_f32_16x16x32_bf16 v[100:103], v[170:173], v[186:189], v[100:103]
	v_mfma_f32_16x16x32_bf16 v[100:103], v[174:177], v[204:207], v[100:103]
	v_mfma_f32_16x16x32_bf16 v[116:119], v[174:177], v[182:185], v[116:119]
	v_mfma_f32_16x16x32_bf16 v[116:119], v[170:173], v[178:181], v[116:119]
	s_barrier
	s_add_i32 s86, s86, s28
	v_lshl_add_u64 v[190:191], s[76:77], 0, v[2:3]
	s_mov_b32 m0, s86
	ds_read_b128 v[178:181], v145 offset:16384
	ds_read_b128 v[182:185], v145 offset:17408
	ds_read_b128 v[186:189], v145 offset:18432
	ds_read_b128 v[204:207], v145 offset:19456
	ds_read_b128 v[208:211], v145 offset:20480
	ds_read_b128 v[212:215], v145 offset:21504
	ds_read_b128 v[216:219], v145 offset:22528
	ds_read_b128 v[220:223], v145 offset:23552
	global_load_lds_dwordx4 v[190:191], off
	s_add_i32 m0, s86, 0x2000
	v_lshl_add_u64 v[224:225], s[76:77], 0, v[136:137]
	s_add_u32 s76, s76, s18
	s_addc_u32 s77, s77, s19
	s_add_i32 s73, s73, s28
	global_load_lds_dwordx4 v[224:225], off
	v_lshl_add_u64 v[226:227], s[76:77], 0, v[2:3]
	s_mov_b32 m0, s73
	v_lshl_add_u64 v[228:229], s[76:77], 0, v[136:137]
	global_load_lds_dwordx4 v[226:227], off
	s_add_i32 m0, s73, 0x2000
	v_lshl_add_u64 v[240:241], s[48:49], 0, v[132:133]
	global_load_lds_dwordx4 v[228:229], off
	s_mov_b32 m0, s47
	v_lshl_add_u64 v[242:243], s[48:49], 0, v[134:135]
	global_load_lds_dwordx4 v[240:241], off
	s_mov_b32 m0, s50
	s_nop 0
	global_load_lds_dwordx4 v[242:243], off
	s_waitcnt vmcnt(8)
	s_waitcnt lgkmcnt(0)
	s_barrier
; #define PG8_STAGE(bufoff, gbase, voff) do { _Pragma("unroll") for (int _i = 0; _i < 2; ++_i) \
;         __builtin_amdgcn_global_load_lds((const unsigned*)((const char*)(gbase) + (voff)[_i]), (PG8_LAS unsigned*)(lds + (bufoff) + ldsw + _i * 8192), 16, 0, 0); } while (0)
; #define PG8_LDA(dst, b, h) do { _Pragma("unroll") for (int m = 0; m < 4; ++m) _Pragma("unroll") for (int k = 0; k < 2; ++k) dst[m][k] = *(const PG8_LAS bf16x8*)(lds + PG8_SA(b, h) + aoff + m * 2048 + k * 1024); } while (0)
; #define PG8_LDB(dst, b, h) do { _Pragma("unroll") for (int n = 0; n < 2; ++n) _Pragma("unroll") for (int k = 0; k < 2; ++k) dst[n][k] = *(const PG8_LAS bf16x8*)(lds + PG8_SB(b, h) + boff + n * 2048 + k * 1024); } while (0)
; #define PG8_WAIT_V(n) asm volatile("s_waitcnt vmcnt(" #n ")" ::: "memory")
; #define PG8_WAIT_L(n) asm volatile("s_waitcnt lgkmcnt(" #n ")" ::: "memory")
; #define PG8_BAR __builtin_amdgcn_s_barrier()
; #define PG8_SCHED __builtin_amdgcn_sched_barrier(0)
; template <class Epi, class Sched, bool ALIGN_EPI = false, bool SP2 = false, bool I8 = false>
; __device__ __forceinline__ void gemm_phase(PG8_LAS unsigned char* lds, const Gemm g, const Sched& S, const Epi& E) {
;     ...
;             PG8_WAIT_V(8); PG8_WAIT_L(0); PG8_BAR; PG8_MMA(1, 0, At, B0); PG8_MMA(1, 1, At, B1); PG8_BAR; PG8_SCHED;
;             PG8_LDB(B0, 1, 0); PG8_LDB(B1, 1, 1); PG8_SCHED; PG8_LDA(At, 1, 0); PG8_STAGE(PG8_SA(0, 1), a2 + hstep, voffA);
;             PG8_WAIT_V(8); PG8_WAIT_L(0); PG8_BAR; PG8_MMA(0, 0, At, B0); PG8_MMA(0, 1, At, B1); PG8_BAR; PG8_SCHED;
	s_waitcnt lgkmcnt(0)
	v_mfma_f32_16x16x32_bf16 v[64:67], v[146:149], v[178:181], v[64:67]
	v_mfma_f32_16x16x32_bf16 v[64:67], v[150:153], v[182:185], v[64:67]
	v_mfma_f32_16x16x32_bf16 v[48:51], v[150:153], v[204:207], v[48:51]
	v_mfma_f32_16x16x32_bf16 v[48:51], v[146:149], v[186:189], v[48:51]
	v_mfma_f32_16x16x32_bf16 v[32:35], v[146:149], v[208:211], v[32:35]
	v_mfma_f32_16x16x32_bf16 v[32:35], v[150:153], v[212:215], v[32:35]
	v_mfma_f32_16x16x32_bf16 v[16:19], v[150:153], v[220:223], v[16:19]
	v_mfma_f32_16x16x32_bf16 v[16:19], v[146:149], v[216:219], v[16:19]
	v_mfma_f32_16x16x32_bf16 v[12:15], v[154:157], v[216:219], v[12:15]
	v_mfma_f32_16x16x32_bf16 v[12:15], v[158:161], v[220:223], v[12:15]
	v_mfma_f32_16x16x32_bf16 v[28:31], v[158:161], v[212:215], v[28:31]
	v_mfma_f32_16x16x32_bf16 v[28:31], v[154:157], v[208:211], v[28:31]
	v_mfma_f32_16x16x32_bf16 v[44:47], v[154:157], v[186:189], v[44:47]
	v_mfma_f32_16x16x32_bf16 v[44:47], v[158:161], v[204:207], v[44:47]
	v_mfma_f32_16x16x32_bf16 v[60:63], v[158:161], v[182:185], v[60:63]
	v_mfma_f32_16x16x32_bf16 v[60:63], v[154:157], v[178:181], v[60:63]
	v_mfma_f32_16x16x32_bf16 v[56:59], v[162:165], v[178:181], v[56:59]
	v_mfma_f32_16x16x32_bf16 v[56:59], v[166:169], v[182:185], v[56:59]
	v_mfma_f32_16x16x32_bf16 v[40:43], v[166:169], v[204:207], v[40:43]
	v_mfma_f32_16x16x32_bf16 v[40:43], v[162:165], v[186:189], v[40:43]
	v_mfma_f32_16x16x32_bf16 v[24:27], v[162:165], v[208:211], v[24:27]
	v_mfma_f32_16x16x32_bf16 v[24:27], v[166:169], v[212:215], v[24:27]
	v_mfma_f32_16x16x32_bf16 v[8:11], v[166:169], v[220:223], v[8:11]
	v_mfma_f32_16x16x32_bf16 v[8:11], v[162:165], v[216:219], v[8:11]
	v_mfma_f32_16x16x32_bf16 v[4:7], v[170:173], v[216:219], v[4:7]
	v_mfma_f32_16x16x32_bf16 v[4:7], v[174:177], v[220:223], v[4:7]
	v_mfma_f32_16x16x32_bf16 v[20:23], v[174:177], v[212:215], v[20:23]
	v_mfma_f32_16x16x32_bf16 v[20:23], v[170:173], v[208:211], v[20:23]
	v_mfma_f32_16x16x32_bf16 v[36:39], v[170:173], v[186:189], v[36:39]
	v_mfma_f32_16x16x32_bf16 v[36:39], v[174:177], v[204:207], v[36:39]
	v_mfma_f32_16x16x32_bf16 v[52:55], v[174:177], v[182:185], v[52:55]
	v_mfma_f32_16x16x32_bf16 v[52:55], v[170:173], v[178:181], v[52:55]
	s_barrier
	s_add_i32 s73, 0, 0x18000
	s_add_i32 s76, 0, 0x1c000
	v_add_u32_e32 v158, s73, v143
	v_add_u32_e32 v174, s76, v143
	ds_read_b128 v[146:149], v158
	ds_read_b128 v[150:153], v158 offset:1024
	ds_read_b128 v[154:157], v158 offset:2048
	ds_read_b128 v[158:161], v158 offset:3072
	ds_read_b128 v[162:165], v174
	ds_read_b128 v[166:169], v174 offset:1024
	ds_read_b128 v[170:173], v174 offset:2048
	ds_read_b128 v[174:177], v174 offset:3072
	s_add_u32 s48, s48, s18
	s_addc_u32 s49, s49, s19
	s_mov_b32 m0, s51
	v_lshl_add_u64 v[244:245], s[48:49], 0, v[132:133]
	ds_read_b128 v[178:181], v145 offset:32768
	ds_read_b128 v[182:185], v145 offset:33792
	ds_read_b128 v[186:189], v145 offset:34816
	ds_read_b128 v[204:207], v145 offset:35840
	ds_read_b128 v[208:211], v145 offset:36864
	ds_read_b128 v[212:215], v145 offset:37888
	ds_read_b128 v[216:219], v145 offset:38912
	ds_read_b128 v[220:223], v145 offset:39936
	global_load_lds_dwordx4 v[244:245], off
	v_lshl_add_u64 v[244:245], s[48:49], 0, v[134:135]
	s_mov_b32 m0, s52
	s_nop 0
	global_load_lds_dwordx4 v[244:245], off
	s_waitcnt vmcnt(8)
	s_waitcnt lgkmcnt(0)
	s_barrier
	s_waitcnt lgkmcnt(0)
	v_mfma_f32_16x16x32_bf16 v[124:127], v[146:149], v[178:181], v[124:127]
	v_mfma_f32_16x16x32_bf16 v[124:127], v[150:153], v[182:185], v[124:127]
	v_mfma_f32_16x16x32_bf16 v[112:115], v[150:153], v[204:207], v[112:115]
	v_mfma_f32_16x16x32_bf16 v[112:115], v[146:149], v[186:189], v[112:115]
	v_mfma_f32_16x16x32_bf16 v[96:99], v[146:149], v[208:211], v[96:99]
	v_mfma_f32_16x16x32_bf16 v[96:99], v[150:153], v[212:215], v[96:99]
	v_mfma_f32_16x16x32_bf16 v[80:83], v[150:153], v[220:223], v[80:83]
	v_mfma_f32_16x16x32_bf16 v[80:83], v[146:149], v[216:219], v[80:83]
	v_mfma_f32_16x16x32_bf16 v[76:79], v[154:157], v[216:219], v[76:79]
	v_mfma_f32_16x16x32_bf16 v[76:79], v[158:161], v[220:223], v[76:79]
	v_mfma_f32_16x16x32_bf16 v[92:95], v[158:161], v[212:215], v[92:95]
	v_mfma_f32_16x16x32_bf16 v[92:95], v[154:157], v[208:211], v[92:95]
	v_mfma_f32_16x16x32_bf16 v[108:111], v[154:157], v[186:189], v[108:111]
	v_mfma_f32_16x16x32_bf16 v[108:111], v[158:161], v[204:207], v[108:111]
	v_mfma_f32_16x16x32_bf16 v[128:131], v[158:161], v[182:185], v[128:131]
	v_mfma_f32_16x16x32_bf16 v[128:131], v[154:157], v[178:181], v[128:131]
	v_mfma_f32_16x16x32_bf16 v[120:123], v[162:165], v[178:181], v[120:123]
	v_mfma_f32_16x16x32_bf16 v[120:123], v[166:169], v[182:185], v[120:123]
	v_mfma_f32_16x16x32_bf16 v[104:107], v[166:169], v[204:207], v[104:107]
	v_mfma_f32_16x16x32_bf16 v[104:107], v[162:165], v[186:189], v[104:107]
	v_mfma_f32_16x16x32_bf16 v[88:91], v[162:165], v[208:211], v[88:91]
	v_mfma_f32_16x16x32_bf16 v[88:91], v[166:169], v[212:215], v[88:91]
	v_mfma_f32_16x16x32_bf16 v[72:75], v[166:169], v[220:223], v[72:75]
	v_mfma_f32_16x16x32_bf16 v[72:75], v[162:165], v[216:219], v[72:75]
	v_mfma_f32_16x16x32_bf16 v[68:71], v[170:173], v[216:219], v[68:71]
	v_mfma_f32_16x16x32_bf16 v[68:71], v[174:177], v[220:223], v[68:71]
	v_mfma_f32_16x16x32_bf16 v[84:87], v[174:177], v[212:215], v[84:87]
	v_mfma_f32_16x16x32_bf16 v[84:87], v[170:173], v[208:211], v[84:87]
	v_mfma_f32_16x16x32_bf16 v[100:103], v[170:173], v[186:189], v[100:103]
	v_mfma_f32_16x16x32_bf16 v[100:103], v[174:177], v[204:207], v[100:103]
	v_mfma_f32_16x16x32_bf16 v[116:119], v[174:177], v[182:185], v[116:119]
	v_mfma_f32_16x16x32_bf16 v[116:119], v[170:173], v[178:181], v[116:119]
	s_barrier
; #define PG8_STAGE(bufoff, gbase, voff) do { _Pragma("unroll") for (int _i = 0; _i < 2; ++_i) \
;         __builtin_amdgcn_global_load_lds((const unsigned*)((const char*)(gbase) + (voff)[_i]), (PG8_LAS unsigned*)(lds + (bufoff) + ldsw + _i * 8192), 16, 0, 0); } while (0)
; #define PG8_LDA(dst, b, h) do { _Pragma("unroll") for (int m = 0; m < 4; ++m) _Pragma("unroll") for (int k = 0; k < 2; ++k) dst[m][k] = *(const PG8_LAS bf16x8*)(lds + PG8_SA(b, h) + aoff + m * 2048 + k * 1024); } while (0)
; #define PG8_WAIT_V(n) asm volatile("s_waitcnt vmcnt(" #n ")" ::: "memory")
; #define PG8_WAIT_L(n) asm volatile("s_waitcnt lgkmcnt(" #n ")" ::: "memory")
; #define PG8_BAR __builtin_amdgcn_s_barrier()
; #define PG8_SCHED __builtin_amdgcn_sched_barrier(0)
; template <class Epi, class Sched, bool ALIGN_EPI = false, bool SP2 = false, bool I8 = false>
; __device__ __forceinline__ void gemm_phase(PG8_LAS unsigned char* lds, const Gemm g, const Sched& S, const Epi& E) {
;     ...
;             PG8_LDA(At, 1, 1); PG8_STAGE(PG8_SB(1, 0), b3, voffB); PG8_STAGE(PG8_SB(1, 1), b3 + hstep, voffB); PG8_STAGE(PG8_SA(1, 0), a3, voffA);
;             PG8_WAIT_V(8); PG8_WAIT_L(0); PG8_BAR; PG8_MMA(1, 0, At, B0); PG8_MMA(1, 1, At, B1); PG8_BAR; PG8_SCHED;
	s_add_i32 s48, s73, s28
	v_lshl_add_u64 v[190:191], v[190:191], 0, s[84:85]
	s_mov_b32 m0, s48
	ds_read_b128 v[178:181], v145 offset:49152
	ds_read_b128 v[182:185], v145 offset:50176
	ds_read_b128 v[186:189], v145 offset:51200
	ds_read_b128 v[204:207], v145 offset:52224
	ds_read_b128 v[208:211], v145 offset:53248
	ds_read_b128 v[212:215], v145 offset:54272
	ds_read_b128 v[216:219], v145 offset:55296
	ds_read_b128 v[220:223], v145 offset:56320
	global_load_lds_dwordx4 v[190:191], off
	v_lshl_add_u64 v[190:191], v[224:225], 0, s[84:85]
	s_add_i32 m0, s48, 0x2000
	s_add_i32 s48, s76, s28
	global_load_lds_dwordx4 v[190:191], off
	v_lshl_add_u64 v[190:191], v[226:227], 0, s[84:85]
	s_mov_b32 m0, s48
	s_nop 0
	global_load_lds_dwordx4 v[190:191], off
	v_lshl_add_u64 v[190:191], v[228:229], 0, s[84:85]
	s_add_i32 m0, s48, 0x2000
	s_nop 0
	global_load_lds_dwordx4 v[190:191], off
	v_lshl_add_u64 v[190:191], v[240:241], 0, s[84:85]
	s_mov_b32 m0, s55
	s_nop 0
	global_load_lds_dwordx4 v[190:191], off
	v_lshl_add_u64 v[190:191], v[242:243], 0, s[84:85]
	s_mov_b32 m0, s56
	s_nop 0
	global_load_lds_dwordx4 v[190:191], off
	s_waitcnt vmcnt(8)
	s_waitcnt lgkmcnt(0)
	s_barrier
	s_waitcnt lgkmcnt(0)
	v_mfma_f32_16x16x32_bf16 v[64:67], v[146:149], v[178:181], v[64:67]
	v_mfma_f32_16x16x32_bf16 v[64:67], v[150:153], v[182:185], v[64:67]
	v_mfma_f32_16x16x32_bf16 v[48:51], v[150:153], v[204:207], v[48:51]
	v_mfma_f32_16x16x32_bf16 v[48:51], v[146:149], v[186:189], v[48:51]
	v_mfma_f32_16x16x32_bf16 v[32:35], v[146:149], v[208:211], v[32:35]
	v_mfma_f32_16x16x32_bf16 v[32:35], v[150:153], v[212:215], v[32:35]
	v_mfma_f32_16x16x32_bf16 v[16:19], v[150:153], v[220:223], v[16:19]
	v_mfma_f32_16x16x32_bf16 v[16:19], v[146:149], v[216:219], v[16:19]
	v_mfma_f32_16x16x32_bf16 v[12:15], v[154:157], v[216:219], v[12:15]
	v_mfma_f32_16x16x32_bf16 v[12:15], v[158:161], v[220:223], v[12:15]
	v_mfma_f32_16x16x32_bf16 v[28:31], v[158:161], v[212:215], v[28:31]
	v_mfma_f32_16x16x32_bf16 v[28:31], v[154:157], v[208:211], v[28:31]
	v_mfma_f32_16x16x32_bf16 v[44:47], v[154:157], v[186:189], v[44:47]
	v_mfma_f32_16x16x32_bf16 v[44:47], v[158:161], v[204:207], v[44:47]
	v_mfma_f32_16x16x32_bf16 v[60:63], v[158:161], v[182:185], v[60:63]
	v_mfma_f32_16x16x32_bf16 v[60:63], v[154:157], v[178:181], v[60:63]
	v_mfma_f32_16x16x32_bf16 v[56:59], v[162:165], v[178:181], v[56:59]
	v_mfma_f32_16x16x32_bf16 v[56:59], v[166:169], v[182:185], v[56:59]
	v_mfma_f32_16x16x32_bf16 v[40:43], v[166:169], v[204:207], v[40:43]
	v_mfma_f32_16x16x32_bf16 v[40:43], v[162:165], v[186:189], v[40:43]
	v_mfma_f32_16x16x32_bf16 v[24:27], v[162:165], v[208:211], v[24:27]
	v_mfma_f32_16x16x32_bf16 v[24:27], v[166:169], v[212:215], v[24:27]
	v_mfma_f32_16x16x32_bf16 v[8:11], v[166:169], v[220:223], v[8:11]
	v_mfma_f32_16x16x32_bf16 v[8:11], v[162:165], v[216:219], v[8:11]
	v_mfma_f32_16x16x32_bf16 v[4:7], v[170:173], v[216:219], v[4:7]
	v_mfma_f32_16x16x32_bf16 v[4:7], v[174:177], v[220:223], v[4:7]
	v_mfma_f32_16x16x32_bf16 v[20:23], v[174:177], v[212:215], v[20:23]
	v_mfma_f32_16x16x32_bf16 v[20:23], v[170:173], v[208:211], v[20:23]
	v_mfma_f32_16x16x32_bf16 v[36:39], v[170:173], v[186:189], v[36:39]
	v_mfma_f32_16x16x32_bf16 v[36:39], v[174:177], v[204:207], v[36:39]
	v_mfma_f32_16x16x32_bf16 v[52:55], v[174:177], v[182:185], v[52:55]
	v_mfma_f32_16x16x32_bf16 v[52:55], v[170:173], v[178:181], v[52:55]
	s_barrier
	s_add_u32 s44, s44, 0x100
	s_addc_u32 s45, s45, 0
	s_add_u32 s65, s65, 0x100
	s_addc_u32 s67, s67, 0
	s_cmp_ge_i32 s72, s53
	s_mov_b32 s48, s72
	s_cbranch_scc0 .LBB0_1623

; #define PG8_STAGE(bufoff, gbase, voff) do { _Pragma("unroll") for (int _i = 0; _i < 2; ++_i) \
;         __builtin_amdgcn_global_load_lds((const unsigned*)((const char*)(gbase) + (voff)[_i]), (PG8_LAS unsigned*)(lds + (bufoff) + ldsw + _i * 8192), 16, 0, 0); } while (0)
; #define PG8_LDA(dst, b, h) do { _Pragma("unroll") for (int m = 0; m < 4; ++m) _Pragma("unroll") for (int k = 0; k < 2; ++k) dst[m][k] = *(const PG8_LAS bf16x8*)(lds + PG8_SA(b, h) + aoff + m * 2048 + k * 1024); } while (0)
; #define PG8_LDB(dst, b, h) do { _Pragma("unroll") for (int n = 0; n < 2; ++n) _Pragma("unroll") for (int k = 0; k < 2; ++k) dst[n][k] = *(const PG8_LAS bf16x8*)(lds + PG8_SB(b, h) + boff + n * 2048 + k * 1024); } while (0)
; #define PG8_WAIT_V(n) asm volatile("s_waitcnt vmcnt(" #n ")" ::: "memory")
; #define PG8_WAIT_L(n) asm volatile("s_waitcnt lgkmcnt(" #n ")" ::: "memory")
; #define PG8_BAR __builtin_amdgcn_s_barrier()
; #define PG8_SCHED __builtin_amdgcn_sched_barrier(0)
; template <class Epi, class Sched, bool ALIGN_EPI = false, bool SP2 = false, bool I8 = false>
; __device__ __forceinline__ void gemm_phase(PG8_LAS unsigned char* lds, const Gemm g, const Sched& S, const Epi& E) {
;     ...
;         const char* nA = has_next ? (const char*)g.A + (size_t)nxt.pm * tstep : cA; const char* nB = has_next ? (const char*)g.Bt + (size_t)nxt.pn * tstep : cB;
;         for (int t = 0; t < nt; t += 2) {
;             const bool last = (t == nt - 2);
;             const char* a1 = cA + (size_t)(t + 1) * kstep;
;             const char* a2 = last ? nA : cA + (size_t)(t + 2) * kstep; const char* b2 = last ? nB : cB + (size_t)(t + 2) * kstep;
;             const char* a3 = a2 + kstep; const char* b3 = b2 + kstep;
;             if (last && has_next) S.a_ready(nxt);
;             if constexpr (SP2) {
;             PG8_LDB(B0, 0, 0); PG8_LDB(B1, 0, 1); PG8_SCHED; PG8_LDA(At, 0, 0); PG8_STAGE(PG8_SA(1, 1), a1 + hstep, voffA);
;             PG8_WAIT_V(8); PG8_WAIT_L(0); PG8_BAR; PG8_MMA(0, 0, At, B0); PG8_MMA(0, 1, At, B1); PG8_BAR; PG8_SCHED;
;             PG8_LDA(At, 0, 1); PG8_STAGE(PG8_SB(0, 0), b2, voffB); PG8_STAGE(PG8_SB(0, 1), b2 + hstep, voffB); PG8_STAGE(PG8_SA(0, 0), a2, voffA);
;             PG8_WAIT_V(8); PG8_WAIT_L(0); PG8_BAR; PG8_MMA(1, 0, At, B0); PG8_MMA(1, 1, At, B1); PG8_BAR; PG8_SCHED;
.LBB0_1699:
	s_add_u32 s53, s24, 0x100
	s_addc_u32 s54, s25, 0
	s_mov_b32 s55, -2
	s_add_u32 s24, s22, 0x100
	s_addc_u32 s25, s23, 0
	s_add_i32 s56, 0, 0x10000
	s_cmpk_eq_i32 s55, 0xa8
	s_cselect_b32 s37, s13, s25
	s_cselect_b32 s36, s12, s24
	s_cselect_b32 s27, s21, s54
	s_cselect_b32 s26, s20, s53
	s_add_i32 s57, 0, 0x14000
	v_add_u32_e32 v144, s56, v240
	v_add_u32_e32 v160, s57, v240
	ds_read_b128 v[124:127], v144
	ds_read_b128 v[128:131], v144 offset:1024
	ds_read_b128 v[132:135], v144 offset:2048
	ds_read_b128 v[144:147], v144 offset:3072
	ds_read_b128 v[148:151], v160
	ds_read_b128 v[152:155], v160 offset:1024
	ds_read_b128 v[156:159], v160 offset:2048
	ds_read_b128 v[160:163], v160 offset:3072
	v_lshl_add_u64 v[218:219], s[22:23], 0, v[210:211]
	s_add_i32 m0, s42, 0xc000
	ds_read_b128 v[164:167], v242
	ds_read_b128 v[168:171], v242 offset:1024
	ds_read_b128 v[172:175], v242 offset:2048
	ds_read_b128 v[176:179], v242 offset:3072
	ds_read_b128 v[180:183], v242 offset:4096
	ds_read_b128 v[184:187], v242 offset:5120
	ds_read_b128 v[188:191], v242 offset:6144
	ds_read_b128 v[214:217], v242 offset:7168
	global_load_lds_dwordx4 v[218:219], off
	v_lshl_add_u64 v[218:219], s[22:23], 0, v[212:213]
	s_add_i32 m0, s42, 0xe000
	s_nop 0
	global_load_lds_dwordx4 v[218:219], off
	s_waitcnt vmcnt(8)
	s_waitcnt lgkmcnt(0)
	s_barrier
	s_waitcnt lgkmcnt(0)
	v_mfma_f32_16x16x32_bf16 v[140:143], v[124:127], v[164:167], 0
	v_mfma_f32_16x16x32_bf16 v[140:143], v[128:131], v[168:171], v[140:143]
	v_mfma_f32_16x16x32_bf16 v[112:115], v[128:131], v[176:179], 0
	v_mfma_f32_16x16x32_bf16 v[112:115], v[124:127], v[172:175], v[112:115]
	v_mfma_f32_16x16x32_bf16 v[96:99], v[124:127], v[180:183], 0
	v_mfma_f32_16x16x32_bf16 v[96:99], v[128:131], v[184:187], v[96:99]
	v_mfma_f32_16x16x32_bf16 v[80:83], v[128:131], v[214:217], 0
	v_mfma_f32_16x16x32_bf16 v[80:83], v[124:127], v[188:191], v[80:83]
	v_mfma_f32_16x16x32_bf16 v[76:79], v[132:135], v[188:191], 0
	v_mfma_f32_16x16x32_bf16 v[76:79], v[144:147], v[214:217], v[76:79]
	v_mfma_f32_16x16x32_bf16 v[92:95], v[144:147], v[184:187], 0
	v_mfma_f32_16x16x32_bf16 v[92:95], v[132:135], v[180:183], v[92:95]
	v_mfma_f32_16x16x32_bf16 v[108:111], v[132:135], v[172:175], 0
	v_mfma_f32_16x16x32_bf16 v[108:111], v[144:147], v[176:179], v[108:111]
	v_mfma_f32_16x16x32_bf16 v[136:139], v[144:147], v[168:171], 0
	v_mfma_f32_16x16x32_bf16 v[136:139], v[132:135], v[164:167], v[136:139]
	v_mfma_f32_16x16x32_bf16 v[120:123], v[148:151], v[164:167], 0
	v_mfma_f32_16x16x32_bf16 v[120:123], v[152:155], v[168:171], v[120:123]
	v_mfma_f32_16x16x32_bf16 v[104:107], v[152:155], v[176:179], 0
	v_mfma_f32_16x16x32_bf16 v[104:107], v[148:151], v[172:175], v[104:107]
	v_mfma_f32_16x16x32_bf16 v[88:91], v[148:151], v[180:183], 0
	v_mfma_f32_16x16x32_bf16 v[88:91], v[152:155], v[184:187], v[88:91]
	v_mfma_f32_16x16x32_bf16 v[72:75], v[152:155], v[214:217], 0
	v_mfma_f32_16x16x32_bf16 v[72:75], v[148:151], v[188:191], v[72:75]
	v_mfma_f32_16x16x32_bf16 v[68:71], v[156:159], v[188:191], 0
	v_mfma_f32_16x16x32_bf16 v[68:71], v[160:163], v[214:217], v[68:71]
	v_mfma_f32_16x16x32_bf16 v[84:87], v[160:163], v[184:187], 0
	v_mfma_f32_16x16x32_bf16 v[84:87], v[156:159], v[180:183], v[84:87]
	v_mfma_f32_16x16x32_bf16 v[100:103], v[156:159], v[172:175], 0
	v_mfma_f32_16x16x32_bf16 v[100:103], v[160:163], v[176:179], v[100:103]
	v_mfma_f32_16x16x32_bf16 v[116:119], v[160:163], v[168:171], 0
	v_mfma_f32_16x16x32_bf16 v[116:119], v[156:159], v[164:167], v[116:119]
	s_barrier
	s_add_i32 s22, s56, s41
	v_lshl_add_u64 v[218:219], s[26:27], 0, v[2:3]
	s_mov_b32 m0, s22
	ds_read_b128 v[164:167], v242 offset:16384
	ds_read_b128 v[168:171], v242 offset:17408
	ds_read_b128 v[172:175], v242 offset:18432
	ds_read_b128 v[176:179], v242 offset:19456
	ds_read_b128 v[180:183], v242 offset:20480
	ds_read_b128 v[184:187], v242 offset:21504
	ds_read_b128 v[188:191], v242 offset:22528
	ds_read_b128 v[214:217], v242 offset:23552
	global_load_lds_dwordx4 v[218:219], off
	s_add_i32 m0, s22, 0x2000
	s_add_u32 s22, s26, 0x2b0000
	v_lshl_add_u64 v[220:221], s[26:27], 0, v[204:205]
	s_addc_u32 s23, s27, 0
	s_add_i32 s56, s57, s41
	global_load_lds_dwordx4 v[220:221], off
	v_lshl_add_u64 v[222:223], s[22:23], 0, v[2:3]
	s_mov_b32 m0, s56
	v_lshl_add_u64 v[224:225], s[36:37], 0, v[206:207]
	global_load_lds_dwordx4 v[222:223], off
	v_lshl_add_u64 v[222:223], s[22:23], 0, v[204:205]
	s_add_i32 m0, s56, 0x2000
	s_nop 0
	global_load_lds_dwordx4 v[222:223], off
	v_lshl_add_u64 v[222:223], s[36:37], 0, v[208:209]
	s_mov_b32 m0, s42
	s_nop 0
	global_load_lds_dwordx4 v[222:223], off
	s_mov_b32 m0, s43
	s_nop 0
	global_load_lds_dwordx4 v[224:225], off
	s_waitcnt vmcnt(8)
	s_waitcnt lgkmcnt(0)
	s_barrier
; #define PG8_STAGE(bufoff, gbase, voff) do { _Pragma("unroll") for (int _i = 0; _i < 2; ++_i) \
;         __builtin_amdgcn_global_load_lds((const unsigned*)((const char*)(gbase) + (voff)[_i]), (PG8_LAS unsigned*)(lds + (bufoff) + ldsw + _i * 8192), 16, 0, 0); } while (0)
; #define PG8_LDA(dst, b, h) do { _Pragma("unroll") for (int m = 0; m < 4; ++m) _Pragma("unroll") for (int k = 0; k < 2; ++k) dst[m][k] = *(const PG8_LAS bf16x8*)(lds + PG8_SA(b, h) + aoff + m * 2048 + k * 1024); } while (0)
; #define PG8_LDB(dst, b, h) do { _Pragma("unroll") for (int n = 0; n < 2; ++n) _Pragma("unroll") for (int k = 0; k < 2; ++k) dst[n][k] = *(const PG8_LAS bf16x8*)(lds + PG8_SB(b, h) + boff + n * 2048 + k * 1024); } while (0)
; #define PG8_WAIT_V(n) asm volatile("s_waitcnt vmcnt(" #n ")" ::: "memory")
; #define PG8_WAIT_L(n) asm volatile("s_waitcnt lgkmcnt(" #n ")" ::: "memory")
; #define PG8_BAR __builtin_amdgcn_s_barrier()
; #define PG8_SCHED __builtin_amdgcn_sched_barrier(0)
; template <class Epi, class Sched, bool ALIGN_EPI = false, bool SP2 = false, bool I8 = false>
; __device__ __forceinline__ void gemm_phase(PG8_LAS unsigned char* lds, const Gemm g, const Sched& S, const Epi& E) {
;     ...
;             PG8_WAIT_V(8); PG8_WAIT_L(0); PG8_BAR; PG8_MMA(1, 0, At, B0); PG8_MMA(1, 1, At, B1); PG8_BAR; PG8_SCHED;
;             PG8_LDB(B0, 1, 0); PG8_LDB(B1, 1, 1); PG8_SCHED; PG8_LDA(At, 1, 0); PG8_STAGE(PG8_SA(0, 1), a2 + hstep, voffA);
;             PG8_WAIT_V(8); PG8_WAIT_L(0); PG8_BAR; PG8_MMA(0, 0, At, B0); PG8_MMA(0, 1, At, B1); PG8_BAR; PG8_SCHED;
	s_waitcnt lgkmcnt(0)
	v_mfma_f32_16x16x32_bf16 v[64:67], v[124:127], v[164:167], 0
	v_mfma_f32_16x16x32_bf16 v[64:67], v[128:131], v[168:171], v[64:67]
	v_mfma_f32_16x16x32_bf16 v[48:51], v[128:131], v[176:179], 0
	v_mfma_f32_16x16x32_bf16 v[48:51], v[124:127], v[172:175], v[48:51]
	v_mfma_f32_16x16x32_bf16 v[32:35], v[124:127], v[180:183], 0
	v_mfma_f32_16x16x32_bf16 v[32:35], v[128:131], v[184:187], v[32:35]
	v_mfma_f32_16x16x32_bf16 v[16:19], v[128:131], v[214:217], 0
	v_mfma_f32_16x16x32_bf16 v[16:19], v[124:127], v[188:191], v[16:19]
	v_mfma_f32_16x16x32_bf16 v[12:15], v[132:135], v[188:191], 0
	v_mfma_f32_16x16x32_bf16 v[12:15], v[144:147], v[214:217], v[12:15]
	v_mfma_f32_16x16x32_bf16 v[28:31], v[144:147], v[184:187], 0
	v_mfma_f32_16x16x32_bf16 v[28:31], v[132:135], v[180:183], v[28:31]
	v_mfma_f32_16x16x32_bf16 v[44:47], v[132:135], v[172:175], 0
	v_mfma_f32_16x16x32_bf16 v[44:47], v[144:147], v[176:179], v[44:47]
	v_mfma_f32_16x16x32_bf16 v[60:63], v[144:147], v[168:171], 0
	v_mfma_f32_16x16x32_bf16 v[60:63], v[132:135], v[164:167], v[60:63]
	v_mfma_f32_16x16x32_bf16 v[56:59], v[148:151], v[164:167], 0
	v_mfma_f32_16x16x32_bf16 v[56:59], v[152:155], v[168:171], v[56:59]
	v_mfma_f32_16x16x32_bf16 v[40:43], v[152:155], v[176:179], 0
	v_mfma_f32_16x16x32_bf16 v[40:43], v[148:151], v[172:175], v[40:43]
	v_mfma_f32_16x16x32_bf16 v[24:27], v[148:151], v[180:183], 0
	v_mfma_f32_16x16x32_bf16 v[24:27], v[152:155], v[184:187], v[24:27]
	v_mfma_f32_16x16x32_bf16 v[8:11], v[152:155], v[214:217], 0
	v_mfma_f32_16x16x32_bf16 v[8:11], v[148:151], v[188:191], v[8:11]
	v_mfma_f32_16x16x32_bf16 v[4:7], v[156:159], v[188:191], 0
	v_mfma_f32_16x16x32_bf16 v[4:7], v[160:163], v[214:217], v[4:7]
	v_mfma_f32_16x16x32_bf16 v[20:23], v[160:163], v[184:187], 0
	v_mfma_f32_16x16x32_bf16 v[20:23], v[156:159], v[180:183], v[20:23]
	v_mfma_f32_16x16x32_bf16 v[36:39], v[156:159], v[172:175], 0
	v_mfma_f32_16x16x32_bf16 v[36:39], v[160:163], v[176:179], v[36:39]
	v_mfma_f32_16x16x32_bf16 v[52:55], v[160:163], v[168:171], 0
	v_mfma_f32_16x16x32_bf16 v[52:55], v[156:159], v[164:167], v[52:55]
	s_barrier
	s_add_i32 s56, 0, 0x18000
	s_add_i32 s57, 0, 0x1c000
	v_add_u32_e32 v144, s56, v240
	v_add_u32_e32 v160, s57, v240
	ds_read_b128 v[124:127], v144
	ds_read_b128 v[128:131], v144 offset:1024
	ds_read_b128 v[132:135], v144 offset:2048
	ds_read_b128 v[144:147], v144 offset:3072
	ds_read_b128 v[148:151], v160
	ds_read_b128 v[152:155], v160 offset:1024
	ds_read_b128 v[156:159], v160 offset:2048
	ds_read_b128 v[160:163], v160 offset:3072
	s_add_u32 s22, s36, 0x2b0000
	s_addc_u32 s23, s37, 0
	s_mov_b32 m0, s44
	v_lshl_add_u64 v[226:227], s[22:23], 0, v[208:209]
	ds_read_b128 v[164:167], v242 offset:32768
	ds_read_b128 v[168:171], v242 offset:33792
	ds_read_b128 v[172:175], v242 offset:34816
	ds_read_b128 v[176:179], v242 offset:35840
	ds_read_b128 v[180:183], v242 offset:36864
	ds_read_b128 v[184:187], v242 offset:37888
	ds_read_b128 v[188:191], v242 offset:38912
	ds_read_b128 v[214:217], v242 offset:39936
	global_load_lds_dwordx4 v[226:227], off
	v_lshl_add_u64 v[226:227], s[22:23], 0, v[206:207]
	s_mov_b32 m0, s45
	s_nop 0
	global_load_lds_dwordx4 v[226:227], off
	s_waitcnt vmcnt(8)
	s_waitcnt lgkmcnt(0)
	s_barrier
	s_waitcnt lgkmcnt(0)
	v_mfma_f32_16x16x32_bf16 v[140:143], v[124:127], v[164:167], v[140:143]
	v_mfma_f32_16x16x32_bf16 v[140:143], v[128:131], v[168:171], v[140:143]
	v_mfma_f32_16x16x32_bf16 v[112:115], v[128:131], v[176:179], v[112:115]
	v_mfma_f32_16x16x32_bf16 v[112:115], v[124:127], v[172:175], v[112:115]
	v_mfma_f32_16x16x32_bf16 v[96:99], v[124:127], v[180:183], v[96:99]
	v_mfma_f32_16x16x32_bf16 v[96:99], v[128:131], v[184:187], v[96:99]
	v_mfma_f32_16x16x32_bf16 v[80:83], v[128:131], v[214:217], v[80:83]
	v_mfma_f32_16x16x32_bf16 v[80:83], v[124:127], v[188:191], v[80:83]
	v_mfma_f32_16x16x32_bf16 v[76:79], v[132:135], v[188:191], v[76:79]
	v_mfma_f32_16x16x32_bf16 v[76:79], v[144:147], v[214:217], v[76:79]
	v_mfma_f32_16x16x32_bf16 v[92:95], v[144:147], v[184:187], v[92:95]
	v_mfma_f32_16x16x32_bf16 v[92:95], v[132:135], v[180:183], v[92:95]
	v_mfma_f32_16x16x32_bf16 v[108:111], v[132:135], v[172:175], v[108:111]
	v_mfma_f32_16x16x32_bf16 v[108:111], v[144:147], v[176:179], v[108:111]
	v_mfma_f32_16x16x32_bf16 v[136:139], v[144:147], v[168:171], v[136:139]
	v_mfma_f32_16x16x32_bf16 v[136:139], v[132:135], v[164:167], v[136:139]
	v_mfma_f32_16x16x32_bf16 v[120:123], v[148:151], v[164:167], v[120:123]
	v_mfma_f32_16x16x32_bf16 v[120:123], v[152:155], v[168:171], v[120:123]
	v_mfma_f32_16x16x32_bf16 v[104:107], v[152:155], v[176:179], v[104:107]
	v_mfma_f32_16x16x32_bf16 v[104:107], v[148:151], v[172:175], v[104:107]
	v_mfma_f32_16x16x32_bf16 v[88:91], v[148:151], v[180:183], v[88:91]
	v_mfma_f32_16x16x32_bf16 v[88:91], v[152:155], v[184:187], v[88:91]
	v_mfma_f32_16x16x32_bf16 v[72:75], v[152:155], v[214:217], v[72:75]
	v_mfma_f32_16x16x32_bf16 v[72:75], v[148:151], v[188:191], v[72:75]
	v_mfma_f32_16x16x32_bf16 v[68:71], v[156:159], v[188:191], v[68:71]
	v_mfma_f32_16x16x32_bf16 v[68:71], v[160:163], v[214:217], v[68:71]
	v_mfma_f32_16x16x32_bf16 v[84:87], v[160:163], v[184:187], v[84:87]
	v_mfma_f32_16x16x32_bf16 v[84:87], v[156:159], v[180:183], v[84:87]
	v_mfma_f32_16x16x32_bf16 v[100:103], v[156:159], v[172:175], v[100:103]
	v_mfma_f32_16x16x32_bf16 v[100:103], v[160:163], v[176:179], v[100:103]
	v_mfma_f32_16x16x32_bf16 v[116:119], v[160:163], v[168:171], v[116:119]
	v_mfma_f32_16x16x32_bf16 v[116:119], v[156:159], v[164:167], v[116:119]
	s_barrier
; #define PG8_STAGE(bufoff, gbase, voff) do { _Pragma("unroll") for (int _i = 0; _i < 2; ++_i) \
;         __builtin_amdgcn_global_load_lds((const unsigned*)((const char*)(gbase) + (voff)[_i]), (PG8_LAS unsigned*)(lds + (bufoff) + ldsw + _i * 8192), 16, 0, 0); } while (0)
; #define PG8_LDA(dst, b, h) do { _Pragma("unroll") for (int m = 0; m < 4; ++m) _Pragma("unroll") for (int k = 0; k < 2; ++k) dst[m][k] = *(const PG8_LAS bf16x8*)(lds + PG8_SA(b, h) + aoff + m * 2048 + k * 1024); } while (0)
; #define PG8_LDB(dst, b, h) do { _Pragma("unroll") for (int n = 0; n < 2; ++n) _Pragma("unroll") for (int k = 0; k < 2; ++k) dst[n][k] = *(const PG8_LAS bf16x8*)(lds + PG8_SB(b, h) + boff + n * 2048 + k * 1024); } while (0)
; #define PG8_WAIT_V(n) asm volatile("s_waitcnt vmcnt(" #n ")" ::: "memory")
; template <class Epi, class Sched, bool ALIGN_EPI = false, bool SP2 = false, bool I8 = false>
; __device__ __forceinline__ void gemm_phase(PG8_LAS unsigned char* lds, const Gemm g, const Sched& S, const Epi& E) {
;     ...
;             const char* a1 = cA + (size_t)(t + 1) * kstep;
;             const char* a2 = last ? nA : cA + (size_t)(t + 2) * kstep; const char* b2 = last ? nB : cB + (size_t)(t + 2) * kstep;
;             const char* a3 = a2 + kstep; const char* b3 = b2 + kstep;
;             if (last && has_next) S.a_ready(nxt);
;             if constexpr (SP2) {
;             PG8_LDB(B0, 0, 0); PG8_LDB(B1, 0, 1); PG8_SCHED; PG8_LDA(At, 0, 0); PG8_STAGE(PG8_SA(1, 1), a1 + hstep, voffA);
;             PG8_WAIT_V(8); PG8_WAIT_L(0); PG8_BAR; PG8_MMA(0, 0, At, B0); PG8_MMA(0, 1, At, B1); PG8_BAR; PG8_SCHED;
;             PG8_LDA(At, 0, 1); PG8_STAGE(PG8_SB(0, 0), b2, voffB); PG8_STAGE(PG8_SB(0, 1), b2 + hstep, voffB); PG8_STAGE(PG8_SA(0, 0), a2, voffA);
;             PG8_WAIT_V(8); PG8_WAIT_L(0); PG8_BAR; PG8_MMA(1, 0, At, B0); PG8_MMA(1, 1, At, B1); PG8_BAR; PG8_SCHED;
;             PG8_LDB(B0, 1, 0); PG8_LDB(B1, 1, 1); PG8_SCHED; PG8_LDA(At, 1, 0); PG8_STAGE(PG8_SA(0, 1), a2 + hstep, voffA);
;             PG8_WAIT_V(8); PG8_WAIT_L(0); PG8_BAR; PG8_MMA(0, 0, At, B0); PG8_MMA(0, 1, At, B1); PG8_BAR; PG8_SCHED;
;             PG8_LDA(At, 1, 1); PG8_STAGE(PG8_SB(1, 0), b3, voffB); PG8_STAGE(PG8_SB(1, 1), b3 + hstep, voffB); PG8_STAGE(PG8_SA(1, 0), a3, voffA);
;             PG8_WAIT_V(8); PG8_WAIT_L(0); PG8_BAR; PG8_MMA(1, 0, At, B0); PG8_MMA(1, 1, At, B1); PG8_BAR; PG8_SCHED;
	s_add_i32 s22, s56, s41
	v_lshl_add_u64 v[218:219], v[218:219], 0, s[84:85]
	s_mov_b32 m0, s22
	ds_read_b128 v[164:167], v242 offset:49152
	ds_read_b128 v[168:171], v242 offset:50176
	ds_read_b128 v[172:175], v242 offset:51200
	ds_read_b128 v[176:179], v242 offset:52224
	ds_read_b128 v[180:183], v242 offset:53248
	ds_read_b128 v[184:187], v242 offset:54272
	ds_read_b128 v[188:191], v242 offset:55296
	ds_read_b128 v[214:217], v242 offset:56320
	global_load_lds_dwordx4 v[218:219], off
	s_add_i32 m0, s22, 0x2000
	s_add_u32 s22, s26, 0x2b0080
	v_lshl_add_u64 v[218:219], v[220:221], 0, s[84:85]
	s_addc_u32 s23, s27, 0
	s_add_i32 s26, s57, s41
	global_load_lds_dwordx4 v[218:219], off
	v_lshl_add_u64 v[218:219], s[22:23], 0, v[2:3]
	s_mov_b32 m0, s26
	s_nop 0
	global_load_lds_dwordx4 v[218:219], off
	v_lshl_add_u64 v[218:219], s[22:23], 0, v[204:205]
	s_add_i32 m0, s26, 0x2000
	s_nop 0
	global_load_lds_dwordx4 v[218:219], off
	v_lshl_add_u64 v[218:219], v[222:223], 0, s[84:85]
	s_mov_b32 m0, s46
	s_nop 0
	global_load_lds_dwordx4 v[218:219], off
	v_lshl_add_u64 v[218:219], v[224:225], 0, s[84:85]
	s_mov_b32 m0, s47
	s_nop 0
	global_load_lds_dwordx4 v[218:219], off
	s_waitcnt vmcnt(8)
	s_waitcnt lgkmcnt(0)
	s_barrier
	s_waitcnt lgkmcnt(0)
	v_mfma_f32_16x16x32_bf16 v[64:67], v[124:127], v[164:167], v[64:67]
	v_mfma_f32_16x16x32_bf16 v[64:67], v[128:131], v[168:171], v[64:67]
	v_mfma_f32_16x16x32_bf16 v[48:51], v[128:131], v[176:179], v[48:51]
	v_mfma_f32_16x16x32_bf16 v[48:51], v[124:127], v[172:175], v[48:51]
	v_mfma_f32_16x16x32_bf16 v[32:35], v[124:127], v[180:183], v[32:35]
	v_mfma_f32_16x16x32_bf16 v[32:35], v[128:131], v[184:187], v[32:35]
	v_mfma_f32_16x16x32_bf16 v[16:19], v[128:131], v[214:217], v[16:19]
	v_mfma_f32_16x16x32_bf16 v[16:19], v[124:127], v[188:191], v[16:19]
	v_mfma_f32_16x16x32_bf16 v[12:15], v[132:135], v[188:191], v[12:15]
	v_mfma_f32_16x16x32_bf16 v[12:15], v[144:147], v[214:217], v[12:15]
	v_mfma_f32_16x16x32_bf16 v[28:31], v[144:147], v[184:187], v[28:31]
	v_mfma_f32_16x16x32_bf16 v[28:31], v[132:135], v[180:183], v[28:31]
	v_mfma_f32_16x16x32_bf16 v[44:47], v[132:135], v[172:175], v[44:47]
	v_mfma_f32_16x16x32_bf16 v[44:47], v[144:147], v[176:179], v[44:47]
	v_mfma_f32_16x16x32_bf16 v[60:63], v[144:147], v[168:171], v[60:63]
	v_mfma_f32_16x16x32_bf16 v[60:63], v[132:135], v[164:167], v[60:63]
	v_mfma_f32_16x16x32_bf16 v[56:59], v[148:151], v[164:167], v[56:59]
	v_mfma_f32_16x16x32_bf16 v[56:59], v[152:155], v[168:171], v[56:59]
	v_mfma_f32_16x16x32_bf16 v[40:43], v[152:155], v[176:179], v[40:43]
	v_mfma_f32_16x16x32_bf16 v[40:43], v[148:151], v[172:175], v[40:43]
	v_mfma_f32_16x16x32_bf16 v[24:27], v[148:151], v[180:183], v[24:27]
	v_mfma_f32_16x16x32_bf16 v[24:27], v[152:155], v[184:187], v[24:27]
	v_mfma_f32_16x16x32_bf16 v[8:11], v[152:155], v[214:217], v[8:11]
	v_mfma_f32_16x16x32_bf16 v[8:11], v[148:151], v[188:191], v[8:11]
	v_mfma_f32_16x16x32_bf16 v[4:7], v[156:159], v[188:191], v[4:7]
	v_mfma_f32_16x16x32_bf16 v[4:7], v[160:163], v[214:217], v[4:7]
	v_mfma_f32_16x16x32_bf16 v[20:23], v[160:163], v[184:187], v[20:23]
	v_mfma_f32_16x16x32_bf16 v[20:23], v[156:159], v[180:183], v[20:23]
	v_mfma_f32_16x16x32_bf16 v[36:39], v[156:159], v[172:175], v[36:39]
	v_mfma_f32_16x16x32_bf16 v[36:39], v[160:163], v[176:179], v[36:39]
	v_mfma_f32_16x16x32_bf16 v[52:55], v[160:163], v[168:171], v[52:55]
	v_mfma_f32_16x16x32_bf16 v[52:55], v[156:159], v[164:167], v[52:55]
	s_barrier
	s_add_i32 s55, s55, 2
	s_add_u32 s53, s53, 0x100
	s_addc_u32 s54, s54, 0
	s_cmpk_gt_u32 s55, 0xa9
	s_mov_b64 s[22:23], s[24:25]
	s_cbranch_scc1 .Lkloop_exit_5
.LBB0_1700:
	s_add_u32 s24, s22, 0x100
	s_addc_u32 s25, s23, 0
	s_add_i32 s56, 0, 0x10000
	s_cmpk_eq_i32 s55, 0xa8
	s_cselect_b32 s37, s13, s25
	s_cselect_b32 s36, s12, s24
	s_cselect_b32 s27, s21, s54
	s_cselect_b32 s26, s20, s53
	s_add_i32 s57, 0, 0x14000
	v_add_u32_e32 v144, s56, v240
	v_add_u32_e32 v160, s57, v240
	ds_read_b128 v[124:127], v144
	ds_read_b128 v[128:131], v144 offset:1024
	ds_read_b128 v[132:135], v144 offset:2048
	ds_read_b128 v[144:147], v144 offset:3072
	ds_read_b128 v[148:151], v160
	ds_read_b128 v[152:155], v160 offset:1024
	ds_read_b128 v[156:159], v160 offset:2048
	ds_read_b128 v[160:163], v160 offset:3072
	v_lshl_add_u64 v[218:219], s[22:23], 0, v[210:211]
	s_add_i32 m0, s42, 0xc000
	ds_read_b128 v[164:167], v242
	ds_read_b128 v[168:171], v242 offset:1024
	ds_read_b128 v[172:175], v242 offset:2048
	ds_read_b128 v[176:179], v242 offset:3072
	ds_read_b128 v[180:183], v242 offset:4096
	ds_read_b128 v[184:187], v242 offset:5120
	ds_read_b128 v[188:191], v242 offset:6144
	ds_read_b128 v[214:217], v242 offset:7168
	global_load_lds_dwordx4 v[218:219], off
	v_lshl_add_u64 v[218:219], s[22:23], 0, v[212:213]
	s_add_i32 m0, s42, 0xe000
	s_nop 0
	global_load_lds_dwordx4 v[218:219], off
	s_waitcnt vmcnt(8)
	s_waitcnt lgkmcnt(0)
	s_barrier
; #define PG8_STAGE(bufoff, gbase, voff) do { _Pragma("unroll") for (int _i = 0; _i < 2; ++_i) \
;         __builtin_amdgcn_global_load_lds((const unsigned*)((const char*)(gbase) + (voff)[_i]), (PG8_LAS unsigned*)(lds + (bufoff) + ldsw + _i * 8192), 16, 0, 0); } while (0)
; #define PG8_LDA(dst, b, h) do { _Pragma("unroll") for (int m = 0; m < 4; ++m) _Pragma("unroll") for (int k = 0; k < 2; ++k) dst[m][k] = *(const PG8_LAS bf16x8*)(lds + PG8_SA(b, h) + aoff + m * 2048 + k * 1024); } while (0)
; #define PG8_LDB(dst, b, h) do { _Pragma("unroll") for (int n = 0; n < 2; ++n) _Pragma("unroll") for (int k = 0; k < 2; ++k) dst[n][k] = *(const PG8_LAS bf16x8*)(lds + PG8_SB(b, h) + boff + n * 2048 + k * 1024); } while (0)
; #define PG8_WAIT_V(n) asm volatile("s_waitcnt vmcnt(" #n ")" ::: "memory")
; #define PG8_WAIT_L(n) asm volatile("s_waitcnt lgkmcnt(" #n ")" ::: "memory")
; #define PG8_BAR __builtin_amdgcn_s_barrier()
; #define PG8_SCHED __builtin_amdgcn_sched_barrier(0)
; template <class Epi, class Sched, bool ALIGN_EPI = false, bool SP2 = false, bool I8 = false>
; __device__ __forceinline__ void gemm_phase(PG8_LAS unsigned char* lds, const Gemm g, const Sched& S, const Epi& E) {
;     ...
;             PG8_WAIT_V(8); PG8_WAIT_L(0); PG8_BAR; PG8_MMA(0, 0, At, B0); PG8_MMA(0, 1, At, B1); PG8_BAR; PG8_SCHED;
;             PG8_LDA(At, 0, 1); PG8_STAGE(PG8_SB(0, 0), b2, voffB); PG8_STAGE(PG8_SB(0, 1), b2 + hstep, voffB); PG8_STAGE(PG8_SA(0, 0), a2, voffA);
;             PG8_WAIT_V(8); PG8_WAIT_L(0); PG8_BAR; PG8_MMA(1, 0, At, B0); PG8_MMA(1, 1, At, B1); PG8_BAR; PG8_SCHED;
;             PG8_LDB(B0, 1, 0); PG8_LDB(B1, 1, 1); PG8_SCHED; PG8_LDA(At, 1, 0); PG8_STAGE(PG8_SA(0, 1), a2 + hstep, voffA);
;             PG8_WAIT_V(8); PG8_WAIT_L(0); PG8_BAR; PG8_MMA(0, 0, At, B0); PG8_MMA(0, 1, At, B1); PG8_BAR; PG8_SCHED;
	s_waitcnt lgkmcnt(0)
	v_mfma_f32_16x16x32_bf16 v[140:143], v[124:127], v[164:167], v[140:143]
	v_mfma_f32_16x16x32_bf16 v[140:143], v[128:131], v[168:171], v[140:143]
	v_mfma_f32_16x16x32_bf16 v[112:115], v[128:131], v[176:179], v[112:115]
	v_mfma_f32_16x16x32_bf16 v[112:115], v[124:127], v[172:175], v[112:115]
	v_mfma_f32_16x16x32_bf16 v[96:99], v[124:127], v[180:183], v[96:99]
	v_mfma_f32_16x16x32_bf16 v[96:99], v[128:131], v[184:187], v[96:99]
	v_mfma_f32_16x16x32_bf16 v[80:83], v[128:131], v[214:217], v[80:83]
	v_mfma_f32_16x16x32_bf16 v[80:83], v[124:127], v[188:191], v[80:83]
	v_mfma_f32_16x16x32_bf16 v[76:79], v[132:135], v[188:191], v[76:79]
	v_mfma_f32_16x16x32_bf16 v[76:79], v[144:147], v[214:217], v[76:79]
	v_mfma_f32_16x16x32_bf16 v[92:95], v[144:147], v[184:187], v[92:95]
	v_mfma_f32_16x16x32_bf16 v[92:95], v[132:135], v[180:183], v[92:95]
	v_mfma_f32_16x16x32_bf16 v[108:111], v[132:135], v[172:175], v[108:111]
	v_mfma_f32_16x16x32_bf16 v[108:111], v[144:147], v[176:179], v[108:111]
	v_mfma_f32_16x16x32_bf16 v[136:139], v[144:147], v[168:171], v[136:139]
	v_mfma_f32_16x16x32_bf16 v[136:139], v[132:135], v[164:167], v[136:139]
	v_mfma_f32_16x16x32_bf16 v[120:123], v[148:151], v[164:167], v[120:123]
	v_mfma_f32_16x16x32_bf16 v[120:123], v[152:155], v[168:171], v[120:123]
	v_mfma_f32_16x16x32_bf16 v[104:107], v[152:155], v[176:179], v[104:107]
	v_mfma_f32_16x16x32_bf16 v[104:107], v[148:151], v[172:175], v[104:107]
	v_mfma_f32_16x16x32_bf16 v[88:91], v[148:151], v[180:183], v[88:91]
	v_mfma_f32_16x16x32_bf16 v[88:91], v[152:155], v[184:187], v[88:91]
	v_mfma_f32_16x16x32_bf16 v[72:75], v[152:155], v[214:217], v[72:75]
	v_mfma_f32_16x16x32_bf16 v[72:75], v[148:151], v[188:191], v[72:75]
	v_mfma_f32_16x16x32_bf16 v[68:71], v[156:159], v[188:191], v[68:71]
	v_mfma_f32_16x16x32_bf16 v[68:71], v[160:163], v[214:217], v[68:71]
	v_mfma_f32_16x16x32_bf16 v[84:87], v[160:163], v[184:187], v[84:87]
	v_mfma_f32_16x16x32_bf16 v[84:87], v[156:159], v[180:183], v[84:87]
	v_mfma_f32_16x16x32_bf16 v[100:103], v[156:159], v[172:175], v[100:103]
	v_mfma_f32_16x16x32_bf16 v[100:103], v[160:163], v[176:179], v[100:103]
	v_mfma_f32_16x16x32_bf16 v[116:119], v[160:163], v[168:171], v[116:119]
	v_mfma_f32_16x16x32_bf16 v[116:119], v[156:159], v[164:167], v[116:119]
	s_barrier
	s_add_i32 s22, s56, s41
	v_lshl_add_u64 v[218:219], s[26:27], 0, v[2:3]
	s_mov_b32 m0, s22
	ds_read_b128 v[164:167], v242 offset:16384
	ds_read_b128 v[168:171], v242 offset:17408
	ds_read_b128 v[172:175], v242 offset:18432
	ds_read_b128 v[176:179], v242 offset:19456
	ds_read_b128 v[180:183], v242 offset:20480
	ds_read_b128 v[184:187], v242 offset:21504
	ds_read_b128 v[188:191], v242 offset:22528
	ds_read_b128 v[214:217], v242 offset:23552
	global_load_lds_dwordx4 v[218:219], off
	s_add_i32 m0, s22, 0x2000
	s_add_u32 s22, s26, 0x2b0000
	v_lshl_add_u64 v[220:221], s[26:27], 0, v[204:205]
	s_addc_u32 s23, s27, 0
	s_add_i32 s56, s57, s41
	global_load_lds_dwordx4 v[220:221], off
	v_lshl_add_u64 v[222:223], s[22:23], 0, v[2:3]
	s_mov_b32 m0, s56
	v_lshl_add_u64 v[224:225], s[36:37], 0, v[206:207]
	global_load_lds_dwordx4 v[222:223], off
	v_lshl_add_u64 v[222:223], s[22:23], 0, v[204:205]
	s_add_i32 m0, s56, 0x2000
	s_nop 0
	global_load_lds_dwordx4 v[222:223], off
	v_lshl_add_u64 v[222:223], s[36:37], 0, v[208:209]
	s_mov_b32 m0, s42
	s_nop 0
	global_load_lds_dwordx4 v[222:223], off
	s_mov_b32 m0, s43
	s_nop 0
	global_load_lds_dwordx4 v[224:225], off
	s_waitcnt vmcnt(8)
	s_waitcnt lgkmcnt(0)
	s_barrier
	s_waitcnt lgkmcnt(0)
	v_mfma_f32_16x16x32_bf16 v[64:67], v[124:127], v[164:167], v[64:67]
	v_mfma_f32_16x16x32_bf16 v[64:67], v[128:131], v[168:171], v[64:67]
	v_mfma_f32_16x16x32_bf16 v[48:51], v[128:131], v[176:179], v[48:51]
	v_mfma_f32_16x16x32_bf16 v[48:51], v[124:127], v[172:175], v[48:51]
	v_mfma_f32_16x16x32_bf16 v[32:35], v[124:127], v[180:183], v[32:35]
	v_mfma_f32_16x16x32_bf16 v[32:35], v[128:131], v[184:187], v[32:35]
	v_mfma_f32_16x16x32_bf16 v[16:19], v[128:131], v[214:217], v[16:19]
	v_mfma_f32_16x16x32_bf16 v[16:19], v[124:127], v[188:191], v[16:19]
	v_mfma_f32_16x16x32_bf16 v[12:15], v[132:135], v[188:191], v[12:15]
	v_mfma_f32_16x16x32_bf16 v[12:15], v[144:147], v[214:217], v[12:15]
	v_mfma_f32_16x16x32_bf16 v[28:31], v[144:147], v[184:187], v[28:31]
	v_mfma_f32_16x16x32_bf16 v[28:31], v[132:135], v[180:183], v[28:31]
	v_mfma_f32_16x16x32_bf16 v[44:47], v[132:135], v[172:175], v[44:47]
	v_mfma_f32_16x16x32_bf16 v[44:47], v[144:147], v[176:179], v[44:47]
	v_mfma_f32_16x16x32_bf16 v[60:63], v[144:147], v[168:171], v[60:63]
	v_mfma_f32_16x16x32_bf16 v[60:63], v[132:135], v[164:167], v[60:63]
	v_mfma_f32_16x16x32_bf16 v[56:59], v[148:151], v[164:167], v[56:59]
	v_mfma_f32_16x16x32_bf16 v[56:59], v[152:155], v[168:171], v[56:59]
	v_mfma_f32_16x16x32_bf16 v[40:43], v[152:155], v[176:179], v[40:43]
	v_mfma_f32_16x16x32_bf16 v[40:43], v[148:151], v[172:175], v[40:43]
	v_mfma_f32_16x16x32_bf16 v[24:27], v[148:151], v[180:183], v[24:27]
	v_mfma_f32_16x16x32_bf16 v[24:27], v[152:155], v[184:187], v[24:27]
	v_mfma_f32_16x16x32_bf16 v[8:11], v[152:155], v[214:217], v[8:11]
	v_mfma_f32_16x16x32_bf16 v[8:11], v[148:151], v[188:191], v[8:11]
	v_mfma_f32_16x16x32_bf16 v[4:7], v[156:159], v[188:191], v[4:7]
	v_mfma_f32_16x16x32_bf16 v[4:7], v[160:163], v[214:217], v[4:7]
	v_mfma_f32_16x16x32_bf16 v[20:23], v[160:163], v[184:187], v[20:23]
	v_mfma_f32_16x16x32_bf16 v[20:23], v[156:159], v[180:183], v[20:23]
	v_mfma_f32_16x16x32_bf16 v[36:39], v[156:159], v[172:175], v[36:39]
	v_mfma_f32_16x16x32_bf16 v[36:39], v[160:163], v[176:179], v[36:39]
	v_mfma_f32_16x16x32_bf16 v[52:55], v[160:163], v[168:171], v[52:55]
	v_mfma_f32_16x16x32_bf16 v[52:55], v[156:159], v[164:167], v[52:55]
	s_barrier
; #define PG8_STAGE(bufoff, gbase, voff) do { _Pragma("unroll") for (int _i = 0; _i < 2; ++_i) \
;         __builtin_amdgcn_global_load_lds((const unsigned*)((const char*)(gbase) + (voff)[_i]), (PG8_LAS unsigned*)(lds + (bufoff) + ldsw + _i * 8192), 16, 0, 0); } while (0)
; #define PG8_LDA(dst, b, h) do { _Pragma("unroll") for (int m = 0; m < 4; ++m) _Pragma("unroll") for (int k = 0; k < 2; ++k) dst[m][k] = *(const PG8_LAS bf16x8*)(lds + PG8_SA(b, h) + aoff + m * 2048 + k * 1024); } while (0)
; #define PG8_LDB(dst, b, h) do { _Pragma("unroll") for (int n = 0; n < 2; ++n) _Pragma("unroll") for (int k = 0; k < 2; ++k) dst[n][k] = *(const PG8_LAS bf16x8*)(lds + PG8_SB(b, h) + boff + n * 2048 + k * 1024); } while (0)
; #define PG8_WAIT_V(n) asm volatile("s_waitcnt vmcnt(" #n ")" ::: "memory")
; #define PG8_WAIT_L(n) asm volatile("s_waitcnt lgkmcnt(" #n ")" ::: "memory")
; #define PG8_BAR __builtin_amdgcn_s_barrier()
; #define PG8_SCHED __builtin_amdgcn_sched_barrier(0)
; template <class Epi, class Sched, bool ALIGN_EPI = false, bool SP2 = false, bool I8 = false>
; __device__ __forceinline__ void gemm_phase(PG8_LAS unsigned char* lds, const Gemm g, const Sched& S, const Epi& E) {
;     ...
;             PG8_LDB(B0, 1, 0); PG8_LDB(B1, 1, 1); PG8_SCHED; PG8_LDA(At, 1, 0); PG8_STAGE(PG8_SA(0, 1), a2 + hstep, voffA);
;             PG8_WAIT_V(8); PG8_WAIT_L(0); PG8_BAR; PG8_MMA(0, 0, At, B0); PG8_MMA(0, 1, At, B1); PG8_BAR; PG8_SCHED;
;             PG8_LDA(At, 1, 1); PG8_STAGE(PG8_SB(1, 0), b3, voffB); PG8_STAGE(PG8_SB(1, 1), b3 + hstep, voffB); PG8_STAGE(PG8_SA(1, 0), a3, voffA);
;             PG8_WAIT_V(8); PG8_WAIT_L(0); PG8_BAR; PG8_MMA(1, 0, At, B0); PG8_MMA(1, 1, At, B1); PG8_BAR; PG8_SCHED;
	s_add_i32 s56, 0, 0x18000
	s_add_i32 s57, 0, 0x1c000
	v_add_u32_e32 v144, s56, v240
	v_add_u32_e32 v160, s57, v240
	ds_read_b128 v[124:127], v144
	ds_read_b128 v[128:131], v144 offset:1024
	ds_read_b128 v[132:135], v144 offset:2048
	ds_read_b128 v[144:147], v144 offset:3072
	ds_read_b128 v[148:151], v160
	ds_read_b128 v[152:155], v160 offset:1024
	ds_read_b128 v[156:159], v160 offset:2048
	ds_read_b128 v[160:163], v160 offset:3072
	s_add_u32 s22, s36, 0x2b0000
	s_addc_u32 s23, s37, 0
	s_mov_b32 m0, s44
	v_lshl_add_u64 v[226:227], s[22:23], 0, v[208:209]
	ds_read_b128 v[164:167], v242 offset:32768
	ds_read_b128 v[168:171], v242 offset:33792
	ds_read_b128 v[172:175], v242 offset:34816
	ds_read_b128 v[176:179], v242 offset:35840
	ds_read_b128 v[180:183], v242 offset:36864
	ds_read_b128 v[184:187], v242 offset:37888
	ds_read_b128 v[188:191], v242 offset:38912
	ds_read_b128 v[214:217], v242 offset:39936
	global_load_lds_dwordx4 v[226:227], off
	v_lshl_add_u64 v[226:227], s[22:23], 0, v[206:207]
	s_mov_b32 m0, s45
	s_nop 0
	global_load_lds_dwordx4 v[226:227], off
	s_waitcnt vmcnt(8)
	s_waitcnt lgkmcnt(0)
	s_barrier
	s_waitcnt lgkmcnt(0)
	v_mfma_f32_16x16x32_bf16 v[140:143], v[124:127], v[164:167], v[140:143]
	v_mfma_f32_16x16x32_bf16 v[140:143], v[128:131], v[168:171], v[140:143]
	v_mfma_f32_16x16x32_bf16 v[112:115], v[128:131], v[176:179], v[112:115]
	v_mfma_f32_16x16x32_bf16 v[112:115], v[124:127], v[172:175], v[112:115]
	v_mfma_f32_16x16x32_bf16 v[96:99], v[124:127], v[180:183], v[96:99]
	v_mfma_f32_16x16x32_bf16 v[96:99], v[128:131], v[184:187], v[96:99]
	v_mfma_f32_16x16x32_bf16 v[80:83], v[128:131], v[214:217], v[80:83]
	v_mfma_f32_16x16x32_bf16 v[80:83], v[124:127], v[188:191], v[80:83]
	v_mfma_f32_16x16x32_bf16 v[76:79], v[132:135], v[188:191], v[76:79]
	v_mfma_f32_16x16x32_bf16 v[76:79], v[144:147], v[214:217], v[76:79]
	v_mfma_f32_16x16x32_bf16 v[92:95], v[144:147], v[184:187], v[92:95]
	v_mfma_f32_16x16x32_bf16 v[92:95], v[132:135], v[180:183], v[92:95]
	v_mfma_f32_16x16x32_bf16 v[108:111], v[132:135], v[172:175], v[108:111]
	v_mfma_f32_16x16x32_bf16 v[108:111], v[144:147], v[176:179], v[108:111]
	v_mfma_f32_16x16x32_bf16 v[136:139], v[144:147], v[168:171], v[136:139]
	v_mfma_f32_16x16x32_bf16 v[136:139], v[132:135], v[164:167], v[136:139]
	v_mfma_f32_16x16x32_bf16 v[120:123], v[148:151], v[164:167], v[120:123]
	v_mfma_f32_16x16x32_bf16 v[120:123], v[152:155], v[168:171], v[120:123]
	v_mfma_f32_16x16x32_bf16 v[104:107], v[152:155], v[176:179], v[104:107]
	v_mfma_f32_16x16x32_bf16 v[104:107], v[148:151], v[172:175], v[104:107]
	v_mfma_f32_16x16x32_bf16 v[88:91], v[148:151], v[180:183], v[88:91]
	v_mfma_f32_16x16x32_bf16 v[88:91], v[152:155], v[184:187], v[88:91]
	v_mfma_f32_16x16x32_bf16 v[72:75], v[152:155], v[214:217], v[72:75]
	v_mfma_f32_16x16x32_bf16 v[72:75], v[148:151], v[188:191], v[72:75]
	v_mfma_f32_16x16x32_bf16 v[68:71], v[156:159], v[188:191], v[68:71]
	v_mfma_f32_16x16x32_bf16 v[68:71], v[160:163], v[214:217], v[68:71]
	v_mfma_f32_16x16x32_bf16 v[84:87], v[160:163], v[184:187], v[84:87]
	v_mfma_f32_16x16x32_bf16 v[84:87], v[156:159], v[180:183], v[84:87]
	v_mfma_f32_16x16x32_bf16 v[100:103], v[156:159], v[172:175], v[100:103]
	v_mfma_f32_16x16x32_bf16 v[100:103], v[160:163], v[176:179], v[100:103]
	v_mfma_f32_16x16x32_bf16 v[116:119], v[160:163], v[168:171], v[116:119]
	v_mfma_f32_16x16x32_bf16 v[116:119], v[156:159], v[164:167], v[116:119]
	s_barrier
	s_add_i32 s22, s56, s41
	v_lshl_add_u64 v[218:219], v[218:219], 0, s[84:85]
	s_mov_b32 m0, s22
	ds_read_b128 v[164:167], v242 offset:49152
	ds_read_b128 v[168:171], v242 offset:50176
	ds_read_b128 v[172:175], v242 offset:51200
	ds_read_b128 v[176:179], v242 offset:52224
	ds_read_b128 v[180:183], v242 offset:53248
	ds_read_b128 v[184:187], v242 offset:54272
	ds_read_b128 v[188:191], v242 offset:55296
	ds_read_b128 v[214:217], v242 offset:56320
	global_load_lds_dwordx4 v[218:219], off
	s_add_i32 m0, s22, 0x2000
	s_add_u32 s22, s26, 0x2b0080
	v_lshl_add_u64 v[218:219], v[220:221], 0, s[84:85]
	s_addc_u32 s23, s27, 0
	s_add_i32 s26, s57, s41
	global_load_lds_dwordx4 v[218:219], off
	v_lshl_add_u64 v[218:219], s[22:23], 0, v[2:3]
	s_mov_b32 m0, s26
	s_nop 0
	global_load_lds_dwordx4 v[218:219], off
	v_lshl_add_u64 v[218:219], s[22:23], 0, v[204:205]
	s_add_i32 m0, s26, 0x2000
	s_nop 0
	global_load_lds_dwordx4 v[218:219], off
	v_lshl_add_u64 v[218:219], v[222:223], 0, s[84:85]
	s_mov_b32 m0, s46
	s_nop 0
	global_load_lds_dwordx4 v[218:219], off
	v_lshl_add_u64 v[218:219], v[224:225], 0, s[84:85]
	s_mov_b32 m0, s47
	s_nop 0
	global_load_lds_dwordx4 v[218:219], off
	s_waitcnt vmcnt(8)
	s_waitcnt lgkmcnt(0)
	s_barrier
	s_waitcnt lgkmcnt(0)
	v_mfma_f32_16x16x32_bf16 v[64:67], v[124:127], v[164:167], v[64:67]
	v_mfma_f32_16x16x32_bf16 v[64:67], v[128:131], v[168:171], v[64:67]
	v_mfma_f32_16x16x32_bf16 v[48:51], v[128:131], v[176:179], v[48:51]
	v_mfma_f32_16x16x32_bf16 v[48:51], v[124:127], v[172:175], v[48:51]
	v_mfma_f32_16x16x32_bf16 v[32:35], v[124:127], v[180:183], v[32:35]
	v_mfma_f32_16x16x32_bf16 v[32:35], v[128:131], v[184:187], v[32:35]
	v_mfma_f32_16x16x32_bf16 v[16:19], v[128:131], v[214:217], v[16:19]
	v_mfma_f32_16x16x32_bf16 v[16:19], v[124:127], v[188:191], v[16:19]
	v_mfma_f32_16x16x32_bf16 v[12:15], v[132:135], v[188:191], v[12:15]
	v_mfma_f32_16x16x32_bf16 v[12:15], v[144:147], v[214:217], v[12:15]
	v_mfma_f32_16x16x32_bf16 v[28:31], v[144:147], v[184:187], v[28:31]
	v_mfma_f32_16x16x32_bf16 v[28:31], v[132:135], v[180:183], v[28:31]
	v_mfma_f32_16x16x32_bf16 v[44:47], v[132:135], v[172:175], v[44:47]
	v_mfma_f32_16x16x32_bf16 v[44:47], v[144:147], v[176:179], v[44:47]
	v_mfma_f32_16x16x32_bf16 v[60:63], v[144:147], v[168:171], v[60:63]
	v_mfma_f32_16x16x32_bf16 v[60:63], v[132:135], v[164:167], v[60:63]
	v_mfma_f32_16x16x32_bf16 v[56:59], v[148:151], v[164:167], v[56:59]
	v_mfma_f32_16x16x32_bf16 v[56:59], v[152:155], v[168:171], v[56:59]
	v_mfma_f32_16x16x32_bf16 v[40:43], v[152:155], v[176:179], v[40:43]
	v_mfma_f32_16x16x32_bf16 v[40:43], v[148:151], v[172:175], v[40:43]
	v_mfma_f32_16x16x32_bf16 v[24:27], v[148:151], v[180:183], v[24:27]
	v_mfma_f32_16x16x32_bf16 v[24:27], v[152:155], v[184:187], v[24:27]
	v_mfma_f32_16x16x32_bf16 v[8:11], v[152:155], v[214:217], v[8:11]
	v_mfma_f32_16x16x32_bf16 v[8:11], v[148:151], v[188:191], v[8:11]
	v_mfma_f32_16x16x32_bf16 v[4:7], v[156:159], v[188:191], v[4:7]
	v_mfma_f32_16x16x32_bf16 v[4:7], v[160:163], v[214:217], v[4:7]
	v_mfma_f32_16x16x32_bf16 v[20:23], v[160:163], v[184:187], v[20:23]
	v_mfma_f32_16x16x32_bf16 v[20:23], v[156:159], v[180:183], v[20:23]
	v_mfma_f32_16x16x32_bf16 v[36:39], v[156:159], v[172:175], v[36:39]
	v_mfma_f32_16x16x32_bf16 v[36:39], v[160:163], v[176:179], v[36:39]
	v_mfma_f32_16x16x32_bf16 v[52:55], v[160:163], v[168:171], v[52:55]
	v_mfma_f32_16x16x32_bf16 v[52:55], v[156:159], v[164:167], v[52:55]
	s_barrier
	s_add_i32 s55, s55, 2
	s_add_u32 s53, s53, 0x100
	s_addc_u32 s54, s54, 0
	s_cmpk_gt_u32 s55, 0xa9
	s_mov_b64 s[22:23], s[24:25]
	s_cbranch_scc0 .LBB0_1700

; #define PG8_STAGE(bufoff, gbase, voff) do { _Pragma("unroll") for (int _i = 0; _i < 2; ++_i) \
;         __builtin_amdgcn_global_load_lds((const unsigned*)((const char*)(gbase) + (voff)[_i]), (PG8_LAS unsigned*)(lds + (bufoff) + ldsw + _i * 8192), 16, 0, 0); } while (0)
; #define PG8_LDA(dst, b, h) do { _Pragma("unroll") for (int m = 0; m < 4; ++m) _Pragma("unroll") for (int k = 0; k < 2; ++k) dst[m][k] = *(const PG8_LAS bf16x8*)(lds + PG8_SA(b, h) + aoff + m * 2048 + k * 1024); } while (0)
; #define PG8_LDB(dst, b, h) do { _Pragma("unroll") for (int n = 0; n < 2; ++n) _Pragma("unroll") for (int k = 0; k < 2; ++k) dst[n][k] = *(const PG8_LAS bf16x8*)(lds + PG8_SB(b, h) + boff + n * 2048 + k * 1024); } while (0)
; #define PG8_WAIT_V(n) asm volatile("s_waitcnt vmcnt(" #n ")" ::: "memory")
; #define PG8_WAIT_L(n) asm volatile("s_waitcnt lgkmcnt(" #n ")" ::: "memory")
; #define PG8_BAR __builtin_amdgcn_s_barrier()
; #define PG8_SCHED __builtin_amdgcn_sched_barrier(0)
; template <class Epi, class Sched, bool ALIGN_EPI = false, bool SP2 = false, bool I8 = false>
; __device__ __forceinline__ void gemm_phase(PG8_LAS unsigned char* lds, const Gemm g, const Sched& S, const Epi& E) {
;     ...
;         const char* nA = has_next ? (const char*)g.A + (size_t)nxt.pm * tstep : cA; const char* nB = has_next ? (const char*)g.Bt + (size_t)nxt.pn * tstep : cB;
;         for (int t = 0; t < nt; t += 2) {
;             const bool last = (t == nt - 2);
;             const char* a1 = cA + (size_t)(t + 1) * kstep;
;             const char* a2 = last ? nA : cA + (size_t)(t + 2) * kstep; const char* b2 = last ? nB : cB + (size_t)(t + 2) * kstep;
;             const char* a3 = a2 + kstep; const char* b3 = b2 + kstep;
;             if (last && has_next) S.a_ready(nxt);
;             if constexpr (SP2) {
;             PG8_LDB(B0, 0, 0); PG8_LDB(B1, 0, 1); PG8_SCHED; PG8_LDA(At, 0, 0); PG8_STAGE(PG8_SA(1, 1), a1 + hstep, voffA);
;             PG8_WAIT_V(8); PG8_WAIT_L(0); PG8_BAR; PG8_MMA(0, 0, At, B0); PG8_MMA(0, 1, At, B1); PG8_BAR; PG8_SCHED;
;             PG8_LDA(At, 0, 1); PG8_STAGE(PG8_SB(0, 0), b2, voffB); PG8_STAGE(PG8_SB(0, 1), b2 + hstep, voffB); PG8_STAGE(PG8_SA(0, 0), a2, voffA);
;             PG8_WAIT_V(8); PG8_WAIT_L(0); PG8_BAR; PG8_MMA(1, 0, At, B0); PG8_MMA(1, 1, At, B1); PG8_BAR; PG8_SCHED;
.LBB0_1842:
	s_ashr_i32 s45, s44, 31
	s_lshl_b64 s[34:35], s[44:45], 20
	s_add_u32 s50, s47, s34
	s_addc_u32 s51, s52, s35
	s_and_b64 s[34:35], s[8:9], exec
	s_cselect_b32 s11, s51, s55
	s_cselect_b32 s13, s50, s54
	s_ashr_i32 s49, s48, 31
	s_lshl_b64 s[34:35], s[48:49], 20
	s_add_u32 s56, s53, s34
	s_addc_u32 s57, s64, s35
	s_and_b64 s[34:35], s[8:9], exec
	s_cselect_b32 s34, s57, s59
	s_cselect_b32 s35, s56, s58
	s_add_u32 s54, s54, 0x80080
	s_addc_u32 s55, s55, 0
	s_add_u32 s45, s58, 0x100
	s_addc_u32 s49, s59, 0
	s_mov_b32 s86, -2
	s_waitcnt lgkmcnt(0)
	s_add_u32 s58, s54, 0xfff80080
	s_addc_u32 s59, s55, -1
	s_add_i32 s87, 0, 0x10000
	s_cmp_eq_u32 s86, 28
	s_cselect_b32 s61, s11, s59
	s_cselect_b32 s60, s13, s58
	s_cselect_b32 s59, s34, s49
	s_cselect_b32 s58, s35, s45
	s_add_i32 vcc_lo, 0, 0x14000
	v_add_u32_e32 v40, s87, v217
	v_add_u32_e32 v160, vcc_lo, v217
	ds_read_b128 v[28:31], v40
	ds_read_b128 v[32:35], v40 offset:1024
	ds_read_b128 v[36:39], v40 offset:2048
	ds_read_b128 v[40:43], v40 offset:3072
	ds_read_b128 v[140:143], v160
	ds_read_b128 v[144:147], v160 offset:1024
	ds_read_b128 v[156:159], v160 offset:2048
	ds_read_b128 v[160:163], v160 offset:3072
	v_lshl_add_u64 v[190:191], s[54:55], 0, v[186:187]
	s_add_i32 m0, s65, 0xc000
	ds_read_b128 v[164:167], v219
	ds_read_b128 v[168:171], v219 offset:1024
	ds_read_b128 v[172:175], v219 offset:2048
	ds_read_b128 v[176:179], v219 offset:3072
	ds_read_b128 v[204:207], v219 offset:4096
	ds_read_b128 v[208:211], v219 offset:5120
	ds_read_b128 v[212:215], v219 offset:6144
	ds_read_b128 v[220:223], v219 offset:7168
	global_load_lds_dwordx4 v[190:191], off
	v_lshl_add_u64 v[190:191], s[54:55], 0, v[188:189]
	s_add_i32 m0, s65, 0xe000
	s_nop 0
	global_load_lds_dwordx4 v[190:191], off
	s_waitcnt vmcnt(8)
	s_waitcnt lgkmcnt(0)
	s_barrier
	s_waitcnt lgkmcnt(0)
	v_mfma_i32_16x16x64_i8 v[152:155], v[28:31], v[164:167], 0
	v_mfma_i32_16x16x64_i8 v[152:155], v[32:35], v[168:171], v[152:155]
	v_mfma_i32_16x16x64_i8 v[128:131], v[32:35], v[176:179], 0
	v_mfma_i32_16x16x64_i8 v[128:131], v[28:31], v[172:175], v[128:131]
	v_mfma_i32_16x16x64_i8 v[112:115], v[28:31], v[204:207], 0
	v_mfma_i32_16x16x64_i8 v[112:115], v[32:35], v[208:211], v[112:115]
	v_mfma_i32_16x16x64_i8 v[96:99], v[32:35], v[220:223], 0
	v_mfma_i32_16x16x64_i8 v[96:99], v[28:31], v[212:215], v[96:99]
	v_mfma_i32_16x16x64_i8 v[92:95], v[36:39], v[212:215], 0
	v_mfma_i32_16x16x64_i8 v[92:95], v[40:43], v[220:223], v[92:95]
	v_mfma_i32_16x16x64_i8 v[108:111], v[40:43], v[208:211], 0
	v_mfma_i32_16x16x64_i8 v[108:111], v[36:39], v[204:207], v[108:111]
	v_mfma_i32_16x16x64_i8 v[124:127], v[36:39], v[172:175], 0
	v_mfma_i32_16x16x64_i8 v[124:127], v[40:43], v[176:179], v[124:127]
	v_mfma_i32_16x16x64_i8 v[148:151], v[40:43], v[168:171], 0
	v_mfma_i32_16x16x64_i8 v[148:151], v[36:39], v[164:167], v[148:151]
	v_mfma_i32_16x16x64_i8 v[136:139], v[140:143], v[164:167], 0
	v_mfma_i32_16x16x64_i8 v[136:139], v[144:147], v[168:171], v[136:139]
	v_mfma_i32_16x16x64_i8 v[120:123], v[144:147], v[176:179], 0
	v_mfma_i32_16x16x64_i8 v[120:123], v[140:143], v[172:175], v[120:123]
	v_mfma_i32_16x16x64_i8 v[104:107], v[140:143], v[204:207], 0
	v_mfma_i32_16x16x64_i8 v[104:107], v[144:147], v[208:211], v[104:107]
	v_mfma_i32_16x16x64_i8 v[88:91], v[144:147], v[220:223], 0
	v_mfma_i32_16x16x64_i8 v[88:91], v[140:143], v[212:215], v[88:91]
	v_mfma_i32_16x16x64_i8 v[84:87], v[156:159], v[212:215], 0
	v_mfma_i32_16x16x64_i8 v[84:87], v[160:163], v[220:223], v[84:87]
	v_mfma_i32_16x16x64_i8 v[100:103], v[160:163], v[208:211], 0
	v_mfma_i32_16x16x64_i8 v[100:103], v[156:159], v[204:207], v[100:103]
	v_mfma_i32_16x16x64_i8 v[116:119], v[156:159], v[172:175], 0
	v_mfma_i32_16x16x64_i8 v[116:119], v[160:163], v[176:179], v[116:119]
	v_mfma_i32_16x16x64_i8 v[132:135], v[160:163], v[168:171], 0
	v_mfma_i32_16x16x64_i8 v[132:135], v[156:159], v[164:167], v[132:135]
	s_barrier
	s_add_i32 s87, s87, s46
	v_lshl_add_u64 v[190:191], s[58:59], 0, v[2:3]
	s_mov_b32 m0, s87
	ds_read_b128 v[164:167], v219 offset:16384
	ds_read_b128 v[168:171], v219 offset:17408
	ds_read_b128 v[172:175], v219 offset:18432
	ds_read_b128 v[176:179], v219 offset:19456
	ds_read_b128 v[204:207], v219 offset:20480
	ds_read_b128 v[208:211], v219 offset:21504
	ds_read_b128 v[212:215], v219 offset:22528
	ds_read_b128 v[220:223], v219 offset:23552
	global_load_lds_dwordx4 v[190:191], off
	s_add_i32 m0, s87, 0x2000
	s_add_u32 s96, s58, 0x80000
	v_lshl_add_u64 v[224:225], s[58:59], 0, v[184:185]
	s_addc_u32 s97, s59, 0
	s_add_i32 s87, vcc_lo, s46
	global_load_lds_dwordx4 v[224:225], off
	v_lshl_add_u64 v[226:227], s[96:97], 0, v[2:3]
	s_mov_b32 m0, s87
	v_lshl_add_u64 v[228:229], s[60:61], 0, v[182:183]
	global_load_lds_dwordx4 v[226:227], off
	v_lshl_add_u64 v[226:227], s[96:97], 0, v[184:185]
	s_add_i32 m0, s87, 0x2000
	s_nop 0
	global_load_lds_dwordx4 v[226:227], off
	v_lshl_add_u64 v[226:227], s[60:61], 0, v[180:181]
	s_mov_b32 m0, s65
	s_nop 0
	global_load_lds_dwordx4 v[226:227], off
	s_mov_b32 m0, s67
	s_nop 0
	global_load_lds_dwordx4 v[228:229], off
	s_waitcnt vmcnt(8)
	s_waitcnt lgkmcnt(0)
	s_barrier
; #define PG8_STAGE(bufoff, gbase, voff) do { _Pragma("unroll") for (int _i = 0; _i < 2; ++_i) \
;         __builtin_amdgcn_global_load_lds((const unsigned*)((const char*)(gbase) + (voff)[_i]), (PG8_LAS unsigned*)(lds + (bufoff) + ldsw + _i * 8192), 16, 0, 0); } while (0)
; #define PG8_LDA(dst, b, h) do { _Pragma("unroll") for (int m = 0; m < 4; ++m) _Pragma("unroll") for (int k = 0; k < 2; ++k) dst[m][k] = *(const PG8_LAS bf16x8*)(lds + PG8_SA(b, h) + aoff + m * 2048 + k * 1024); } while (0)
; #define PG8_LDB(dst, b, h) do { _Pragma("unroll") for (int n = 0; n < 2; ++n) _Pragma("unroll") for (int k = 0; k < 2; ++k) dst[n][k] = *(const PG8_LAS bf16x8*)(lds + PG8_SB(b, h) + boff + n * 2048 + k * 1024); } while (0)
; #define PG8_WAIT_V(n) asm volatile("s_waitcnt vmcnt(" #n ")" ::: "memory")
; #define PG8_WAIT_L(n) asm volatile("s_waitcnt lgkmcnt(" #n ")" ::: "memory")
; #define PG8_BAR __builtin_amdgcn_s_barrier()
; #define PG8_SCHED __builtin_amdgcn_sched_barrier(0)
; template <class Epi, class Sched, bool ALIGN_EPI = false, bool SP2 = false, bool I8 = false>
; __device__ __forceinline__ void gemm_phase(PG8_LAS unsigned char* lds, const Gemm g, const Sched& S, const Epi& E) {
;     ...
;             PG8_WAIT_V(8); PG8_WAIT_L(0); PG8_BAR; PG8_MMA(1, 0, At, B0); PG8_MMA(1, 1, At, B1); PG8_BAR; PG8_SCHED;
;             PG8_LDB(B0, 1, 0); PG8_LDB(B1, 1, 1); PG8_SCHED; PG8_LDA(At, 1, 0); PG8_STAGE(PG8_SA(0, 1), a2 + hstep, voffA);
;             PG8_WAIT_V(8); PG8_WAIT_L(0); PG8_BAR; PG8_MMA(0, 0, At, B0); PG8_MMA(0, 1, At, B1); PG8_BAR; PG8_SCHED;
	s_waitcnt lgkmcnt(0)
	v_mfma_i32_16x16x64_i8 v[80:83], v[28:31], v[164:167], 0
	v_mfma_i32_16x16x64_i8 v[80:83], v[32:35], v[168:171], v[80:83]
	v_mfma_i32_16x16x64_i8 v[64:67], v[32:35], v[176:179], 0
	v_mfma_i32_16x16x64_i8 v[64:67], v[28:31], v[172:175], v[64:67]
	v_mfma_i32_16x16x64_i8 v[48:51], v[28:31], v[204:207], 0
	v_mfma_i32_16x16x64_i8 v[48:51], v[32:35], v[208:211], v[48:51]
	v_mfma_i32_16x16x64_i8 v[16:19], v[32:35], v[220:223], 0
	v_mfma_i32_16x16x64_i8 v[16:19], v[28:31], v[212:215], v[16:19]
	v_mfma_i32_16x16x64_i8 v[12:15], v[36:39], v[212:215], 0
	v_mfma_i32_16x16x64_i8 v[12:15], v[40:43], v[220:223], v[12:15]
	v_mfma_i32_16x16x64_i8 v[44:47], v[40:43], v[208:211], 0
	v_mfma_i32_16x16x64_i8 v[44:47], v[36:39], v[204:207], v[44:47]
	v_mfma_i32_16x16x64_i8 v[60:63], v[36:39], v[172:175], 0
	v_mfma_i32_16x16x64_i8 v[60:63], v[40:43], v[176:179], v[60:63]
	v_mfma_i32_16x16x64_i8 v[76:79], v[40:43], v[168:171], 0
	v_mfma_i32_16x16x64_i8 v[76:79], v[36:39], v[164:167], v[76:79]
	v_mfma_i32_16x16x64_i8 v[28:31], v[140:143], v[164:167], 0
	v_mfma_i32_16x16x64_i8 v[28:31], v[144:147], v[168:171], v[28:31]
	v_mfma_i32_16x16x64_i8 v[36:39], v[144:147], v[176:179], 0
	v_mfma_i32_16x16x64_i8 v[36:39], v[140:143], v[172:175], v[36:39]
	v_mfma_i32_16x16x64_i8 v[24:27], v[140:143], v[204:207], 0
	v_mfma_i32_16x16x64_i8 v[24:27], v[144:147], v[208:211], v[24:27]
	v_mfma_i32_16x16x64_i8 v[8:11], v[144:147], v[220:223], 0
	v_mfma_i32_16x16x64_i8 v[8:11], v[140:143], v[212:215], v[8:11]
	v_mfma_i32_16x16x64_i8 v[4:7], v[156:159], v[212:215], 0
	v_mfma_i32_16x16x64_i8 v[4:7], v[160:163], v[220:223], v[4:7]
	v_mfma_i32_16x16x64_i8 v[20:23], v[160:163], v[208:211], 0
	v_mfma_i32_16x16x64_i8 v[20:23], v[156:159], v[204:207], v[20:23]
	v_mfma_i32_16x16x64_i8 v[40:43], v[156:159], v[172:175], 0
	v_mfma_i32_16x16x64_i8 v[40:43], v[160:163], v[176:179], v[40:43]
	v_mfma_i32_16x16x64_i8 v[32:35], v[160:163], v[168:171], 0
	v_mfma_i32_16x16x64_i8 v[32:35], v[156:159], v[164:167], v[32:35]
	s_barrier
	s_add_i32 s87, 0, 0x18000
	s_add_i32 s96, 0, 0x1c000
	v_add_u32_e32 v72, s87, v217
	v_add_u32_e32 v160, s96, v217
	ds_read_b128 v[52:55], v72
	ds_read_b128 v[56:59], v72 offset:1024
	ds_read_b128 v[68:71], v72 offset:2048
	ds_read_b128 v[72:75], v72 offset:3072
	ds_read_b128 v[140:143], v160
	ds_read_b128 v[144:147], v160 offset:1024
	ds_read_b128 v[156:159], v160 offset:2048
	ds_read_b128 v[160:163], v160 offset:3072
	s_add_u32 s60, s60, 0x80000
	s_addc_u32 s61, s61, 0
	s_mov_b32 m0, s72
	v_lshl_add_u64 v[240:241], s[60:61], 0, v[180:181]
	ds_read_b128 v[164:167], v219 offset:32768
	ds_read_b128 v[168:171], v219 offset:33792
	ds_read_b128 v[172:175], v219 offset:34816
	ds_read_b128 v[176:179], v219 offset:35840
	ds_read_b128 v[204:207], v219 offset:36864
	ds_read_b128 v[208:211], v219 offset:37888
	ds_read_b128 v[212:215], v219 offset:38912
	ds_read_b128 v[220:223], v219 offset:39936
	global_load_lds_dwordx4 v[240:241], off
	v_lshl_add_u64 v[240:241], s[60:61], 0, v[182:183]
	s_mov_b32 m0, s73
	s_nop 0
	global_load_lds_dwordx4 v[240:241], off
	s_waitcnt vmcnt(8)
	s_waitcnt lgkmcnt(0)
	s_barrier
	s_waitcnt lgkmcnt(0)
	v_mfma_i32_16x16x64_i8 v[152:155], v[52:55], v[164:167], v[152:155]
	v_mfma_i32_16x16x64_i8 v[152:155], v[56:59], v[168:171], v[152:155]
	v_mfma_i32_16x16x64_i8 v[128:131], v[56:59], v[176:179], v[128:131]
	v_mfma_i32_16x16x64_i8 v[128:131], v[52:55], v[172:175], v[128:131]
	v_mfma_i32_16x16x64_i8 v[112:115], v[52:55], v[204:207], v[112:115]
	v_mfma_i32_16x16x64_i8 v[112:115], v[56:59], v[208:211], v[112:115]
	v_mfma_i32_16x16x64_i8 v[96:99], v[56:59], v[220:223], v[96:99]
	v_mfma_i32_16x16x64_i8 v[96:99], v[52:55], v[212:215], v[96:99]
	v_mfma_i32_16x16x64_i8 v[92:95], v[68:71], v[212:215], v[92:95]
	v_mfma_i32_16x16x64_i8 v[92:95], v[72:75], v[220:223], v[92:95]
	v_mfma_i32_16x16x64_i8 v[108:111], v[72:75], v[208:211], v[108:111]
	v_mfma_i32_16x16x64_i8 v[108:111], v[68:71], v[204:207], v[108:111]
	v_mfma_i32_16x16x64_i8 v[124:127], v[68:71], v[172:175], v[124:127]
	v_mfma_i32_16x16x64_i8 v[124:127], v[72:75], v[176:179], v[124:127]
	v_mfma_i32_16x16x64_i8 v[148:151], v[72:75], v[168:171], v[148:151]
	v_mfma_i32_16x16x64_i8 v[148:151], v[68:71], v[164:167], v[148:151]
	v_mfma_i32_16x16x64_i8 v[136:139], v[140:143], v[164:167], v[136:139]
	v_mfma_i32_16x16x64_i8 v[136:139], v[144:147], v[168:171], v[136:139]
	v_mfma_i32_16x16x64_i8 v[120:123], v[144:147], v[176:179], v[120:123]
	v_mfma_i32_16x16x64_i8 v[120:123], v[140:143], v[172:175], v[120:123]
	v_mfma_i32_16x16x64_i8 v[104:107], v[140:143], v[204:207], v[104:107]
	v_mfma_i32_16x16x64_i8 v[104:107], v[144:147], v[208:211], v[104:107]
	v_mfma_i32_16x16x64_i8 v[88:91], v[144:147], v[220:223], v[88:91]
	v_mfma_i32_16x16x64_i8 v[88:91], v[140:143], v[212:215], v[88:91]
	v_mfma_i32_16x16x64_i8 v[84:87], v[156:159], v[212:215], v[84:87]
	v_mfma_i32_16x16x64_i8 v[84:87], v[160:163], v[220:223], v[84:87]
	v_mfma_i32_16x16x64_i8 v[100:103], v[160:163], v[208:211], v[100:103]
	v_mfma_i32_16x16x64_i8 v[100:103], v[156:159], v[204:207], v[100:103]
	v_mfma_i32_16x16x64_i8 v[116:119], v[156:159], v[172:175], v[116:119]
	v_mfma_i32_16x16x64_i8 v[116:119], v[160:163], v[176:179], v[116:119]
	v_mfma_i32_16x16x64_i8 v[132:135], v[160:163], v[168:171], v[132:135]
	v_mfma_i32_16x16x64_i8 v[132:135], v[156:159], v[164:167], v[132:135]
	s_barrier
; #define PG8_STAGE(bufoff, gbase, voff) do { _Pragma("unroll") for (int _i = 0; _i < 2; ++_i) \
;         __builtin_amdgcn_global_load_lds((const unsigned*)((const char*)(gbase) + (voff)[_i]), (PG8_LAS unsigned*)(lds + (bufoff) + ldsw + _i * 8192), 16, 0, 0); } while (0)
; #define PG8_LDA(dst, b, h) do { _Pragma("unroll") for (int m = 0; m < 4; ++m) _Pragma("unroll") for (int k = 0; k < 2; ++k) dst[m][k] = *(const PG8_LAS bf16x8*)(lds + PG8_SA(b, h) + aoff + m * 2048 + k * 1024); } while (0)
; #define PG8_LDB(dst, b, h) do { _Pragma("unroll") for (int n = 0; n < 2; ++n) _Pragma("unroll") for (int k = 0; k < 2; ++k) dst[n][k] = *(const PG8_LAS bf16x8*)(lds + PG8_SB(b, h) + boff + n * 2048 + k * 1024); } while (0)
; #define PG8_WAIT_V(n) asm volatile("s_waitcnt vmcnt(" #n ")" ::: "memory")
; template <class Epi, class Sched, bool ALIGN_EPI = false, bool SP2 = false, bool I8 = false>
; __device__ __forceinline__ void gemm_phase(PG8_LAS unsigned char* lds, const Gemm g, const Sched& S, const Epi& E) {
;     ...
;             const char* a1 = cA + (size_t)(t + 1) * kstep;
;             const char* a2 = last ? nA : cA + (size_t)(t + 2) * kstep; const char* b2 = last ? nB : cB + (size_t)(t + 2) * kstep;
;             const char* a3 = a2 + kstep; const char* b3 = b2 + kstep;
;             if (last && has_next) S.a_ready(nxt);
;             if constexpr (SP2) {
;             PG8_LDB(B0, 0, 0); PG8_LDB(B1, 0, 1); PG8_SCHED; PG8_LDA(At, 0, 0); PG8_STAGE(PG8_SA(1, 1), a1 + hstep, voffA);
;             PG8_WAIT_V(8); PG8_WAIT_L(0); PG8_BAR; PG8_MMA(0, 0, At, B0); PG8_MMA(0, 1, At, B1); PG8_BAR; PG8_SCHED;
;             PG8_LDA(At, 0, 1); PG8_STAGE(PG8_SB(0, 0), b2, voffB); PG8_STAGE(PG8_SB(0, 1), b2 + hstep, voffB); PG8_STAGE(PG8_SA(0, 0), a2, voffA);
;             PG8_WAIT_V(8); PG8_WAIT_L(0); PG8_BAR; PG8_MMA(1, 0, At, B0); PG8_MMA(1, 1, At, B1); PG8_BAR; PG8_SCHED;
;             PG8_LDB(B0, 1, 0); PG8_LDB(B1, 1, 1); PG8_SCHED; PG8_LDA(At, 1, 0); PG8_STAGE(PG8_SA(0, 1), a2 + hstep, voffA);
;             PG8_WAIT_V(8); PG8_WAIT_L(0); PG8_BAR; PG8_MMA(0, 0, At, B0); PG8_MMA(0, 1, At, B1); PG8_BAR; PG8_SCHED;
;             PG8_LDA(At, 1, 1); PG8_STAGE(PG8_SB(1, 0), b3, voffB); PG8_STAGE(PG8_SB(1, 1), b3 + hstep, voffB); PG8_STAGE(PG8_SA(1, 0), a3, voffA);
;             PG8_WAIT_V(8); PG8_WAIT_L(0); PG8_BAR; PG8_MMA(1, 0, At, B0); PG8_MMA(1, 1, At, B1); PG8_BAR; PG8_SCHED;
	s_add_i32 s60, s87, s46
	v_lshl_add_u64 v[190:191], v[190:191], 0, s[84:85]
	s_mov_b32 m0, s60
	ds_read_b128 v[164:167], v219 offset:49152
	ds_read_b128 v[168:171], v219 offset:50176
	ds_read_b128 v[172:175], v219 offset:51200
	ds_read_b128 v[176:179], v219 offset:52224
	ds_read_b128 v[204:207], v219 offset:53248
	ds_read_b128 v[208:211], v219 offset:54272
	ds_read_b128 v[212:215], v219 offset:55296
	ds_read_b128 v[220:223], v219 offset:56320
	global_load_lds_dwordx4 v[190:191], off
	s_add_i32 m0, s60, 0x2000
	s_add_u32 s58, s58, 0x80080
	v_lshl_add_u64 v[190:191], v[224:225], 0, s[84:85]
	s_addc_u32 s59, s59, 0
	s_add_i32 s60, s96, s46
	global_load_lds_dwordx4 v[190:191], off
	v_lshl_add_u64 v[190:191], s[58:59], 0, v[2:3]
	s_mov_b32 m0, s60
	s_nop 0
	global_load_lds_dwordx4 v[190:191], off
	v_lshl_add_u64 v[190:191], s[58:59], 0, v[184:185]
	s_add_i32 m0, s60, 0x2000
	s_nop 0
	global_load_lds_dwordx4 v[190:191], off
	v_lshl_add_u64 v[190:191], v[226:227], 0, s[84:85]
	s_mov_b32 m0, s28
	s_nop 0
	global_load_lds_dwordx4 v[190:191], off
	v_lshl_add_u64 v[190:191], v[228:229], 0, s[84:85]
	s_mov_b32 m0, s77
	s_nop 0
	global_load_lds_dwordx4 v[190:191], off
	s_waitcnt vmcnt(8)
	s_waitcnt lgkmcnt(0)
	s_barrier
	s_waitcnt lgkmcnt(0)
	v_mfma_i32_16x16x64_i8 v[80:83], v[52:55], v[164:167], v[80:83]
	v_mfma_i32_16x16x64_i8 v[80:83], v[56:59], v[168:171], v[80:83]
	v_mfma_i32_16x16x64_i8 v[64:67], v[56:59], v[176:179], v[64:67]
	v_mfma_i32_16x16x64_i8 v[64:67], v[52:55], v[172:175], v[64:67]
	v_mfma_i32_16x16x64_i8 v[48:51], v[52:55], v[204:207], v[48:51]
	v_mfma_i32_16x16x64_i8 v[48:51], v[56:59], v[208:211], v[48:51]
	v_mfma_i32_16x16x64_i8 v[16:19], v[56:59], v[220:223], v[16:19]
	v_mfma_i32_16x16x64_i8 v[16:19], v[52:55], v[212:215], v[16:19]
	v_mfma_i32_16x16x64_i8 v[12:15], v[68:71], v[212:215], v[12:15]
	v_mfma_i32_16x16x64_i8 v[12:15], v[72:75], v[220:223], v[12:15]
	v_mfma_i32_16x16x64_i8 v[44:47], v[72:75], v[208:211], v[44:47]
	v_mfma_i32_16x16x64_i8 v[44:47], v[68:71], v[204:207], v[44:47]
	v_mfma_i32_16x16x64_i8 v[60:63], v[68:71], v[172:175], v[60:63]
	v_mfma_i32_16x16x64_i8 v[60:63], v[72:75], v[176:179], v[60:63]
	v_mfma_i32_16x16x64_i8 v[76:79], v[72:75], v[168:171], v[76:79]
	v_mfma_i32_16x16x64_i8 v[76:79], v[68:71], v[164:167], v[76:79]
	v_mfma_i32_16x16x64_i8 v[28:31], v[140:143], v[164:167], v[28:31]
	v_mfma_i32_16x16x64_i8 v[72:75], v[144:147], v[168:171], v[28:31]
	v_mfma_i32_16x16x64_i8 v[28:31], v[144:147], v[176:179], v[36:39]
	v_mfma_i32_16x16x64_i8 v[56:59], v[140:143], v[172:175], v[28:31]
	v_mfma_i32_16x16x64_i8 v[24:27], v[140:143], v[204:207], v[24:27]
	v_mfma_i32_16x16x64_i8 v[24:27], v[144:147], v[208:211], v[24:27]
	v_mfma_i32_16x16x64_i8 v[8:11], v[144:147], v[220:223], v[8:11]
	v_mfma_i32_16x16x64_i8 v[8:11], v[140:143], v[212:215], v[8:11]
	v_mfma_i32_16x16x64_i8 v[4:7], v[156:159], v[212:215], v[4:7]
	v_mfma_i32_16x16x64_i8 v[4:7], v[160:163], v[220:223], v[4:7]
	v_mfma_i32_16x16x64_i8 v[20:23], v[160:163], v[208:211], v[20:23]
	v_mfma_i32_16x16x64_i8 v[20:23], v[156:159], v[204:207], v[20:23]
	v_mfma_i32_16x16x64_i8 v[28:31], v[156:159], v[172:175], v[40:43]
	v_mfma_i32_16x16x64_i8 v[52:55], v[160:163], v[176:179], v[28:31]
	v_mfma_i32_16x16x64_i8 v[28:31], v[160:163], v[168:171], v[32:35]
	v_mfma_i32_16x16x64_i8 v[68:71], v[156:159], v[164:167], v[28:31]
	s_barrier
	s_add_i32 s86, s86, 2
	s_add_u32 s54, s54, 0x100
	s_addc_u32 s55, s55, 0
	s_add_u32 s45, s45, 0x100
	s_addc_u32 s49, s49, 0
	s_cmp_gt_u32 s86, 29
	s_cbranch_scc1 .Lkloop_exit_6
.LBB0_1843:
	s_add_u32 s58, s54, 0xfff80080
	s_addc_u32 s59, s55, -1
	s_add_i32 s87, 0, 0x10000
	s_cmp_eq_u32 s86, 28
	s_cselect_b32 s61, s11, s59
	s_cselect_b32 s60, s13, s58
	s_cselect_b32 s59, s34, s49
	s_cselect_b32 s58, s35, s45
	s_add_i32 vcc_lo, 0, 0x14000
	v_add_u32_e32 v40, s87, v217
	v_add_u32_e32 v160, vcc_lo, v217
	ds_read_b128 v[28:31], v40
	ds_read_b128 v[32:35], v40 offset:1024
	ds_read_b128 v[36:39], v40 offset:2048
	ds_read_b128 v[40:43], v40 offset:3072
	ds_read_b128 v[140:143], v160
	ds_read_b128 v[144:147], v160 offset:1024
	ds_read_b128 v[156:159], v160 offset:2048
	ds_read_b128 v[160:163], v160 offset:3072
	v_lshl_add_u64 v[190:191], s[54:55], 0, v[186:187]
	s_add_i32 m0, s65, 0xc000
	ds_read_b128 v[164:167], v219
	ds_read_b128 v[168:171], v219 offset:1024
	ds_read_b128 v[172:175], v219 offset:2048
	ds_read_b128 v[176:179], v219 offset:3072
	ds_read_b128 v[204:207], v219 offset:4096
	ds_read_b128 v[208:211], v219 offset:5120
	ds_read_b128 v[212:215], v219 offset:6144
	ds_read_b128 v[220:223], v219 offset:7168
	global_load_lds_dwordx4 v[190:191], off
	v_lshl_add_u64 v[190:191], s[54:55], 0, v[188:189]
	s_add_i32 m0, s65, 0xe000
	s_nop 0
	global_load_lds_dwordx4 v[190:191], off
	s_waitcnt vmcnt(8)
	s_waitcnt lgkmcnt(0)
	s_barrier
; #define PG8_STAGE(bufoff, gbase, voff) do { _Pragma("unroll") for (int _i = 0; _i < 2; ++_i) \
;         __builtin_amdgcn_global_load_lds((const unsigned*)((const char*)(gbase) + (voff)[_i]), (PG8_LAS unsigned*)(lds + (bufoff) + ldsw + _i * 8192), 16, 0, 0); } while (0)
; #define PG8_LDA(dst, b, h) do { _Pragma("unroll") for (int m = 0; m < 4; ++m) _Pragma("unroll") for (int k = 0; k < 2; ++k) dst[m][k] = *(const PG8_LAS bf16x8*)(lds + PG8_SA(b, h) + aoff + m * 2048 + k * 1024); } while (0)
; #define PG8_LDB(dst, b, h) do { _Pragma("unroll") for (int n = 0; n < 2; ++n) _Pragma("unroll") for (int k = 0; k < 2; ++k) dst[n][k] = *(const PG8_LAS bf16x8*)(lds + PG8_SB(b, h) + boff + n * 2048 + k * 1024); } while (0)
; #define PG8_WAIT_V(n) asm volatile("s_waitcnt vmcnt(" #n ")" ::: "memory")
; #define PG8_WAIT_L(n) asm volatile("s_waitcnt lgkmcnt(" #n ")" ::: "memory")
; #define PG8_BAR __builtin_amdgcn_s_barrier()
; #define PG8_SCHED __builtin_amdgcn_sched_barrier(0)
; template <class Epi, class Sched, bool ALIGN_EPI = false, bool SP2 = false, bool I8 = false>
; __device__ __forceinline__ void gemm_phase(PG8_LAS unsigned char* lds, const Gemm g, const Sched& S, const Epi& E) {
;     ...
;             PG8_WAIT_V(8); PG8_WAIT_L(0); PG8_BAR; PG8_MMA(0, 0, At, B0); PG8_MMA(0, 1, At, B1); PG8_BAR; PG8_SCHED;
;             PG8_LDA(At, 0, 1); PG8_STAGE(PG8_SB(0, 0), b2, voffB); PG8_STAGE(PG8_SB(0, 1), b2 + hstep, voffB); PG8_STAGE(PG8_SA(0, 0), a2, voffA);
;             PG8_WAIT_V(8); PG8_WAIT_L(0); PG8_BAR; PG8_MMA(1, 0, At, B0); PG8_MMA(1, 1, At, B1); PG8_BAR; PG8_SCHED;
;             PG8_LDB(B0, 1, 0); PG8_LDB(B1, 1, 1); PG8_SCHED; PG8_LDA(At, 1, 0); PG8_STAGE(PG8_SA(0, 1), a2 + hstep, voffA);
;             PG8_WAIT_V(8); PG8_WAIT_L(0); PG8_BAR; PG8_MMA(0, 0, At, B0); PG8_MMA(0, 1, At, B1); PG8_BAR; PG8_SCHED;
	s_waitcnt lgkmcnt(0)
	v_mfma_i32_16x16x64_i8 v[152:155], v[28:31], v[164:167], v[152:155]
	v_mfma_i32_16x16x64_i8 v[152:155], v[32:35], v[168:171], v[152:155]
	v_mfma_i32_16x16x64_i8 v[128:131], v[32:35], v[176:179], v[128:131]
	v_mfma_i32_16x16x64_i8 v[128:131], v[28:31], v[172:175], v[128:131]
	v_mfma_i32_16x16x64_i8 v[112:115], v[28:31], v[204:207], v[112:115]
	v_mfma_i32_16x16x64_i8 v[112:115], v[32:35], v[208:211], v[112:115]
	v_mfma_i32_16x16x64_i8 v[96:99], v[32:35], v[220:223], v[96:99]
	v_mfma_i32_16x16x64_i8 v[96:99], v[28:31], v[212:215], v[96:99]
	v_mfma_i32_16x16x64_i8 v[92:95], v[36:39], v[212:215], v[92:95]
	v_mfma_i32_16x16x64_i8 v[92:95], v[40:43], v[220:223], v[92:95]
	v_mfma_i32_16x16x64_i8 v[108:111], v[40:43], v[208:211], v[108:111]
	v_mfma_i32_16x16x64_i8 v[108:111], v[36:39], v[204:207], v[108:111]
	v_mfma_i32_16x16x64_i8 v[124:127], v[36:39], v[172:175], v[124:127]
	v_mfma_i32_16x16x64_i8 v[124:127], v[40:43], v[176:179], v[124:127]
	v_mfma_i32_16x16x64_i8 v[148:151], v[40:43], v[168:171], v[148:151]
	v_mfma_i32_16x16x64_i8 v[148:151], v[36:39], v[164:167], v[148:151]
	v_mfma_i32_16x16x64_i8 v[136:139], v[140:143], v[164:167], v[136:139]
	v_mfma_i32_16x16x64_i8 v[136:139], v[144:147], v[168:171], v[136:139]
	v_mfma_i32_16x16x64_i8 v[120:123], v[144:147], v[176:179], v[120:123]
	v_mfma_i32_16x16x64_i8 v[120:123], v[140:143], v[172:175], v[120:123]
	v_mfma_i32_16x16x64_i8 v[104:107], v[140:143], v[204:207], v[104:107]
	v_mfma_i32_16x16x64_i8 v[104:107], v[144:147], v[208:211], v[104:107]
	v_mfma_i32_16x16x64_i8 v[88:91], v[144:147], v[220:223], v[88:91]
	v_mfma_i32_16x16x64_i8 v[88:91], v[140:143], v[212:215], v[88:91]
	v_mfma_i32_16x16x64_i8 v[84:87], v[156:159], v[212:215], v[84:87]
	v_mfma_i32_16x16x64_i8 v[84:87], v[160:163], v[220:223], v[84:87]
	v_mfma_i32_16x16x64_i8 v[100:103], v[160:163], v[208:211], v[100:103]
	v_mfma_i32_16x16x64_i8 v[100:103], v[156:159], v[204:207], v[100:103]
	v_mfma_i32_16x16x64_i8 v[116:119], v[156:159], v[172:175], v[116:119]
	v_mfma_i32_16x16x64_i8 v[116:119], v[160:163], v[176:179], v[116:119]
	v_mfma_i32_16x16x64_i8 v[132:135], v[160:163], v[168:171], v[132:135]
	v_mfma_i32_16x16x64_i8 v[132:135], v[156:159], v[164:167], v[132:135]
	s_barrier
	s_add_i32 s87, s87, s46
	v_lshl_add_u64 v[190:191], s[58:59], 0, v[2:3]
	s_mov_b32 m0, s87
	ds_read_b128 v[164:167], v219 offset:16384
	ds_read_b128 v[168:171], v219 offset:17408
	ds_read_b128 v[172:175], v219 offset:18432
	ds_read_b128 v[176:179], v219 offset:19456
	ds_read_b128 v[204:207], v219 offset:20480
	ds_read_b128 v[208:211], v219 offset:21504
	ds_read_b128 v[212:215], v219 offset:22528
	ds_read_b128 v[220:223], v219 offset:23552
	global_load_lds_dwordx4 v[190:191], off
	s_add_i32 m0, s87, 0x2000
	s_add_u32 s96, s58, 0x80000
	v_lshl_add_u64 v[224:225], s[58:59], 0, v[184:185]
	s_addc_u32 s97, s59, 0
	s_add_i32 s87, vcc_lo, s46
	global_load_lds_dwordx4 v[224:225], off
	v_lshl_add_u64 v[226:227], s[96:97], 0, v[2:3]
	s_mov_b32 m0, s87
	v_lshl_add_u64 v[228:229], s[60:61], 0, v[182:183]
	global_load_lds_dwordx4 v[226:227], off
	v_lshl_add_u64 v[226:227], s[96:97], 0, v[184:185]
	s_add_i32 m0, s87, 0x2000
	s_nop 0
	global_load_lds_dwordx4 v[226:227], off
	v_lshl_add_u64 v[226:227], s[60:61], 0, v[180:181]
	s_mov_b32 m0, s65
	s_nop 0
	global_load_lds_dwordx4 v[226:227], off
	s_mov_b32 m0, s67
	s_nop 0
	global_load_lds_dwordx4 v[228:229], off
	s_waitcnt vmcnt(8)
	s_waitcnt lgkmcnt(0)
	s_barrier
	s_waitcnt lgkmcnt(0)
	v_mfma_i32_16x16x64_i8 v[80:83], v[28:31], v[164:167], v[80:83]
	v_mfma_i32_16x16x64_i8 v[80:83], v[32:35], v[168:171], v[80:83]
	v_mfma_i32_16x16x64_i8 v[64:67], v[32:35], v[176:179], v[64:67]
	v_mfma_i32_16x16x64_i8 v[64:67], v[28:31], v[172:175], v[64:67]
	v_mfma_i32_16x16x64_i8 v[48:51], v[28:31], v[204:207], v[48:51]
	v_mfma_i32_16x16x64_i8 v[48:51], v[32:35], v[208:211], v[48:51]
	v_mfma_i32_16x16x64_i8 v[16:19], v[32:35], v[220:223], v[16:19]
	v_mfma_i32_16x16x64_i8 v[16:19], v[28:31], v[212:215], v[16:19]
	v_mfma_i32_16x16x64_i8 v[12:15], v[36:39], v[212:215], v[12:15]
	v_mfma_i32_16x16x64_i8 v[12:15], v[40:43], v[220:223], v[12:15]
	v_mfma_i32_16x16x64_i8 v[44:47], v[40:43], v[208:211], v[44:47]
	v_mfma_i32_16x16x64_i8 v[44:47], v[36:39], v[204:207], v[44:47]
	v_mfma_i32_16x16x64_i8 v[60:63], v[36:39], v[172:175], v[60:63]
	v_mfma_i32_16x16x64_i8 v[60:63], v[40:43], v[176:179], v[60:63]
	v_mfma_i32_16x16x64_i8 v[76:79], v[40:43], v[168:171], v[76:79]
	v_mfma_i32_16x16x64_i8 v[76:79], v[36:39], v[164:167], v[76:79]
	v_mfma_i32_16x16x64_i8 v[28:31], v[140:143], v[164:167], v[72:75]
	v_mfma_i32_16x16x64_i8 v[28:31], v[144:147], v[168:171], v[28:31]
	v_mfma_i32_16x16x64_i8 v[36:39], v[144:147], v[176:179], v[56:59]
	v_mfma_i32_16x16x64_i8 v[36:39], v[140:143], v[172:175], v[36:39]
	v_mfma_i32_16x16x64_i8 v[24:27], v[140:143], v[204:207], v[24:27]
	v_mfma_i32_16x16x64_i8 v[24:27], v[144:147], v[208:211], v[24:27]
	v_mfma_i32_16x16x64_i8 v[8:11], v[144:147], v[220:223], v[8:11]
	v_mfma_i32_16x16x64_i8 v[8:11], v[140:143], v[212:215], v[8:11]
	v_mfma_i32_16x16x64_i8 v[4:7], v[156:159], v[212:215], v[4:7]
	v_mfma_i32_16x16x64_i8 v[4:7], v[160:163], v[220:223], v[4:7]
	v_mfma_i32_16x16x64_i8 v[20:23], v[160:163], v[208:211], v[20:23]
	v_mfma_i32_16x16x64_i8 v[20:23], v[156:159], v[204:207], v[20:23]
	v_mfma_i32_16x16x64_i8 v[40:43], v[156:159], v[172:175], v[52:55]
	v_mfma_i32_16x16x64_i8 v[40:43], v[160:163], v[176:179], v[40:43]
	v_mfma_i32_16x16x64_i8 v[32:35], v[160:163], v[168:171], v[68:71]
	v_mfma_i32_16x16x64_i8 v[32:35], v[156:159], v[164:167], v[32:35]
	s_barrier
; #define PG8_STAGE(bufoff, gbase, voff) do { _Pragma("unroll") for (int _i = 0; _i < 2; ++_i) \
;         __builtin_amdgcn_global_load_lds((const unsigned*)((const char*)(gbase) + (voff)[_i]), (PG8_LAS unsigned*)(lds + (bufoff) + ldsw + _i * 8192), 16, 0, 0); } while (0)
; #define PG8_LDA(dst, b, h) do { _Pragma("unroll") for (int m = 0; m < 4; ++m) _Pragma("unroll") for (int k = 0; k < 2; ++k) dst[m][k] = *(const PG8_LAS bf16x8*)(lds + PG8_SA(b, h) + aoff + m * 2048 + k * 1024); } while (0)
; #define PG8_LDB(dst, b, h) do { _Pragma("unroll") for (int n = 0; n < 2; ++n) _Pragma("unroll") for (int k = 0; k < 2; ++k) dst[n][k] = *(const PG8_LAS bf16x8*)(lds + PG8_SB(b, h) + boff + n * 2048 + k * 1024); } while (0)
; #define PG8_WAIT_V(n) asm volatile("s_waitcnt vmcnt(" #n ")" ::: "memory")
; #define PG8_WAIT_L(n) asm volatile("s_waitcnt lgkmcnt(" #n ")" ::: "memory")
; #define PG8_BAR __builtin_amdgcn_s_barrier()
; #define PG8_SCHED __builtin_amdgcn_sched_barrier(0)
; template <class Epi, class Sched, bool ALIGN_EPI = false, bool SP2 = false, bool I8 = false>
; __device__ __forceinline__ void gemm_phase(PG8_LAS unsigned char* lds, const Gemm g, const Sched& S, const Epi& E) {
;     ...
;             PG8_LDB(B0, 1, 0); PG8_LDB(B1, 1, 1); PG8_SCHED; PG8_LDA(At, 1, 0); PG8_STAGE(PG8_SA(0, 1), a2 + hstep, voffA);
;             PG8_WAIT_V(8); PG8_WAIT_L(0); PG8_BAR; PG8_MMA(0, 0, At, B0); PG8_MMA(0, 1, At, B1); PG8_BAR; PG8_SCHED;
;             PG8_LDA(At, 1, 1); PG8_STAGE(PG8_SB(1, 0), b3, voffB); PG8_STAGE(PG8_SB(1, 1), b3 + hstep, voffB); PG8_STAGE(PG8_SA(1, 0), a3, voffA);
;             PG8_WAIT_V(8); PG8_WAIT_L(0); PG8_BAR; PG8_MMA(1, 0, At, B0); PG8_MMA(1, 1, At, B1); PG8_BAR; PG8_SCHED;
	s_add_i32 s87, 0, 0x18000
	s_add_i32 s96, 0, 0x1c000
	v_add_u32_e32 v72, s87, v217
	v_add_u32_e32 v160, s96, v217
	ds_read_b128 v[52:55], v72
	ds_read_b128 v[56:59], v72 offset:1024
	ds_read_b128 v[68:71], v72 offset:2048
	ds_read_b128 v[72:75], v72 offset:3072
	ds_read_b128 v[140:143], v160
	ds_read_b128 v[144:147], v160 offset:1024
	ds_read_b128 v[156:159], v160 offset:2048
	ds_read_b128 v[160:163], v160 offset:3072
	s_add_u32 s60, s60, 0x80000
	s_addc_u32 s61, s61, 0
	s_mov_b32 m0, s72
	v_lshl_add_u64 v[240:241], s[60:61], 0, v[180:181]
	ds_read_b128 v[164:167], v219 offset:32768
	ds_read_b128 v[168:171], v219 offset:33792
	ds_read_b128 v[172:175], v219 offset:34816
	ds_read_b128 v[176:179], v219 offset:35840
	ds_read_b128 v[204:207], v219 offset:36864
	ds_read_b128 v[208:211], v219 offset:37888
	ds_read_b128 v[212:215], v219 offset:38912
	ds_read_b128 v[220:223], v219 offset:39936
	global_load_lds_dwordx4 v[240:241], off
	v_lshl_add_u64 v[240:241], s[60:61], 0, v[182:183]
	s_mov_b32 m0, s73
	s_nop 0
	global_load_lds_dwordx4 v[240:241], off
	s_waitcnt vmcnt(8)
	s_waitcnt lgkmcnt(0)
	s_barrier
	s_waitcnt lgkmcnt(0)
	v_mfma_i32_16x16x64_i8 v[152:155], v[52:55], v[164:167], v[152:155]
	v_mfma_i32_16x16x64_i8 v[152:155], v[56:59], v[168:171], v[152:155]
	v_mfma_i32_16x16x64_i8 v[128:131], v[56:59], v[176:179], v[128:131]
	v_mfma_i32_16x16x64_i8 v[128:131], v[52:55], v[172:175], v[128:131]
	v_mfma_i32_16x16x64_i8 v[112:115], v[52:55], v[204:207], v[112:115]
	v_mfma_i32_16x16x64_i8 v[112:115], v[56:59], v[208:211], v[112:115]
	v_mfma_i32_16x16x64_i8 v[96:99], v[56:59], v[220:223], v[96:99]
	v_mfma_i32_16x16x64_i8 v[96:99], v[52:55], v[212:215], v[96:99]
	v_mfma_i32_16x16x64_i8 v[92:95], v[68:71], v[212:215], v[92:95]
	v_mfma_i32_16x16x64_i8 v[92:95], v[72:75], v[220:223], v[92:95]
	v_mfma_i32_16x16x64_i8 v[108:111], v[72:75], v[208:211], v[108:111]
	v_mfma_i32_16x16x64_i8 v[108:111], v[68:71], v[204:207], v[108:111]
	v_mfma_i32_16x16x64_i8 v[124:127], v[68:71], v[172:175], v[124:127]
	v_mfma_i32_16x16x64_i8 v[124:127], v[72:75], v[176:179], v[124:127]
	v_mfma_i32_16x16x64_i8 v[148:151], v[72:75], v[168:171], v[148:151]
	v_mfma_i32_16x16x64_i8 v[148:151], v[68:71], v[164:167], v[148:151]
	v_mfma_i32_16x16x64_i8 v[136:139], v[140:143], v[164:167], v[136:139]
	v_mfma_i32_16x16x64_i8 v[136:139], v[144:147], v[168:171], v[136:139]
	v_mfma_i32_16x16x64_i8 v[120:123], v[144:147], v[176:179], v[120:123]
	v_mfma_i32_16x16x64_i8 v[120:123], v[140:143], v[172:175], v[120:123]
	v_mfma_i32_16x16x64_i8 v[104:107], v[140:143], v[204:207], v[104:107]
	v_mfma_i32_16x16x64_i8 v[104:107], v[144:147], v[208:211], v[104:107]
	v_mfma_i32_16x16x64_i8 v[88:91], v[144:147], v[220:223], v[88:91]
	v_mfma_i32_16x16x64_i8 v[88:91], v[140:143], v[212:215], v[88:91]
	v_mfma_i32_16x16x64_i8 v[84:87], v[156:159], v[212:215], v[84:87]
	v_mfma_i32_16x16x64_i8 v[84:87], v[160:163], v[220:223], v[84:87]
	v_mfma_i32_16x16x64_i8 v[100:103], v[160:163], v[208:211], v[100:103]
	v_mfma_i32_16x16x64_i8 v[100:103], v[156:159], v[204:207], v[100:103]
	v_mfma_i32_16x16x64_i8 v[116:119], v[156:159], v[172:175], v[116:119]
	v_mfma_i32_16x16x64_i8 v[116:119], v[160:163], v[176:179], v[116:119]
	v_mfma_i32_16x16x64_i8 v[132:135], v[160:163], v[168:171], v[132:135]
	v_mfma_i32_16x16x64_i8 v[132:135], v[156:159], v[164:167], v[132:135]
	s_barrier
	s_add_i32 s60, s87, s46
	v_lshl_add_u64 v[190:191], v[190:191], 0, s[84:85]
	s_mov_b32 m0, s60
	ds_read_b128 v[164:167], v219 offset:49152
	ds_read_b128 v[168:171], v219 offset:50176
	ds_read_b128 v[172:175], v219 offset:51200
	ds_read_b128 v[176:179], v219 offset:52224
	ds_read_b128 v[204:207], v219 offset:53248
	ds_read_b128 v[208:211], v219 offset:54272
	ds_read_b128 v[212:215], v219 offset:55296
	ds_read_b128 v[220:223], v219 offset:56320
	global_load_lds_dwordx4 v[190:191], off
	s_add_i32 m0, s60, 0x2000
	s_add_u32 s58, s58, 0x80080
	v_lshl_add_u64 v[190:191], v[224:225], 0, s[84:85]
	s_addc_u32 s59, s59, 0
	s_add_i32 s60, s96, s46
	global_load_lds_dwordx4 v[190:191], off
	v_lshl_add_u64 v[190:191], s[58:59], 0, v[2:3]
	s_mov_b32 m0, s60
	s_nop 0
	global_load_lds_dwordx4 v[190:191], off
	v_lshl_add_u64 v[190:191], s[58:59], 0, v[184:185]
	s_add_i32 m0, s60, 0x2000
	s_nop 0
	global_load_lds_dwordx4 v[190:191], off
	v_lshl_add_u64 v[190:191], v[226:227], 0, s[84:85]
	s_mov_b32 m0, s28
	s_nop 0
	global_load_lds_dwordx4 v[190:191], off
	v_lshl_add_u64 v[190:191], v[228:229], 0, s[84:85]
	s_mov_b32 m0, s77
	s_nop 0
	global_load_lds_dwordx4 v[190:191], off
	s_waitcnt vmcnt(8)
	s_waitcnt lgkmcnt(0)
	s_barrier
	s_waitcnt lgkmcnt(0)
	v_mfma_i32_16x16x64_i8 v[80:83], v[52:55], v[164:167], v[80:83]
	v_mfma_i32_16x16x64_i8 v[80:83], v[56:59], v[168:171], v[80:83]
	v_mfma_i32_16x16x64_i8 v[64:67], v[56:59], v[176:179], v[64:67]
	v_mfma_i32_16x16x64_i8 v[64:67], v[52:55], v[172:175], v[64:67]
	v_mfma_i32_16x16x64_i8 v[48:51], v[52:55], v[204:207], v[48:51]
	v_mfma_i32_16x16x64_i8 v[48:51], v[56:59], v[208:211], v[48:51]
	v_mfma_i32_16x16x64_i8 v[16:19], v[56:59], v[220:223], v[16:19]
	v_mfma_i32_16x16x64_i8 v[16:19], v[52:55], v[212:215], v[16:19]
	v_mfma_i32_16x16x64_i8 v[12:15], v[68:71], v[212:215], v[12:15]
	v_mfma_i32_16x16x64_i8 v[12:15], v[72:75], v[220:223], v[12:15]
	v_mfma_i32_16x16x64_i8 v[44:47], v[72:75], v[208:211], v[44:47]
	v_mfma_i32_16x16x64_i8 v[44:47], v[68:71], v[204:207], v[44:47]
	v_mfma_i32_16x16x64_i8 v[60:63], v[68:71], v[172:175], v[60:63]
	v_mfma_i32_16x16x64_i8 v[60:63], v[72:75], v[176:179], v[60:63]
	v_mfma_i32_16x16x64_i8 v[76:79], v[72:75], v[168:171], v[76:79]
	v_mfma_i32_16x16x64_i8 v[76:79], v[68:71], v[164:167], v[76:79]
	v_mfma_i32_16x16x64_i8 v[28:31], v[140:143], v[164:167], v[28:31]
	v_mfma_i32_16x16x64_i8 v[72:75], v[144:147], v[168:171], v[28:31]
	v_mfma_i32_16x16x64_i8 v[28:31], v[144:147], v[176:179], v[36:39]
	v_mfma_i32_16x16x64_i8 v[56:59], v[140:143], v[172:175], v[28:31]
	v_mfma_i32_16x16x64_i8 v[24:27], v[140:143], v[204:207], v[24:27]
	v_mfma_i32_16x16x64_i8 v[24:27], v[144:147], v[208:211], v[24:27]
	v_mfma_i32_16x16x64_i8 v[8:11], v[144:147], v[220:223], v[8:11]
	v_mfma_i32_16x16x64_i8 v[8:11], v[140:143], v[212:215], v[8:11]
	v_mfma_i32_16x16x64_i8 v[4:7], v[156:159], v[212:215], v[4:7]
	v_mfma_i32_16x16x64_i8 v[4:7], v[160:163], v[220:223], v[4:7]
	v_mfma_i32_16x16x64_i8 v[20:23], v[160:163], v[208:211], v[20:23]
	v_mfma_i32_16x16x64_i8 v[20:23], v[156:159], v[204:207], v[20:23]
	v_mfma_i32_16x16x64_i8 v[28:31], v[156:159], v[172:175], v[40:43]
	v_mfma_i32_16x16x64_i8 v[52:55], v[160:163], v[176:179], v[28:31]
	v_mfma_i32_16x16x64_i8 v[28:31], v[160:163], v[168:171], v[32:35]
	v_mfma_i32_16x16x64_i8 v[68:71], v[156:159], v[164:167], v[28:31]
	s_barrier
	s_add_i32 s86, s86, 2
	s_add_u32 s54, s54, 0x100
	s_addc_u32 s55, s55, 0
	s_add_u32 s45, s45, 0x100
	s_addc_u32 s49, s49, 0
	s_cmp_gt_u32 s86, 29
	s_cbranch_scc0 .LBB0_1843
